# speedup vs baseline: 1.0048x; 1.0048x over previous
; #define WAIT_V(n) asm volatile("s_waitcnt vmcnt(%0)" ::"n"(n) : "memory")
; #define WAIT_L(n) asm volatile("s_waitcnt lgkmcnt(%0)" ::"n"(n) : "memory")
; #define SBAR() __builtin_amdgcn_sched_barrier(0)
; #define STAGE(P, base, kt) do { _Pragma("unroll") for (int _i = 0; _i < 2; ++_i)                                        \
;       __builtin_amdgcn_global_load_lds((const unsigned*)((base) + (size_t)(sOff[_i] + (unsigned)(kt) * (BK * 2))),        \
;                                        (unsigned*)((P) + wid * 1024 + _i * 8192), 16, 0, 0); } while (0)
; #define LDA(dst, b, h) _Pragma("unroll") for (int m = 0; m < 4; ++m) _Pragma("unroll") for (int k = 0; k < 2; ++k) \
;       dst[m][k] = *(const bf16x8*)(SA(b, h) + aoff + (m * 2048 + k * 1024))
; #define LDB(dst, b, h) _Pragma("unroll") for (int n = 0; n < 2; ++n) _Pragma("unroll") for (int k = 0; k < 2; ++k) \
;       dst[n][k] = *(const bf16x8*)(SB(b, h) + boff + (n * 256 + k * 1024))
; #define BAR __builtin_amdgcn_s_barrier()
; template <int EPI, int N, int K>
; __device__ __forceinline__ void phase_gemm(const Params& p, const u16* __restrict__ A, const u16* __restrict__ Bt, int nM, char* shm,
;                            u16* __restrict__ outp, float* __restrict__ rowss) {
;     ...
;   for (;;) {
;     const char* A1 = A0 + (size_t)128 * K * 2;
;     const char* B1p = B0p + (size_t)128 * K * 2;
;     f32x4 acc[2][2][4][2] = {};
;     bf16x8 At[4][2], B0[2][2], B1[2][2];
;     if (wr == 1) BAR;
;     WAIT_V(0); BAR;
;     BAR;
;     for (int t = 0; t < nt - 2; t += 2) {
;       LDB(B0, 0, 0); SBAR(); LDA(At, 0, 0); STAGE(SA(1, 1), A1, t + 1);
;       WAIT_L(8); BAR; WAIT_L(0); MMA(0, 0, At, B0); BAR; SBAR();
;       LDB(B1, 0, 1); STAGE(SB(0, 0), B0p, t + 2);
;       BAR; WAIT_L(0); MMA(0, 1, At, B1); BAR;
;       LDA(At, 0, 1); STAGE(SA(0, 0), A0, t + 2);
;       BAR; WAIT_L(0); MMA(1, 0, At, B0); BAR; SBAR();
;       STAGE(SB(0, 1), B1p, t + 2);
;       WAIT_V(6); BAR; MMA(1, 1, At, B1); BAR;
.LBB0_93:
	s_add_u32 s6, s14, 0xb0000
	s_addc_u32 s7, s15, 0
	s_waitcnt vmcnt(0)
	s_add_u32 s22, s12, 0xb0000
	s_addc_u32 s23, s13, 0
	s_mov_b32 s61, -2
	v_mov_b32_e32 v96, v150
	v_mov_b32_e32 v142, v149
	s_waitcnt lgkmcnt(0)
	s_barrier
	s_barrier
	v_or_b32_e32 v143, 0x10000, v146
	v_add_u32_e32 v145, 0x10100, v146
	v_add_u32_e32 v144, 0x10400, v146
	ds_read_b128 v[156:159], v143
	ds_read_b128 v[160:163], v144
	v_add_u32_e32 v151, 0x10500, v146
	ds_read_b128 v[164:167], v145
	ds_read_b128 v[168:171], v151
	v_add_u32_e32 v240, v148, v96
	s_mov_b32 m0, s56
	v_add_u32_e32 v152, 0x80, v240
	v_add_u32_e32 v241, v148, v142
	ds_read_b128 v[172:175], v147
	ds_read_b128 v[176:179], v147 offset:1024
	ds_read_b128 v[180:183], v147 offset:2048
	ds_read_b128 v[196:199], v147 offset:3072
	ds_read_b128 v[200:203], v147 offset:4096
	ds_read_b128 v[204:207], v147 offset:5120
	ds_read_b128 v[208:211], v147 offset:6144
	ds_read_b128 v[212:215], v147 offset:7168
	global_load_lds_dwordx4 v152, s[6:7]
	v_add_u32_e32 v152, 0x80, v241
	s_mov_b32 m0, s57
	s_nop 0
	global_load_lds_dwordx4 v152, s[6:7]
	s_waitcnt lgkmcnt(8)
	s_barrier
	s_waitcnt lgkmcnt(0)
	s_waitcnt lgkmcnt(0)
	v_mfma_f32_16x16x32_bf16 v[126:129], v[156:159], v[172:175], 0
	v_mfma_f32_16x16x32_bf16 v[122:125], v[164:167], v[172:175], 0
	v_mfma_f32_16x16x32_bf16 v[118:121], v[156:159], v[180:183], 0
	v_mfma_f32_16x16x32_bf16 v[114:117], v[164:167], v[180:183], 0
	v_mfma_f32_16x16x32_bf16 v[110:113], v[156:159], v[200:203], 0
	v_mfma_f32_16x16x32_bf16 v[106:109], v[164:167], v[200:203], 0
	v_mfma_f32_16x16x32_bf16 v[102:105], v[156:159], v[208:211], 0
	v_mfma_f32_16x16x32_bf16 v[98:101], v[164:167], v[208:211], 0
	v_mfma_f32_16x16x32_bf16 v[126:129], v[160:163], v[176:179], v[126:129]
	v_mfma_f32_16x16x32_bf16 v[122:125], v[168:171], v[176:179], v[122:125]
	v_mfma_f32_16x16x32_bf16 v[118:121], v[160:163], v[196:199], v[118:121]
	v_mfma_f32_16x16x32_bf16 v[114:117], v[168:171], v[196:199], v[114:117]
	v_mfma_f32_16x16x32_bf16 v[110:113], v[160:163], v[204:207], v[110:113]
	v_mfma_f32_16x16x32_bf16 v[106:109], v[168:171], v[204:207], v[106:109]
	v_mfma_f32_16x16x32_bf16 v[102:105], v[160:163], v[212:215], v[102:105]
	v_mfma_f32_16x16x32_bf16 v[98:101], v[168:171], v[212:215], v[98:101]
	s_barrier
	s_mov_b32 m0, s26
	v_or_b32_e32 v152, 0x14000, v146
	v_add_u32_e32 v154, 0x14100, v146
	v_add_u32_e32 v232, 0x100, v240
	v_add_u32_e32 v153, 0x14400, v146
	ds_read_b128 v[216:219], v152
	ds_read_b128 v[220:223], v153
	v_add_u32_e32 v155, 0x14500, v146
	ds_read_b128 v[224:227], v154
	ds_read_b128 v[228:231], v155
	global_load_lds_dwordx4 v232, s[12:13]
	v_add_u32_e32 v233, 0x100, v241
	s_mov_b32 m0, s27
	s_nop 0
	global_load_lds_dwordx4 v233, s[12:13]
	s_barrier
	s_waitcnt lgkmcnt(0)
	s_waitcnt lgkmcnt(0)
	v_mfma_f32_16x16x32_bf16 v[92:95], v[216:219], v[172:175], 0
	v_mfma_f32_16x16x32_bf16 v[88:91], v[224:227], v[172:175], 0
	v_mfma_f32_16x16x32_bf16 v[84:87], v[216:219], v[180:183], 0
	v_mfma_f32_16x16x32_bf16 v[80:83], v[224:227], v[180:183], 0
	v_mfma_f32_16x16x32_bf16 v[76:79], v[216:219], v[200:203], 0
	v_mfma_f32_16x16x32_bf16 v[72:75], v[224:227], v[200:203], 0
	v_mfma_f32_16x16x32_bf16 v[68:71], v[216:219], v[208:211], 0
	v_mfma_f32_16x16x32_bf16 v[64:67], v[224:227], v[208:211], 0
	v_mfma_f32_16x16x32_bf16 v[92:95], v[220:223], v[176:179], v[92:95]
	v_mfma_f32_16x16x32_bf16 v[88:91], v[228:231], v[176:179], v[88:91]
	v_mfma_f32_16x16x32_bf16 v[84:87], v[220:223], v[196:199], v[84:87]
	v_mfma_f32_16x16x32_bf16 v[80:83], v[228:231], v[196:199], v[80:83]
	v_mfma_f32_16x16x32_bf16 v[76:79], v[220:223], v[204:207], v[76:79]
	v_mfma_f32_16x16x32_bf16 v[72:75], v[228:231], v[204:207], v[72:75]
	v_mfma_f32_16x16x32_bf16 v[68:71], v[220:223], v[212:215], v[68:71]
	v_mfma_f32_16x16x32_bf16 v[64:67], v[228:231], v[212:215], v[64:67]
	s_mov_b32 m0, s5
	s_barrier
	ds_read_b128 v[172:175], v147 offset:16384
	ds_read_b128 v[176:179], v147 offset:17408
	ds_read_b128 v[180:183], v147 offset:18432
	ds_read_b128 v[196:199], v147 offset:19456
	ds_read_b128 v[200:203], v147 offset:20480
	ds_read_b128 v[204:207], v147 offset:21504
	ds_read_b128 v[208:211], v147 offset:22528
	ds_read_b128 v[212:215], v147 offset:23552
	global_load_lds_dwordx4 v232, s[14:15]
	s_mov_b32 m0, s24
	s_nop 0
	global_load_lds_dwordx4 v233, s[14:15]
	s_barrier
	s_waitcnt lgkmcnt(0)
	s_waitcnt lgkmcnt(0)
	v_mfma_f32_16x16x32_bf16 v[60:63], v[156:159], v[172:175], 0
	v_mfma_f32_16x16x32_bf16 v[56:59], v[164:167], v[172:175], 0
	v_mfma_f32_16x16x32_bf16 v[52:55], v[156:159], v[180:183], 0
	v_mfma_f32_16x16x32_bf16 v[48:51], v[164:167], v[180:183], 0
	v_mfma_f32_16x16x32_bf16 v[44:47], v[156:159], v[200:203], 0
	v_mfma_f32_16x16x32_bf16 v[40:43], v[164:167], v[200:203], 0
	v_mfma_f32_16x16x32_bf16 v[36:39], v[156:159], v[208:211], 0
	v_mfma_f32_16x16x32_bf16 v[32:35], v[164:167], v[208:211], 0
	v_mfma_f32_16x16x32_bf16 v[60:63], v[160:163], v[176:179], v[60:63]
	v_mfma_f32_16x16x32_bf16 v[56:59], v[168:171], v[176:179], v[56:59]
	v_mfma_f32_16x16x32_bf16 v[52:55], v[160:163], v[196:199], v[52:55]
	v_mfma_f32_16x16x32_bf16 v[48:51], v[168:171], v[196:199], v[48:51]
	v_mfma_f32_16x16x32_bf16 v[44:47], v[160:163], v[204:207], v[44:47]
	v_mfma_f32_16x16x32_bf16 v[40:43], v[168:171], v[204:207], v[40:43]
	v_mfma_f32_16x16x32_bf16 v[36:39], v[160:163], v[212:215], v[36:39]
	v_mfma_f32_16x16x32_bf16 v[32:35], v[168:171], v[212:215], v[32:35]
	s_barrier
	s_mov_b32 m0, s28
	s_nop 0
	global_load_lds_dwordx4 v232, s[22:23]
	s_mov_b32 m0, s29
	s_nop 0
	global_load_lds_dwordx4 v233, s[22:23]
	s_waitcnt vmcnt(6)
	s_barrier
; #define WAIT_V(n) asm volatile("s_waitcnt vmcnt(%0)" ::"n"(n) : "memory")
; #define WAIT_L(n) asm volatile("s_waitcnt lgkmcnt(%0)" ::"n"(n) : "memory")
; #define SBAR() __builtin_amdgcn_sched_barrier(0)
; #define STAGE(P, base, kt) do { _Pragma("unroll") for (int _i = 0; _i < 2; ++_i)                                        \
;       __builtin_amdgcn_global_load_lds((const unsigned*)((base) + (size_t)(sOff[_i] + (unsigned)(kt) * (BK * 2))),        \
;                                        (unsigned*)((P) + wid * 1024 + _i * 8192), 16, 0, 0); } while (0)
; #define LDA(dst, b, h) _Pragma("unroll") for (int m = 0; m < 4; ++m) _Pragma("unroll") for (int k = 0; k < 2; ++k) \
;       dst[m][k] = *(const bf16x8*)(SA(b, h) + aoff + (m * 2048 + k * 1024))
; #define LDB(dst, b, h) _Pragma("unroll") for (int n = 0; n < 2; ++n) _Pragma("unroll") for (int k = 0; k < 2; ++k) \
;       dst[n][k] = *(const bf16x8*)(SB(b, h) + boff + (n * 256 + k * 1024))
; #define BAR __builtin_amdgcn_s_barrier()
; template <int EPI, int N, int K>
; __device__ __forceinline__ void phase_gemm(const Params& p, const u16* __restrict__ A, const u16* __restrict__ Bt, int nM, char* shm,
;                            u16* __restrict__ outp, float* __restrict__ rowss) {
;     ...
;       WAIT_V(6); BAR; MMA(1, 1, At, B1); BAR;
;       LDB(B0, 1, 0); SBAR(); LDA(At, 1, 0); STAGE(SA(0, 1), A1, t + 2);
;       WAIT_L(8); BAR; WAIT_L(0); MMA(0, 0, At, B0); BAR; SBAR();
;       LDB(B1, 1, 1); STAGE(SB(1, 0), B0p, t + 3);
;       BAR; WAIT_L(0); MMA(0, 1, At, B1); BAR;
;       LDA(At, 1, 1); STAGE(SA(1, 0), A0, t + 3);
;       BAR; WAIT_L(0); MMA(1, 0, At, B0); BAR; SBAR();
	v_mfma_f32_16x16x32_bf16 v[28:31], v[216:219], v[172:175], 0
	v_mfma_f32_16x16x32_bf16 v[24:27], v[224:227], v[172:175], 0
	v_mfma_f32_16x16x32_bf16 v[20:23], v[216:219], v[180:183], 0
	v_mfma_f32_16x16x32_bf16 v[16:19], v[224:227], v[180:183], 0
	v_mfma_f32_16x16x32_bf16 v[12:15], v[216:219], v[200:203], 0
	v_mfma_f32_16x16x32_bf16 v[8:11], v[224:227], v[200:203], 0
	v_mfma_f32_16x16x32_bf16 v[4:7], v[216:219], v[208:211], 0
	v_mfma_f32_16x16x32_bf16 v[0:3], v[224:227], v[208:211], 0
	v_mfma_f32_16x16x32_bf16 v[28:31], v[220:223], v[176:179], v[28:31]
	v_mfma_f32_16x16x32_bf16 v[24:27], v[228:231], v[176:179], v[24:27]
	v_mfma_f32_16x16x32_bf16 v[20:23], v[220:223], v[196:199], v[20:23]
	v_mfma_f32_16x16x32_bf16 v[16:19], v[228:231], v[196:199], v[16:19]
	v_mfma_f32_16x16x32_bf16 v[12:15], v[220:223], v[204:207], v[12:15]
	v_mfma_f32_16x16x32_bf16 v[8:11], v[228:231], v[204:207], v[8:11]
	v_mfma_f32_16x16x32_bf16 v[4:7], v[220:223], v[212:215], v[4:7]
	v_mfma_f32_16x16x32_bf16 v[0:3], v[228:231], v[212:215], v[0:3]
	v_or_b32_e32 v156, 0x18000, v146
	v_add_u32_e32 v158, 0x18100, v146
	s_barrier
	v_add_u32_e32 v157, 0x18400, v146
	ds_read_b128 v[164:167], v156
	ds_read_b128 v[168:171], v157
	v_add_u32_e32 v159, 0x18500, v146
	ds_read_b128 v[172:175], v158
	ds_read_b128 v[176:179], v159
	s_mov_b32 m0, s30
	ds_read_b128 v[180:183], v147 offset:32768
	ds_read_b128 v[196:199], v147 offset:33792
	ds_read_b128 v[200:203], v147 offset:34816
	ds_read_b128 v[204:207], v147 offset:35840
	ds_read_b128 v[208:211], v147 offset:36864
	ds_read_b128 v[212:215], v147 offset:37888
	ds_read_b128 v[216:219], v147 offset:38912
	ds_read_b128 v[220:223], v147 offset:39936
	global_load_lds_dwordx4 v232, s[6:7]
	s_mov_b32 m0, s31
	s_nop 0
	global_load_lds_dwordx4 v233, s[6:7]
	s_waitcnt lgkmcnt(8)
	s_barrier
	s_waitcnt lgkmcnt(0)
	s_waitcnt lgkmcnt(0)
	v_mfma_f32_16x16x32_bf16 v[126:129], v[164:167], v[180:183], v[126:129]
	v_mfma_f32_16x16x32_bf16 v[122:125], v[172:175], v[180:183], v[122:125]
	v_mfma_f32_16x16x32_bf16 v[118:121], v[164:167], v[200:203], v[118:121]
	v_mfma_f32_16x16x32_bf16 v[114:117], v[172:175], v[200:203], v[114:117]
	v_mfma_f32_16x16x32_bf16 v[110:113], v[164:167], v[208:211], v[110:113]
	v_mfma_f32_16x16x32_bf16 v[106:109], v[172:175], v[208:211], v[106:109]
	v_mfma_f32_16x16x32_bf16 v[102:105], v[164:167], v[216:219], v[102:105]
	v_mfma_f32_16x16x32_bf16 v[98:101], v[172:175], v[216:219], v[98:101]
	v_mfma_f32_16x16x32_bf16 v[126:129], v[168:171], v[196:199], v[126:129]
	v_mfma_f32_16x16x32_bf16 v[122:125], v[176:179], v[196:199], v[122:125]
	v_mfma_f32_16x16x32_bf16 v[118:121], v[168:171], v[204:207], v[118:121]
	v_mfma_f32_16x16x32_bf16 v[114:117], v[176:179], v[204:207], v[114:117]
	v_mfma_f32_16x16x32_bf16 v[110:113], v[168:171], v[212:215], v[110:113]
	v_mfma_f32_16x16x32_bf16 v[106:109], v[176:179], v[212:215], v[106:109]
	v_mfma_f32_16x16x32_bf16 v[102:105], v[168:171], v[220:223], v[102:105]
	v_mfma_f32_16x16x32_bf16 v[98:101], v[176:179], v[220:223], v[98:101]
	s_barrier
	s_mov_b32 m0, s33
	v_or_b32_e32 v160, 0x1c000, v146
	v_add_u32_e32 v162, 0x1c100, v146
	v_add_u32_e32 v240, 0x180, v240
	v_add_u32_e32 v161, 0x1c400, v146
	ds_read_b128 v[224:227], v160
	ds_read_b128 v[228:231], v161
	v_add_u32_e32 v163, 0x1c500, v146
	ds_read_b128 v[232:235], v162
	ds_read_b128 v[236:239], v163
	global_load_lds_dwordx4 v240, s[12:13]
	v_add_u32_e32 v241, 0x180, v241
	s_mov_b32 m0, s35
	s_nop 0
	global_load_lds_dwordx4 v241, s[12:13]
	s_barrier
	s_waitcnt lgkmcnt(0)
	s_waitcnt lgkmcnt(0)
	v_mfma_f32_16x16x32_bf16 v[92:95], v[224:227], v[180:183], v[92:95]
	v_mfma_f32_16x16x32_bf16 v[88:91], v[232:235], v[180:183], v[88:91]
	v_mfma_f32_16x16x32_bf16 v[84:87], v[224:227], v[200:203], v[84:87]
	v_mfma_f32_16x16x32_bf16 v[80:83], v[232:235], v[200:203], v[80:83]
	v_mfma_f32_16x16x32_bf16 v[76:79], v[224:227], v[208:211], v[76:79]
	v_mfma_f32_16x16x32_bf16 v[72:75], v[232:235], v[208:211], v[72:75]
	v_mfma_f32_16x16x32_bf16 v[68:71], v[224:227], v[216:219], v[68:71]
	v_mfma_f32_16x16x32_bf16 v[64:67], v[232:235], v[216:219], v[64:67]
	v_mfma_f32_16x16x32_bf16 v[92:95], v[228:231], v[196:199], v[92:95]
	v_mfma_f32_16x16x32_bf16 v[88:91], v[236:239], v[196:199], v[88:91]
	v_mfma_f32_16x16x32_bf16 v[84:87], v[228:231], v[204:207], v[84:87]
	v_mfma_f32_16x16x32_bf16 v[80:83], v[236:239], v[204:207], v[80:83]
	v_mfma_f32_16x16x32_bf16 v[76:79], v[228:231], v[212:215], v[76:79]
	v_mfma_f32_16x16x32_bf16 v[72:75], v[236:239], v[212:215], v[72:75]
	v_mfma_f32_16x16x32_bf16 v[68:71], v[228:231], v[220:223], v[68:71]
	v_mfma_f32_16x16x32_bf16 v[64:67], v[236:239], v[220:223], v[64:67]
	s_mov_b32 m0, s93
	s_barrier
	ds_read_b128 v[180:183], v147 offset:49152
	ds_read_b128 v[196:199], v147 offset:50176
	ds_read_b128 v[200:203], v147 offset:51200
	ds_read_b128 v[204:207], v147 offset:52224
	ds_read_b128 v[208:211], v147 offset:53248
	ds_read_b128 v[212:215], v147 offset:54272
	ds_read_b128 v[216:219], v147 offset:55296
	ds_read_b128 v[220:223], v147 offset:56320
	global_load_lds_dwordx4 v240, s[14:15]
	s_mov_b32 m0, s96
	s_nop 0
	global_load_lds_dwordx4 v241, s[14:15]
	s_barrier
; #define WAIT_V(n) asm volatile("s_waitcnt vmcnt(%0)" ::"n"(n) : "memory")
; #define WAIT_L(n) asm volatile("s_waitcnt lgkmcnt(%0)" ::"n"(n) : "memory")
; #define SBAR() __builtin_amdgcn_sched_barrier(0)
; #define STAGE(P, base, kt) do { _Pragma("unroll") for (int _i = 0; _i < 2; ++_i)                                        \
;       __builtin_amdgcn_global_load_lds((const unsigned*)((base) + (size_t)(sOff[_i] + (unsigned)(kt) * (BK * 2))),        \
;                                        (unsigned*)((P) + wid * 1024 + _i * 8192), 16, 0, 0); } while (0)
; #define LDA(dst, b, h) _Pragma("unroll") for (int m = 0; m < 4; ++m) _Pragma("unroll") for (int k = 0; k < 2; ++k) \
;       dst[m][k] = *(const bf16x8*)(SA(b, h) + aoff + (m * 2048 + k * 1024))
; #define LDB(dst, b, h) _Pragma("unroll") for (int n = 0; n < 2; ++n) _Pragma("unroll") for (int k = 0; k < 2; ++k) \
;       dst[n][k] = *(const bf16x8*)(SB(b, h) + boff + (n * 256 + k * 1024))
; #define BAR __builtin_amdgcn_s_barrier()
; template <int EPI, int N, int K>
; __device__ __forceinline__ void phase_gemm(const Params& p, const u16* __restrict__ A, const u16* __restrict__ Bt, int nM, char* shm,
;                            u16* __restrict__ outp, float* __restrict__ rowss) {
;     ...
;     for (int t = 0; t < nt - 2; t += 2) {
;       LDB(B0, 0, 0); SBAR(); LDA(At, 0, 0); STAGE(SA(1, 1), A1, t + 1);
;       WAIT_L(8); BAR; WAIT_L(0); MMA(0, 0, At, B0); BAR; SBAR();
;       LDB(B1, 0, 1); STAGE(SB(0, 0), B0p, t + 2);
;       BAR; WAIT_L(0); MMA(0, 1, At, B1); BAR;
;       LDA(At, 0, 1); STAGE(SA(0, 0), A0, t + 2);
;     ...
;       BAR; WAIT_L(0); MMA(1, 0, At, B0); BAR; SBAR();
;       STAGE(SB(1, 1), B1p, t + 3);
;       WAIT_V(6); BAR; MMA(1, 1, At, B1); BAR;
	s_waitcnt lgkmcnt(0)
	s_waitcnt lgkmcnt(0)
	v_mfma_f32_16x16x32_bf16 v[60:63], v[164:167], v[180:183], v[60:63]
	v_mfma_f32_16x16x32_bf16 v[56:59], v[172:175], v[180:183], v[56:59]
	v_mfma_f32_16x16x32_bf16 v[52:55], v[164:167], v[200:203], v[52:55]
	v_mfma_f32_16x16x32_bf16 v[48:51], v[172:175], v[200:203], v[48:51]
	v_mfma_f32_16x16x32_bf16 v[44:47], v[164:167], v[208:211], v[44:47]
	v_mfma_f32_16x16x32_bf16 v[40:43], v[172:175], v[208:211], v[40:43]
	v_mfma_f32_16x16x32_bf16 v[36:39], v[164:167], v[216:219], v[36:39]
	v_mfma_f32_16x16x32_bf16 v[32:35], v[172:175], v[216:219], v[32:35]
	v_mfma_f32_16x16x32_bf16 v[60:63], v[168:171], v[196:199], v[60:63]
	v_mfma_f32_16x16x32_bf16 v[56:59], v[176:179], v[196:199], v[56:59]
	v_mfma_f32_16x16x32_bf16 v[52:55], v[168:171], v[204:207], v[52:55]
	v_mfma_f32_16x16x32_bf16 v[48:51], v[176:179], v[204:207], v[48:51]
	v_mfma_f32_16x16x32_bf16 v[44:47], v[168:171], v[212:215], v[44:47]
	v_mfma_f32_16x16x32_bf16 v[40:43], v[176:179], v[212:215], v[40:43]
	v_mfma_f32_16x16x32_bf16 v[36:39], v[168:171], v[220:223], v[36:39]
	v_mfma_f32_16x16x32_bf16 v[32:35], v[176:179], v[220:223], v[32:35]
	s_barrier
	s_mov_b32 m0, s52
	s_nop 0
	global_load_lds_dwordx4 v240, s[22:23]
	s_mov_b32 m0, s53
	s_nop 0
	global_load_lds_dwordx4 v241, s[22:23]
	s_waitcnt vmcnt(6)
	s_barrier
	v_mfma_f32_16x16x32_bf16 v[28:31], v[224:227], v[180:183], v[28:31]
	v_mfma_f32_16x16x32_bf16 v[24:27], v[232:235], v[180:183], v[24:27]
	v_mfma_f32_16x16x32_bf16 v[20:23], v[224:227], v[200:203], v[20:23]
	v_mfma_f32_16x16x32_bf16 v[16:19], v[232:235], v[200:203], v[16:19]
	v_mfma_f32_16x16x32_bf16 v[12:15], v[224:227], v[208:211], v[12:15]
	v_mfma_f32_16x16x32_bf16 v[8:11], v[232:235], v[208:211], v[8:11]
	v_mfma_f32_16x16x32_bf16 v[4:7], v[224:227], v[216:219], v[4:7]
	v_mfma_f32_16x16x32_bf16 v[0:3], v[232:235], v[216:219], v[0:3]
	v_mfma_f32_16x16x32_bf16 v[28:31], v[228:231], v[196:199], v[28:31]
	v_mfma_f32_16x16x32_bf16 v[24:27], v[236:239], v[196:199], v[24:27]
	v_mfma_f32_16x16x32_bf16 v[20:23], v[228:231], v[204:207], v[20:23]
	v_mfma_f32_16x16x32_bf16 v[16:19], v[236:239], v[204:207], v[16:19]
	v_mfma_f32_16x16x32_bf16 v[12:15], v[228:231], v[212:215], v[12:15]
	v_mfma_f32_16x16x32_bf16 v[8:11], v[236:239], v[212:215], v[8:11]
	v_mfma_f32_16x16x32_bf16 v[4:7], v[228:231], v[220:223], v[4:7]
	v_mfma_f32_16x16x32_bf16 v[0:3], v[236:239], v[220:223], v[0:3]
	s_add_i32 s61, s61, 2
	v_add_u32_e32 v142, 0x100, v142
	s_cmp_lt_u32 s61, 40
	v_add_u32_e32 v96, 0x100, v96
	s_barrier
.LBB0_94:
	v_or_b32_e32 v143, 0x10000, v146
	v_add_u32_e32 v145, 0x10100, v146
	v_add_u32_e32 v144, 0x10400, v146
	ds_read_b128 v[156:159], v143
	ds_read_b128 v[160:163], v144
	v_add_u32_e32 v151, 0x10500, v146
	ds_read_b128 v[164:167], v145
	ds_read_b128 v[168:171], v151
	v_add_u32_e32 v240, v148, v96
	s_mov_b32 m0, s56
	v_add_u32_e32 v152, 0x80, v240
	v_add_u32_e32 v241, v148, v142
	ds_read_b128 v[172:175], v147
	ds_read_b128 v[176:179], v147 offset:1024
	ds_read_b128 v[180:183], v147 offset:2048
	ds_read_b128 v[196:199], v147 offset:3072
	ds_read_b128 v[200:203], v147 offset:4096
	ds_read_b128 v[204:207], v147 offset:5120
	ds_read_b128 v[208:211], v147 offset:6144
	ds_read_b128 v[212:215], v147 offset:7168
	global_load_lds_dwordx4 v152, s[6:7]
	v_add_u32_e32 v152, 0x80, v241
	s_mov_b32 m0, s57
	s_nop 0
	global_load_lds_dwordx4 v152, s[6:7]
	s_waitcnt lgkmcnt(8)
	s_barrier
	s_waitcnt lgkmcnt(0)
	s_waitcnt lgkmcnt(0)
	v_mfma_f32_16x16x32_bf16 v[126:129], v[156:159], v[172:175], v[126:129]
	v_mfma_f32_16x16x32_bf16 v[122:125], v[164:167], v[172:175], v[122:125]
	v_mfma_f32_16x16x32_bf16 v[118:121], v[156:159], v[180:183], v[118:121]
	v_mfma_f32_16x16x32_bf16 v[114:117], v[164:167], v[180:183], v[114:117]
	v_mfma_f32_16x16x32_bf16 v[110:113], v[156:159], v[200:203], v[110:113]
	v_mfma_f32_16x16x32_bf16 v[106:109], v[164:167], v[200:203], v[106:109]
	v_mfma_f32_16x16x32_bf16 v[102:105], v[156:159], v[208:211], v[102:105]
	v_mfma_f32_16x16x32_bf16 v[98:101], v[164:167], v[208:211], v[98:101]
	v_mfma_f32_16x16x32_bf16 v[126:129], v[160:163], v[176:179], v[126:129]
	v_mfma_f32_16x16x32_bf16 v[122:125], v[168:171], v[176:179], v[122:125]
	v_mfma_f32_16x16x32_bf16 v[118:121], v[160:163], v[196:199], v[118:121]
	v_mfma_f32_16x16x32_bf16 v[114:117], v[168:171], v[196:199], v[114:117]
	v_mfma_f32_16x16x32_bf16 v[110:113], v[160:163], v[204:207], v[110:113]
	v_mfma_f32_16x16x32_bf16 v[106:109], v[168:171], v[204:207], v[106:109]
	v_mfma_f32_16x16x32_bf16 v[102:105], v[160:163], v[212:215], v[102:105]
	v_mfma_f32_16x16x32_bf16 v[98:101], v[168:171], v[212:215], v[98:101]
	s_barrier
	s_mov_b32 m0, s26
	v_or_b32_e32 v152, 0x14000, v146
	v_add_u32_e32 v154, 0x14100, v146
	v_add_u32_e32 v232, 0x100, v240
	v_add_u32_e32 v153, 0x14400, v146
	ds_read_b128 v[216:219], v152
	ds_read_b128 v[220:223], v153
	v_add_u32_e32 v155, 0x14500, v146
	ds_read_b128 v[224:227], v154
	ds_read_b128 v[228:231], v155
	global_load_lds_dwordx4 v232, s[12:13]
	v_add_u32_e32 v233, 0x100, v241
	s_mov_b32 m0, s27
	s_nop 0
	global_load_lds_dwordx4 v233, s[12:13]
	s_barrier
; #define WAIT_V(n) asm volatile("s_waitcnt vmcnt(%0)" ::"n"(n) : "memory")
; #define WAIT_L(n) asm volatile("s_waitcnt lgkmcnt(%0)" ::"n"(n) : "memory")
; #define SBAR() __builtin_amdgcn_sched_barrier(0)
; #define STAGE(P, base, kt) do { _Pragma("unroll") for (int _i = 0; _i < 2; ++_i)                                        \
;       __builtin_amdgcn_global_load_lds((const unsigned*)((base) + (size_t)(sOff[_i] + (unsigned)(kt) * (BK * 2))),        \
;                                        (unsigned*)((P) + wid * 1024 + _i * 8192), 16, 0, 0); } while (0)
; #define LDA(dst, b, h) _Pragma("unroll") for (int m = 0; m < 4; ++m) _Pragma("unroll") for (int k = 0; k < 2; ++k) \
;       dst[m][k] = *(const bf16x8*)(SA(b, h) + aoff + (m * 2048 + k * 1024))
; #define LDB(dst, b, h) _Pragma("unroll") for (int n = 0; n < 2; ++n) _Pragma("unroll") for (int k = 0; k < 2; ++k) \
;       dst[n][k] = *(const bf16x8*)(SB(b, h) + boff + (n * 256 + k * 1024))
; #define BAR __builtin_amdgcn_s_barrier()
; template <int EPI, int N, int K>
; __device__ __forceinline__ void phase_gemm(const Params& p, const u16* __restrict__ A, const u16* __restrict__ Bt, int nM, char* shm,
;                            u16* __restrict__ outp, float* __restrict__ rowss) {
;     ...
;       BAR; WAIT_L(0); MMA(1, 0, At, B0); BAR; SBAR();
;       STAGE(SB(0, 1), B1p, t + 2);
;       WAIT_V(6); BAR; MMA(1, 1, At, B1); BAR;
;       LDB(B0, 1, 0); SBAR(); LDA(At, 1, 0); STAGE(SA(0, 1), A1, t + 2);
;       WAIT_L(8); BAR; WAIT_L(0); MMA(0, 0, At, B0); BAR; SBAR();
	s_waitcnt lgkmcnt(0)
	s_waitcnt lgkmcnt(0)
	v_mfma_f32_16x16x32_bf16 v[92:95], v[216:219], v[172:175], v[92:95]
	v_mfma_f32_16x16x32_bf16 v[88:91], v[224:227], v[172:175], v[88:91]
	v_mfma_f32_16x16x32_bf16 v[84:87], v[216:219], v[180:183], v[84:87]
	v_mfma_f32_16x16x32_bf16 v[80:83], v[224:227], v[180:183], v[80:83]
	v_mfma_f32_16x16x32_bf16 v[76:79], v[216:219], v[200:203], v[76:79]
	v_mfma_f32_16x16x32_bf16 v[72:75], v[224:227], v[200:203], v[72:75]
	v_mfma_f32_16x16x32_bf16 v[68:71], v[216:219], v[208:211], v[68:71]
	v_mfma_f32_16x16x32_bf16 v[64:67], v[224:227], v[208:211], v[64:67]
	v_mfma_f32_16x16x32_bf16 v[92:95], v[220:223], v[176:179], v[92:95]
	v_mfma_f32_16x16x32_bf16 v[88:91], v[228:231], v[176:179], v[88:91]
	v_mfma_f32_16x16x32_bf16 v[84:87], v[220:223], v[196:199], v[84:87]
	v_mfma_f32_16x16x32_bf16 v[80:83], v[228:231], v[196:199], v[80:83]
	v_mfma_f32_16x16x32_bf16 v[76:79], v[220:223], v[204:207], v[76:79]
	v_mfma_f32_16x16x32_bf16 v[72:75], v[228:231], v[204:207], v[72:75]
	v_mfma_f32_16x16x32_bf16 v[68:71], v[220:223], v[212:215], v[68:71]
	v_mfma_f32_16x16x32_bf16 v[64:67], v[228:231], v[212:215], v[64:67]
	s_mov_b32 m0, s5
	s_barrier
	ds_read_b128 v[172:175], v147 offset:16384
	ds_read_b128 v[176:179], v147 offset:17408
	ds_read_b128 v[180:183], v147 offset:18432
	ds_read_b128 v[196:199], v147 offset:19456
	ds_read_b128 v[200:203], v147 offset:20480
	ds_read_b128 v[204:207], v147 offset:21504
	ds_read_b128 v[208:211], v147 offset:22528
	ds_read_b128 v[212:215], v147 offset:23552
	global_load_lds_dwordx4 v232, s[14:15]
	s_mov_b32 m0, s24
	s_nop 0
	global_load_lds_dwordx4 v233, s[14:15]
	s_barrier
	s_waitcnt lgkmcnt(0)
	s_waitcnt lgkmcnt(0)
	v_mfma_f32_16x16x32_bf16 v[60:63], v[156:159], v[172:175], v[60:63]
	v_mfma_f32_16x16x32_bf16 v[56:59], v[164:167], v[172:175], v[56:59]
	v_mfma_f32_16x16x32_bf16 v[52:55], v[156:159], v[180:183], v[52:55]
	v_mfma_f32_16x16x32_bf16 v[48:51], v[164:167], v[180:183], v[48:51]
	v_mfma_f32_16x16x32_bf16 v[44:47], v[156:159], v[200:203], v[44:47]
	v_mfma_f32_16x16x32_bf16 v[40:43], v[164:167], v[200:203], v[40:43]
	v_mfma_f32_16x16x32_bf16 v[36:39], v[156:159], v[208:211], v[36:39]
	v_mfma_f32_16x16x32_bf16 v[32:35], v[164:167], v[208:211], v[32:35]
	v_mfma_f32_16x16x32_bf16 v[60:63], v[160:163], v[176:179], v[60:63]
	v_mfma_f32_16x16x32_bf16 v[56:59], v[168:171], v[176:179], v[56:59]
	v_mfma_f32_16x16x32_bf16 v[52:55], v[160:163], v[196:199], v[52:55]
	v_mfma_f32_16x16x32_bf16 v[48:51], v[168:171], v[196:199], v[48:51]
	v_mfma_f32_16x16x32_bf16 v[44:47], v[160:163], v[204:207], v[44:47]
	v_mfma_f32_16x16x32_bf16 v[40:43], v[168:171], v[204:207], v[40:43]
	v_mfma_f32_16x16x32_bf16 v[36:39], v[160:163], v[212:215], v[36:39]
	v_mfma_f32_16x16x32_bf16 v[32:35], v[168:171], v[212:215], v[32:35]
	s_barrier
	s_mov_b32 m0, s28
	s_nop 0
	global_load_lds_dwordx4 v232, s[22:23]
	s_mov_b32 m0, s29
	s_nop 0
	global_load_lds_dwordx4 v233, s[22:23]
	s_waitcnt vmcnt(6)
	s_barrier
	v_mfma_f32_16x16x32_bf16 v[28:31], v[216:219], v[172:175], v[28:31]
	v_mfma_f32_16x16x32_bf16 v[24:27], v[224:227], v[172:175], v[24:27]
	v_mfma_f32_16x16x32_bf16 v[20:23], v[216:219], v[180:183], v[20:23]
	v_mfma_f32_16x16x32_bf16 v[16:19], v[224:227], v[180:183], v[16:19]
	v_mfma_f32_16x16x32_bf16 v[12:15], v[216:219], v[200:203], v[12:15]
	v_mfma_f32_16x16x32_bf16 v[8:11], v[224:227], v[200:203], v[8:11]
	v_mfma_f32_16x16x32_bf16 v[4:7], v[216:219], v[208:211], v[4:7]
	v_mfma_f32_16x16x32_bf16 v[0:3], v[224:227], v[208:211], v[0:3]
	v_mfma_f32_16x16x32_bf16 v[28:31], v[220:223], v[176:179], v[28:31]
	v_mfma_f32_16x16x32_bf16 v[24:27], v[228:231], v[176:179], v[24:27]
	v_mfma_f32_16x16x32_bf16 v[20:23], v[220:223], v[196:199], v[20:23]
	v_mfma_f32_16x16x32_bf16 v[16:19], v[228:231], v[196:199], v[16:19]
	v_mfma_f32_16x16x32_bf16 v[12:15], v[220:223], v[204:207], v[12:15]
	v_mfma_f32_16x16x32_bf16 v[8:11], v[228:231], v[204:207], v[8:11]
	v_mfma_f32_16x16x32_bf16 v[4:7], v[220:223], v[212:215], v[4:7]
	v_mfma_f32_16x16x32_bf16 v[0:3], v[228:231], v[212:215], v[0:3]
	v_or_b32_e32 v156, 0x18000, v146
	v_add_u32_e32 v158, 0x18100, v146
	s_barrier
	v_add_u32_e32 v157, 0x18400, v146
	ds_read_b128 v[164:167], v156
	ds_read_b128 v[168:171], v157
	v_add_u32_e32 v159, 0x18500, v146
	ds_read_b128 v[172:175], v158
	ds_read_b128 v[176:179], v159
	s_mov_b32 m0, s30
	ds_read_b128 v[180:183], v147 offset:32768
	ds_read_b128 v[196:199], v147 offset:33792
	ds_read_b128 v[200:203], v147 offset:34816
	ds_read_b128 v[204:207], v147 offset:35840
	ds_read_b128 v[208:211], v147 offset:36864
	ds_read_b128 v[212:215], v147 offset:37888
	ds_read_b128 v[216:219], v147 offset:38912
	ds_read_b128 v[220:223], v147 offset:39936
	global_load_lds_dwordx4 v232, s[6:7]
	s_mov_b32 m0, s31
	s_nop 0
	global_load_lds_dwordx4 v233, s[6:7]
	s_waitcnt lgkmcnt(8)
	s_barrier
	s_waitcnt lgkmcnt(0)
	s_waitcnt lgkmcnt(0)
	v_mfma_f32_16x16x32_bf16 v[126:129], v[164:167], v[180:183], v[126:129]
	v_mfma_f32_16x16x32_bf16 v[122:125], v[172:175], v[180:183], v[122:125]
	v_mfma_f32_16x16x32_bf16 v[118:121], v[164:167], v[200:203], v[118:121]
	v_mfma_f32_16x16x32_bf16 v[114:117], v[172:175], v[200:203], v[114:117]
	v_mfma_f32_16x16x32_bf16 v[110:113], v[164:167], v[208:211], v[110:113]
	v_mfma_f32_16x16x32_bf16 v[106:109], v[172:175], v[208:211], v[106:109]
	v_mfma_f32_16x16x32_bf16 v[102:105], v[164:167], v[216:219], v[102:105]
	v_mfma_f32_16x16x32_bf16 v[98:101], v[172:175], v[216:219], v[98:101]
	v_mfma_f32_16x16x32_bf16 v[126:129], v[168:171], v[196:199], v[126:129]
	v_mfma_f32_16x16x32_bf16 v[122:125], v[176:179], v[196:199], v[122:125]
	v_mfma_f32_16x16x32_bf16 v[118:121], v[168:171], v[204:207], v[118:121]
	v_mfma_f32_16x16x32_bf16 v[114:117], v[176:179], v[204:207], v[114:117]
	v_mfma_f32_16x16x32_bf16 v[110:113], v[168:171], v[212:215], v[110:113]
	v_mfma_f32_16x16x32_bf16 v[106:109], v[176:179], v[212:215], v[106:109]
	v_mfma_f32_16x16x32_bf16 v[102:105], v[168:171], v[220:223], v[102:105]
	v_mfma_f32_16x16x32_bf16 v[98:101], v[176:179], v[220:223], v[98:101]
	s_barrier
; #define WAIT_V(n) asm volatile("s_waitcnt vmcnt(%0)" ::"n"(n) : "memory")
; #define WAIT_L(n) asm volatile("s_waitcnt lgkmcnt(%0)" ::"n"(n) : "memory")
; #define SBAR() __builtin_amdgcn_sched_barrier(0)
; #define STAGE(P, base, kt) do { _Pragma("unroll") for (int _i = 0; _i < 2; ++_i)                                        \
;       __builtin_amdgcn_global_load_lds((const unsigned*)((base) + (size_t)(sOff[_i] + (unsigned)(kt) * (BK * 2))),        \
;                                        (unsigned*)((P) + wid * 1024 + _i * 8192), 16, 0, 0); } while (0)
; #define LDA(dst, b, h) _Pragma("unroll") for (int m = 0; m < 4; ++m) _Pragma("unroll") for (int k = 0; k < 2; ++k) \
;       dst[m][k] = *(const bf16x8*)(SA(b, h) + aoff + (m * 2048 + k * 1024))
; #define LDB(dst, b, h) _Pragma("unroll") for (int n = 0; n < 2; ++n) _Pragma("unroll") for (int k = 0; k < 2; ++k) \
;       dst[n][k] = *(const bf16x8*)(SB(b, h) + boff + (n * 256 + k * 1024))
; #define BAR __builtin_amdgcn_s_barrier()
; template <int EPI, int N, int K>
; __device__ __forceinline__ void phase_gemm(const Params& p, const u16* __restrict__ A, const u16* __restrict__ Bt, int nM, char* shm,
;                            u16* __restrict__ outp, float* __restrict__ rowss) {
;     ...
;       LDB(B1, 1, 1); STAGE(SB(1, 0), B0p, t + 3);
;       BAR; WAIT_L(0); MMA(0, 1, At, B1); BAR;
;       LDA(At, 1, 1); STAGE(SA(1, 0), A0, t + 3);
;       BAR; WAIT_L(0); MMA(1, 0, At, B0); BAR; SBAR();
;       STAGE(SB(1, 1), B1p, t + 3);
;       WAIT_V(6); BAR; MMA(1, 1, At, B1); BAR;
;     }
;     { LDB(B0, 0, 0); LDA(At, 0, 0); STAGE(SA(1, 1), A1, nt - 1);
	s_mov_b32 m0, s33
	v_or_b32_e32 v160, 0x1c000, v146
	v_add_u32_e32 v162, 0x1c100, v146
	v_add_u32_e32 v240, 0x180, v240
	v_add_u32_e32 v161, 0x1c400, v146
	ds_read_b128 v[224:227], v160
	ds_read_b128 v[228:231], v161
	v_add_u32_e32 v163, 0x1c500, v146
	ds_read_b128 v[232:235], v162
	ds_read_b128 v[236:239], v163
	global_load_lds_dwordx4 v240, s[12:13]
	v_add_u32_e32 v241, 0x180, v241
	s_mov_b32 m0, s35
	s_nop 0
	global_load_lds_dwordx4 v241, s[12:13]
	s_barrier
	s_waitcnt lgkmcnt(0)
	s_waitcnt lgkmcnt(0)
	v_mfma_f32_16x16x32_bf16 v[92:95], v[224:227], v[180:183], v[92:95]
	v_mfma_f32_16x16x32_bf16 v[88:91], v[232:235], v[180:183], v[88:91]
	v_mfma_f32_16x16x32_bf16 v[84:87], v[224:227], v[200:203], v[84:87]
	v_mfma_f32_16x16x32_bf16 v[80:83], v[232:235], v[200:203], v[80:83]
	v_mfma_f32_16x16x32_bf16 v[76:79], v[224:227], v[208:211], v[76:79]
	v_mfma_f32_16x16x32_bf16 v[72:75], v[232:235], v[208:211], v[72:75]
	v_mfma_f32_16x16x32_bf16 v[68:71], v[224:227], v[216:219], v[68:71]
	v_mfma_f32_16x16x32_bf16 v[64:67], v[232:235], v[216:219], v[64:67]
	v_mfma_f32_16x16x32_bf16 v[92:95], v[228:231], v[196:199], v[92:95]
	v_mfma_f32_16x16x32_bf16 v[88:91], v[236:239], v[196:199], v[88:91]
	v_mfma_f32_16x16x32_bf16 v[84:87], v[228:231], v[204:207], v[84:87]
	v_mfma_f32_16x16x32_bf16 v[80:83], v[236:239], v[204:207], v[80:83]
	v_mfma_f32_16x16x32_bf16 v[76:79], v[228:231], v[212:215], v[76:79]
	v_mfma_f32_16x16x32_bf16 v[72:75], v[236:239], v[212:215], v[72:75]
	v_mfma_f32_16x16x32_bf16 v[68:71], v[228:231], v[220:223], v[68:71]
	v_mfma_f32_16x16x32_bf16 v[64:67], v[236:239], v[220:223], v[64:67]
	s_mov_b32 m0, s93
	s_barrier
	ds_read_b128 v[180:183], v147 offset:49152
	ds_read_b128 v[196:199], v147 offset:50176
	ds_read_b128 v[200:203], v147 offset:51200
	ds_read_b128 v[204:207], v147 offset:52224
	ds_read_b128 v[208:211], v147 offset:53248
	ds_read_b128 v[212:215], v147 offset:54272
	ds_read_b128 v[216:219], v147 offset:55296
	ds_read_b128 v[220:223], v147 offset:56320
	global_load_lds_dwordx4 v240, s[14:15]
	s_mov_b32 m0, s96
	s_nop 0
	global_load_lds_dwordx4 v241, s[14:15]
	s_barrier
	s_waitcnt lgkmcnt(0)
	s_waitcnt lgkmcnt(0)
	v_mfma_f32_16x16x32_bf16 v[60:63], v[164:167], v[180:183], v[60:63]
	v_mfma_f32_16x16x32_bf16 v[56:59], v[172:175], v[180:183], v[56:59]
	v_mfma_f32_16x16x32_bf16 v[52:55], v[164:167], v[200:203], v[52:55]
	v_mfma_f32_16x16x32_bf16 v[48:51], v[172:175], v[200:203], v[48:51]
	v_mfma_f32_16x16x32_bf16 v[44:47], v[164:167], v[208:211], v[44:47]
	v_mfma_f32_16x16x32_bf16 v[40:43], v[172:175], v[208:211], v[40:43]
	v_mfma_f32_16x16x32_bf16 v[36:39], v[164:167], v[216:219], v[36:39]
	v_mfma_f32_16x16x32_bf16 v[32:35], v[172:175], v[216:219], v[32:35]
	v_mfma_f32_16x16x32_bf16 v[60:63], v[168:171], v[196:199], v[60:63]
	v_mfma_f32_16x16x32_bf16 v[56:59], v[176:179], v[196:199], v[56:59]
	v_mfma_f32_16x16x32_bf16 v[52:55], v[168:171], v[204:207], v[52:55]
	v_mfma_f32_16x16x32_bf16 v[48:51], v[176:179], v[204:207], v[48:51]
	v_mfma_f32_16x16x32_bf16 v[44:47], v[168:171], v[212:215], v[44:47]
	v_mfma_f32_16x16x32_bf16 v[40:43], v[176:179], v[212:215], v[40:43]
	v_mfma_f32_16x16x32_bf16 v[36:39], v[168:171], v[220:223], v[36:39]
	v_mfma_f32_16x16x32_bf16 v[32:35], v[176:179], v[220:223], v[32:35]
	s_barrier
	s_mov_b32 m0, s52
	s_nop 0
	global_load_lds_dwordx4 v240, s[22:23]
	s_mov_b32 m0, s53
	s_nop 0
	global_load_lds_dwordx4 v241, s[22:23]
	s_waitcnt vmcnt(6)
	s_barrier
	v_mfma_f32_16x16x32_bf16 v[28:31], v[224:227], v[180:183], v[28:31]
	v_mfma_f32_16x16x32_bf16 v[24:27], v[232:235], v[180:183], v[24:27]
	v_mfma_f32_16x16x32_bf16 v[20:23], v[224:227], v[200:203], v[20:23]
	v_mfma_f32_16x16x32_bf16 v[16:19], v[232:235], v[200:203], v[16:19]
	v_mfma_f32_16x16x32_bf16 v[12:15], v[224:227], v[208:211], v[12:15]
	v_mfma_f32_16x16x32_bf16 v[8:11], v[232:235], v[208:211], v[8:11]
	v_mfma_f32_16x16x32_bf16 v[4:7], v[224:227], v[216:219], v[4:7]
	v_mfma_f32_16x16x32_bf16 v[0:3], v[232:235], v[216:219], v[0:3]
	v_mfma_f32_16x16x32_bf16 v[28:31], v[228:231], v[196:199], v[28:31]
	v_mfma_f32_16x16x32_bf16 v[24:27], v[236:239], v[196:199], v[24:27]
	v_mfma_f32_16x16x32_bf16 v[20:23], v[228:231], v[204:207], v[20:23]
	v_mfma_f32_16x16x32_bf16 v[16:19], v[236:239], v[204:207], v[16:19]
	v_mfma_f32_16x16x32_bf16 v[12:15], v[228:231], v[212:215], v[12:15]
	v_mfma_f32_16x16x32_bf16 v[8:11], v[236:239], v[212:215], v[8:11]
	v_mfma_f32_16x16x32_bf16 v[4:7], v[228:231], v[220:223], v[4:7]
	v_mfma_f32_16x16x32_bf16 v[0:3], v[236:239], v[220:223], v[0:3]
	s_add_i32 s61, s61, 2
	v_add_u32_e32 v142, 0x100, v142
	s_cmp_lt_u32 s61, 40
	v_add_u32_e32 v96, 0x100, v96
	s_barrier
	s_cbranch_scc1 .LBB0_94
	s_mov_b32 m0, s56
	v_lshl_add_u64 v[220:221], s[6:7], 0, v[138:139]
	ds_read_b128 v[164:167], v143
	ds_read_b128 v[168:171], v144
	ds_read_b128 v[142:145], v145
	ds_read_b128 v[172:175], v151
	ds_read_b128 v[176:179], v147
	ds_read_b128 v[180:183], v147 offset:1024
	ds_read_b128 v[196:199], v147 offset:2048
	ds_read_b128 v[200:203], v147 offset:3072
	ds_read_b128 v[204:207], v147 offset:4096
	ds_read_b128 v[208:211], v147 offset:5120
	ds_read_b128 v[212:215], v147 offset:6144
	ds_read_b128 v[216:219], v147 offset:7168
	global_load_lds_dwordx4 v[220:221], off
	v_lshl_add_u64 v[220:221], s[6:7], 0, v[140:141]
	s_mov_b32 m0, s57
	s_nop 0
	global_load_lds_dwordx4 v[220:221], off
	s_barrier
; #define WAIT_V(n) asm volatile("s_waitcnt vmcnt(%0)" ::"n"(n) : "memory")
; #define WAIT_L(n) asm volatile("s_waitcnt lgkmcnt(%0)" ::"n"(n) : "memory")
; #define STAGE(P, base, kt) do { _Pragma("unroll") for (int _i = 0; _i < 2; ++_i)                                        \
;       __builtin_amdgcn_global_load_lds((const unsigned*)((base) + (size_t)(sOff[_i] + (unsigned)(kt) * (BK * 2))),        \
;                                        (unsigned*)((P) + wid * 1024 + _i * 8192), 16, 0, 0); } while (0)
; #define LDA(dst, b, h) _Pragma("unroll") for (int m = 0; m < 4; ++m) _Pragma("unroll") for (int k = 0; k < 2; ++k) \
;       dst[m][k] = *(const bf16x8*)(SA(b, h) + aoff + (m * 2048 + k * 1024))
; #define LDB(dst, b, h) _Pragma("unroll") for (int n = 0; n < 2; ++n) _Pragma("unroll") for (int k = 0; k < 2; ++k) \
;       dst[n][k] = *(const bf16x8*)(SB(b, h) + boff + (n * 256 + k * 1024))
; #define BAR __builtin_amdgcn_s_barrier()
; template <int EPI, int N, int K>
; __device__ __forceinline__ void phase_gemm(const Params& p, const u16* __restrict__ A, const u16* __restrict__ Bt, int nM, char* shm,
;                            u16* __restrict__ outp, float* __restrict__ rowss) {
;     ...
;     { LDB(B0, 0, 0); LDA(At, 0, 0); STAGE(SA(1, 1), A1, nt - 1);
;       BAR; WAIT_L(0); MMA(0, 0, At, B0); BAR;
;       LDB(B1, 0, 1); BAR; WAIT_L(0); MMA(0, 1, At, B1); BAR;
;       LDA(At, 0, 1); WAIT_V(4); BAR; WAIT_L(0); MMA(1, 0, At, B0); MMA(1, 1, At, B1); BAR; }
;     { LDB(B0, 1, 0); LDA(At, 1, 0); WAIT_V(2); BAR; WAIT_L(0); MMA(0, 0, At, B0); BAR;
;       LDB(B1, 1, 1); WAIT_V(0); BAR; WAIT_L(0); MMA(0, 1, At, B1); BAR;
	s_waitcnt lgkmcnt(0)
	s_waitcnt lgkmcnt(0)
	v_mfma_f32_16x16x32_bf16 v[126:129], v[164:167], v[176:179], v[126:129]
	v_mfma_f32_16x16x32_bf16 v[122:125], v[142:145], v[176:179], v[122:125]
	v_mfma_f32_16x16x32_bf16 v[118:121], v[164:167], v[196:199], v[118:121]
	v_mfma_f32_16x16x32_bf16 v[102:105], v[164:167], v[212:215], v[102:105]
	v_mfma_f32_16x16x32_bf16 v[98:101], v[142:145], v[212:215], v[98:101]
	v_mfma_f32_16x16x32_bf16 v[126:129], v[168:171], v[180:183], v[126:129]
	v_mfma_f32_16x16x32_bf16 v[122:125], v[172:175], v[180:183], v[122:125]
	v_mfma_f32_16x16x32_bf16 v[118:121], v[168:171], v[200:203], v[118:121]
	v_mfma_f32_16x16x32_bf16 v[114:117], v[142:145], v[196:199], v[114:117]
	v_mfma_f32_16x16x32_bf16 v[110:113], v[164:167], v[204:207], v[110:113]
	v_mfma_f32_16x16x32_bf16 v[106:109], v[142:145], v[204:207], v[106:109]
	v_mfma_f32_16x16x32_bf16 v[102:105], v[168:171], v[216:219], v[102:105]
	v_mfma_f32_16x16x32_bf16 v[98:101], v[172:175], v[216:219], v[98:101]
	v_mfma_f32_16x16x32_bf16 v[220:223], v[172:175], v[200:203], v[114:117]
	v_mfma_f32_16x16x32_bf16 v[224:227], v[168:171], v[208:211], v[110:113]
	v_mfma_f32_16x16x32_bf16 v[228:231], v[172:175], v[208:211], v[106:109]
	s_barrier
	s_nop 0
	ds_read_b128 v[106:109], v152
	ds_read_b128 v[110:113], v153
	ds_read_b128 v[114:117], v154
	ds_read_b128 v[152:155], v155
	s_barrier
	s_waitcnt lgkmcnt(0)
	s_waitcnt lgkmcnt(0)
	v_mfma_f32_16x16x32_bf16 v[84:87], v[106:109], v[196:199], v[84:87]
	v_mfma_f32_16x16x32_bf16 v[80:83], v[114:117], v[196:199], v[80:83]
	v_mfma_f32_16x16x32_bf16 v[68:71], v[106:109], v[212:215], v[68:71]
	v_mfma_f32_16x16x32_bf16 v[92:95], v[106:109], v[176:179], v[92:95]
	v_mfma_f32_16x16x32_bf16 v[88:91], v[114:117], v[176:179], v[88:91]
	v_mfma_f32_16x16x32_bf16 v[84:87], v[110:113], v[200:203], v[84:87]
	v_mfma_f32_16x16x32_bf16 v[80:83], v[152:155], v[200:203], v[80:83]
	v_mfma_f32_16x16x32_bf16 v[76:79], v[106:109], v[204:207], v[76:79]
	v_mfma_f32_16x16x32_bf16 v[72:75], v[114:117], v[204:207], v[72:75]
	v_mfma_f32_16x16x32_bf16 v[68:71], v[110:113], v[216:219], v[68:71]
	v_mfma_f32_16x16x32_bf16 v[64:67], v[114:117], v[212:215], v[64:67]
	v_mfma_f32_16x16x32_bf16 v[232:235], v[110:113], v[180:183], v[92:95]
	v_mfma_f32_16x16x32_bf16 v[176:179], v[152:155], v[180:183], v[88:91]
	v_mfma_f32_16x16x32_bf16 v[180:183], v[110:113], v[208:211], v[76:79]
	v_mfma_f32_16x16x32_bf16 v[196:199], v[152:155], v[208:211], v[72:75]
	v_mfma_f32_16x16x32_bf16 v[200:203], v[152:155], v[216:219], v[64:67]
	s_barrier
	s_nop 0
	ds_read_b128 v[64:67], v147 offset:16384
	ds_read_b128 v[72:75], v147 offset:17408
	ds_read_b128 v[76:79], v147 offset:18432
	ds_read_b128 v[88:91], v147 offset:19456
	ds_read_b128 v[92:95], v147 offset:20480
	ds_read_b128 v[204:207], v147 offset:21504
	ds_read_b128 v[208:211], v147 offset:22528
	ds_read_b128 v[212:215], v147 offset:23552
	s_waitcnt vmcnt(4)
	s_barrier
	s_waitcnt lgkmcnt(0)
	s_waitcnt lgkmcnt(0)
	v_mfma_f32_16x16x32_bf16 v[60:63], v[164:167], v[64:67], v[60:63]
	v_mfma_f32_16x16x32_bf16 v[52:55], v[164:167], v[76:79], v[52:55]
	v_mfma_f32_16x16x32_bf16 v[48:51], v[142:145], v[76:79], v[48:51]
	v_mfma_f32_16x16x32_bf16 v[36:39], v[164:167], v[208:211], v[36:39]
	v_mfma_f32_16x16x32_bf16 v[32:35], v[142:145], v[208:211], v[32:35]
	v_mfma_f32_16x16x32_bf16 v[60:63], v[168:171], v[72:75], v[60:63]
	v_mfma_f32_16x16x32_bf16 v[56:59], v[142:145], v[64:67], v[56:59]
	v_mfma_f32_16x16x32_bf16 v[52:55], v[168:171], v[88:91], v[52:55]
	v_mfma_f32_16x16x32_bf16 v[48:51], v[172:175], v[88:91], v[48:51]
	v_mfma_f32_16x16x32_bf16 v[44:47], v[164:167], v[92:95], v[44:47]
	v_mfma_f32_16x16x32_bf16 v[40:43], v[142:145], v[92:95], v[40:43]
	v_mfma_f32_16x16x32_bf16 v[36:39], v[168:171], v[212:215], v[36:39]
	v_mfma_f32_16x16x32_bf16 v[32:35], v[172:175], v[212:215], v[32:35]
	v_mfma_f32_16x16x32_bf16 v[216:219], v[172:175], v[72:75], v[56:59]
	v_mfma_f32_16x16x32_bf16 v[236:239], v[168:171], v[204:207], v[44:47]
	v_mfma_f32_16x16x32_bf16 v[240:243], v[172:175], v[204:207], v[40:43]
	v_mfma_f32_16x16x32_bf16 v[20:23], v[106:109], v[76:79], v[20:23]
	v_mfma_f32_16x16x32_bf16 v[16:19], v[114:117], v[76:79], v[16:19]
	v_mfma_f32_16x16x32_bf16 v[4:7], v[106:109], v[208:211], v[4:7]
	v_mfma_f32_16x16x32_bf16 v[28:31], v[106:109], v[64:67], v[28:31]
	v_mfma_f32_16x16x32_bf16 v[24:27], v[114:117], v[64:67], v[24:27]
	v_mfma_f32_16x16x32_bf16 v[20:23], v[110:113], v[88:91], v[20:23]
	v_mfma_f32_16x16x32_bf16 v[16:19], v[152:155], v[88:91], v[16:19]
	v_mfma_f32_16x16x32_bf16 v[12:15], v[106:109], v[92:95], v[12:15]
	v_mfma_f32_16x16x32_bf16 v[8:11], v[114:117], v[92:95], v[8:11]
	v_mfma_f32_16x16x32_bf16 v[4:7], v[110:113], v[212:215], v[4:7]
	v_mfma_f32_16x16x32_bf16 v[0:3], v[114:117], v[208:211], v[0:3]
	v_mfma_f32_16x16x32_bf16 v[142:145], v[110:113], v[72:75], v[28:31]
	v_mfma_f32_16x16x32_bf16 v[164:167], v[152:155], v[72:75], v[24:27]
	v_mfma_f32_16x16x32_bf16 v[168:171], v[110:113], v[204:207], v[12:15]
	v_mfma_f32_16x16x32_bf16 v[172:175], v[152:155], v[204:207], v[8:11]
	v_mfma_f32_16x16x32_bf16 v[152:155], v[152:155], v[212:215], v[0:3]
	s_barrier
; #define WAIT_V(n) asm volatile("s_waitcnt vmcnt(%0)" ::"n"(n) : "memory")
; #define WAIT_L(n) asm volatile("s_waitcnt lgkmcnt(%0)" ::"n"(n) : "memory")
; #define LDA(dst, b, h) _Pragma("unroll") for (int m = 0; m < 4; ++m) _Pragma("unroll") for (int k = 0; k < 2; ++k) \
;       dst[m][k] = *(const bf16x8*)(SA(b, h) + aoff + (m * 2048 + k * 1024))
; #define LDB(dst, b, h) _Pragma("unroll") for (int n = 0; n < 2; ++n) _Pragma("unroll") for (int k = 0; k < 2; ++k) \
;       dst[n][k] = *(const bf16x8*)(SB(b, h) + boff + (n * 256 + k * 1024))
; #define BAR __builtin_amdgcn_s_barrier()
; template <int EPI, int N, int K>
; __device__ __forceinline__ void phase_gemm(const Params& p, const u16* __restrict__ A, const u16* __restrict__ Bt, int nM, char* shm,
;                            u16* __restrict__ outp, float* __restrict__ rowss) {
;     ...
;     { LDB(B0, 1, 0); LDA(At, 1, 0); WAIT_V(2); BAR; WAIT_L(0); MMA(0, 0, At, B0); BAR;
;       LDB(B1, 1, 1); WAIT_V(0); BAR; WAIT_L(0); MMA(0, 1, At, B1); BAR;
;       LDA(At, 1, 1); BAR; WAIT_L(0); MMA(1, 0, At, B0); MMA(1, 1, At, B1); BAR; }
;     if (wr == 0) BAR;
	s_nop 0
	ds_read_b128 v[0:3], v156
	ds_read_b128 v[8:11], v157
	ds_read_b128 v[12:15], v158
	ds_read_b128 v[156:159], v159
	ds_read_b128 v[24:27], v147 offset:32768
	ds_read_b128 v[28:31], v147 offset:33792
	ds_read_b128 v[40:43], v147 offset:34816
	ds_read_b128 v[44:47], v147 offset:35840
	ds_read_b128 v[56:59], v147 offset:36864
	ds_read_b128 v[64:67], v147 offset:37888
	ds_read_b128 v[204:207], v147 offset:38912
	ds_read_b128 v[208:211], v147 offset:39936
	s_waitcnt vmcnt(2)
	s_barrier
	s_waitcnt lgkmcnt(0)
	s_waitcnt lgkmcnt(0)
	v_mfma_f32_16x16x32_bf16 v[72:75], v[0:3], v[24:27], v[126:129]
	v_mfma_f32_16x16x32_bf16 v[126:129], v[8:11], v[28:31], v[72:75]
	v_mfma_f32_16x16x32_bf16 v[72:75], v[12:15], v[24:27], v[122:125]
	v_mfma_f32_16x16x32_bf16 v[114:117], v[156:159], v[28:31], v[72:75]
	v_mfma_f32_16x16x32_bf16 v[72:75], v[0:3], v[40:43], v[118:121]
	v_mfma_f32_16x16x32_bf16 v[106:109], v[8:11], v[44:47], v[72:75]
	v_mfma_f32_16x16x32_bf16 v[72:75], v[12:15], v[40:43], v[220:223]
	v_mfma_f32_16x16x32_bf16 v[110:113], v[156:159], v[44:47], v[72:75]
	v_mfma_f32_16x16x32_bf16 v[72:75], v[0:3], v[56:59], v[224:227]
	v_mfma_f32_16x16x32_bf16 v[88:91], v[8:11], v[64:67], v[72:75]
	v_mfma_f32_16x16x32_bf16 v[72:75], v[12:15], v[56:59], v[228:231]
	v_mfma_f32_16x16x32_bf16 v[92:95], v[156:159], v[64:67], v[72:75]
	v_mfma_f32_16x16x32_bf16 v[72:75], v[0:3], v[204:207], v[102:105]
	v_mfma_f32_16x16x32_bf16 v[76:79], v[12:15], v[204:207], v[98:101]
	v_mfma_f32_16x16x32_bf16 v[72:75], v[8:11], v[208:211], v[72:75]
	v_mfma_f32_16x16x32_bf16 v[76:79], v[156:159], v[208:211], v[76:79]
	s_barrier
	ds_read_b128 v[212:215], v160
	ds_read_b128 v[220:223], v161
	ds_read_b128 v[224:227], v162
	ds_read_b128 v[160:163], v163
	s_waitcnt vmcnt(0)
	s_barrier
	s_waitcnt lgkmcnt(0)
	s_waitcnt lgkmcnt(0)
	v_mfma_f32_16x16x32_bf16 v[98:101], v[212:215], v[24:27], v[232:235]
	v_mfma_f32_16x16x32_bf16 v[24:27], v[224:227], v[24:27], v[176:179]
	v_mfma_f32_16x16x32_bf16 v[122:125], v[160:163], v[28:31], v[24:27]
	v_mfma_f32_16x16x32_bf16 v[24:27], v[212:215], v[40:43], v[84:87]
	v_mfma_f32_16x16x32_bf16 v[118:121], v[220:223], v[28:31], v[98:101]
	v_mfma_f32_16x16x32_bf16 v[98:101], v[220:223], v[44:47], v[24:27]
	v_mfma_f32_16x16x32_bf16 v[24:27], v[224:227], v[40:43], v[80:83]
	v_mfma_f32_16x16x32_bf16 v[102:105], v[160:163], v[44:47], v[24:27]
	v_mfma_f32_16x16x32_bf16 v[24:27], v[212:215], v[56:59], v[180:183]
	v_mfma_f32_16x16x32_bf16 v[80:83], v[220:223], v[64:67], v[24:27]
	v_mfma_f32_16x16x32_bf16 v[24:27], v[224:227], v[56:59], v[196:199]
	v_mfma_f32_16x16x32_bf16 v[84:87], v[160:163], v[64:67], v[24:27]
	v_mfma_f32_16x16x32_bf16 v[24:27], v[212:215], v[204:207], v[68:71]
	v_mfma_f32_16x16x32_bf16 v[64:67], v[220:223], v[208:211], v[24:27]
	v_mfma_f32_16x16x32_bf16 v[24:27], v[224:227], v[204:207], v[200:203]
	v_mfma_f32_16x16x32_bf16 v[68:71], v[160:163], v[208:211], v[24:27]
	s_barrier
	ds_read_b128 v[176:179], v147 offset:49152
	ds_read_b128 v[180:183], v147 offset:50176
	ds_read_b128 v[196:199], v147 offset:51200
	ds_read_b128 v[200:203], v147 offset:52224
	ds_read_b128 v[204:207], v147 offset:53248
	ds_read_b128 v[208:211], v147 offset:54272
	ds_read_b128 v[228:231], v147 offset:55296
	ds_read_b128 v[232:235], v147 offset:56320
	s_barrier
	s_waitcnt lgkmcnt(0)
	s_waitcnt lgkmcnt(0)
	v_mfma_f32_16x16x32_bf16 v[24:27], v[0:3], v[176:179], v[60:63]
	v_mfma_f32_16x16x32_bf16 v[56:59], v[8:11], v[180:183], v[24:27]
	v_mfma_f32_16x16x32_bf16 v[24:27], v[12:15], v[176:179], v[216:219]
	v_mfma_f32_16x16x32_bf16 v[60:63], v[156:159], v[180:183], v[24:27]
	v_mfma_f32_16x16x32_bf16 v[24:27], v[0:3], v[196:199], v[52:55]
	v_mfma_f32_16x16x32_bf16 v[40:43], v[8:11], v[200:203], v[24:27]
	v_mfma_f32_16x16x32_bf16 v[24:27], v[12:15], v[196:199], v[48:51]
	v_mfma_f32_16x16x32_bf16 v[44:47], v[156:159], v[200:203], v[24:27]
	v_mfma_f32_16x16x32_bf16 v[24:27], v[0:3], v[204:207], v[236:239]
	v_mfma_f32_16x16x32_bf16 v[0:3], v[0:3], v[228:231], v[36:39]
	v_mfma_f32_16x16x32_bf16 v[24:27], v[8:11], v[208:211], v[24:27]
	v_mfma_f32_16x16x32_bf16 v[28:31], v[12:15], v[204:207], v[240:243]
	v_mfma_f32_16x16x32_bf16 v[8:11], v[8:11], v[232:235], v[0:3]
	v_mfma_f32_16x16x32_bf16 v[0:3], v[12:15], v[228:231], v[32:35]
	v_mfma_f32_16x16x32_bf16 v[28:31], v[156:159], v[208:211], v[28:31]
	v_mfma_f32_16x16x32_bf16 v[12:15], v[156:159], v[232:235], v[0:3]
	v_mfma_f32_16x16x32_bf16 v[0:3], v[212:215], v[176:179], v[142:145]
	v_mfma_f32_16x16x32_bf16 v[48:51], v[220:223], v[180:183], v[0:3]
	v_mfma_f32_16x16x32_bf16 v[0:3], v[224:227], v[176:179], v[164:167]
	v_mfma_f32_16x16x32_bf16 v[52:55], v[160:163], v[180:183], v[0:3]
	v_mfma_f32_16x16x32_bf16 v[0:3], v[212:215], v[196:199], v[20:23]
	v_mfma_f32_16x16x32_bf16 v[32:35], v[220:223], v[200:203], v[0:3]
	v_mfma_f32_16x16x32_bf16 v[0:3], v[224:227], v[196:199], v[16:19]
	v_mfma_f32_16x16x32_bf16 v[36:39], v[160:163], v[200:203], v[0:3]
	v_mfma_f32_16x16x32_bf16 v[0:3], v[212:215], v[204:207], v[168:171]
	v_mfma_f32_16x16x32_bf16 v[16:19], v[220:223], v[208:211], v[0:3]
	v_mfma_f32_16x16x32_bf16 v[0:3], v[224:227], v[204:207], v[172:175]
	v_mfma_f32_16x16x32_bf16 v[20:23], v[160:163], v[208:211], v[0:3]
	v_mfma_f32_16x16x32_bf16 v[0:3], v[212:215], v[228:231], v[4:7]
	v_mfma_f32_16x16x32_bf16 v[4:7], v[224:227], v[228:231], v[152:155]
	v_mfma_f32_16x16x32_bf16 v[0:3], v[220:223], v[232:235], v[0:3]
	v_mfma_f32_16x16x32_bf16 v[4:7], v[160:163], v[232:235], v[4:7]
	s_andn2_b64 vcc, exec, s[18:19]
	s_barrier
	s_cbranch_vccnz .LBB0_97
	s_barrier

; #define WAIT_V(n) asm volatile("s_waitcnt vmcnt(%0)" ::"n"(n) : "memory")
; #define WAIT_L(n) asm volatile("s_waitcnt lgkmcnt(%0)" ::"n"(n) : "memory")
; #define SBAR() __builtin_amdgcn_sched_barrier(0)
; #define STAGE(P, base, kt) do { _Pragma("unroll") for (int _i = 0; _i < 2; ++_i)                                        \
;       __builtin_amdgcn_global_load_lds((const unsigned*)((base) + (size_t)(sOff[_i] + (unsigned)(kt) * (BK * 2))),        \
;                                        (unsigned*)((P) + wid * 1024 + _i * 8192), 16, 0, 0); } while (0)
; #define LDA(dst, b, h) _Pragma("unroll") for (int m = 0; m < 4; ++m) _Pragma("unroll") for (int k = 0; k < 2; ++k) \
;       dst[m][k] = *(const bf16x8*)(SA(b, h) + aoff + (m * 2048 + k * 1024))
; #define LDB(dst, b, h) _Pragma("unroll") for (int n = 0; n < 2; ++n) _Pragma("unroll") for (int k = 0; k < 2; ++k) \
;       dst[n][k] = *(const bf16x8*)(SB(b, h) + boff + (n * 256 + k * 1024))
; #define BAR __builtin_amdgcn_s_barrier()
; template <int EPI, int N, int K>
; __device__ __forceinline__ void phase_gemm(const Params& p, const u16* __restrict__ A, const u16* __restrict__ Bt, int nM, char* shm,
;                            u16* __restrict__ outp, float* __restrict__ rowss) {
;     ...
;   for (;;) {
;     const char* A1 = A0 + (size_t)128 * K * 2;
;     const char* B1p = B0p + (size_t)128 * K * 2;
;     f32x4 acc[2][2][4][2] = {};
;     bf16x8 At[4][2], B0[2][2], B1[2][2];
;     if (wr == 1) BAR;
;     WAIT_V(0); BAR;
;     BAR;
;     for (int t = 0; t < nt - 2; t += 2) {
;       LDB(B0, 0, 0); SBAR(); LDA(At, 0, 0); STAGE(SA(1, 1), A1, t + 1);
;       WAIT_L(8); BAR; WAIT_L(0); MMA(0, 0, At, B0); BAR; SBAR();
;       LDB(B1, 0, 1); STAGE(SB(0, 0), B0p, t + 2);
;       BAR; WAIT_L(0); MMA(0, 1, At, B1); BAR;
;       LDA(At, 0, 1); STAGE(SA(0, 0), A0, t + 2);
;       BAR; WAIT_L(0); MMA(1, 0, At, B0); BAR; SBAR();
;       STAGE(SB(0, 1), B1p, t + 2);
;       WAIT_V(6); BAR; MMA(1, 1, At, B1); BAR;
.LBB0_129:
	s_add_u32 s16, s10, 0x40000
	s_addc_u32 s17, s11, 0
	s_waitcnt vmcnt(0)
	s_add_u32 s18, s8, 0x40000
	s_addc_u32 s19, s9, 0
	s_mov_b32 s53, -2
	v_mov_b32_e32 v140, v146
	v_mov_b32_e32 v141, v145
	s_barrier
	s_barrier
	v_or_b32_e32 v147, 0x10000, v143
	v_add_u32_e32 v149, 0x10100, v143
	v_add_u32_e32 v148, 0x10400, v143
	ds_read_b128 v[156:159], v147
	ds_read_b128 v[160:163], v148
	v_add_u32_e32 v150, 0x10500, v143
	ds_read_b128 v[164:167], v149
	ds_read_b128 v[168:171], v150
	v_add_u32_e32 v240, v142, v140
	s_add_i32 s55, s5, 0xc000
	v_add_u32_e32 v151, 0x80, v240
	s_mov_b32 m0, s55
	v_add_u32_e32 v241, v142, v141
	s_add_i32 s54, s5, 0xe000
	ds_read_b128 v[172:175], v144
	ds_read_b128 v[176:179], v144 offset:1024
	ds_read_b128 v[180:183], v144 offset:2048
	ds_read_b128 v[196:199], v144 offset:3072
	ds_read_b128 v[200:203], v144 offset:4096
	ds_read_b128 v[204:207], v144 offset:5120
	ds_read_b128 v[208:211], v144 offset:6144
	ds_read_b128 v[212:215], v144 offset:7168
	global_load_lds_dwordx4 v151, s[16:17]
	v_add_u32_e32 v151, 0x80, v241
	s_mov_b32 m0, s54
	s_nop 0
	global_load_lds_dwordx4 v151, s[16:17]
	s_waitcnt lgkmcnt(8)
	s_barrier
	s_waitcnt lgkmcnt(0)
	s_waitcnt lgkmcnt(0)
	v_mfma_f32_16x16x32_bf16 v[126:129], v[156:159], v[172:175], 0
	v_mfma_f32_16x16x32_bf16 v[122:125], v[164:167], v[172:175], 0
	v_mfma_f32_16x16x32_bf16 v[118:121], v[156:159], v[180:183], 0
	v_mfma_f32_16x16x32_bf16 v[114:117], v[164:167], v[180:183], 0
	v_mfma_f32_16x16x32_bf16 v[110:113], v[156:159], v[200:203], 0
	v_mfma_f32_16x16x32_bf16 v[106:109], v[164:167], v[200:203], 0
	v_mfma_f32_16x16x32_bf16 v[102:105], v[156:159], v[208:211], 0
	v_mfma_f32_16x16x32_bf16 v[98:101], v[164:167], v[208:211], 0
	v_mfma_f32_16x16x32_bf16 v[126:129], v[160:163], v[176:179], v[126:129]
	v_mfma_f32_16x16x32_bf16 v[122:125], v[168:171], v[176:179], v[122:125]
	v_mfma_f32_16x16x32_bf16 v[118:121], v[160:163], v[196:199], v[118:121]
	v_mfma_f32_16x16x32_bf16 v[114:117], v[168:171], v[196:199], v[114:117]
	v_mfma_f32_16x16x32_bf16 v[110:113], v[160:163], v[204:207], v[110:113]
	v_mfma_f32_16x16x32_bf16 v[106:109], v[168:171], v[204:207], v[106:109]
	v_mfma_f32_16x16x32_bf16 v[102:105], v[160:163], v[212:215], v[102:105]
	v_mfma_f32_16x16x32_bf16 v[98:101], v[168:171], v[212:215], v[98:101]
	s_barrier
	s_mov_b32 m0, s23
	v_or_b32_e32 v151, 0x14000, v143
	v_add_u32_e32 v153, 0x14100, v143
	v_add_u32_e32 v232, 0x100, v240
	v_add_u32_e32 v152, 0x14400, v143
	ds_read_b128 v[216:219], v151
	ds_read_b128 v[220:223], v152
	v_add_u32_e32 v154, 0x14500, v143
	ds_read_b128 v[224:227], v153
	ds_read_b128 v[228:231], v154
	global_load_lds_dwordx4 v232, s[8:9]
	v_add_u32_e32 v233, 0x100, v241
	s_mov_b32 m0, s94
	s_nop 0
	global_load_lds_dwordx4 v233, s[8:9]
	s_barrier
	s_waitcnt lgkmcnt(0)
	s_waitcnt lgkmcnt(0)
	v_mfma_f32_16x16x32_bf16 v[92:95], v[216:219], v[172:175], 0
	v_mfma_f32_16x16x32_bf16 v[88:91], v[224:227], v[172:175], 0
	v_mfma_f32_16x16x32_bf16 v[84:87], v[216:219], v[180:183], 0
	v_mfma_f32_16x16x32_bf16 v[80:83], v[224:227], v[180:183], 0
	v_mfma_f32_16x16x32_bf16 v[76:79], v[216:219], v[200:203], 0
	v_mfma_f32_16x16x32_bf16 v[72:75], v[224:227], v[200:203], 0
	v_mfma_f32_16x16x32_bf16 v[68:71], v[216:219], v[208:211], 0
	v_mfma_f32_16x16x32_bf16 v[64:67], v[224:227], v[208:211], 0
	v_mfma_f32_16x16x32_bf16 v[92:95], v[220:223], v[176:179], v[92:95]
	v_mfma_f32_16x16x32_bf16 v[88:91], v[228:231], v[176:179], v[88:91]
	v_mfma_f32_16x16x32_bf16 v[84:87], v[220:223], v[196:199], v[84:87]
	v_mfma_f32_16x16x32_bf16 v[80:83], v[228:231], v[196:199], v[80:83]
	v_mfma_f32_16x16x32_bf16 v[76:79], v[220:223], v[204:207], v[76:79]
	v_mfma_f32_16x16x32_bf16 v[72:75], v[228:231], v[204:207], v[72:75]
	v_mfma_f32_16x16x32_bf16 v[68:71], v[220:223], v[212:215], v[68:71]
	v_mfma_f32_16x16x32_bf16 v[64:67], v[228:231], v[212:215], v[64:67]
	s_mov_b32 m0, s5
	s_barrier
	ds_read_b128 v[172:175], v144 offset:16384
	ds_read_b128 v[176:179], v144 offset:17408
	ds_read_b128 v[180:183], v144 offset:18432
	ds_read_b128 v[196:199], v144 offset:19456
	ds_read_b128 v[200:203], v144 offset:20480
	ds_read_b128 v[204:207], v144 offset:21504
	ds_read_b128 v[208:211], v144 offset:22528
	ds_read_b128 v[212:215], v144 offset:23552
	global_load_lds_dwordx4 v232, s[10:11]
	s_mov_b32 m0, s22
	s_nop 0
	global_load_lds_dwordx4 v233, s[10:11]
	s_barrier
	s_waitcnt lgkmcnt(0)
	s_waitcnt lgkmcnt(0)
	v_mfma_f32_16x16x32_bf16 v[60:63], v[156:159], v[172:175], 0
	v_mfma_f32_16x16x32_bf16 v[56:59], v[164:167], v[172:175], 0
	v_mfma_f32_16x16x32_bf16 v[52:55], v[156:159], v[180:183], 0
	v_mfma_f32_16x16x32_bf16 v[48:51], v[164:167], v[180:183], 0
	v_mfma_f32_16x16x32_bf16 v[44:47], v[156:159], v[200:203], 0
	v_mfma_f32_16x16x32_bf16 v[40:43], v[164:167], v[200:203], 0
	v_mfma_f32_16x16x32_bf16 v[36:39], v[156:159], v[208:211], 0
	v_mfma_f32_16x16x32_bf16 v[32:35], v[164:167], v[208:211], 0
	v_mfma_f32_16x16x32_bf16 v[60:63], v[160:163], v[176:179], v[60:63]
	v_mfma_f32_16x16x32_bf16 v[56:59], v[168:171], v[176:179], v[56:59]
	v_mfma_f32_16x16x32_bf16 v[52:55], v[160:163], v[196:199], v[52:55]
	v_mfma_f32_16x16x32_bf16 v[48:51], v[168:171], v[196:199], v[48:51]
	v_mfma_f32_16x16x32_bf16 v[44:47], v[160:163], v[204:207], v[44:47]
	v_mfma_f32_16x16x32_bf16 v[40:43], v[168:171], v[204:207], v[40:43]
	v_mfma_f32_16x16x32_bf16 v[36:39], v[160:163], v[212:215], v[36:39]
	v_mfma_f32_16x16x32_bf16 v[32:35], v[168:171], v[212:215], v[32:35]
	s_barrier
	s_mov_b32 m0, s95
	s_nop 0
	global_load_lds_dwordx4 v232, s[18:19]
	s_mov_b32 m0, s96
	s_nop 0
	global_load_lds_dwordx4 v233, s[18:19]
	s_waitcnt vmcnt(6)
	s_barrier
; #define WAIT_V(n) asm volatile("s_waitcnt vmcnt(%0)" ::"n"(n) : "memory")
; #define WAIT_L(n) asm volatile("s_waitcnt lgkmcnt(%0)" ::"n"(n) : "memory")
; #define SBAR() __builtin_amdgcn_sched_barrier(0)
; #define STAGE(P, base, kt) do { _Pragma("unroll") for (int _i = 0; _i < 2; ++_i)                                        \
;       __builtin_amdgcn_global_load_lds((const unsigned*)((base) + (size_t)(sOff[_i] + (unsigned)(kt) * (BK * 2))),        \
;                                        (unsigned*)((P) + wid * 1024 + _i * 8192), 16, 0, 0); } while (0)
; #define LDA(dst, b, h) _Pragma("unroll") for (int m = 0; m < 4; ++m) _Pragma("unroll") for (int k = 0; k < 2; ++k) \
;       dst[m][k] = *(const bf16x8*)(SA(b, h) + aoff + (m * 2048 + k * 1024))
; #define LDB(dst, b, h) _Pragma("unroll") for (int n = 0; n < 2; ++n) _Pragma("unroll") for (int k = 0; k < 2; ++k) \
;       dst[n][k] = *(const bf16x8*)(SB(b, h) + boff + (n * 256 + k * 1024))
; #define BAR __builtin_amdgcn_s_barrier()
; template <int EPI, int N, int K>
; __device__ __forceinline__ void phase_gemm(const Params& p, const u16* __restrict__ A, const u16* __restrict__ Bt, int nM, char* shm,
;                            u16* __restrict__ outp, float* __restrict__ rowss) {
;     ...
;       WAIT_V(6); BAR; MMA(1, 1, At, B1); BAR;
;       LDB(B0, 1, 0); SBAR(); LDA(At, 1, 0); STAGE(SA(0, 1), A1, t + 2);
;       WAIT_L(8); BAR; WAIT_L(0); MMA(0, 0, At, B0); BAR; SBAR();
;       LDB(B1, 1, 1); STAGE(SB(1, 0), B0p, t + 3);
;       BAR; WAIT_L(0); MMA(0, 1, At, B1); BAR;
;       LDA(At, 1, 1); STAGE(SA(1, 0), A0, t + 3);
;       BAR; WAIT_L(0); MMA(1, 0, At, B0); BAR; SBAR();
	v_mfma_f32_16x16x32_bf16 v[28:31], v[216:219], v[172:175], 0
	v_mfma_f32_16x16x32_bf16 v[24:27], v[224:227], v[172:175], 0
	v_mfma_f32_16x16x32_bf16 v[20:23], v[216:219], v[180:183], 0
	v_mfma_f32_16x16x32_bf16 v[16:19], v[224:227], v[180:183], 0
	v_mfma_f32_16x16x32_bf16 v[12:15], v[216:219], v[200:203], 0
	v_mfma_f32_16x16x32_bf16 v[8:11], v[224:227], v[200:203], 0
	v_mfma_f32_16x16x32_bf16 v[4:7], v[216:219], v[208:211], 0
	v_mfma_f32_16x16x32_bf16 v[0:3], v[224:227], v[208:211], 0
	v_mfma_f32_16x16x32_bf16 v[28:31], v[220:223], v[176:179], v[28:31]
	v_mfma_f32_16x16x32_bf16 v[24:27], v[228:231], v[176:179], v[24:27]
	v_mfma_f32_16x16x32_bf16 v[20:23], v[220:223], v[196:199], v[20:23]
	v_mfma_f32_16x16x32_bf16 v[16:19], v[228:231], v[196:199], v[16:19]
	v_mfma_f32_16x16x32_bf16 v[12:15], v[220:223], v[204:207], v[12:15]
	v_mfma_f32_16x16x32_bf16 v[8:11], v[228:231], v[204:207], v[8:11]
	v_mfma_f32_16x16x32_bf16 v[4:7], v[220:223], v[212:215], v[4:7]
	v_mfma_f32_16x16x32_bf16 v[0:3], v[228:231], v[212:215], v[0:3]
	v_or_b32_e32 v155, 0x18000, v143
	v_add_u32_e32 v157, 0x18100, v143
	s_barrier
	v_add_u32_e32 v156, 0x18400, v143
	ds_read_b128 v[164:167], v155
	ds_read_b128 v[168:171], v156
	v_add_u32_e32 v158, 0x18500, v143
	ds_read_b128 v[172:175], v157
	ds_read_b128 v[176:179], v158
	s_mov_b32 m0, s97
	ds_read_b128 v[180:183], v144 offset:32768
	ds_read_b128 v[196:199], v144 offset:33792
	ds_read_b128 v[200:203], v144 offset:34816
	ds_read_b128 v[204:207], v144 offset:35840
	ds_read_b128 v[208:211], v144 offset:36864
	ds_read_b128 v[212:215], v144 offset:37888
	ds_read_b128 v[216:219], v144 offset:38912
	ds_read_b128 v[220:223], v144 offset:39936
	global_load_lds_dwordx4 v232, s[16:17]
	s_mov_b32 m0, s33
	s_nop 0
	global_load_lds_dwordx4 v233, s[16:17]
	s_waitcnt lgkmcnt(8)
	s_barrier
	s_waitcnt lgkmcnt(0)
	s_waitcnt lgkmcnt(0)
	v_mfma_f32_16x16x32_bf16 v[126:129], v[164:167], v[180:183], v[126:129]
	v_mfma_f32_16x16x32_bf16 v[122:125], v[172:175], v[180:183], v[122:125]
	v_mfma_f32_16x16x32_bf16 v[118:121], v[164:167], v[200:203], v[118:121]
	v_mfma_f32_16x16x32_bf16 v[114:117], v[172:175], v[200:203], v[114:117]
	v_mfma_f32_16x16x32_bf16 v[110:113], v[164:167], v[208:211], v[110:113]
	v_mfma_f32_16x16x32_bf16 v[106:109], v[172:175], v[208:211], v[106:109]
	v_mfma_f32_16x16x32_bf16 v[102:105], v[164:167], v[216:219], v[102:105]
	v_mfma_f32_16x16x32_bf16 v[98:101], v[172:175], v[216:219], v[98:101]
	v_mfma_f32_16x16x32_bf16 v[126:129], v[168:171], v[196:199], v[126:129]
	v_mfma_f32_16x16x32_bf16 v[122:125], v[176:179], v[196:199], v[122:125]
	v_mfma_f32_16x16x32_bf16 v[118:121], v[168:171], v[204:207], v[118:121]
	v_mfma_f32_16x16x32_bf16 v[114:117], v[176:179], v[204:207], v[114:117]
	v_mfma_f32_16x16x32_bf16 v[110:113], v[168:171], v[212:215], v[110:113]
	v_mfma_f32_16x16x32_bf16 v[106:109], v[176:179], v[212:215], v[106:109]
	v_mfma_f32_16x16x32_bf16 v[102:105], v[168:171], v[220:223], v[102:105]
	v_mfma_f32_16x16x32_bf16 v[98:101], v[176:179], v[220:223], v[98:101]
	s_barrier
	s_mov_b32 m0, s35
	v_or_b32_e32 v159, 0x1c000, v143
	v_add_u32_e32 v161, 0x1c100, v143
	v_add_u32_e32 v163, 0x180, v240
	v_add_u32_e32 v160, 0x1c400, v143
	ds_read_b128 v[224:227], v159
	ds_read_b128 v[228:231], v160
	v_add_u32_e32 v162, 0x1c500, v143
	ds_read_b128 v[232:235], v161
	ds_read_b128 v[236:239], v162
	global_load_lds_dwordx4 v163, s[8:9]
	v_add_u32_e32 v240, 0x180, v241
	s_mov_b32 m0, s93
	s_nop 0
	global_load_lds_dwordx4 v240, s[8:9]
	s_barrier
	s_waitcnt lgkmcnt(0)
	s_waitcnt lgkmcnt(0)
	v_mfma_f32_16x16x32_bf16 v[92:95], v[224:227], v[180:183], v[92:95]
	v_mfma_f32_16x16x32_bf16 v[88:91], v[232:235], v[180:183], v[88:91]
	v_mfma_f32_16x16x32_bf16 v[84:87], v[224:227], v[200:203], v[84:87]
	v_mfma_f32_16x16x32_bf16 v[80:83], v[232:235], v[200:203], v[80:83]
	v_mfma_f32_16x16x32_bf16 v[76:79], v[224:227], v[208:211], v[76:79]
	v_mfma_f32_16x16x32_bf16 v[72:75], v[232:235], v[208:211], v[72:75]
	v_mfma_f32_16x16x32_bf16 v[68:71], v[224:227], v[216:219], v[68:71]
	v_mfma_f32_16x16x32_bf16 v[64:67], v[232:235], v[216:219], v[64:67]
	v_mfma_f32_16x16x32_bf16 v[92:95], v[228:231], v[196:199], v[92:95]
	v_mfma_f32_16x16x32_bf16 v[88:91], v[236:239], v[196:199], v[88:91]
	v_mfma_f32_16x16x32_bf16 v[84:87], v[228:231], v[204:207], v[84:87]
	v_mfma_f32_16x16x32_bf16 v[80:83], v[236:239], v[204:207], v[80:83]
	v_mfma_f32_16x16x32_bf16 v[76:79], v[228:231], v[212:215], v[76:79]
	v_mfma_f32_16x16x32_bf16 v[72:75], v[236:239], v[212:215], v[72:75]
	v_mfma_f32_16x16x32_bf16 v[68:71], v[228:231], v[220:223], v[68:71]
	v_mfma_f32_16x16x32_bf16 v[64:67], v[236:239], v[220:223], v[64:67]
	s_mov_b32 m0, s24
	s_barrier
	ds_read_b128 v[180:183], v144 offset:49152
	ds_read_b128 v[196:199], v144 offset:50176
	ds_read_b128 v[200:203], v144 offset:51200
	ds_read_b128 v[204:207], v144 offset:52224
	ds_read_b128 v[208:211], v144 offset:53248
	ds_read_b128 v[212:215], v144 offset:54272
	ds_read_b128 v[216:219], v144 offset:55296
	ds_read_b128 v[220:223], v144 offset:56320
	global_load_lds_dwordx4 v163, s[10:11]
	s_mov_b32 m0, s25
	s_nop 0
	global_load_lds_dwordx4 v240, s[10:11]
	s_barrier
; #define WAIT_V(n) asm volatile("s_waitcnt vmcnt(%0)" ::"n"(n) : "memory")
; #define WAIT_L(n) asm volatile("s_waitcnt lgkmcnt(%0)" ::"n"(n) : "memory")
; #define SBAR() __builtin_amdgcn_sched_barrier(0)
; #define STAGE(P, base, kt) do { _Pragma("unroll") for (int _i = 0; _i < 2; ++_i)                                        \
;       __builtin_amdgcn_global_load_lds((const unsigned*)((base) + (size_t)(sOff[_i] + (unsigned)(kt) * (BK * 2))),        \
;                                        (unsigned*)((P) + wid * 1024 + _i * 8192), 16, 0, 0); } while (0)
; #define LDA(dst, b, h) _Pragma("unroll") for (int m = 0; m < 4; ++m) _Pragma("unroll") for (int k = 0; k < 2; ++k) \
;       dst[m][k] = *(const bf16x8*)(SA(b, h) + aoff + (m * 2048 + k * 1024))
; #define LDB(dst, b, h) _Pragma("unroll") for (int n = 0; n < 2; ++n) _Pragma("unroll") for (int k = 0; k < 2; ++k) \
;       dst[n][k] = *(const bf16x8*)(SB(b, h) + boff + (n * 256 + k * 1024))
; #define BAR __builtin_amdgcn_s_barrier()
; template <int EPI, int N, int K>
; __device__ __forceinline__ void phase_gemm(const Params& p, const u16* __restrict__ A, const u16* __restrict__ Bt, int nM, char* shm,
;                            u16* __restrict__ outp, float* __restrict__ rowss) {
;     ...
;     for (int t = 0; t < nt - 2; t += 2) {
;       LDB(B0, 0, 0); SBAR(); LDA(At, 0, 0); STAGE(SA(1, 1), A1, t + 1);
;       WAIT_L(8); BAR; WAIT_L(0); MMA(0, 0, At, B0); BAR; SBAR();
;       LDB(B1, 0, 1); STAGE(SB(0, 0), B0p, t + 2);
;       BAR; WAIT_L(0); MMA(0, 1, At, B1); BAR;
;       LDA(At, 0, 1); STAGE(SA(0, 0), A0, t + 2);
;     ...
;       BAR; WAIT_L(0); MMA(1, 0, At, B0); BAR; SBAR();
;       STAGE(SB(1, 1), B1p, t + 3);
;       WAIT_V(6); BAR; MMA(1, 1, At, B1); BAR;
	s_waitcnt lgkmcnt(0)
	s_waitcnt lgkmcnt(0)
	v_mfma_f32_16x16x32_bf16 v[60:63], v[164:167], v[180:183], v[60:63]
	v_mfma_f32_16x16x32_bf16 v[56:59], v[172:175], v[180:183], v[56:59]
	v_mfma_f32_16x16x32_bf16 v[52:55], v[164:167], v[200:203], v[52:55]
	v_mfma_f32_16x16x32_bf16 v[48:51], v[172:175], v[200:203], v[48:51]
	v_mfma_f32_16x16x32_bf16 v[44:47], v[164:167], v[208:211], v[44:47]
	v_mfma_f32_16x16x32_bf16 v[40:43], v[172:175], v[208:211], v[40:43]
	v_mfma_f32_16x16x32_bf16 v[36:39], v[164:167], v[216:219], v[36:39]
	v_mfma_f32_16x16x32_bf16 v[32:35], v[172:175], v[216:219], v[32:35]
	v_mfma_f32_16x16x32_bf16 v[60:63], v[168:171], v[196:199], v[60:63]
	v_mfma_f32_16x16x32_bf16 v[56:59], v[176:179], v[196:199], v[56:59]
	v_mfma_f32_16x16x32_bf16 v[52:55], v[168:171], v[204:207], v[52:55]
	v_mfma_f32_16x16x32_bf16 v[48:51], v[176:179], v[204:207], v[48:51]
	v_mfma_f32_16x16x32_bf16 v[44:47], v[168:171], v[212:215], v[44:47]
	v_mfma_f32_16x16x32_bf16 v[40:43], v[176:179], v[212:215], v[40:43]
	v_mfma_f32_16x16x32_bf16 v[36:39], v[168:171], v[220:223], v[36:39]
	v_mfma_f32_16x16x32_bf16 v[32:35], v[176:179], v[220:223], v[32:35]
	s_barrier
	s_mov_b32 m0, s26
	s_nop 0
	global_load_lds_dwordx4 v163, s[18:19]
	s_mov_b32 m0, s27
	s_nop 0
	global_load_lds_dwordx4 v240, s[18:19]
	s_waitcnt vmcnt(6)
	s_barrier
	v_mfma_f32_16x16x32_bf16 v[28:31], v[224:227], v[180:183], v[28:31]
	v_mfma_f32_16x16x32_bf16 v[24:27], v[232:235], v[180:183], v[24:27]
	v_mfma_f32_16x16x32_bf16 v[20:23], v[224:227], v[200:203], v[20:23]
	v_mfma_f32_16x16x32_bf16 v[16:19], v[232:235], v[200:203], v[16:19]
	v_mfma_f32_16x16x32_bf16 v[12:15], v[224:227], v[208:211], v[12:15]
	v_mfma_f32_16x16x32_bf16 v[8:11], v[232:235], v[208:211], v[8:11]
	v_mfma_f32_16x16x32_bf16 v[4:7], v[224:227], v[216:219], v[4:7]
	v_mfma_f32_16x16x32_bf16 v[0:3], v[232:235], v[216:219], v[0:3]
	v_mfma_f32_16x16x32_bf16 v[28:31], v[228:231], v[196:199], v[28:31]
	v_mfma_f32_16x16x32_bf16 v[24:27], v[236:239], v[196:199], v[24:27]
	v_mfma_f32_16x16x32_bf16 v[20:23], v[228:231], v[204:207], v[20:23]
	v_mfma_f32_16x16x32_bf16 v[16:19], v[236:239], v[204:207], v[16:19]
	v_mfma_f32_16x16x32_bf16 v[12:15], v[228:231], v[212:215], v[12:15]
	v_mfma_f32_16x16x32_bf16 v[8:11], v[236:239], v[212:215], v[8:11]
	v_mfma_f32_16x16x32_bf16 v[4:7], v[228:231], v[220:223], v[4:7]
	v_mfma_f32_16x16x32_bf16 v[0:3], v[236:239], v[220:223], v[0:3]
	s_add_i32 s53, s53, 2
	v_add_u32_e32 v141, 0x100, v141
	s_cmp_lt_u32 s53, 12
	v_add_u32_e32 v140, 0x100, v140
	s_barrier
.LBB0_130:
	v_or_b32_e32 v147, 0x10000, v143
	v_add_u32_e32 v149, 0x10100, v143
	v_add_u32_e32 v148, 0x10400, v143
	ds_read_b128 v[156:159], v147
	ds_read_b128 v[160:163], v148
	v_add_u32_e32 v150, 0x10500, v143
	ds_read_b128 v[164:167], v149
	ds_read_b128 v[168:171], v150
	v_add_u32_e32 v240, v142, v140
	s_add_i32 s55, s5, 0xc000
	v_add_u32_e32 v151, 0x80, v240
	s_mov_b32 m0, s55
	v_add_u32_e32 v241, v142, v141
	s_add_i32 s54, s5, 0xe000
	ds_read_b128 v[172:175], v144
	ds_read_b128 v[176:179], v144 offset:1024
	ds_read_b128 v[180:183], v144 offset:2048
	ds_read_b128 v[196:199], v144 offset:3072
	ds_read_b128 v[200:203], v144 offset:4096
	ds_read_b128 v[204:207], v144 offset:5120
	ds_read_b128 v[208:211], v144 offset:6144
	ds_read_b128 v[212:215], v144 offset:7168
	global_load_lds_dwordx4 v151, s[16:17]
	v_add_u32_e32 v151, 0x80, v241
	s_mov_b32 m0, s54
	s_nop 0
	global_load_lds_dwordx4 v151, s[16:17]
	s_waitcnt lgkmcnt(8)
	s_barrier
	s_waitcnt lgkmcnt(0)
	s_waitcnt lgkmcnt(0)
	v_mfma_f32_16x16x32_bf16 v[126:129], v[156:159], v[172:175], v[126:129]
	v_mfma_f32_16x16x32_bf16 v[122:125], v[164:167], v[172:175], v[122:125]
	v_mfma_f32_16x16x32_bf16 v[118:121], v[156:159], v[180:183], v[118:121]
	v_mfma_f32_16x16x32_bf16 v[114:117], v[164:167], v[180:183], v[114:117]
	v_mfma_f32_16x16x32_bf16 v[110:113], v[156:159], v[200:203], v[110:113]
	v_mfma_f32_16x16x32_bf16 v[106:109], v[164:167], v[200:203], v[106:109]
	v_mfma_f32_16x16x32_bf16 v[102:105], v[156:159], v[208:211], v[102:105]
	v_mfma_f32_16x16x32_bf16 v[98:101], v[164:167], v[208:211], v[98:101]
	v_mfma_f32_16x16x32_bf16 v[126:129], v[160:163], v[176:179], v[126:129]
	v_mfma_f32_16x16x32_bf16 v[122:125], v[168:171], v[176:179], v[122:125]
	v_mfma_f32_16x16x32_bf16 v[118:121], v[160:163], v[196:199], v[118:121]
	v_mfma_f32_16x16x32_bf16 v[114:117], v[168:171], v[196:199], v[114:117]
	v_mfma_f32_16x16x32_bf16 v[110:113], v[160:163], v[204:207], v[110:113]
	v_mfma_f32_16x16x32_bf16 v[106:109], v[168:171], v[204:207], v[106:109]
	v_mfma_f32_16x16x32_bf16 v[102:105], v[160:163], v[212:215], v[102:105]
	v_mfma_f32_16x16x32_bf16 v[98:101], v[168:171], v[212:215], v[98:101]
	s_barrier
	s_mov_b32 m0, s23
	v_or_b32_e32 v151, 0x14000, v143
	v_add_u32_e32 v153, 0x14100, v143
	v_add_u32_e32 v232, 0x100, v240
	v_add_u32_e32 v152, 0x14400, v143
	ds_read_b128 v[216:219], v151
	ds_read_b128 v[220:223], v152
	v_add_u32_e32 v154, 0x14500, v143
	ds_read_b128 v[224:227], v153
	ds_read_b128 v[228:231], v154
	global_load_lds_dwordx4 v232, s[8:9]
	v_add_u32_e32 v233, 0x100, v241
	s_mov_b32 m0, s94
	s_nop 0
	global_load_lds_dwordx4 v233, s[8:9]
	s_barrier
; #define WAIT_V(n) asm volatile("s_waitcnt vmcnt(%0)" ::"n"(n) : "memory")
; #define WAIT_L(n) asm volatile("s_waitcnt lgkmcnt(%0)" ::"n"(n) : "memory")
; #define SBAR() __builtin_amdgcn_sched_barrier(0)
; #define STAGE(P, base, kt) do { _Pragma("unroll") for (int _i = 0; _i < 2; ++_i)                                        \
;       __builtin_amdgcn_global_load_lds((const unsigned*)((base) + (size_t)(sOff[_i] + (unsigned)(kt) * (BK * 2))),        \
;                                        (unsigned*)((P) + wid * 1024 + _i * 8192), 16, 0, 0); } while (0)
; #define LDA(dst, b, h) _Pragma("unroll") for (int m = 0; m < 4; ++m) _Pragma("unroll") for (int k = 0; k < 2; ++k) \
;       dst[m][k] = *(const bf16x8*)(SA(b, h) + aoff + (m * 2048 + k * 1024))
; #define LDB(dst, b, h) _Pragma("unroll") for (int n = 0; n < 2; ++n) _Pragma("unroll") for (int k = 0; k < 2; ++k) \
;       dst[n][k] = *(const bf16x8*)(SB(b, h) + boff + (n * 256 + k * 1024))
; #define BAR __builtin_amdgcn_s_barrier()
; template <int EPI, int N, int K>
; __device__ __forceinline__ void phase_gemm(const Params& p, const u16* __restrict__ A, const u16* __restrict__ Bt, int nM, char* shm,
;                            u16* __restrict__ outp, float* __restrict__ rowss) {
;     ...
;       BAR; WAIT_L(0); MMA(1, 0, At, B0); BAR; SBAR();
;       STAGE(SB(0, 1), B1p, t + 2);
;       WAIT_V(6); BAR; MMA(1, 1, At, B1); BAR;
;       LDB(B0, 1, 0); SBAR(); LDA(At, 1, 0); STAGE(SA(0, 1), A1, t + 2);
;       WAIT_L(8); BAR; WAIT_L(0); MMA(0, 0, At, B0); BAR; SBAR();
	s_waitcnt lgkmcnt(0)
	s_waitcnt lgkmcnt(0)
	v_mfma_f32_16x16x32_bf16 v[92:95], v[216:219], v[172:175], v[92:95]
	v_mfma_f32_16x16x32_bf16 v[88:91], v[224:227], v[172:175], v[88:91]
	v_mfma_f32_16x16x32_bf16 v[84:87], v[216:219], v[180:183], v[84:87]
	v_mfma_f32_16x16x32_bf16 v[80:83], v[224:227], v[180:183], v[80:83]
	v_mfma_f32_16x16x32_bf16 v[76:79], v[216:219], v[200:203], v[76:79]
	v_mfma_f32_16x16x32_bf16 v[72:75], v[224:227], v[200:203], v[72:75]
	v_mfma_f32_16x16x32_bf16 v[68:71], v[216:219], v[208:211], v[68:71]
	v_mfma_f32_16x16x32_bf16 v[64:67], v[224:227], v[208:211], v[64:67]
	v_mfma_f32_16x16x32_bf16 v[92:95], v[220:223], v[176:179], v[92:95]
	v_mfma_f32_16x16x32_bf16 v[88:91], v[228:231], v[176:179], v[88:91]
	v_mfma_f32_16x16x32_bf16 v[84:87], v[220:223], v[196:199], v[84:87]
	v_mfma_f32_16x16x32_bf16 v[80:83], v[228:231], v[196:199], v[80:83]
	v_mfma_f32_16x16x32_bf16 v[76:79], v[220:223], v[204:207], v[76:79]
	v_mfma_f32_16x16x32_bf16 v[72:75], v[228:231], v[204:207], v[72:75]
	v_mfma_f32_16x16x32_bf16 v[68:71], v[220:223], v[212:215], v[68:71]
	v_mfma_f32_16x16x32_bf16 v[64:67], v[228:231], v[212:215], v[64:67]
	s_mov_b32 m0, s5
	s_barrier
	ds_read_b128 v[172:175], v144 offset:16384
	ds_read_b128 v[176:179], v144 offset:17408
	ds_read_b128 v[180:183], v144 offset:18432
	ds_read_b128 v[196:199], v144 offset:19456
	ds_read_b128 v[200:203], v144 offset:20480
	ds_read_b128 v[204:207], v144 offset:21504
	ds_read_b128 v[208:211], v144 offset:22528
	ds_read_b128 v[212:215], v144 offset:23552
	global_load_lds_dwordx4 v232, s[10:11]
	s_mov_b32 m0, s22
	s_nop 0
	global_load_lds_dwordx4 v233, s[10:11]
	s_barrier
	s_waitcnt lgkmcnt(0)
	s_waitcnt lgkmcnt(0)
	v_mfma_f32_16x16x32_bf16 v[60:63], v[156:159], v[172:175], v[60:63]
	v_mfma_f32_16x16x32_bf16 v[56:59], v[164:167], v[172:175], v[56:59]
	v_mfma_f32_16x16x32_bf16 v[52:55], v[156:159], v[180:183], v[52:55]
	v_mfma_f32_16x16x32_bf16 v[48:51], v[164:167], v[180:183], v[48:51]
	v_mfma_f32_16x16x32_bf16 v[44:47], v[156:159], v[200:203], v[44:47]
	v_mfma_f32_16x16x32_bf16 v[40:43], v[164:167], v[200:203], v[40:43]
	v_mfma_f32_16x16x32_bf16 v[36:39], v[156:159], v[208:211], v[36:39]
	v_mfma_f32_16x16x32_bf16 v[32:35], v[164:167], v[208:211], v[32:35]
	v_mfma_f32_16x16x32_bf16 v[60:63], v[160:163], v[176:179], v[60:63]
	v_mfma_f32_16x16x32_bf16 v[56:59], v[168:171], v[176:179], v[56:59]
	v_mfma_f32_16x16x32_bf16 v[52:55], v[160:163], v[196:199], v[52:55]
	v_mfma_f32_16x16x32_bf16 v[48:51], v[168:171], v[196:199], v[48:51]
	v_mfma_f32_16x16x32_bf16 v[44:47], v[160:163], v[204:207], v[44:47]
	v_mfma_f32_16x16x32_bf16 v[40:43], v[168:171], v[204:207], v[40:43]
	v_mfma_f32_16x16x32_bf16 v[36:39], v[160:163], v[212:215], v[36:39]
	v_mfma_f32_16x16x32_bf16 v[32:35], v[168:171], v[212:215], v[32:35]
	s_barrier
	s_mov_b32 m0, s95
	s_nop 0
	global_load_lds_dwordx4 v232, s[18:19]
	s_mov_b32 m0, s96
	s_nop 0
	global_load_lds_dwordx4 v233, s[18:19]
	s_waitcnt vmcnt(6)
	s_barrier
	v_mfma_f32_16x16x32_bf16 v[28:31], v[216:219], v[172:175], v[28:31]
	v_mfma_f32_16x16x32_bf16 v[24:27], v[224:227], v[172:175], v[24:27]
	v_mfma_f32_16x16x32_bf16 v[20:23], v[216:219], v[180:183], v[20:23]
	v_mfma_f32_16x16x32_bf16 v[16:19], v[224:227], v[180:183], v[16:19]
	v_mfma_f32_16x16x32_bf16 v[12:15], v[216:219], v[200:203], v[12:15]
	v_mfma_f32_16x16x32_bf16 v[8:11], v[224:227], v[200:203], v[8:11]
	v_mfma_f32_16x16x32_bf16 v[4:7], v[216:219], v[208:211], v[4:7]
	v_mfma_f32_16x16x32_bf16 v[0:3], v[224:227], v[208:211], v[0:3]
	v_mfma_f32_16x16x32_bf16 v[28:31], v[220:223], v[176:179], v[28:31]
	v_mfma_f32_16x16x32_bf16 v[24:27], v[228:231], v[176:179], v[24:27]
	v_mfma_f32_16x16x32_bf16 v[20:23], v[220:223], v[196:199], v[20:23]
	v_mfma_f32_16x16x32_bf16 v[16:19], v[228:231], v[196:199], v[16:19]
	v_mfma_f32_16x16x32_bf16 v[12:15], v[220:223], v[204:207], v[12:15]
	v_mfma_f32_16x16x32_bf16 v[8:11], v[228:231], v[204:207], v[8:11]
	v_mfma_f32_16x16x32_bf16 v[4:7], v[220:223], v[212:215], v[4:7]
	v_mfma_f32_16x16x32_bf16 v[0:3], v[228:231], v[212:215], v[0:3]
	v_or_b32_e32 v155, 0x18000, v143
	v_add_u32_e32 v157, 0x18100, v143
	s_barrier
	v_add_u32_e32 v156, 0x18400, v143
	ds_read_b128 v[164:167], v155
	ds_read_b128 v[168:171], v156
	v_add_u32_e32 v158, 0x18500, v143
	ds_read_b128 v[172:175], v157
	ds_read_b128 v[176:179], v158
	s_mov_b32 m0, s97
	ds_read_b128 v[180:183], v144 offset:32768
	ds_read_b128 v[196:199], v144 offset:33792
	ds_read_b128 v[200:203], v144 offset:34816
	ds_read_b128 v[204:207], v144 offset:35840
	ds_read_b128 v[208:211], v144 offset:36864
	ds_read_b128 v[212:215], v144 offset:37888
	ds_read_b128 v[216:219], v144 offset:38912
	ds_read_b128 v[220:223], v144 offset:39936
	global_load_lds_dwordx4 v232, s[16:17]
	s_mov_b32 m0, s33
	s_nop 0
	global_load_lds_dwordx4 v233, s[16:17]
	s_waitcnt lgkmcnt(8)
	s_barrier
	s_waitcnt lgkmcnt(0)
	s_waitcnt lgkmcnt(0)
	v_mfma_f32_16x16x32_bf16 v[126:129], v[164:167], v[180:183], v[126:129]
	v_mfma_f32_16x16x32_bf16 v[122:125], v[172:175], v[180:183], v[122:125]
	v_mfma_f32_16x16x32_bf16 v[118:121], v[164:167], v[200:203], v[118:121]
	v_mfma_f32_16x16x32_bf16 v[114:117], v[172:175], v[200:203], v[114:117]
	v_mfma_f32_16x16x32_bf16 v[110:113], v[164:167], v[208:211], v[110:113]
	v_mfma_f32_16x16x32_bf16 v[106:109], v[172:175], v[208:211], v[106:109]
	v_mfma_f32_16x16x32_bf16 v[102:105], v[164:167], v[216:219], v[102:105]
	v_mfma_f32_16x16x32_bf16 v[98:101], v[172:175], v[216:219], v[98:101]
	v_mfma_f32_16x16x32_bf16 v[126:129], v[168:171], v[196:199], v[126:129]
	v_mfma_f32_16x16x32_bf16 v[122:125], v[176:179], v[196:199], v[122:125]
	v_mfma_f32_16x16x32_bf16 v[118:121], v[168:171], v[204:207], v[118:121]
	v_mfma_f32_16x16x32_bf16 v[114:117], v[176:179], v[204:207], v[114:117]
	v_mfma_f32_16x16x32_bf16 v[110:113], v[168:171], v[212:215], v[110:113]
	v_mfma_f32_16x16x32_bf16 v[106:109], v[176:179], v[212:215], v[106:109]
	v_mfma_f32_16x16x32_bf16 v[102:105], v[168:171], v[220:223], v[102:105]
	v_mfma_f32_16x16x32_bf16 v[98:101], v[176:179], v[220:223], v[98:101]
	s_barrier
; #define WAIT_V(n) asm volatile("s_waitcnt vmcnt(%0)" ::"n"(n) : "memory")
; #define WAIT_L(n) asm volatile("s_waitcnt lgkmcnt(%0)" ::"n"(n) : "memory")
; #define SBAR() __builtin_amdgcn_sched_barrier(0)
; #define STAGE(P, base, kt) do { _Pragma("unroll") for (int _i = 0; _i < 2; ++_i)                                        \
;       __builtin_amdgcn_global_load_lds((const unsigned*)((base) + (size_t)(sOff[_i] + (unsigned)(kt) * (BK * 2))),        \
;                                        (unsigned*)((P) + wid * 1024 + _i * 8192), 16, 0, 0); } while (0)
; #define LDA(dst, b, h) _Pragma("unroll") for (int m = 0; m < 4; ++m) _Pragma("unroll") for (int k = 0; k < 2; ++k) \
;       dst[m][k] = *(const bf16x8*)(SA(b, h) + aoff + (m * 2048 + k * 1024))
; #define LDB(dst, b, h) _Pragma("unroll") for (int n = 0; n < 2; ++n) _Pragma("unroll") for (int k = 0; k < 2; ++k) \
;       dst[n][k] = *(const bf16x8*)(SB(b, h) + boff + (n * 256 + k * 1024))
; #define BAR __builtin_amdgcn_s_barrier()
; template <int EPI, int N, int K>
; __device__ __forceinline__ void phase_gemm(const Params& p, const u16* __restrict__ A, const u16* __restrict__ Bt, int nM, char* shm,
;                            u16* __restrict__ outp, float* __restrict__ rowss) {
;     ...
;       LDB(B1, 1, 1); STAGE(SB(1, 0), B0p, t + 3);
;       BAR; WAIT_L(0); MMA(0, 1, At, B1); BAR;
;       LDA(At, 1, 1); STAGE(SA(1, 0), A0, t + 3);
;       BAR; WAIT_L(0); MMA(1, 0, At, B0); BAR; SBAR();
;       STAGE(SB(1, 1), B1p, t + 3);
;       WAIT_V(6); BAR; MMA(1, 1, At, B1); BAR;
;     }
;     { LDB(B0, 0, 0); LDA(At, 0, 0); STAGE(SA(1, 1), A1, nt - 1);
	s_mov_b32 m0, s35
	v_or_b32_e32 v159, 0x1c000, v143
	v_add_u32_e32 v161, 0x1c100, v143
	v_add_u32_e32 v163, 0x180, v240
	v_add_u32_e32 v160, 0x1c400, v143
	ds_read_b128 v[224:227], v159
	ds_read_b128 v[228:231], v160
	v_add_u32_e32 v162, 0x1c500, v143
	ds_read_b128 v[232:235], v161
	ds_read_b128 v[236:239], v162
	global_load_lds_dwordx4 v163, s[8:9]
	v_add_u32_e32 v240, 0x180, v241
	s_mov_b32 m0, s93
	s_nop 0
	global_load_lds_dwordx4 v240, s[8:9]
	s_barrier
	s_waitcnt lgkmcnt(0)
	s_waitcnt lgkmcnt(0)
	v_mfma_f32_16x16x32_bf16 v[92:95], v[224:227], v[180:183], v[92:95]
	v_mfma_f32_16x16x32_bf16 v[88:91], v[232:235], v[180:183], v[88:91]
	v_mfma_f32_16x16x32_bf16 v[84:87], v[224:227], v[200:203], v[84:87]
	v_mfma_f32_16x16x32_bf16 v[80:83], v[232:235], v[200:203], v[80:83]
	v_mfma_f32_16x16x32_bf16 v[76:79], v[224:227], v[208:211], v[76:79]
	v_mfma_f32_16x16x32_bf16 v[72:75], v[232:235], v[208:211], v[72:75]
	v_mfma_f32_16x16x32_bf16 v[68:71], v[224:227], v[216:219], v[68:71]
	v_mfma_f32_16x16x32_bf16 v[64:67], v[232:235], v[216:219], v[64:67]
	v_mfma_f32_16x16x32_bf16 v[92:95], v[228:231], v[196:199], v[92:95]
	v_mfma_f32_16x16x32_bf16 v[88:91], v[236:239], v[196:199], v[88:91]
	v_mfma_f32_16x16x32_bf16 v[84:87], v[228:231], v[204:207], v[84:87]
	v_mfma_f32_16x16x32_bf16 v[80:83], v[236:239], v[204:207], v[80:83]
	v_mfma_f32_16x16x32_bf16 v[76:79], v[228:231], v[212:215], v[76:79]
	v_mfma_f32_16x16x32_bf16 v[72:75], v[236:239], v[212:215], v[72:75]
	v_mfma_f32_16x16x32_bf16 v[68:71], v[228:231], v[220:223], v[68:71]
	v_mfma_f32_16x16x32_bf16 v[64:67], v[236:239], v[220:223], v[64:67]
	s_mov_b32 m0, s24
	s_barrier
	ds_read_b128 v[180:183], v144 offset:49152
	ds_read_b128 v[196:199], v144 offset:50176
	ds_read_b128 v[200:203], v144 offset:51200
	ds_read_b128 v[204:207], v144 offset:52224
	ds_read_b128 v[208:211], v144 offset:53248
	ds_read_b128 v[212:215], v144 offset:54272
	ds_read_b128 v[216:219], v144 offset:55296
	ds_read_b128 v[220:223], v144 offset:56320
	global_load_lds_dwordx4 v163, s[10:11]
	s_mov_b32 m0, s25
	s_nop 0
	global_load_lds_dwordx4 v240, s[10:11]
	s_barrier
	s_waitcnt lgkmcnt(0)
	s_waitcnt lgkmcnt(0)
	v_mfma_f32_16x16x32_bf16 v[60:63], v[164:167], v[180:183], v[60:63]
	v_mfma_f32_16x16x32_bf16 v[56:59], v[172:175], v[180:183], v[56:59]
	v_mfma_f32_16x16x32_bf16 v[52:55], v[164:167], v[200:203], v[52:55]
	v_mfma_f32_16x16x32_bf16 v[48:51], v[172:175], v[200:203], v[48:51]
	v_mfma_f32_16x16x32_bf16 v[44:47], v[164:167], v[208:211], v[44:47]
	v_mfma_f32_16x16x32_bf16 v[40:43], v[172:175], v[208:211], v[40:43]
	v_mfma_f32_16x16x32_bf16 v[36:39], v[164:167], v[216:219], v[36:39]
	v_mfma_f32_16x16x32_bf16 v[32:35], v[172:175], v[216:219], v[32:35]
	v_mfma_f32_16x16x32_bf16 v[60:63], v[168:171], v[196:199], v[60:63]
	v_mfma_f32_16x16x32_bf16 v[56:59], v[176:179], v[196:199], v[56:59]
	v_mfma_f32_16x16x32_bf16 v[52:55], v[168:171], v[204:207], v[52:55]
	v_mfma_f32_16x16x32_bf16 v[48:51], v[176:179], v[204:207], v[48:51]
	v_mfma_f32_16x16x32_bf16 v[44:47], v[168:171], v[212:215], v[44:47]
	v_mfma_f32_16x16x32_bf16 v[40:43], v[176:179], v[212:215], v[40:43]
	v_mfma_f32_16x16x32_bf16 v[36:39], v[168:171], v[220:223], v[36:39]
	v_mfma_f32_16x16x32_bf16 v[32:35], v[176:179], v[220:223], v[32:35]
	s_barrier
	s_mov_b32 m0, s26
	s_nop 0
	global_load_lds_dwordx4 v163, s[18:19]
	s_mov_b32 m0, s27
	s_nop 0
	global_load_lds_dwordx4 v240, s[18:19]
	s_waitcnt vmcnt(6)
	s_barrier
	v_mfma_f32_16x16x32_bf16 v[28:31], v[224:227], v[180:183], v[28:31]
	v_mfma_f32_16x16x32_bf16 v[24:27], v[232:235], v[180:183], v[24:27]
	v_mfma_f32_16x16x32_bf16 v[20:23], v[224:227], v[200:203], v[20:23]
	v_mfma_f32_16x16x32_bf16 v[16:19], v[232:235], v[200:203], v[16:19]
	v_mfma_f32_16x16x32_bf16 v[12:15], v[224:227], v[208:211], v[12:15]
	v_mfma_f32_16x16x32_bf16 v[8:11], v[232:235], v[208:211], v[8:11]
	v_mfma_f32_16x16x32_bf16 v[4:7], v[224:227], v[216:219], v[4:7]
	v_mfma_f32_16x16x32_bf16 v[0:3], v[232:235], v[216:219], v[0:3]
	v_mfma_f32_16x16x32_bf16 v[28:31], v[228:231], v[196:199], v[28:31]
	v_mfma_f32_16x16x32_bf16 v[24:27], v[236:239], v[196:199], v[24:27]
	v_mfma_f32_16x16x32_bf16 v[20:23], v[228:231], v[204:207], v[20:23]
	v_mfma_f32_16x16x32_bf16 v[16:19], v[236:239], v[204:207], v[16:19]
	v_mfma_f32_16x16x32_bf16 v[12:15], v[228:231], v[212:215], v[12:15]
	v_mfma_f32_16x16x32_bf16 v[8:11], v[236:239], v[212:215], v[8:11]
	v_mfma_f32_16x16x32_bf16 v[4:7], v[228:231], v[220:223], v[4:7]
	v_mfma_f32_16x16x32_bf16 v[0:3], v[236:239], v[220:223], v[0:3]
	s_add_i32 s53, s53, 2
	v_add_u32_e32 v141, 0x100, v141
	s_cmp_lt_u32 s53, 12
	v_add_u32_e32 v140, 0x100, v140
	s_barrier
	s_cbranch_scc1 .LBB0_130
	s_mov_b32 m0, s55
	v_lshl_add_u64 v[140:141], s[16:17], 0, v[136:137]
	ds_read_b128 v[164:167], v147
	ds_read_b128 v[168:171], v148
	ds_read_b128 v[172:175], v149
	ds_read_b128 v[176:179], v150
	ds_read_b128 v[180:183], v144
	ds_read_b128 v[196:199], v144 offset:1024
	ds_read_b128 v[200:203], v144 offset:2048
	ds_read_b128 v[204:207], v144 offset:3072
	ds_read_b128 v[208:211], v144 offset:4096
	ds_read_b128 v[212:215], v144 offset:5120
	ds_read_b128 v[216:219], v144 offset:6144
	ds_read_b128 v[220:223], v144 offset:7168
	global_load_lds_dwordx4 v[140:141], off
	v_lshl_add_u64 v[140:141], s[16:17], 0, v[138:139]
	s_mov_b32 m0, s54
	s_nop 0
	global_load_lds_dwordx4 v[140:141], off
	s_barrier
; #define WAIT_V(n) asm volatile("s_waitcnt vmcnt(%0)" ::"n"(n) : "memory")
; #define WAIT_L(n) asm volatile("s_waitcnt lgkmcnt(%0)" ::"n"(n) : "memory")
; #define STAGE(P, base, kt) do { _Pragma("unroll") for (int _i = 0; _i < 2; ++_i)                                        \
;       __builtin_amdgcn_global_load_lds((const unsigned*)((base) + (size_t)(sOff[_i] + (unsigned)(kt) * (BK * 2))),        \
;                                        (unsigned*)((P) + wid * 1024 + _i * 8192), 16, 0, 0); } while (0)
; #define LDA(dst, b, h) _Pragma("unroll") for (int m = 0; m < 4; ++m) _Pragma("unroll") for (int k = 0; k < 2; ++k) \
;       dst[m][k] = *(const bf16x8*)(SA(b, h) + aoff + (m * 2048 + k * 1024))
; #define LDB(dst, b, h) _Pragma("unroll") for (int n = 0; n < 2; ++n) _Pragma("unroll") for (int k = 0; k < 2; ++k) \
;       dst[n][k] = *(const bf16x8*)(SB(b, h) + boff + (n * 256 + k * 1024))
; #define BAR __builtin_amdgcn_s_barrier()
; template <int EPI, int N, int K>
; __device__ __forceinline__ void phase_gemm(const Params& p, const u16* __restrict__ A, const u16* __restrict__ Bt, int nM, char* shm,
;                            u16* __restrict__ outp, float* __restrict__ rowss) {
;     ...
;     { LDB(B0, 0, 0); LDA(At, 0, 0); STAGE(SA(1, 1), A1, nt - 1);
;       BAR; WAIT_L(0); MMA(0, 0, At, B0); BAR;
;       LDB(B1, 0, 1); BAR; WAIT_L(0); MMA(0, 1, At, B1); BAR;
;       LDA(At, 0, 1); WAIT_V(4); BAR; WAIT_L(0); MMA(1, 0, At, B0); MMA(1, 1, At, B1); BAR; }
;     { LDB(B0, 1, 0); LDA(At, 1, 0); WAIT_V(2); BAR; WAIT_L(0); MMA(0, 0, At, B0); BAR;
;       LDB(B1, 1, 1); WAIT_V(0); BAR; WAIT_L(0); MMA(0, 1, At, B1); BAR;
	s_waitcnt lgkmcnt(0)
	s_waitcnt lgkmcnt(0)
	v_mfma_f32_16x16x32_bf16 v[126:129], v[164:167], v[180:183], v[126:129]
	v_mfma_f32_16x16x32_bf16 v[118:121], v[164:167], v[200:203], v[118:121]
	v_mfma_f32_16x16x32_bf16 v[110:113], v[164:167], v[208:211], v[110:113]
	v_mfma_f32_16x16x32_bf16 v[102:105], v[164:167], v[216:219], v[102:105]
	v_mfma_f32_16x16x32_bf16 v[126:129], v[168:171], v[196:199], v[126:129]
	v_mfma_f32_16x16x32_bf16 v[122:125], v[172:175], v[180:183], v[122:125]
	v_mfma_f32_16x16x32_bf16 v[118:121], v[168:171], v[204:207], v[118:121]
	v_mfma_f32_16x16x32_bf16 v[114:117], v[172:175], v[200:203], v[114:117]
	v_mfma_f32_16x16x32_bf16 v[110:113], v[168:171], v[212:215], v[110:113]
	v_mfma_f32_16x16x32_bf16 v[106:109], v[172:175], v[208:211], v[106:109]
	v_mfma_f32_16x16x32_bf16 v[102:105], v[168:171], v[220:223], v[102:105]
	v_mfma_f32_16x16x32_bf16 v[98:101], v[172:175], v[216:219], v[98:101]
	v_mfma_f32_16x16x32_bf16 v[224:227], v[176:179], v[196:199], v[122:125]
	v_mfma_f32_16x16x32_bf16 v[228:231], v[176:179], v[204:207], v[114:117]
	v_mfma_f32_16x16x32_bf16 v[232:235], v[176:179], v[212:215], v[106:109]
	v_mfma_f32_16x16x32_bf16 v[236:239], v[176:179], v[220:223], v[98:101]
	s_barrier
	s_nop 1
	ds_read_b128 v[98:101], v151
	ds_read_b128 v[106:109], v152
	ds_read_b128 v[114:117], v153
	ds_read_b128 v[122:125], v154
	s_barrier
	s_waitcnt lgkmcnt(0)
	s_waitcnt lgkmcnt(0)
	v_mfma_f32_16x16x32_bf16 v[92:95], v[98:101], v[180:183], v[92:95]
	v_mfma_f32_16x16x32_bf16 v[84:87], v[98:101], v[200:203], v[84:87]
	v_mfma_f32_16x16x32_bf16 v[76:79], v[98:101], v[208:211], v[76:79]
	v_mfma_f32_16x16x32_bf16 v[68:71], v[98:101], v[216:219], v[68:71]
	v_mfma_f32_16x16x32_bf16 v[92:95], v[106:109], v[196:199], v[92:95]
	v_mfma_f32_16x16x32_bf16 v[88:91], v[114:117], v[180:183], v[88:91]
	v_mfma_f32_16x16x32_bf16 v[84:87], v[106:109], v[204:207], v[84:87]
	v_mfma_f32_16x16x32_bf16 v[80:83], v[114:117], v[200:203], v[80:83]
	v_mfma_f32_16x16x32_bf16 v[76:79], v[106:109], v[212:215], v[76:79]
	v_mfma_f32_16x16x32_bf16 v[72:75], v[114:117], v[208:211], v[72:75]
	v_mfma_f32_16x16x32_bf16 v[68:71], v[106:109], v[220:223], v[68:71]
	v_mfma_f32_16x16x32_bf16 v[64:67], v[114:117], v[216:219], v[64:67]
	v_mfma_f32_16x16x32_bf16 v[148:151], v[122:125], v[196:199], v[88:91]
	v_mfma_f32_16x16x32_bf16 v[180:183], v[122:125], v[204:207], v[80:83]
	v_mfma_f32_16x16x32_bf16 v[196:199], v[122:125], v[212:215], v[72:75]
	v_mfma_f32_16x16x32_bf16 v[200:203], v[122:125], v[220:223], v[64:67]
	s_barrier
	s_nop 1
	ds_read_b128 v[64:67], v144 offset:16384
	ds_read_b128 v[72:75], v144 offset:17408
	ds_read_b128 v[80:83], v144 offset:18432
	ds_read_b128 v[88:91], v144 offset:19456
	ds_read_b128 v[204:207], v144 offset:20480
	ds_read_b128 v[208:211], v144 offset:21504
	ds_read_b128 v[212:215], v144 offset:22528
	ds_read_b128 v[216:219], v144 offset:23552
	s_waitcnt vmcnt(4)
	s_barrier
	s_waitcnt lgkmcnt(0)
	s_waitcnt lgkmcnt(0)
	v_mfma_f32_16x16x32_bf16 v[60:63], v[164:167], v[64:67], v[60:63]
	v_mfma_f32_16x16x32_bf16 v[52:55], v[164:167], v[80:83], v[52:55]
	v_mfma_f32_16x16x32_bf16 v[44:47], v[164:167], v[204:207], v[44:47]
	v_mfma_f32_16x16x32_bf16 v[36:39], v[164:167], v[212:215], v[36:39]
	v_mfma_f32_16x16x32_bf16 v[60:63], v[168:171], v[72:75], v[60:63]
	v_mfma_f32_16x16x32_bf16 v[56:59], v[172:175], v[64:67], v[56:59]
	v_mfma_f32_16x16x32_bf16 v[52:55], v[168:171], v[88:91], v[52:55]
	v_mfma_f32_16x16x32_bf16 v[48:51], v[172:175], v[80:83], v[48:51]
	v_mfma_f32_16x16x32_bf16 v[44:47], v[168:171], v[208:211], v[44:47]
	v_mfma_f32_16x16x32_bf16 v[40:43], v[172:175], v[204:207], v[40:43]
	v_mfma_f32_16x16x32_bf16 v[36:39], v[168:171], v[216:219], v[36:39]
	v_mfma_f32_16x16x32_bf16 v[32:35], v[172:175], v[212:215], v[32:35]
	v_mfma_f32_16x16x32_bf16 v[220:223], v[176:179], v[72:75], v[56:59]
	v_mfma_f32_16x16x32_bf16 v[240:243], v[176:179], v[88:91], v[48:51]
	v_mfma_f32_16x16x32_bf16 v[244:247], v[176:179], v[208:211], v[40:43]
	v_mfma_f32_16x16x32_bf16 v[164:167], v[176:179], v[216:219], v[32:35]
	v_mfma_f32_16x16x32_bf16 v[28:31], v[98:101], v[64:67], v[28:31]
	v_mfma_f32_16x16x32_bf16 v[20:23], v[98:101], v[80:83], v[20:23]
	v_mfma_f32_16x16x32_bf16 v[12:15], v[98:101], v[204:207], v[12:15]
	v_mfma_f32_16x16x32_bf16 v[4:7], v[98:101], v[212:215], v[4:7]
	v_mfma_f32_16x16x32_bf16 v[28:31], v[106:109], v[72:75], v[28:31]
	v_mfma_f32_16x16x32_bf16 v[24:27], v[114:117], v[64:67], v[24:27]
	v_mfma_f32_16x16x32_bf16 v[20:23], v[106:109], v[88:91], v[20:23]
	v_mfma_f32_16x16x32_bf16 v[16:19], v[114:117], v[80:83], v[16:19]
	v_mfma_f32_16x16x32_bf16 v[12:15], v[106:109], v[208:211], v[12:15]
	v_mfma_f32_16x16x32_bf16 v[8:11], v[114:117], v[204:207], v[8:11]
	v_mfma_f32_16x16x32_bf16 v[4:7], v[106:109], v[216:219], v[4:7]
	v_mfma_f32_16x16x32_bf16 v[0:3], v[114:117], v[212:215], v[0:3]
	v_mfma_f32_16x16x32_bf16 v[168:171], v[122:125], v[72:75], v[24:27]
	v_mfma_f32_16x16x32_bf16 v[172:175], v[122:125], v[88:91], v[16:19]
	v_mfma_f32_16x16x32_bf16 v[176:179], v[122:125], v[208:211], v[8:11]
	v_mfma_f32_16x16x32_bf16 v[204:207], v[122:125], v[216:219], v[0:3]
	s_barrier
; #define WAIT_V(n) asm volatile("s_waitcnt vmcnt(%0)" ::"n"(n) : "memory")
; #define WAIT_L(n) asm volatile("s_waitcnt lgkmcnt(%0)" ::"n"(n) : "memory")
; #define LDA(dst, b, h) _Pragma("unroll") for (int m = 0; m < 4; ++m) _Pragma("unroll") for (int k = 0; k < 2; ++k) \
;       dst[m][k] = *(const bf16x8*)(SA(b, h) + aoff + (m * 2048 + k * 1024))
; #define LDB(dst, b, h) _Pragma("unroll") for (int n = 0; n < 2; ++n) _Pragma("unroll") for (int k = 0; k < 2; ++k) \
;       dst[n][k] = *(const bf16x8*)(SB(b, h) + boff + (n * 256 + k * 1024))
; #define BAR __builtin_amdgcn_s_barrier()
; template <int EPI, int N, int K>
; __device__ __forceinline__ void phase_gemm(const Params& p, const u16* __restrict__ A, const u16* __restrict__ Bt, int nM, char* shm,
;                            u16* __restrict__ outp, float* __restrict__ rowss) {
;     ...
;     { LDB(B0, 1, 0); LDA(At, 1, 0); WAIT_V(2); BAR; WAIT_L(0); MMA(0, 0, At, B0); BAR;
;       LDB(B1, 1, 1); WAIT_V(0); BAR; WAIT_L(0); MMA(0, 1, At, B1); BAR;
;       LDA(At, 1, 1); BAR; WAIT_L(0); MMA(1, 0, At, B0); MMA(1, 1, At, B1); BAR; }
;     if (wr == 0) BAR;
	s_nop 1
	ds_read_b128 v[0:3], v155
	ds_read_b128 v[8:11], v156
	ds_read_b128 v[152:155], v157
	ds_read_b128 v[208:211], v158
	ds_read_b128 v[16:19], v144 offset:32768
	ds_read_b128 v[24:27], v144 offset:33792
	ds_read_b128 v[32:35], v144 offset:34816
	ds_read_b128 v[40:43], v144 offset:35840
	ds_read_b128 v[48:51], v144 offset:36864
	ds_read_b128 v[56:59], v144 offset:37888
	ds_read_b128 v[212:215], v144 offset:38912
	ds_read_b128 v[216:219], v144 offset:39936
	s_waitcnt vmcnt(2)
	s_barrier
	s_waitcnt lgkmcnt(0)
	s_waitcnt lgkmcnt(0)
	v_mfma_f32_16x16x32_bf16 v[64:67], v[0:3], v[16:19], v[126:129]
	v_mfma_f32_16x16x32_bf16 v[122:125], v[8:11], v[24:27], v[64:67]
	v_mfma_f32_16x16x32_bf16 v[64:67], v[152:155], v[16:19], v[224:227]
	v_mfma_f32_16x16x32_bf16 v[114:117], v[208:211], v[24:27], v[64:67]
	v_mfma_f32_16x16x32_bf16 v[64:67], v[0:3], v[32:35], v[118:121]
	v_mfma_f32_16x16x32_bf16 v[106:109], v[8:11], v[40:43], v[64:67]
	v_mfma_f32_16x16x32_bf16 v[64:67], v[152:155], v[32:35], v[228:231]
	v_mfma_f32_16x16x32_bf16 v[98:101], v[208:211], v[40:43], v[64:67]
	v_mfma_f32_16x16x32_bf16 v[64:67], v[0:3], v[48:51], v[110:113]
	v_mfma_f32_16x16x32_bf16 v[88:91], v[8:11], v[56:59], v[64:67]
	v_mfma_f32_16x16x32_bf16 v[64:67], v[152:155], v[48:51], v[232:235]
	v_mfma_f32_16x16x32_bf16 v[80:83], v[208:211], v[56:59], v[64:67]
	v_mfma_f32_16x16x32_bf16 v[64:67], v[0:3], v[212:215], v[102:105]
	v_mfma_f32_16x16x32_bf16 v[72:75], v[8:11], v[216:219], v[64:67]
	v_mfma_f32_16x16x32_bf16 v[64:67], v[152:155], v[212:215], v[236:239]
	v_mfma_f32_16x16x32_bf16 v[64:67], v[208:211], v[216:219], v[64:67]
	s_barrier
	ds_read_b128 v[156:159], v159
	ds_read_b128 v[224:227], v160
	ds_read_b128 v[228:231], v161
	ds_read_b128 v[160:163], v162
	s_waitcnt vmcnt(0)
	s_barrier
	s_waitcnt lgkmcnt(0)
	s_waitcnt lgkmcnt(0)
	v_mfma_f32_16x16x32_bf16 v[92:95], v[156:159], v[16:19], v[92:95]
	v_mfma_f32_16x16x32_bf16 v[16:19], v[228:231], v[16:19], v[148:151]
	v_mfma_f32_16x16x32_bf16 v[118:121], v[160:163], v[24:27], v[16:19]
	v_mfma_f32_16x16x32_bf16 v[16:19], v[156:159], v[32:35], v[84:87]
	v_mfma_f32_16x16x32_bf16 v[110:113], v[224:227], v[40:43], v[16:19]
	v_mfma_f32_16x16x32_bf16 v[16:19], v[228:231], v[32:35], v[180:183]
	v_mfma_f32_16x16x32_bf16 v[102:105], v[160:163], v[40:43], v[16:19]
	v_mfma_f32_16x16x32_bf16 v[16:19], v[156:159], v[48:51], v[76:79]
	v_mfma_f32_16x16x32_bf16 v[126:129], v[224:227], v[24:27], v[92:95]
	v_mfma_f32_16x16x32_bf16 v[92:95], v[224:227], v[56:59], v[16:19]
	v_mfma_f32_16x16x32_bf16 v[16:19], v[228:231], v[48:51], v[196:199]
	v_mfma_f32_16x16x32_bf16 v[84:87], v[160:163], v[56:59], v[16:19]
	v_mfma_f32_16x16x32_bf16 v[16:19], v[156:159], v[212:215], v[68:71]
	v_mfma_f32_16x16x32_bf16 v[76:79], v[224:227], v[216:219], v[16:19]
	v_mfma_f32_16x16x32_bf16 v[16:19], v[228:231], v[212:215], v[200:203]
	v_mfma_f32_16x16x32_bf16 v[68:71], v[160:163], v[216:219], v[16:19]
	s_barrier
	ds_read_b128 v[148:151], v144 offset:49152
	ds_read_b128 v[180:183], v144 offset:50176
	ds_read_b128 v[196:199], v144 offset:51200
	ds_read_b128 v[200:203], v144 offset:52224
	ds_read_b128 v[212:215], v144 offset:53248
	ds_read_b128 v[216:219], v144 offset:54272
	ds_read_b128 v[232:235], v144 offset:55296
	ds_read_b128 v[236:239], v144 offset:56320
	s_barrier
	s_waitcnt lgkmcnt(0)
	s_waitcnt lgkmcnt(0)
	v_mfma_f32_16x16x32_bf16 v[16:19], v[0:3], v[148:151], v[60:63]
	v_mfma_f32_16x16x32_bf16 v[56:59], v[8:11], v[180:183], v[16:19]
	v_mfma_f32_16x16x32_bf16 v[16:19], v[152:155], v[148:151], v[220:223]
	v_mfma_f32_16x16x32_bf16 v[48:51], v[208:211], v[180:183], v[16:19]
	v_mfma_f32_16x16x32_bf16 v[16:19], v[0:3], v[196:199], v[52:55]
	v_mfma_f32_16x16x32_bf16 v[40:43], v[8:11], v[200:203], v[16:19]
	v_mfma_f32_16x16x32_bf16 v[16:19], v[152:155], v[196:199], v[240:243]
	v_mfma_f32_16x16x32_bf16 v[32:35], v[208:211], v[200:203], v[16:19]
	v_mfma_f32_16x16x32_bf16 v[16:19], v[0:3], v[212:215], v[44:47]
	v_mfma_f32_16x16x32_bf16 v[0:3], v[0:3], v[232:235], v[36:39]
	v_mfma_f32_16x16x32_bf16 v[24:27], v[8:11], v[216:219], v[16:19]
	v_mfma_f32_16x16x32_bf16 v[16:19], v[152:155], v[212:215], v[244:247]
	v_mfma_f32_16x16x32_bf16 v[8:11], v[8:11], v[236:239], v[0:3]
	v_mfma_f32_16x16x32_bf16 v[0:3], v[152:155], v[232:235], v[164:167]
	v_mfma_f32_16x16x32_bf16 v[16:19], v[208:211], v[216:219], v[16:19]
	v_mfma_f32_16x16x32_bf16 v[0:3], v[208:211], v[236:239], v[0:3]
	v_mfma_f32_16x16x32_bf16 v[28:31], v[156:159], v[148:151], v[28:31]
	v_mfma_f32_16x16x32_bf16 v[60:63], v[224:227], v[180:183], v[28:31]
	v_mfma_f32_16x16x32_bf16 v[28:31], v[228:231], v[148:151], v[168:171]
	v_mfma_f32_16x16x32_bf16 v[20:23], v[156:159], v[196:199], v[20:23]
	v_mfma_f32_16x16x32_bf16 v[12:15], v[156:159], v[212:215], v[12:15]
	v_mfma_f32_16x16x32_bf16 v[52:55], v[160:163], v[180:183], v[28:31]
	v_mfma_f32_16x16x32_bf16 v[44:47], v[224:227], v[200:203], v[20:23]
	v_mfma_f32_16x16x32_bf16 v[20:23], v[228:231], v[196:199], v[172:175]
	v_mfma_f32_16x16x32_bf16 v[28:31], v[224:227], v[216:219], v[12:15]
	v_mfma_f32_16x16x32_bf16 v[12:15], v[228:231], v[212:215], v[176:179]
	v_mfma_f32_16x16x32_bf16 v[4:7], v[156:159], v[232:235], v[4:7]
	v_mfma_f32_16x16x32_bf16 v[36:39], v[160:163], v[200:203], v[20:23]
	v_mfma_f32_16x16x32_bf16 v[20:23], v[160:163], v[216:219], v[12:15]
	v_mfma_f32_16x16x32_bf16 v[12:15], v[224:227], v[236:239], v[4:7]
	v_mfma_f32_16x16x32_bf16 v[4:7], v[228:231], v[232:235], v[204:207]
	v_mfma_f32_16x16x32_bf16 v[4:7], v[160:163], v[236:239], v[4:7]
	s_andn2_b64 vcc, exec, s[14:15]
	s_barrier
	s_cbranch_vccnz .LBB0_133
	s_barrier

; #define WAIT_V(n) asm volatile("s_waitcnt vmcnt(%0)" ::"n"(n) : "memory")
; #define WAIT_L(n) asm volatile("s_waitcnt lgkmcnt(%0)" ::"n"(n) : "memory")
; #define SBAR() __builtin_amdgcn_sched_barrier(0)
; #define STAGE(P, base, kt) do { _Pragma("unroll") for (int _i = 0; _i < 2; ++_i)                                        \
;       __builtin_amdgcn_global_load_lds((const unsigned*)((base) + (size_t)(sOff[_i] + (unsigned)(kt) * (BK * 2))),        \
;                                        (unsigned*)((P) + wid * 1024 + _i * 8192), 16, 0, 0); } while (0)
; #define LDA(dst, b, h) _Pragma("unroll") for (int m = 0; m < 4; ++m) _Pragma("unroll") for (int k = 0; k < 2; ++k) \
;       dst[m][k] = *(const bf16x8*)(SA(b, h) + aoff + (m * 2048 + k * 1024))
; #define LDB(dst, b, h) _Pragma("unroll") for (int n = 0; n < 2; ++n) _Pragma("unroll") for (int k = 0; k < 2; ++k) \
;       dst[n][k] = *(const bf16x8*)(SB(b, h) + boff + (n * 256 + k * 1024))
; #define BAR __builtin_amdgcn_s_barrier()
; template <int EPI, int N, int K>
; __device__ __forceinline__ void phase_gemm(const Params& p, const u16* __restrict__ A, const u16* __restrict__ Bt, int nM, char* shm,
;                            u16* __restrict__ outp, float* __restrict__ rowss) {
;     ...
;   for (;;) {
;     const char* A1 = A0 + (size_t)128 * K * 2;
;     const char* B1p = B0p + (size_t)128 * K * 2;
;     f32x4 acc[2][2][4][2] = {};
;     bf16x8 At[4][2], B0[2][2], B1[2][2];
;     if (wr == 1) BAR;
;     WAIT_V(0); BAR;
;     BAR;
;     for (int t = 0; t < nt - 2; t += 2) {
;       LDB(B0, 0, 0); SBAR(); LDA(At, 0, 0); STAGE(SA(1, 1), A1, t + 1);
;       WAIT_L(8); BAR; WAIT_L(0); MMA(0, 0, At, B0); BAR; SBAR();
;       LDB(B1, 0, 1); STAGE(SB(0, 0), B0p, t + 2);
;       BAR; WAIT_L(0); MMA(0, 1, At, B1); BAR;
;       LDA(At, 0, 1); STAGE(SA(0, 0), A0, t + 2);
;       BAR; WAIT_L(0); MMA(1, 0, At, B0); BAR; SBAR();
;       STAGE(SB(0, 1), B1p, t + 2);
;       WAIT_V(6); BAR; MMA(1, 1, At, B1); BAR;
.LBB0_197:
	s_add_u32 s6, s14, 0x40000
	s_addc_u32 s7, s15, 0
	s_waitcnt vmcnt(0)
	s_add_u32 s22, s12, 0x40000
	s_addc_u32 s23, s13, 0
	s_mov_b32 s59, -2
	v_mov_b32_e32 v96, v150
	v_mov_b32_e32 v142, v149
	s_waitcnt lgkmcnt(0)
	s_barrier
	s_barrier
	v_or_b32_e32 v143, 0x10000, v147
	v_add_u32_e32 v145, 0x10100, v147
	v_add_u32_e32 v144, 0x10400, v147
	ds_read_b128 v[156:159], v143
	ds_read_b128 v[160:163], v144
	v_add_u32_e32 v151, 0x10500, v147
	ds_read_b128 v[164:167], v145
	ds_read_b128 v[168:171], v151
	v_add_u32_e32 v240, v146, v96
	s_add_i32 s61, s5, 0xc000
	v_add_u32_e32 v152, 0x80, v240
	s_mov_b32 m0, s61
	v_add_u32_e32 v241, v146, v142
	s_add_i32 s60, s5, 0xe000
	ds_read_b128 v[172:175], v148
	ds_read_b128 v[176:179], v148 offset:1024
	ds_read_b128 v[180:183], v148 offset:2048
	ds_read_b128 v[196:199], v148 offset:3072
	ds_read_b128 v[200:203], v148 offset:4096
	ds_read_b128 v[204:207], v148 offset:5120
	ds_read_b128 v[208:211], v148 offset:6144
	ds_read_b128 v[212:215], v148 offset:7168
	global_load_lds_dwordx4 v152, s[6:7]
	v_add_u32_e32 v152, 0x80, v241
	s_mov_b32 m0, s60
	s_nop 0
	global_load_lds_dwordx4 v152, s[6:7]
	s_waitcnt lgkmcnt(8)
	s_barrier
	s_waitcnt lgkmcnt(0)
	s_waitcnt lgkmcnt(0)
	v_mfma_f32_16x16x32_bf16 v[126:129], v[156:159], v[172:175], 0
	v_mfma_f32_16x16x32_bf16 v[122:125], v[164:167], v[172:175], 0
	v_mfma_f32_16x16x32_bf16 v[118:121], v[156:159], v[180:183], 0
	v_mfma_f32_16x16x32_bf16 v[114:117], v[164:167], v[180:183], 0
	v_mfma_f32_16x16x32_bf16 v[110:113], v[156:159], v[200:203], 0
	v_mfma_f32_16x16x32_bf16 v[106:109], v[164:167], v[200:203], 0
	v_mfma_f32_16x16x32_bf16 v[102:105], v[156:159], v[208:211], 0
	v_mfma_f32_16x16x32_bf16 v[98:101], v[164:167], v[208:211], 0
	v_mfma_f32_16x16x32_bf16 v[126:129], v[160:163], v[176:179], v[126:129]
	v_mfma_f32_16x16x32_bf16 v[122:125], v[168:171], v[176:179], v[122:125]
	v_mfma_f32_16x16x32_bf16 v[118:121], v[160:163], v[196:199], v[118:121]
	v_mfma_f32_16x16x32_bf16 v[114:117], v[168:171], v[196:199], v[114:117]
	v_mfma_f32_16x16x32_bf16 v[110:113], v[160:163], v[204:207], v[110:113]
	v_mfma_f32_16x16x32_bf16 v[106:109], v[168:171], v[204:207], v[106:109]
	v_mfma_f32_16x16x32_bf16 v[102:105], v[160:163], v[212:215], v[102:105]
	v_mfma_f32_16x16x32_bf16 v[98:101], v[168:171], v[212:215], v[98:101]
	s_barrier
	s_mov_b32 m0, s26
	v_or_b32_e32 v152, 0x14000, v147
	v_add_u32_e32 v154, 0x14100, v147
	v_add_u32_e32 v232, 0x100, v240
	v_add_u32_e32 v153, 0x14400, v147
	ds_read_b128 v[216:219], v152
	ds_read_b128 v[220:223], v153
	v_add_u32_e32 v155, 0x14500, v147
	ds_read_b128 v[224:227], v154
	ds_read_b128 v[228:231], v155
	global_load_lds_dwordx4 v232, s[12:13]
	v_add_u32_e32 v233, 0x100, v241
	s_mov_b32 m0, s27
	s_nop 0
	global_load_lds_dwordx4 v233, s[12:13]
	s_barrier
	s_waitcnt lgkmcnt(0)
	s_waitcnt lgkmcnt(0)
	v_mfma_f32_16x16x32_bf16 v[92:95], v[216:219], v[172:175], 0
	v_mfma_f32_16x16x32_bf16 v[88:91], v[224:227], v[172:175], 0
	v_mfma_f32_16x16x32_bf16 v[84:87], v[216:219], v[180:183], 0
	v_mfma_f32_16x16x32_bf16 v[80:83], v[224:227], v[180:183], 0
	v_mfma_f32_16x16x32_bf16 v[76:79], v[216:219], v[200:203], 0
	v_mfma_f32_16x16x32_bf16 v[72:75], v[224:227], v[200:203], 0
	v_mfma_f32_16x16x32_bf16 v[68:71], v[216:219], v[208:211], 0
	v_mfma_f32_16x16x32_bf16 v[64:67], v[224:227], v[208:211], 0
	v_mfma_f32_16x16x32_bf16 v[92:95], v[220:223], v[176:179], v[92:95]
	v_mfma_f32_16x16x32_bf16 v[88:91], v[228:231], v[176:179], v[88:91]
	v_mfma_f32_16x16x32_bf16 v[84:87], v[220:223], v[196:199], v[84:87]
	v_mfma_f32_16x16x32_bf16 v[80:83], v[228:231], v[196:199], v[80:83]
	v_mfma_f32_16x16x32_bf16 v[76:79], v[220:223], v[204:207], v[76:79]
	v_mfma_f32_16x16x32_bf16 v[72:75], v[228:231], v[204:207], v[72:75]
	v_mfma_f32_16x16x32_bf16 v[68:71], v[220:223], v[212:215], v[68:71]
	v_mfma_f32_16x16x32_bf16 v[64:67], v[228:231], v[212:215], v[64:67]
	s_mov_b32 m0, s5
	s_barrier
	ds_read_b128 v[172:175], v148 offset:16384
	ds_read_b128 v[176:179], v148 offset:17408
	ds_read_b128 v[180:183], v148 offset:18432
	ds_read_b128 v[196:199], v148 offset:19456
	ds_read_b128 v[200:203], v148 offset:20480
	ds_read_b128 v[204:207], v148 offset:21504
	ds_read_b128 v[208:211], v148 offset:22528
	ds_read_b128 v[212:215], v148 offset:23552
	global_load_lds_dwordx4 v232, s[14:15]
	s_mov_b32 m0, s24
	s_nop 0
	global_load_lds_dwordx4 v233, s[14:15]
	s_barrier
	s_waitcnt lgkmcnt(0)
	s_waitcnt lgkmcnt(0)
	v_mfma_f32_16x16x32_bf16 v[60:63], v[156:159], v[172:175], 0
	v_mfma_f32_16x16x32_bf16 v[56:59], v[164:167], v[172:175], 0
	v_mfma_f32_16x16x32_bf16 v[52:55], v[156:159], v[180:183], 0
	v_mfma_f32_16x16x32_bf16 v[48:51], v[164:167], v[180:183], 0
	v_mfma_f32_16x16x32_bf16 v[44:47], v[156:159], v[200:203], 0
	v_mfma_f32_16x16x32_bf16 v[40:43], v[164:167], v[200:203], 0
	v_mfma_f32_16x16x32_bf16 v[36:39], v[156:159], v[208:211], 0
	v_mfma_f32_16x16x32_bf16 v[32:35], v[164:167], v[208:211], 0
	v_mfma_f32_16x16x32_bf16 v[60:63], v[160:163], v[176:179], v[60:63]
	v_mfma_f32_16x16x32_bf16 v[56:59], v[168:171], v[176:179], v[56:59]
	v_mfma_f32_16x16x32_bf16 v[52:55], v[160:163], v[196:199], v[52:55]
	v_mfma_f32_16x16x32_bf16 v[48:51], v[168:171], v[196:199], v[48:51]
	v_mfma_f32_16x16x32_bf16 v[44:47], v[160:163], v[204:207], v[44:47]
	v_mfma_f32_16x16x32_bf16 v[40:43], v[168:171], v[204:207], v[40:43]
	v_mfma_f32_16x16x32_bf16 v[36:39], v[160:163], v[212:215], v[36:39]
	v_mfma_f32_16x16x32_bf16 v[32:35], v[168:171], v[212:215], v[32:35]
	s_barrier
	s_mov_b32 m0, s28
	s_nop 0
	global_load_lds_dwordx4 v232, s[22:23]
	s_mov_b32 m0, s29
	s_nop 0
	global_load_lds_dwordx4 v233, s[22:23]
	s_waitcnt vmcnt(6)
	s_barrier
; #define WAIT_V(n) asm volatile("s_waitcnt vmcnt(%0)" ::"n"(n) : "memory")
; #define WAIT_L(n) asm volatile("s_waitcnt lgkmcnt(%0)" ::"n"(n) : "memory")
; #define SBAR() __builtin_amdgcn_sched_barrier(0)
; #define STAGE(P, base, kt) do { _Pragma("unroll") for (int _i = 0; _i < 2; ++_i)                                        \
;       __builtin_amdgcn_global_load_lds((const unsigned*)((base) + (size_t)(sOff[_i] + (unsigned)(kt) * (BK * 2))),        \
;                                        (unsigned*)((P) + wid * 1024 + _i * 8192), 16, 0, 0); } while (0)
; #define LDA(dst, b, h) _Pragma("unroll") for (int m = 0; m < 4; ++m) _Pragma("unroll") for (int k = 0; k < 2; ++k) \
;       dst[m][k] = *(const bf16x8*)(SA(b, h) + aoff + (m * 2048 + k * 1024))
; #define LDB(dst, b, h) _Pragma("unroll") for (int n = 0; n < 2; ++n) _Pragma("unroll") for (int k = 0; k < 2; ++k) \
;       dst[n][k] = *(const bf16x8*)(SB(b, h) + boff + (n * 256 + k * 1024))
; #define BAR __builtin_amdgcn_s_barrier()
; template <int EPI, int N, int K>
; __device__ __forceinline__ void phase_gemm(const Params& p, const u16* __restrict__ A, const u16* __restrict__ Bt, int nM, char* shm,
;                            u16* __restrict__ outp, float* __restrict__ rowss) {
;     ...
;       WAIT_V(6); BAR; MMA(1, 1, At, B1); BAR;
;       LDB(B0, 1, 0); SBAR(); LDA(At, 1, 0); STAGE(SA(0, 1), A1, t + 2);
;       WAIT_L(8); BAR; WAIT_L(0); MMA(0, 0, At, B0); BAR; SBAR();
;       LDB(B1, 1, 1); STAGE(SB(1, 0), B0p, t + 3);
;       BAR; WAIT_L(0); MMA(0, 1, At, B1); BAR;
;       LDA(At, 1, 1); STAGE(SA(1, 0), A0, t + 3);
;       BAR; WAIT_L(0); MMA(1, 0, At, B0); BAR; SBAR();
	v_mfma_f32_16x16x32_bf16 v[28:31], v[216:219], v[172:175], 0
	v_mfma_f32_16x16x32_bf16 v[24:27], v[224:227], v[172:175], 0
	v_mfma_f32_16x16x32_bf16 v[20:23], v[216:219], v[180:183], 0
	v_mfma_f32_16x16x32_bf16 v[16:19], v[224:227], v[180:183], 0
	v_mfma_f32_16x16x32_bf16 v[12:15], v[216:219], v[200:203], 0
	v_mfma_f32_16x16x32_bf16 v[8:11], v[224:227], v[200:203], 0
	v_mfma_f32_16x16x32_bf16 v[4:7], v[216:219], v[208:211], 0
	v_mfma_f32_16x16x32_bf16 v[0:3], v[224:227], v[208:211], 0
	v_mfma_f32_16x16x32_bf16 v[28:31], v[220:223], v[176:179], v[28:31]
	v_mfma_f32_16x16x32_bf16 v[24:27], v[228:231], v[176:179], v[24:27]
	v_mfma_f32_16x16x32_bf16 v[20:23], v[220:223], v[196:199], v[20:23]
	v_mfma_f32_16x16x32_bf16 v[16:19], v[228:231], v[196:199], v[16:19]
	v_mfma_f32_16x16x32_bf16 v[12:15], v[220:223], v[204:207], v[12:15]
	v_mfma_f32_16x16x32_bf16 v[8:11], v[228:231], v[204:207], v[8:11]
	v_mfma_f32_16x16x32_bf16 v[4:7], v[220:223], v[212:215], v[4:7]
	v_mfma_f32_16x16x32_bf16 v[0:3], v[228:231], v[212:215], v[0:3]
	v_or_b32_e32 v156, 0x18000, v147
	v_add_u32_e32 v158, 0x18100, v147
	s_barrier
	v_add_u32_e32 v157, 0x18400, v147
	ds_read_b128 v[164:167], v156
	ds_read_b128 v[168:171], v157
	v_add_u32_e32 v159, 0x18500, v147
	ds_read_b128 v[172:175], v158
	ds_read_b128 v[176:179], v159
	s_mov_b32 m0, s30
	ds_read_b128 v[180:183], v148 offset:32768
	ds_read_b128 v[196:199], v148 offset:33792
	ds_read_b128 v[200:203], v148 offset:34816
	ds_read_b128 v[204:207], v148 offset:35840
	ds_read_b128 v[208:211], v148 offset:36864
	ds_read_b128 v[212:215], v148 offset:37888
	ds_read_b128 v[216:219], v148 offset:38912
	ds_read_b128 v[220:223], v148 offset:39936
	global_load_lds_dwordx4 v232, s[6:7]
	s_mov_b32 m0, s31
	s_nop 0
	global_load_lds_dwordx4 v233, s[6:7]
	s_waitcnt lgkmcnt(8)
	s_barrier
	s_waitcnt lgkmcnt(0)
	s_waitcnt lgkmcnt(0)
	v_mfma_f32_16x16x32_bf16 v[126:129], v[164:167], v[180:183], v[126:129]
	v_mfma_f32_16x16x32_bf16 v[122:125], v[172:175], v[180:183], v[122:125]
	v_mfma_f32_16x16x32_bf16 v[118:121], v[164:167], v[200:203], v[118:121]
	v_mfma_f32_16x16x32_bf16 v[114:117], v[172:175], v[200:203], v[114:117]
	v_mfma_f32_16x16x32_bf16 v[110:113], v[164:167], v[208:211], v[110:113]
	v_mfma_f32_16x16x32_bf16 v[106:109], v[172:175], v[208:211], v[106:109]
	v_mfma_f32_16x16x32_bf16 v[102:105], v[164:167], v[216:219], v[102:105]
	v_mfma_f32_16x16x32_bf16 v[98:101], v[172:175], v[216:219], v[98:101]
	v_mfma_f32_16x16x32_bf16 v[126:129], v[168:171], v[196:199], v[126:129]
	v_mfma_f32_16x16x32_bf16 v[122:125], v[176:179], v[196:199], v[122:125]
	v_mfma_f32_16x16x32_bf16 v[118:121], v[168:171], v[204:207], v[118:121]
	v_mfma_f32_16x16x32_bf16 v[114:117], v[176:179], v[204:207], v[114:117]
	v_mfma_f32_16x16x32_bf16 v[110:113], v[168:171], v[212:215], v[110:113]
	v_mfma_f32_16x16x32_bf16 v[106:109], v[176:179], v[212:215], v[106:109]
	v_mfma_f32_16x16x32_bf16 v[102:105], v[168:171], v[220:223], v[102:105]
	v_mfma_f32_16x16x32_bf16 v[98:101], v[176:179], v[220:223], v[98:101]
	s_barrier
	s_mov_b32 m0, s33
	v_or_b32_e32 v160, 0x1c000, v147
	v_add_u32_e32 v162, 0x1c100, v147
	v_add_u32_e32 v240, 0x180, v240
	v_add_u32_e32 v161, 0x1c400, v147
	ds_read_b128 v[224:227], v160
	ds_read_b128 v[228:231], v161
	v_add_u32_e32 v163, 0x1c500, v147
	ds_read_b128 v[232:235], v162
	ds_read_b128 v[236:239], v163
	global_load_lds_dwordx4 v240, s[12:13]
	v_add_u32_e32 v241, 0x180, v241
	s_mov_b32 m0, s35
	s_nop 0
	global_load_lds_dwordx4 v241, s[12:13]
	s_barrier
	s_waitcnt lgkmcnt(0)
	s_waitcnt lgkmcnt(0)
	v_mfma_f32_16x16x32_bf16 v[92:95], v[224:227], v[180:183], v[92:95]
	v_mfma_f32_16x16x32_bf16 v[88:91], v[232:235], v[180:183], v[88:91]
	v_mfma_f32_16x16x32_bf16 v[84:87], v[224:227], v[200:203], v[84:87]
	v_mfma_f32_16x16x32_bf16 v[80:83], v[232:235], v[200:203], v[80:83]
	v_mfma_f32_16x16x32_bf16 v[76:79], v[224:227], v[208:211], v[76:79]
	v_mfma_f32_16x16x32_bf16 v[72:75], v[232:235], v[208:211], v[72:75]
	v_mfma_f32_16x16x32_bf16 v[68:71], v[224:227], v[216:219], v[68:71]
	v_mfma_f32_16x16x32_bf16 v[64:67], v[232:235], v[216:219], v[64:67]
	v_mfma_f32_16x16x32_bf16 v[92:95], v[228:231], v[196:199], v[92:95]
	v_mfma_f32_16x16x32_bf16 v[88:91], v[236:239], v[196:199], v[88:91]
	v_mfma_f32_16x16x32_bf16 v[84:87], v[228:231], v[204:207], v[84:87]
	v_mfma_f32_16x16x32_bf16 v[80:83], v[236:239], v[204:207], v[80:83]
	v_mfma_f32_16x16x32_bf16 v[76:79], v[228:231], v[212:215], v[76:79]
	v_mfma_f32_16x16x32_bf16 v[72:75], v[236:239], v[212:215], v[72:75]
	v_mfma_f32_16x16x32_bf16 v[68:71], v[228:231], v[220:223], v[68:71]
	v_mfma_f32_16x16x32_bf16 v[64:67], v[236:239], v[220:223], v[64:67]
	s_mov_b32 m0, s92
	s_barrier
	ds_read_b128 v[180:183], v148 offset:49152
	ds_read_b128 v[196:199], v148 offset:50176
	ds_read_b128 v[200:203], v148 offset:51200
	ds_read_b128 v[204:207], v148 offset:52224
	ds_read_b128 v[208:211], v148 offset:53248
	ds_read_b128 v[212:215], v148 offset:54272
	ds_read_b128 v[216:219], v148 offset:55296
	ds_read_b128 v[220:223], v148 offset:56320
	global_load_lds_dwordx4 v240, s[14:15]
	s_mov_b32 m0, s93
	s_nop 0
	global_load_lds_dwordx4 v241, s[14:15]
	s_barrier
; #define WAIT_V(n) asm volatile("s_waitcnt vmcnt(%0)" ::"n"(n) : "memory")
; #define WAIT_L(n) asm volatile("s_waitcnt lgkmcnt(%0)" ::"n"(n) : "memory")
; #define SBAR() __builtin_amdgcn_sched_barrier(0)
; #define STAGE(P, base, kt) do { _Pragma("unroll") for (int _i = 0; _i < 2; ++_i)                                        \
;       __builtin_amdgcn_global_load_lds((const unsigned*)((base) + (size_t)(sOff[_i] + (unsigned)(kt) * (BK * 2))),        \
;                                        (unsigned*)((P) + wid * 1024 + _i * 8192), 16, 0, 0); } while (0)
; #define LDA(dst, b, h) _Pragma("unroll") for (int m = 0; m < 4; ++m) _Pragma("unroll") for (int k = 0; k < 2; ++k) \
;       dst[m][k] = *(const bf16x8*)(SA(b, h) + aoff + (m * 2048 + k * 1024))
; #define LDB(dst, b, h) _Pragma("unroll") for (int n = 0; n < 2; ++n) _Pragma("unroll") for (int k = 0; k < 2; ++k) \
;       dst[n][k] = *(const bf16x8*)(SB(b, h) + boff + (n * 256 + k * 1024))
; #define BAR __builtin_amdgcn_s_barrier()
; template <int EPI, int N, int K>
; __device__ __forceinline__ void phase_gemm(const Params& p, const u16* __restrict__ A, const u16* __restrict__ Bt, int nM, char* shm,
;                            u16* __restrict__ outp, float* __restrict__ rowss) {
;     ...
;     for (int t = 0; t < nt - 2; t += 2) {
;       LDB(B0, 0, 0); SBAR(); LDA(At, 0, 0); STAGE(SA(1, 1), A1, t + 1);
;       WAIT_L(8); BAR; WAIT_L(0); MMA(0, 0, At, B0); BAR; SBAR();
;       LDB(B1, 0, 1); STAGE(SB(0, 0), B0p, t + 2);
;       BAR; WAIT_L(0); MMA(0, 1, At, B1); BAR;
;       LDA(At, 0, 1); STAGE(SA(0, 0), A0, t + 2);
;     ...
;       BAR; WAIT_L(0); MMA(1, 0, At, B0); BAR; SBAR();
;       STAGE(SB(1, 1), B1p, t + 3);
;       WAIT_V(6); BAR; MMA(1, 1, At, B1); BAR;
	s_waitcnt lgkmcnt(0)
	s_waitcnt lgkmcnt(0)
	v_mfma_f32_16x16x32_bf16 v[60:63], v[164:167], v[180:183], v[60:63]
	v_mfma_f32_16x16x32_bf16 v[56:59], v[172:175], v[180:183], v[56:59]
	v_mfma_f32_16x16x32_bf16 v[52:55], v[164:167], v[200:203], v[52:55]
	v_mfma_f32_16x16x32_bf16 v[48:51], v[172:175], v[200:203], v[48:51]
	v_mfma_f32_16x16x32_bf16 v[44:47], v[164:167], v[208:211], v[44:47]
	v_mfma_f32_16x16x32_bf16 v[40:43], v[172:175], v[208:211], v[40:43]
	v_mfma_f32_16x16x32_bf16 v[36:39], v[164:167], v[216:219], v[36:39]
	v_mfma_f32_16x16x32_bf16 v[32:35], v[172:175], v[216:219], v[32:35]
	v_mfma_f32_16x16x32_bf16 v[60:63], v[168:171], v[196:199], v[60:63]
	v_mfma_f32_16x16x32_bf16 v[56:59], v[176:179], v[196:199], v[56:59]
	v_mfma_f32_16x16x32_bf16 v[52:55], v[168:171], v[204:207], v[52:55]
	v_mfma_f32_16x16x32_bf16 v[48:51], v[176:179], v[204:207], v[48:51]
	v_mfma_f32_16x16x32_bf16 v[44:47], v[168:171], v[212:215], v[44:47]
	v_mfma_f32_16x16x32_bf16 v[40:43], v[176:179], v[212:215], v[40:43]
	v_mfma_f32_16x16x32_bf16 v[36:39], v[168:171], v[220:223], v[36:39]
	v_mfma_f32_16x16x32_bf16 v[32:35], v[176:179], v[220:223], v[32:35]
	s_barrier
	s_mov_b32 m0, s52
	s_nop 0
	global_load_lds_dwordx4 v240, s[22:23]
	s_mov_b32 m0, s53
	s_nop 0
	global_load_lds_dwordx4 v241, s[22:23]
	s_waitcnt vmcnt(6)
	s_barrier
	v_mfma_f32_16x16x32_bf16 v[28:31], v[224:227], v[180:183], v[28:31]
	v_mfma_f32_16x16x32_bf16 v[24:27], v[232:235], v[180:183], v[24:27]
	v_mfma_f32_16x16x32_bf16 v[20:23], v[224:227], v[200:203], v[20:23]
	v_mfma_f32_16x16x32_bf16 v[16:19], v[232:235], v[200:203], v[16:19]
	v_mfma_f32_16x16x32_bf16 v[12:15], v[224:227], v[208:211], v[12:15]
	v_mfma_f32_16x16x32_bf16 v[8:11], v[232:235], v[208:211], v[8:11]
	v_mfma_f32_16x16x32_bf16 v[4:7], v[224:227], v[216:219], v[4:7]
	v_mfma_f32_16x16x32_bf16 v[0:3], v[232:235], v[216:219], v[0:3]
	v_mfma_f32_16x16x32_bf16 v[28:31], v[228:231], v[196:199], v[28:31]
	v_mfma_f32_16x16x32_bf16 v[24:27], v[236:239], v[196:199], v[24:27]
	v_mfma_f32_16x16x32_bf16 v[20:23], v[228:231], v[204:207], v[20:23]
	v_mfma_f32_16x16x32_bf16 v[16:19], v[236:239], v[204:207], v[16:19]
	v_mfma_f32_16x16x32_bf16 v[12:15], v[228:231], v[212:215], v[12:15]
	v_mfma_f32_16x16x32_bf16 v[8:11], v[236:239], v[212:215], v[8:11]
	v_mfma_f32_16x16x32_bf16 v[4:7], v[228:231], v[220:223], v[4:7]
	v_mfma_f32_16x16x32_bf16 v[0:3], v[236:239], v[220:223], v[0:3]
	s_add_i32 s59, s59, 2
	v_add_u32_e32 v142, 0x100, v142
	s_cmp_lt_u32 s59, 12
	v_add_u32_e32 v96, 0x100, v96
	s_barrier
.LBB0_198:
	v_or_b32_e32 v143, 0x10000, v147
	v_add_u32_e32 v145, 0x10100, v147
	v_add_u32_e32 v144, 0x10400, v147
	ds_read_b128 v[156:159], v143
	ds_read_b128 v[160:163], v144
	v_add_u32_e32 v151, 0x10500, v147
	ds_read_b128 v[164:167], v145
	ds_read_b128 v[168:171], v151
	v_add_u32_e32 v240, v146, v96
	s_add_i32 s61, s5, 0xc000
	v_add_u32_e32 v152, 0x80, v240
	s_mov_b32 m0, s61
	v_add_u32_e32 v241, v146, v142
	s_add_i32 s60, s5, 0xe000
	ds_read_b128 v[172:175], v148
	ds_read_b128 v[176:179], v148 offset:1024
	ds_read_b128 v[180:183], v148 offset:2048
	ds_read_b128 v[196:199], v148 offset:3072
	ds_read_b128 v[200:203], v148 offset:4096
	ds_read_b128 v[204:207], v148 offset:5120
	ds_read_b128 v[208:211], v148 offset:6144
	ds_read_b128 v[212:215], v148 offset:7168
	global_load_lds_dwordx4 v152, s[6:7]
	v_add_u32_e32 v152, 0x80, v241
	s_mov_b32 m0, s60
	s_nop 0
	global_load_lds_dwordx4 v152, s[6:7]
	s_waitcnt lgkmcnt(8)
	s_barrier
	s_waitcnt lgkmcnt(0)
	s_waitcnt lgkmcnt(0)
	v_mfma_f32_16x16x32_bf16 v[126:129], v[156:159], v[172:175], v[126:129]
	v_mfma_f32_16x16x32_bf16 v[122:125], v[164:167], v[172:175], v[122:125]
	v_mfma_f32_16x16x32_bf16 v[118:121], v[156:159], v[180:183], v[118:121]
	v_mfma_f32_16x16x32_bf16 v[114:117], v[164:167], v[180:183], v[114:117]
	v_mfma_f32_16x16x32_bf16 v[110:113], v[156:159], v[200:203], v[110:113]
	v_mfma_f32_16x16x32_bf16 v[106:109], v[164:167], v[200:203], v[106:109]
	v_mfma_f32_16x16x32_bf16 v[102:105], v[156:159], v[208:211], v[102:105]
	v_mfma_f32_16x16x32_bf16 v[98:101], v[164:167], v[208:211], v[98:101]
	v_mfma_f32_16x16x32_bf16 v[126:129], v[160:163], v[176:179], v[126:129]
	v_mfma_f32_16x16x32_bf16 v[122:125], v[168:171], v[176:179], v[122:125]
	v_mfma_f32_16x16x32_bf16 v[118:121], v[160:163], v[196:199], v[118:121]
	v_mfma_f32_16x16x32_bf16 v[114:117], v[168:171], v[196:199], v[114:117]
	v_mfma_f32_16x16x32_bf16 v[110:113], v[160:163], v[204:207], v[110:113]
	v_mfma_f32_16x16x32_bf16 v[106:109], v[168:171], v[204:207], v[106:109]
	v_mfma_f32_16x16x32_bf16 v[102:105], v[160:163], v[212:215], v[102:105]
	v_mfma_f32_16x16x32_bf16 v[98:101], v[168:171], v[212:215], v[98:101]
	s_barrier
	s_mov_b32 m0, s26
	v_or_b32_e32 v152, 0x14000, v147
	v_add_u32_e32 v154, 0x14100, v147
	v_add_u32_e32 v232, 0x100, v240
	v_add_u32_e32 v153, 0x14400, v147
	ds_read_b128 v[216:219], v152
	ds_read_b128 v[220:223], v153
	v_add_u32_e32 v155, 0x14500, v147
	ds_read_b128 v[224:227], v154
	ds_read_b128 v[228:231], v155
	global_load_lds_dwordx4 v232, s[12:13]
	v_add_u32_e32 v233, 0x100, v241
	s_mov_b32 m0, s27
	s_nop 0
	global_load_lds_dwordx4 v233, s[12:13]
	s_barrier
; #define WAIT_V(n) asm volatile("s_waitcnt vmcnt(%0)" ::"n"(n) : "memory")
; #define WAIT_L(n) asm volatile("s_waitcnt lgkmcnt(%0)" ::"n"(n) : "memory")
; #define SBAR() __builtin_amdgcn_sched_barrier(0)
; #define STAGE(P, base, kt) do { _Pragma("unroll") for (int _i = 0; _i < 2; ++_i)                                        \
;       __builtin_amdgcn_global_load_lds((const unsigned*)((base) + (size_t)(sOff[_i] + (unsigned)(kt) * (BK * 2))),        \
;                                        (unsigned*)((P) + wid * 1024 + _i * 8192), 16, 0, 0); } while (0)
; #define LDA(dst, b, h) _Pragma("unroll") for (int m = 0; m < 4; ++m) _Pragma("unroll") for (int k = 0; k < 2; ++k) \
;       dst[m][k] = *(const bf16x8*)(SA(b, h) + aoff + (m * 2048 + k * 1024))
; #define LDB(dst, b, h) _Pragma("unroll") for (int n = 0; n < 2; ++n) _Pragma("unroll") for (int k = 0; k < 2; ++k) \
;       dst[n][k] = *(const bf16x8*)(SB(b, h) + boff + (n * 256 + k * 1024))
; #define BAR __builtin_amdgcn_s_barrier()
; template <int EPI, int N, int K>
; __device__ __forceinline__ void phase_gemm(const Params& p, const u16* __restrict__ A, const u16* __restrict__ Bt, int nM, char* shm,
;                            u16* __restrict__ outp, float* __restrict__ rowss) {
;     ...
;       BAR; WAIT_L(0); MMA(1, 0, At, B0); BAR; SBAR();
;       STAGE(SB(0, 1), B1p, t + 2);
;       WAIT_V(6); BAR; MMA(1, 1, At, B1); BAR;
;       LDB(B0, 1, 0); SBAR(); LDA(At, 1, 0); STAGE(SA(0, 1), A1, t + 2);
;       WAIT_L(8); BAR; WAIT_L(0); MMA(0, 0, At, B0); BAR; SBAR();
	s_waitcnt lgkmcnt(0)
	s_waitcnt lgkmcnt(0)
	v_mfma_f32_16x16x32_bf16 v[92:95], v[216:219], v[172:175], v[92:95]
	v_mfma_f32_16x16x32_bf16 v[88:91], v[224:227], v[172:175], v[88:91]
	v_mfma_f32_16x16x32_bf16 v[84:87], v[216:219], v[180:183], v[84:87]
	v_mfma_f32_16x16x32_bf16 v[80:83], v[224:227], v[180:183], v[80:83]
	v_mfma_f32_16x16x32_bf16 v[76:79], v[216:219], v[200:203], v[76:79]
	v_mfma_f32_16x16x32_bf16 v[72:75], v[224:227], v[200:203], v[72:75]
	v_mfma_f32_16x16x32_bf16 v[68:71], v[216:219], v[208:211], v[68:71]
	v_mfma_f32_16x16x32_bf16 v[64:67], v[224:227], v[208:211], v[64:67]
	v_mfma_f32_16x16x32_bf16 v[92:95], v[220:223], v[176:179], v[92:95]
	v_mfma_f32_16x16x32_bf16 v[88:91], v[228:231], v[176:179], v[88:91]
	v_mfma_f32_16x16x32_bf16 v[84:87], v[220:223], v[196:199], v[84:87]
	v_mfma_f32_16x16x32_bf16 v[80:83], v[228:231], v[196:199], v[80:83]
	v_mfma_f32_16x16x32_bf16 v[76:79], v[220:223], v[204:207], v[76:79]
	v_mfma_f32_16x16x32_bf16 v[72:75], v[228:231], v[204:207], v[72:75]
	v_mfma_f32_16x16x32_bf16 v[68:71], v[220:223], v[212:215], v[68:71]
	v_mfma_f32_16x16x32_bf16 v[64:67], v[228:231], v[212:215], v[64:67]
	s_mov_b32 m0, s5
	s_barrier
	ds_read_b128 v[172:175], v148 offset:16384
	ds_read_b128 v[176:179], v148 offset:17408
	ds_read_b128 v[180:183], v148 offset:18432
	ds_read_b128 v[196:199], v148 offset:19456
	ds_read_b128 v[200:203], v148 offset:20480
	ds_read_b128 v[204:207], v148 offset:21504
	ds_read_b128 v[208:211], v148 offset:22528
	ds_read_b128 v[212:215], v148 offset:23552
	global_load_lds_dwordx4 v232, s[14:15]
	s_mov_b32 m0, s24
	s_nop 0
	global_load_lds_dwordx4 v233, s[14:15]
	s_barrier
	s_waitcnt lgkmcnt(0)
	s_waitcnt lgkmcnt(0)
	v_mfma_f32_16x16x32_bf16 v[60:63], v[156:159], v[172:175], v[60:63]
	v_mfma_f32_16x16x32_bf16 v[56:59], v[164:167], v[172:175], v[56:59]
	v_mfma_f32_16x16x32_bf16 v[52:55], v[156:159], v[180:183], v[52:55]
	v_mfma_f32_16x16x32_bf16 v[48:51], v[164:167], v[180:183], v[48:51]
	v_mfma_f32_16x16x32_bf16 v[44:47], v[156:159], v[200:203], v[44:47]
	v_mfma_f32_16x16x32_bf16 v[40:43], v[164:167], v[200:203], v[40:43]
	v_mfma_f32_16x16x32_bf16 v[36:39], v[156:159], v[208:211], v[36:39]
	v_mfma_f32_16x16x32_bf16 v[32:35], v[164:167], v[208:211], v[32:35]
	v_mfma_f32_16x16x32_bf16 v[60:63], v[160:163], v[176:179], v[60:63]
	v_mfma_f32_16x16x32_bf16 v[56:59], v[168:171], v[176:179], v[56:59]
	v_mfma_f32_16x16x32_bf16 v[52:55], v[160:163], v[196:199], v[52:55]
	v_mfma_f32_16x16x32_bf16 v[48:51], v[168:171], v[196:199], v[48:51]
	v_mfma_f32_16x16x32_bf16 v[44:47], v[160:163], v[204:207], v[44:47]
	v_mfma_f32_16x16x32_bf16 v[40:43], v[168:171], v[204:207], v[40:43]
	v_mfma_f32_16x16x32_bf16 v[36:39], v[160:163], v[212:215], v[36:39]
	v_mfma_f32_16x16x32_bf16 v[32:35], v[168:171], v[212:215], v[32:35]
	s_barrier
	s_mov_b32 m0, s28
	s_nop 0
	global_load_lds_dwordx4 v232, s[22:23]
	s_mov_b32 m0, s29
	s_nop 0
	global_load_lds_dwordx4 v233, s[22:23]
	s_waitcnt vmcnt(6)
	s_barrier
	v_mfma_f32_16x16x32_bf16 v[28:31], v[216:219], v[172:175], v[28:31]
	v_mfma_f32_16x16x32_bf16 v[24:27], v[224:227], v[172:175], v[24:27]
	v_mfma_f32_16x16x32_bf16 v[20:23], v[216:219], v[180:183], v[20:23]
	v_mfma_f32_16x16x32_bf16 v[16:19], v[224:227], v[180:183], v[16:19]
	v_mfma_f32_16x16x32_bf16 v[12:15], v[216:219], v[200:203], v[12:15]
	v_mfma_f32_16x16x32_bf16 v[8:11], v[224:227], v[200:203], v[8:11]
	v_mfma_f32_16x16x32_bf16 v[4:7], v[216:219], v[208:211], v[4:7]
	v_mfma_f32_16x16x32_bf16 v[0:3], v[224:227], v[208:211], v[0:3]
	v_mfma_f32_16x16x32_bf16 v[28:31], v[220:223], v[176:179], v[28:31]
	v_mfma_f32_16x16x32_bf16 v[24:27], v[228:231], v[176:179], v[24:27]
	v_mfma_f32_16x16x32_bf16 v[20:23], v[220:223], v[196:199], v[20:23]
	v_mfma_f32_16x16x32_bf16 v[16:19], v[228:231], v[196:199], v[16:19]
	v_mfma_f32_16x16x32_bf16 v[12:15], v[220:223], v[204:207], v[12:15]
	v_mfma_f32_16x16x32_bf16 v[8:11], v[228:231], v[204:207], v[8:11]
	v_mfma_f32_16x16x32_bf16 v[4:7], v[220:223], v[212:215], v[4:7]
	v_mfma_f32_16x16x32_bf16 v[0:3], v[228:231], v[212:215], v[0:3]
	v_or_b32_e32 v156, 0x18000, v147
	v_add_u32_e32 v158, 0x18100, v147
	s_barrier
	v_add_u32_e32 v157, 0x18400, v147
	ds_read_b128 v[164:167], v156
	ds_read_b128 v[168:171], v157
	v_add_u32_e32 v159, 0x18500, v147
	ds_read_b128 v[172:175], v158
	ds_read_b128 v[176:179], v159
	s_mov_b32 m0, s30
	ds_read_b128 v[180:183], v148 offset:32768
	ds_read_b128 v[196:199], v148 offset:33792
	ds_read_b128 v[200:203], v148 offset:34816
	ds_read_b128 v[204:207], v148 offset:35840
	ds_read_b128 v[208:211], v148 offset:36864
	ds_read_b128 v[212:215], v148 offset:37888
	ds_read_b128 v[216:219], v148 offset:38912
	ds_read_b128 v[220:223], v148 offset:39936
	global_load_lds_dwordx4 v232, s[6:7]
	s_mov_b32 m0, s31
	s_nop 0
	global_load_lds_dwordx4 v233, s[6:7]
	s_waitcnt lgkmcnt(8)
	s_barrier
	s_waitcnt lgkmcnt(0)
	s_waitcnt lgkmcnt(0)
	v_mfma_f32_16x16x32_bf16 v[126:129], v[164:167], v[180:183], v[126:129]
	v_mfma_f32_16x16x32_bf16 v[122:125], v[172:175], v[180:183], v[122:125]
	v_mfma_f32_16x16x32_bf16 v[118:121], v[164:167], v[200:203], v[118:121]
	v_mfma_f32_16x16x32_bf16 v[114:117], v[172:175], v[200:203], v[114:117]
	v_mfma_f32_16x16x32_bf16 v[110:113], v[164:167], v[208:211], v[110:113]
	v_mfma_f32_16x16x32_bf16 v[106:109], v[172:175], v[208:211], v[106:109]
	v_mfma_f32_16x16x32_bf16 v[102:105], v[164:167], v[216:219], v[102:105]
	v_mfma_f32_16x16x32_bf16 v[98:101], v[172:175], v[216:219], v[98:101]
	v_mfma_f32_16x16x32_bf16 v[126:129], v[168:171], v[196:199], v[126:129]
	v_mfma_f32_16x16x32_bf16 v[122:125], v[176:179], v[196:199], v[122:125]
	v_mfma_f32_16x16x32_bf16 v[118:121], v[168:171], v[204:207], v[118:121]
	v_mfma_f32_16x16x32_bf16 v[114:117], v[176:179], v[204:207], v[114:117]
	v_mfma_f32_16x16x32_bf16 v[110:113], v[168:171], v[212:215], v[110:113]
	v_mfma_f32_16x16x32_bf16 v[106:109], v[176:179], v[212:215], v[106:109]
	v_mfma_f32_16x16x32_bf16 v[102:105], v[168:171], v[220:223], v[102:105]
	v_mfma_f32_16x16x32_bf16 v[98:101], v[176:179], v[220:223], v[98:101]
	s_barrier
; #define WAIT_V(n) asm volatile("s_waitcnt vmcnt(%0)" ::"n"(n) : "memory")
; #define WAIT_L(n) asm volatile("s_waitcnt lgkmcnt(%0)" ::"n"(n) : "memory")
; #define SBAR() __builtin_amdgcn_sched_barrier(0)
; #define STAGE(P, base, kt) do { _Pragma("unroll") for (int _i = 0; _i < 2; ++_i)                                        \
;       __builtin_amdgcn_global_load_lds((const unsigned*)((base) + (size_t)(sOff[_i] + (unsigned)(kt) * (BK * 2))),        \
;                                        (unsigned*)((P) + wid * 1024 + _i * 8192), 16, 0, 0); } while (0)
; #define LDA(dst, b, h) _Pragma("unroll") for (int m = 0; m < 4; ++m) _Pragma("unroll") for (int k = 0; k < 2; ++k) \
;       dst[m][k] = *(const bf16x8*)(SA(b, h) + aoff + (m * 2048 + k * 1024))
; #define LDB(dst, b, h) _Pragma("unroll") for (int n = 0; n < 2; ++n) _Pragma("unroll") for (int k = 0; k < 2; ++k) \
;       dst[n][k] = *(const bf16x8*)(SB(b, h) + boff + (n * 256 + k * 1024))
; #define BAR __builtin_amdgcn_s_barrier()
; template <int EPI, int N, int K>
; __device__ __forceinline__ void phase_gemm(const Params& p, const u16* __restrict__ A, const u16* __restrict__ Bt, int nM, char* shm,
;                            u16* __restrict__ outp, float* __restrict__ rowss) {
;     ...
;       LDB(B1, 1, 1); STAGE(SB(1, 0), B0p, t + 3);
;       BAR; WAIT_L(0); MMA(0, 1, At, B1); BAR;
;       LDA(At, 1, 1); STAGE(SA(1, 0), A0, t + 3);
;       BAR; WAIT_L(0); MMA(1, 0, At, B0); BAR; SBAR();
;       STAGE(SB(1, 1), B1p, t + 3);
;       WAIT_V(6); BAR; MMA(1, 1, At, B1); BAR;
;     }
;     { LDB(B0, 0, 0); LDA(At, 0, 0); STAGE(SA(1, 1), A1, nt - 1);
	s_mov_b32 m0, s33
	v_or_b32_e32 v160, 0x1c000, v147
	v_add_u32_e32 v162, 0x1c100, v147
	v_add_u32_e32 v240, 0x180, v240
	v_add_u32_e32 v161, 0x1c400, v147
	ds_read_b128 v[224:227], v160
	ds_read_b128 v[228:231], v161
	v_add_u32_e32 v163, 0x1c500, v147
	ds_read_b128 v[232:235], v162
	ds_read_b128 v[236:239], v163
	global_load_lds_dwordx4 v240, s[12:13]
	v_add_u32_e32 v241, 0x180, v241
	s_mov_b32 m0, s35
	s_nop 0
	global_load_lds_dwordx4 v241, s[12:13]
	s_barrier
	s_waitcnt lgkmcnt(0)
	s_waitcnt lgkmcnt(0)
	v_mfma_f32_16x16x32_bf16 v[92:95], v[224:227], v[180:183], v[92:95]
	v_mfma_f32_16x16x32_bf16 v[88:91], v[232:235], v[180:183], v[88:91]
	v_mfma_f32_16x16x32_bf16 v[84:87], v[224:227], v[200:203], v[84:87]
	v_mfma_f32_16x16x32_bf16 v[80:83], v[232:235], v[200:203], v[80:83]
	v_mfma_f32_16x16x32_bf16 v[76:79], v[224:227], v[208:211], v[76:79]
	v_mfma_f32_16x16x32_bf16 v[72:75], v[232:235], v[208:211], v[72:75]
	v_mfma_f32_16x16x32_bf16 v[68:71], v[224:227], v[216:219], v[68:71]
	v_mfma_f32_16x16x32_bf16 v[64:67], v[232:235], v[216:219], v[64:67]
	v_mfma_f32_16x16x32_bf16 v[92:95], v[228:231], v[196:199], v[92:95]
	v_mfma_f32_16x16x32_bf16 v[88:91], v[236:239], v[196:199], v[88:91]
	v_mfma_f32_16x16x32_bf16 v[84:87], v[228:231], v[204:207], v[84:87]
	v_mfma_f32_16x16x32_bf16 v[80:83], v[236:239], v[204:207], v[80:83]
	v_mfma_f32_16x16x32_bf16 v[76:79], v[228:231], v[212:215], v[76:79]
	v_mfma_f32_16x16x32_bf16 v[72:75], v[236:239], v[212:215], v[72:75]
	v_mfma_f32_16x16x32_bf16 v[68:71], v[228:231], v[220:223], v[68:71]
	v_mfma_f32_16x16x32_bf16 v[64:67], v[236:239], v[220:223], v[64:67]
	s_mov_b32 m0, s92
	s_barrier
	ds_read_b128 v[180:183], v148 offset:49152
	ds_read_b128 v[196:199], v148 offset:50176
	ds_read_b128 v[200:203], v148 offset:51200
	ds_read_b128 v[204:207], v148 offset:52224
	ds_read_b128 v[208:211], v148 offset:53248
	ds_read_b128 v[212:215], v148 offset:54272
	ds_read_b128 v[216:219], v148 offset:55296
	ds_read_b128 v[220:223], v148 offset:56320
	global_load_lds_dwordx4 v240, s[14:15]
	s_mov_b32 m0, s93
	s_nop 0
	global_load_lds_dwordx4 v241, s[14:15]
	s_barrier
	s_waitcnt lgkmcnt(0)
	s_waitcnt lgkmcnt(0)
	v_mfma_f32_16x16x32_bf16 v[60:63], v[164:167], v[180:183], v[60:63]
	v_mfma_f32_16x16x32_bf16 v[56:59], v[172:175], v[180:183], v[56:59]
	v_mfma_f32_16x16x32_bf16 v[52:55], v[164:167], v[200:203], v[52:55]
	v_mfma_f32_16x16x32_bf16 v[48:51], v[172:175], v[200:203], v[48:51]
	v_mfma_f32_16x16x32_bf16 v[44:47], v[164:167], v[208:211], v[44:47]
	v_mfma_f32_16x16x32_bf16 v[40:43], v[172:175], v[208:211], v[40:43]
	v_mfma_f32_16x16x32_bf16 v[36:39], v[164:167], v[216:219], v[36:39]
	v_mfma_f32_16x16x32_bf16 v[32:35], v[172:175], v[216:219], v[32:35]
	v_mfma_f32_16x16x32_bf16 v[60:63], v[168:171], v[196:199], v[60:63]
	v_mfma_f32_16x16x32_bf16 v[56:59], v[176:179], v[196:199], v[56:59]
	v_mfma_f32_16x16x32_bf16 v[52:55], v[168:171], v[204:207], v[52:55]
	v_mfma_f32_16x16x32_bf16 v[48:51], v[176:179], v[204:207], v[48:51]
	v_mfma_f32_16x16x32_bf16 v[44:47], v[168:171], v[212:215], v[44:47]
	v_mfma_f32_16x16x32_bf16 v[40:43], v[176:179], v[212:215], v[40:43]
	v_mfma_f32_16x16x32_bf16 v[36:39], v[168:171], v[220:223], v[36:39]
	v_mfma_f32_16x16x32_bf16 v[32:35], v[176:179], v[220:223], v[32:35]
	s_barrier
	s_mov_b32 m0, s52
	s_nop 0
	global_load_lds_dwordx4 v240, s[22:23]
	s_mov_b32 m0, s53
	s_nop 0
	global_load_lds_dwordx4 v241, s[22:23]
	s_waitcnt vmcnt(6)
	s_barrier
	v_mfma_f32_16x16x32_bf16 v[28:31], v[224:227], v[180:183], v[28:31]
	v_mfma_f32_16x16x32_bf16 v[24:27], v[232:235], v[180:183], v[24:27]
	v_mfma_f32_16x16x32_bf16 v[20:23], v[224:227], v[200:203], v[20:23]
	v_mfma_f32_16x16x32_bf16 v[16:19], v[232:235], v[200:203], v[16:19]
	v_mfma_f32_16x16x32_bf16 v[12:15], v[224:227], v[208:211], v[12:15]
	v_mfma_f32_16x16x32_bf16 v[8:11], v[232:235], v[208:211], v[8:11]
	v_mfma_f32_16x16x32_bf16 v[4:7], v[224:227], v[216:219], v[4:7]
	v_mfma_f32_16x16x32_bf16 v[0:3], v[232:235], v[216:219], v[0:3]
	v_mfma_f32_16x16x32_bf16 v[28:31], v[228:231], v[196:199], v[28:31]
	v_mfma_f32_16x16x32_bf16 v[24:27], v[236:239], v[196:199], v[24:27]
	v_mfma_f32_16x16x32_bf16 v[20:23], v[228:231], v[204:207], v[20:23]
	v_mfma_f32_16x16x32_bf16 v[16:19], v[236:239], v[204:207], v[16:19]
	v_mfma_f32_16x16x32_bf16 v[12:15], v[228:231], v[212:215], v[12:15]
	v_mfma_f32_16x16x32_bf16 v[8:11], v[236:239], v[212:215], v[8:11]
	v_mfma_f32_16x16x32_bf16 v[4:7], v[228:231], v[220:223], v[4:7]
	v_mfma_f32_16x16x32_bf16 v[0:3], v[236:239], v[220:223], v[0:3]
	s_add_i32 s59, s59, 2
	v_add_u32_e32 v142, 0x100, v142
	s_cmp_lt_u32 s59, 12
	v_add_u32_e32 v96, 0x100, v96
	s_barrier
	s_cbranch_scc1 .LBB0_198
	s_mov_b32 m0, s61
	v_lshl_add_u64 v[220:221], s[6:7], 0, v[138:139]
	ds_read_b128 v[164:167], v143
	ds_read_b128 v[168:171], v144
	ds_read_b128 v[142:145], v145
	ds_read_b128 v[172:175], v151
	ds_read_b128 v[176:179], v148
	ds_read_b128 v[180:183], v148 offset:1024
	ds_read_b128 v[196:199], v148 offset:2048
	ds_read_b128 v[200:203], v148 offset:3072
	ds_read_b128 v[204:207], v148 offset:4096
	ds_read_b128 v[208:211], v148 offset:5120
	ds_read_b128 v[212:215], v148 offset:6144
	ds_read_b128 v[216:219], v148 offset:7168
	global_load_lds_dwordx4 v[220:221], off
	v_lshl_add_u64 v[220:221], s[6:7], 0, v[140:141]
	s_mov_b32 m0, s60
	s_nop 0
	global_load_lds_dwordx4 v[220:221], off
	s_barrier
; #define WAIT_V(n) asm volatile("s_waitcnt vmcnt(%0)" ::"n"(n) : "memory")
; #define WAIT_L(n) asm volatile("s_waitcnt lgkmcnt(%0)" ::"n"(n) : "memory")
; #define STAGE(P, base, kt) do { _Pragma("unroll") for (int _i = 0; _i < 2; ++_i)                                        \
;       __builtin_amdgcn_global_load_lds((const unsigned*)((base) + (size_t)(sOff[_i] + (unsigned)(kt) * (BK * 2))),        \
;                                        (unsigned*)((P) + wid * 1024 + _i * 8192), 16, 0, 0); } while (0)
; #define LDA(dst, b, h) _Pragma("unroll") for (int m = 0; m < 4; ++m) _Pragma("unroll") for (int k = 0; k < 2; ++k) \
;       dst[m][k] = *(const bf16x8*)(SA(b, h) + aoff + (m * 2048 + k * 1024))
; #define LDB(dst, b, h) _Pragma("unroll") for (int n = 0; n < 2; ++n) _Pragma("unroll") for (int k = 0; k < 2; ++k) \
;       dst[n][k] = *(const bf16x8*)(SB(b, h) + boff + (n * 256 + k * 1024))
; #define BAR __builtin_amdgcn_s_barrier()
; template <int EPI, int N, int K>
; __device__ __forceinline__ void phase_gemm(const Params& p, const u16* __restrict__ A, const u16* __restrict__ Bt, int nM, char* shm,
;                            u16* __restrict__ outp, float* __restrict__ rowss) {
;     ...
;     { LDB(B0, 0, 0); LDA(At, 0, 0); STAGE(SA(1, 1), A1, nt - 1);
;       BAR; WAIT_L(0); MMA(0, 0, At, B0); BAR;
;       LDB(B1, 0, 1); BAR; WAIT_L(0); MMA(0, 1, At, B1); BAR;
;       LDA(At, 0, 1); WAIT_V(4); BAR; WAIT_L(0); MMA(1, 0, At, B0); MMA(1, 1, At, B1); BAR; }
;     { LDB(B0, 1, 0); LDA(At, 1, 0); WAIT_V(2); BAR; WAIT_L(0); MMA(0, 0, At, B0); BAR;
;       LDB(B1, 1, 1); WAIT_V(0); BAR; WAIT_L(0); MMA(0, 1, At, B1); BAR;
	s_waitcnt lgkmcnt(0)
	s_waitcnt lgkmcnt(0)
	v_mfma_f32_16x16x32_bf16 v[126:129], v[164:167], v[176:179], v[126:129]
	v_mfma_f32_16x16x32_bf16 v[122:125], v[142:145], v[176:179], v[122:125]
	v_mfma_f32_16x16x32_bf16 v[118:121], v[164:167], v[196:199], v[118:121]
	v_mfma_f32_16x16x32_bf16 v[102:105], v[164:167], v[212:215], v[102:105]
	v_mfma_f32_16x16x32_bf16 v[98:101], v[142:145], v[212:215], v[98:101]
	v_mfma_f32_16x16x32_bf16 v[126:129], v[168:171], v[180:183], v[126:129]
	v_mfma_f32_16x16x32_bf16 v[122:125], v[172:175], v[180:183], v[122:125]
	v_mfma_f32_16x16x32_bf16 v[118:121], v[168:171], v[200:203], v[118:121]
	v_mfma_f32_16x16x32_bf16 v[114:117], v[142:145], v[196:199], v[114:117]
	v_mfma_f32_16x16x32_bf16 v[110:113], v[164:167], v[204:207], v[110:113]
	v_mfma_f32_16x16x32_bf16 v[106:109], v[142:145], v[204:207], v[106:109]
	v_mfma_f32_16x16x32_bf16 v[102:105], v[168:171], v[216:219], v[102:105]
	v_mfma_f32_16x16x32_bf16 v[98:101], v[172:175], v[216:219], v[98:101]
	v_mfma_f32_16x16x32_bf16 v[220:223], v[172:175], v[200:203], v[114:117]
	v_mfma_f32_16x16x32_bf16 v[224:227], v[168:171], v[208:211], v[110:113]
	v_mfma_f32_16x16x32_bf16 v[228:231], v[172:175], v[208:211], v[106:109]
	s_barrier
	s_nop 0
	ds_read_b128 v[106:109], v152
	ds_read_b128 v[110:113], v153
	ds_read_b128 v[114:117], v154
	ds_read_b128 v[152:155], v155
	s_barrier
	s_waitcnt lgkmcnt(0)
	s_waitcnt lgkmcnt(0)
	v_mfma_f32_16x16x32_bf16 v[84:87], v[106:109], v[196:199], v[84:87]
	v_mfma_f32_16x16x32_bf16 v[80:83], v[114:117], v[196:199], v[80:83]
	v_mfma_f32_16x16x32_bf16 v[68:71], v[106:109], v[212:215], v[68:71]
	v_mfma_f32_16x16x32_bf16 v[92:95], v[106:109], v[176:179], v[92:95]
	v_mfma_f32_16x16x32_bf16 v[88:91], v[114:117], v[176:179], v[88:91]
	v_mfma_f32_16x16x32_bf16 v[84:87], v[110:113], v[200:203], v[84:87]
	v_mfma_f32_16x16x32_bf16 v[80:83], v[152:155], v[200:203], v[80:83]
	v_mfma_f32_16x16x32_bf16 v[76:79], v[106:109], v[204:207], v[76:79]
	v_mfma_f32_16x16x32_bf16 v[72:75], v[114:117], v[204:207], v[72:75]
	v_mfma_f32_16x16x32_bf16 v[68:71], v[110:113], v[216:219], v[68:71]
	v_mfma_f32_16x16x32_bf16 v[64:67], v[114:117], v[212:215], v[64:67]
	v_mfma_f32_16x16x32_bf16 v[232:235], v[110:113], v[180:183], v[92:95]
	v_mfma_f32_16x16x32_bf16 v[176:179], v[152:155], v[180:183], v[88:91]
	v_mfma_f32_16x16x32_bf16 v[180:183], v[110:113], v[208:211], v[76:79]
	v_mfma_f32_16x16x32_bf16 v[196:199], v[152:155], v[208:211], v[72:75]
	v_mfma_f32_16x16x32_bf16 v[200:203], v[152:155], v[216:219], v[64:67]
	s_barrier
	s_nop 0
	ds_read_b128 v[64:67], v148 offset:16384
	ds_read_b128 v[72:75], v148 offset:17408
	ds_read_b128 v[76:79], v148 offset:18432
	ds_read_b128 v[88:91], v148 offset:19456
	ds_read_b128 v[92:95], v148 offset:20480
	ds_read_b128 v[204:207], v148 offset:21504
	ds_read_b128 v[208:211], v148 offset:22528
	ds_read_b128 v[212:215], v148 offset:23552
	s_waitcnt vmcnt(4)
	s_barrier
	s_waitcnt lgkmcnt(0)
	s_waitcnt lgkmcnt(0)
	v_mfma_f32_16x16x32_bf16 v[60:63], v[164:167], v[64:67], v[60:63]
	v_mfma_f32_16x16x32_bf16 v[52:55], v[164:167], v[76:79], v[52:55]
	v_mfma_f32_16x16x32_bf16 v[48:51], v[142:145], v[76:79], v[48:51]
	v_mfma_f32_16x16x32_bf16 v[36:39], v[164:167], v[208:211], v[36:39]
	v_mfma_f32_16x16x32_bf16 v[32:35], v[142:145], v[208:211], v[32:35]
	v_mfma_f32_16x16x32_bf16 v[60:63], v[168:171], v[72:75], v[60:63]
	v_mfma_f32_16x16x32_bf16 v[56:59], v[142:145], v[64:67], v[56:59]
	v_mfma_f32_16x16x32_bf16 v[52:55], v[168:171], v[88:91], v[52:55]
	v_mfma_f32_16x16x32_bf16 v[48:51], v[172:175], v[88:91], v[48:51]
	v_mfma_f32_16x16x32_bf16 v[44:47], v[164:167], v[92:95], v[44:47]
	v_mfma_f32_16x16x32_bf16 v[40:43], v[142:145], v[92:95], v[40:43]
	v_mfma_f32_16x16x32_bf16 v[36:39], v[168:171], v[212:215], v[36:39]
	v_mfma_f32_16x16x32_bf16 v[32:35], v[172:175], v[212:215], v[32:35]
	v_mfma_f32_16x16x32_bf16 v[216:219], v[172:175], v[72:75], v[56:59]
	v_mfma_f32_16x16x32_bf16 v[236:239], v[168:171], v[204:207], v[44:47]
	v_mfma_f32_16x16x32_bf16 v[240:243], v[172:175], v[204:207], v[40:43]
	v_mfma_f32_16x16x32_bf16 v[20:23], v[106:109], v[76:79], v[20:23]
	v_mfma_f32_16x16x32_bf16 v[16:19], v[114:117], v[76:79], v[16:19]
	v_mfma_f32_16x16x32_bf16 v[4:7], v[106:109], v[208:211], v[4:7]
	v_mfma_f32_16x16x32_bf16 v[28:31], v[106:109], v[64:67], v[28:31]
	v_mfma_f32_16x16x32_bf16 v[24:27], v[114:117], v[64:67], v[24:27]
	v_mfma_f32_16x16x32_bf16 v[20:23], v[110:113], v[88:91], v[20:23]
	v_mfma_f32_16x16x32_bf16 v[16:19], v[152:155], v[88:91], v[16:19]
	v_mfma_f32_16x16x32_bf16 v[12:15], v[106:109], v[92:95], v[12:15]
	v_mfma_f32_16x16x32_bf16 v[8:11], v[114:117], v[92:95], v[8:11]
	v_mfma_f32_16x16x32_bf16 v[4:7], v[110:113], v[212:215], v[4:7]
	v_mfma_f32_16x16x32_bf16 v[0:3], v[114:117], v[208:211], v[0:3]
	v_mfma_f32_16x16x32_bf16 v[142:145], v[110:113], v[72:75], v[28:31]
	v_mfma_f32_16x16x32_bf16 v[164:167], v[152:155], v[72:75], v[24:27]
	v_mfma_f32_16x16x32_bf16 v[168:171], v[110:113], v[204:207], v[12:15]
	v_mfma_f32_16x16x32_bf16 v[172:175], v[152:155], v[204:207], v[8:11]
	v_mfma_f32_16x16x32_bf16 v[152:155], v[152:155], v[212:215], v[0:3]
	s_barrier
; #define WAIT_V(n) asm volatile("s_waitcnt vmcnt(%0)" ::"n"(n) : "memory")
; #define WAIT_L(n) asm volatile("s_waitcnt lgkmcnt(%0)" ::"n"(n) : "memory")
; #define LDA(dst, b, h) _Pragma("unroll") for (int m = 0; m < 4; ++m) _Pragma("unroll") for (int k = 0; k < 2; ++k) \
;       dst[m][k] = *(const bf16x8*)(SA(b, h) + aoff + (m * 2048 + k * 1024))
; #define LDB(dst, b, h) _Pragma("unroll") for (int n = 0; n < 2; ++n) _Pragma("unroll") for (int k = 0; k < 2; ++k) \
;       dst[n][k] = *(const bf16x8*)(SB(b, h) + boff + (n * 256 + k * 1024))
; #define BAR __builtin_amdgcn_s_barrier()
; template <int EPI, int N, int K>
; __device__ __forceinline__ void phase_gemm(const Params& p, const u16* __restrict__ A, const u16* __restrict__ Bt, int nM, char* shm,
;                            u16* __restrict__ outp, float* __restrict__ rowss) {
;     ...
;     { LDB(B0, 1, 0); LDA(At, 1, 0); WAIT_V(2); BAR; WAIT_L(0); MMA(0, 0, At, B0); BAR;
;       LDB(B1, 1, 1); WAIT_V(0); BAR; WAIT_L(0); MMA(0, 1, At, B1); BAR;
;       LDA(At, 1, 1); BAR; WAIT_L(0); MMA(1, 0, At, B0); MMA(1, 1, At, B1); BAR; }
;     if (wr == 0) BAR;
	s_nop 0
	ds_read_b128 v[0:3], v156
	ds_read_b128 v[8:11], v157
	ds_read_b128 v[12:15], v158
	ds_read_b128 v[156:159], v159
	ds_read_b128 v[24:27], v148 offset:32768
	ds_read_b128 v[28:31], v148 offset:33792
	ds_read_b128 v[40:43], v148 offset:34816
	ds_read_b128 v[44:47], v148 offset:35840
	ds_read_b128 v[56:59], v148 offset:36864
	ds_read_b128 v[64:67], v148 offset:37888
	ds_read_b128 v[204:207], v148 offset:38912
	ds_read_b128 v[208:211], v148 offset:39936
	s_waitcnt vmcnt(2)
	s_barrier
	s_waitcnt lgkmcnt(0)
	s_waitcnt lgkmcnt(0)
	v_mfma_f32_16x16x32_bf16 v[72:75], v[0:3], v[24:27], v[126:129]
	v_mfma_f32_16x16x32_bf16 v[126:129], v[8:11], v[28:31], v[72:75]
	v_mfma_f32_16x16x32_bf16 v[72:75], v[12:15], v[24:27], v[122:125]
	v_mfma_f32_16x16x32_bf16 v[114:117], v[156:159], v[28:31], v[72:75]
	v_mfma_f32_16x16x32_bf16 v[72:75], v[0:3], v[40:43], v[118:121]
	v_mfma_f32_16x16x32_bf16 v[106:109], v[8:11], v[44:47], v[72:75]
	v_mfma_f32_16x16x32_bf16 v[72:75], v[12:15], v[40:43], v[220:223]
	v_mfma_f32_16x16x32_bf16 v[110:113], v[156:159], v[44:47], v[72:75]
	v_mfma_f32_16x16x32_bf16 v[72:75], v[0:3], v[56:59], v[224:227]
	v_mfma_f32_16x16x32_bf16 v[88:91], v[8:11], v[64:67], v[72:75]
	v_mfma_f32_16x16x32_bf16 v[72:75], v[12:15], v[56:59], v[228:231]
	v_mfma_f32_16x16x32_bf16 v[92:95], v[156:159], v[64:67], v[72:75]
	v_mfma_f32_16x16x32_bf16 v[72:75], v[0:3], v[204:207], v[102:105]
	v_mfma_f32_16x16x32_bf16 v[76:79], v[12:15], v[204:207], v[98:101]
	v_mfma_f32_16x16x32_bf16 v[72:75], v[8:11], v[208:211], v[72:75]
	v_mfma_f32_16x16x32_bf16 v[76:79], v[156:159], v[208:211], v[76:79]
	s_barrier
	ds_read_b128 v[212:215], v160
	ds_read_b128 v[220:223], v161
	ds_read_b128 v[224:227], v162
	ds_read_b128 v[160:163], v163
	s_waitcnt vmcnt(0)
	s_barrier
	s_waitcnt lgkmcnt(0)
	s_waitcnt lgkmcnt(0)
	v_mfma_f32_16x16x32_bf16 v[98:101], v[212:215], v[24:27], v[232:235]
	v_mfma_f32_16x16x32_bf16 v[24:27], v[224:227], v[24:27], v[176:179]
	v_mfma_f32_16x16x32_bf16 v[122:125], v[160:163], v[28:31], v[24:27]
	v_mfma_f32_16x16x32_bf16 v[24:27], v[212:215], v[40:43], v[84:87]
	v_mfma_f32_16x16x32_bf16 v[118:121], v[220:223], v[28:31], v[98:101]
	v_mfma_f32_16x16x32_bf16 v[98:101], v[220:223], v[44:47], v[24:27]
	v_mfma_f32_16x16x32_bf16 v[24:27], v[224:227], v[40:43], v[80:83]
	v_mfma_f32_16x16x32_bf16 v[102:105], v[160:163], v[44:47], v[24:27]
	v_mfma_f32_16x16x32_bf16 v[24:27], v[212:215], v[56:59], v[180:183]
	v_mfma_f32_16x16x32_bf16 v[80:83], v[220:223], v[64:67], v[24:27]
	v_mfma_f32_16x16x32_bf16 v[24:27], v[224:227], v[56:59], v[196:199]
	v_mfma_f32_16x16x32_bf16 v[84:87], v[160:163], v[64:67], v[24:27]
	v_mfma_f32_16x16x32_bf16 v[24:27], v[212:215], v[204:207], v[68:71]
	v_mfma_f32_16x16x32_bf16 v[64:67], v[220:223], v[208:211], v[24:27]
	v_mfma_f32_16x16x32_bf16 v[24:27], v[224:227], v[204:207], v[200:203]
	v_mfma_f32_16x16x32_bf16 v[68:71], v[160:163], v[208:211], v[24:27]
	s_barrier
	ds_read_b128 v[176:179], v148 offset:49152
	ds_read_b128 v[180:183], v148 offset:50176
	ds_read_b128 v[196:199], v148 offset:51200
	ds_read_b128 v[200:203], v148 offset:52224
	ds_read_b128 v[204:207], v148 offset:53248
	ds_read_b128 v[208:211], v148 offset:54272
	ds_read_b128 v[228:231], v148 offset:55296
	ds_read_b128 v[232:235], v148 offset:56320
	s_barrier
	s_waitcnt lgkmcnt(0)
	s_waitcnt lgkmcnt(0)
	v_mfma_f32_16x16x32_bf16 v[24:27], v[0:3], v[176:179], v[60:63]
	v_mfma_f32_16x16x32_bf16 v[56:59], v[8:11], v[180:183], v[24:27]
	v_mfma_f32_16x16x32_bf16 v[24:27], v[12:15], v[176:179], v[216:219]
	v_mfma_f32_16x16x32_bf16 v[60:63], v[156:159], v[180:183], v[24:27]
	v_mfma_f32_16x16x32_bf16 v[24:27], v[0:3], v[196:199], v[52:55]
	v_mfma_f32_16x16x32_bf16 v[40:43], v[8:11], v[200:203], v[24:27]
	v_mfma_f32_16x16x32_bf16 v[24:27], v[12:15], v[196:199], v[48:51]
	v_mfma_f32_16x16x32_bf16 v[44:47], v[156:159], v[200:203], v[24:27]
	v_mfma_f32_16x16x32_bf16 v[24:27], v[0:3], v[204:207], v[236:239]
	v_mfma_f32_16x16x32_bf16 v[0:3], v[0:3], v[228:231], v[36:39]
	v_mfma_f32_16x16x32_bf16 v[24:27], v[8:11], v[208:211], v[24:27]
	v_mfma_f32_16x16x32_bf16 v[28:31], v[12:15], v[204:207], v[240:243]
	v_mfma_f32_16x16x32_bf16 v[8:11], v[8:11], v[232:235], v[0:3]
	v_mfma_f32_16x16x32_bf16 v[0:3], v[12:15], v[228:231], v[32:35]
	v_mfma_f32_16x16x32_bf16 v[28:31], v[156:159], v[208:211], v[28:31]
	v_mfma_f32_16x16x32_bf16 v[12:15], v[156:159], v[232:235], v[0:3]
	v_mfma_f32_16x16x32_bf16 v[0:3], v[212:215], v[176:179], v[142:145]
	v_mfma_f32_16x16x32_bf16 v[48:51], v[220:223], v[180:183], v[0:3]
	v_mfma_f32_16x16x32_bf16 v[0:3], v[224:227], v[176:179], v[164:167]
	v_mfma_f32_16x16x32_bf16 v[52:55], v[160:163], v[180:183], v[0:3]
	v_mfma_f32_16x16x32_bf16 v[0:3], v[212:215], v[196:199], v[20:23]
	v_mfma_f32_16x16x32_bf16 v[32:35], v[220:223], v[200:203], v[0:3]
	v_mfma_f32_16x16x32_bf16 v[0:3], v[224:227], v[196:199], v[16:19]
	v_mfma_f32_16x16x32_bf16 v[36:39], v[160:163], v[200:203], v[0:3]
	v_mfma_f32_16x16x32_bf16 v[0:3], v[212:215], v[204:207], v[168:171]
	v_mfma_f32_16x16x32_bf16 v[16:19], v[220:223], v[208:211], v[0:3]
	v_mfma_f32_16x16x32_bf16 v[0:3], v[224:227], v[204:207], v[172:175]
	v_mfma_f32_16x16x32_bf16 v[20:23], v[160:163], v[208:211], v[0:3]
	v_mfma_f32_16x16x32_bf16 v[0:3], v[212:215], v[228:231], v[4:7]
	v_mfma_f32_16x16x32_bf16 v[4:7], v[224:227], v[228:231], v[152:155]
	v_mfma_f32_16x16x32_bf16 v[0:3], v[220:223], v[232:235], v[0:3]
	v_mfma_f32_16x16x32_bf16 v[4:7], v[160:163], v[232:235], v[4:7]
	s_andn2_b64 vcc, exec, s[18:19]
	s_barrier
	s_cbranch_vccnz .LBB0_201
	s_barrier

; #define WAIT_V(n) asm volatile("s_waitcnt vmcnt(%0)" ::"n"(n) : "memory")
; #define WAIT_L(n) asm volatile("s_waitcnt lgkmcnt(%0)" ::"n"(n) : "memory")
; #define SBAR() __builtin_amdgcn_sched_barrier(0)
; #define STAGE(P, base, kt) do { _Pragma("unroll") for (int _i = 0; _i < 2; ++_i)                                        \
;       __builtin_amdgcn_global_load_lds((const unsigned*)((base) + (size_t)(sOff[_i] + (unsigned)(kt) * (BK * 2))),        \
;                                        (unsigned*)((P) + wid * 1024 + _i * 8192), 16, 0, 0); } while (0)
; #define LDA(dst, b, h) _Pragma("unroll") for (int m = 0; m < 4; ++m) _Pragma("unroll") for (int k = 0; k < 2; ++k) \
;       dst[m][k] = *(const bf16x8*)(SA(b, h) + aoff + (m * 2048 + k * 1024))
; #define LDB(dst, b, h) _Pragma("unroll") for (int n = 0; n < 2; ++n) _Pragma("unroll") for (int k = 0; k < 2; ++k) \
;       dst[n][k] = *(const bf16x8*)(SB(b, h) + boff + (n * 256 + k * 1024))
; #define BAR __builtin_amdgcn_s_barrier()
; template <int EPI, int N, int K>
; __device__ __forceinline__ void phase_gemm(const Params& p, const u16* __restrict__ A, const u16* __restrict__ Bt, int nM, char* shm,
;                            u16* __restrict__ outp, float* __restrict__ rowss) {
;     ...
;   for (;;) {
;     const char* A1 = A0 + (size_t)128 * K * 2;
;     const char* B1p = B0p + (size_t)128 * K * 2;
;     f32x4 acc[2][2][4][2] = {};
;     bf16x8 At[4][2], B0[2][2], B1[2][2];
;     if (wr == 1) BAR;
;     WAIT_V(0); BAR;
;     BAR;
;     for (int t = 0; t < nt - 2; t += 2) {
;       LDB(B0, 0, 0); SBAR(); LDA(At, 0, 0); STAGE(SA(1, 1), A1, t + 1);
;       WAIT_L(8); BAR; WAIT_L(0); MMA(0, 0, At, B0); BAR; SBAR();
;       LDB(B1, 0, 1); STAGE(SB(0, 0), B0p, t + 2);
;       BAR; WAIT_L(0); MMA(0, 1, At, B1); BAR;
;       LDA(At, 0, 1); STAGE(SA(0, 0), A0, t + 2);
;       BAR; WAIT_L(0); MMA(1, 0, At, B0); BAR; SBAR();
;       STAGE(SB(0, 1), B1p, t + 2);
;       WAIT_V(6); BAR; MMA(1, 1, At, B1); BAR;
.LBB0_378:
	s_add_u32 s6, s18, 0x40000
	s_addc_u32 s7, s19, 0
	s_waitcnt vmcnt(0)
	s_add_u32 s8, s16, 0x40000
	s_addc_u32 s9, s17, 0
	s_mov_b32 s11, -2
	v_mov_b32_e32 v96, v153
	v_mov_b32_e32 v130, v152
	s_barrier
	s_barrier
	v_or_b32_e32 v131, 0x10000, v150
	v_add_u32_e32 v133, 0x10100, v150
	v_add_u32_e32 v132, 0x10400, v150
	ds_read_b128 v[156:159], v131
	ds_read_b128 v[160:163], v132
	v_add_u32_e32 v146, 0x10500, v150
	ds_read_b128 v[164:167], v133
	ds_read_b128 v[168:171], v146
	v_add_u32_e32 v240, v147, v96
	s_add_i32 s26, s94, 0xc000
	v_add_u32_e32 v148, 0x80, v240
	s_mov_b32 m0, s26
	v_add_u32_e32 v241, v147, v130
	s_add_i32 s25, s94, 0xe000
	ds_read_b128 v[172:175], v151
	ds_read_b128 v[176:179], v151 offset:1024
	ds_read_b128 v[180:183], v151 offset:2048
	ds_read_b128 v[196:199], v151 offset:3072
	ds_read_b128 v[200:203], v151 offset:4096
	ds_read_b128 v[204:207], v151 offset:5120
	ds_read_b128 v[208:211], v151 offset:6144
	ds_read_b128 v[212:215], v151 offset:7168
	global_load_lds_dwordx4 v148, s[6:7]
	v_add_u32_e32 v148, 0x80, v241
	s_mov_b32 m0, s25
	s_nop 0
	global_load_lds_dwordx4 v148, s[6:7]
	s_waitcnt lgkmcnt(8)
	s_barrier
	s_waitcnt lgkmcnt(0)
	s_waitcnt lgkmcnt(0)
	v_mfma_f32_16x16x32_bf16 v[126:129], v[156:159], v[172:175], 0
	v_mfma_f32_16x16x32_bf16 v[122:125], v[164:167], v[172:175], 0
	v_mfma_f32_16x16x32_bf16 v[118:121], v[156:159], v[180:183], 0
	v_mfma_f32_16x16x32_bf16 v[114:117], v[164:167], v[180:183], 0
	v_mfma_f32_16x16x32_bf16 v[110:113], v[156:159], v[200:203], 0
	v_mfma_f32_16x16x32_bf16 v[106:109], v[164:167], v[200:203], 0
	v_mfma_f32_16x16x32_bf16 v[102:105], v[156:159], v[208:211], 0
	v_mfma_f32_16x16x32_bf16 v[98:101], v[164:167], v[208:211], 0
	v_mfma_f32_16x16x32_bf16 v[126:129], v[160:163], v[176:179], v[126:129]
	v_mfma_f32_16x16x32_bf16 v[122:125], v[168:171], v[176:179], v[122:125]
	v_mfma_f32_16x16x32_bf16 v[118:121], v[160:163], v[196:199], v[118:121]
	v_mfma_f32_16x16x32_bf16 v[114:117], v[168:171], v[196:199], v[114:117]
	v_mfma_f32_16x16x32_bf16 v[110:113], v[160:163], v[204:207], v[110:113]
	v_mfma_f32_16x16x32_bf16 v[106:109], v[168:171], v[204:207], v[106:109]
	v_mfma_f32_16x16x32_bf16 v[102:105], v[160:163], v[212:215], v[102:105]
	v_mfma_f32_16x16x32_bf16 v[98:101], v[168:171], v[212:215], v[98:101]
	s_barrier
	s_mov_b32 m0, s22
	v_or_b32_e32 v148, 0x14000, v150
	v_add_u32_e32 v154, 0x14100, v150
	v_add_u32_e32 v232, 0x100, v240
	v_add_u32_e32 v149, 0x14400, v150
	ds_read_b128 v[216:219], v148
	ds_read_b128 v[220:223], v149
	v_add_u32_e32 v155, 0x14500, v150
	ds_read_b128 v[224:227], v154
	ds_read_b128 v[228:231], v155
	global_load_lds_dwordx4 v232, s[16:17]
	v_add_u32_e32 v233, 0x100, v241
	s_mov_b32 m0, s23
	s_nop 0
	global_load_lds_dwordx4 v233, s[16:17]
	s_barrier
	s_waitcnt lgkmcnt(0)
	s_waitcnt lgkmcnt(0)
	v_mfma_f32_16x16x32_bf16 v[92:95], v[216:219], v[172:175], 0
	v_mfma_f32_16x16x32_bf16 v[88:91], v[224:227], v[172:175], 0
	v_mfma_f32_16x16x32_bf16 v[84:87], v[216:219], v[180:183], 0
	v_mfma_f32_16x16x32_bf16 v[80:83], v[224:227], v[180:183], 0
	v_mfma_f32_16x16x32_bf16 v[76:79], v[216:219], v[200:203], 0
	v_mfma_f32_16x16x32_bf16 v[72:75], v[224:227], v[200:203], 0
	v_mfma_f32_16x16x32_bf16 v[68:71], v[216:219], v[208:211], 0
	v_mfma_f32_16x16x32_bf16 v[64:67], v[224:227], v[208:211], 0
	v_mfma_f32_16x16x32_bf16 v[92:95], v[220:223], v[176:179], v[92:95]
	v_mfma_f32_16x16x32_bf16 v[88:91], v[228:231], v[176:179], v[88:91]
	v_mfma_f32_16x16x32_bf16 v[84:87], v[220:223], v[196:199], v[84:87]
	v_mfma_f32_16x16x32_bf16 v[80:83], v[228:231], v[196:199], v[80:83]
	v_mfma_f32_16x16x32_bf16 v[76:79], v[220:223], v[204:207], v[76:79]
	v_mfma_f32_16x16x32_bf16 v[72:75], v[228:231], v[204:207], v[72:75]
	v_mfma_f32_16x16x32_bf16 v[68:71], v[220:223], v[212:215], v[68:71]
	v_mfma_f32_16x16x32_bf16 v[64:67], v[228:231], v[212:215], v[64:67]
	s_mov_b32 m0, s94
	s_barrier
	ds_read_b128 v[172:175], v151 offset:16384
	ds_read_b128 v[176:179], v151 offset:17408
	ds_read_b128 v[180:183], v151 offset:18432
	ds_read_b128 v[196:199], v151 offset:19456
	ds_read_b128 v[200:203], v151 offset:20480
	ds_read_b128 v[204:207], v151 offset:21504
	ds_read_b128 v[208:211], v151 offset:22528
	ds_read_b128 v[212:215], v151 offset:23552
	global_load_lds_dwordx4 v232, s[18:19]
	s_mov_b32 m0, s95
	s_nop 0
	global_load_lds_dwordx4 v233, s[18:19]
	s_barrier
	s_waitcnt lgkmcnt(0)
	s_waitcnt lgkmcnt(0)
	v_mfma_f32_16x16x32_bf16 v[60:63], v[156:159], v[172:175], 0
	v_mfma_f32_16x16x32_bf16 v[56:59], v[164:167], v[172:175], 0
	v_mfma_f32_16x16x32_bf16 v[52:55], v[156:159], v[180:183], 0
	v_mfma_f32_16x16x32_bf16 v[48:51], v[164:167], v[180:183], 0
	v_mfma_f32_16x16x32_bf16 v[44:47], v[156:159], v[200:203], 0
	v_mfma_f32_16x16x32_bf16 v[40:43], v[164:167], v[200:203], 0
	v_mfma_f32_16x16x32_bf16 v[36:39], v[156:159], v[208:211], 0
	v_mfma_f32_16x16x32_bf16 v[32:35], v[164:167], v[208:211], 0
	v_mfma_f32_16x16x32_bf16 v[60:63], v[160:163], v[176:179], v[60:63]
	v_mfma_f32_16x16x32_bf16 v[56:59], v[168:171], v[176:179], v[56:59]
	v_mfma_f32_16x16x32_bf16 v[52:55], v[160:163], v[196:199], v[52:55]
	v_mfma_f32_16x16x32_bf16 v[48:51], v[168:171], v[196:199], v[48:51]
	v_mfma_f32_16x16x32_bf16 v[44:47], v[160:163], v[204:207], v[44:47]
	v_mfma_f32_16x16x32_bf16 v[40:43], v[168:171], v[204:207], v[40:43]
	v_mfma_f32_16x16x32_bf16 v[36:39], v[160:163], v[212:215], v[36:39]
	v_mfma_f32_16x16x32_bf16 v[32:35], v[168:171], v[212:215], v[32:35]
	s_barrier
	s_mov_b32 m0, s2
	s_nop 0
	global_load_lds_dwordx4 v232, s[8:9]
	s_mov_b32 m0, s3
	s_nop 0
	global_load_lds_dwordx4 v233, s[8:9]
	s_waitcnt vmcnt(6)
	s_barrier
; #define WAIT_V(n) asm volatile("s_waitcnt vmcnt(%0)" ::"n"(n) : "memory")
; #define WAIT_L(n) asm volatile("s_waitcnt lgkmcnt(%0)" ::"n"(n) : "memory")
; #define SBAR() __builtin_amdgcn_sched_barrier(0)
; #define STAGE(P, base, kt) do { _Pragma("unroll") for (int _i = 0; _i < 2; ++_i)                                        \
;       __builtin_amdgcn_global_load_lds((const unsigned*)((base) + (size_t)(sOff[_i] + (unsigned)(kt) * (BK * 2))),        \
;                                        (unsigned*)((P) + wid * 1024 + _i * 8192), 16, 0, 0); } while (0)
; #define LDA(dst, b, h) _Pragma("unroll") for (int m = 0; m < 4; ++m) _Pragma("unroll") for (int k = 0; k < 2; ++k) \
;       dst[m][k] = *(const bf16x8*)(SA(b, h) + aoff + (m * 2048 + k * 1024))
; #define LDB(dst, b, h) _Pragma("unroll") for (int n = 0; n < 2; ++n) _Pragma("unroll") for (int k = 0; k < 2; ++k) \
;       dst[n][k] = *(const bf16x8*)(SB(b, h) + boff + (n * 256 + k * 1024))
; #define BAR __builtin_amdgcn_s_barrier()
; template <int EPI, int N, int K>
; __device__ __forceinline__ void phase_gemm(const Params& p, const u16* __restrict__ A, const u16* __restrict__ Bt, int nM, char* shm,
;                            u16* __restrict__ outp, float* __restrict__ rowss) {
;     ...
;       WAIT_V(6); BAR; MMA(1, 1, At, B1); BAR;
;       LDB(B0, 1, 0); SBAR(); LDA(At, 1, 0); STAGE(SA(0, 1), A1, t + 2);
;       WAIT_L(8); BAR; WAIT_L(0); MMA(0, 0, At, B0); BAR; SBAR();
;       LDB(B1, 1, 1); STAGE(SB(1, 0), B0p, t + 3);
;       BAR; WAIT_L(0); MMA(0, 1, At, B1); BAR;
;       LDA(At, 1, 1); STAGE(SA(1, 0), A0, t + 3);
;       BAR; WAIT_L(0); MMA(1, 0, At, B0); BAR; SBAR();
;       STAGE(SB(1, 1), B1p, t + 3);
;       WAIT_V(6); BAR; MMA(1, 1, At, B1); BAR;
	v_mfma_f32_16x16x32_bf16 v[28:31], v[216:219], v[172:175], 0
	v_mfma_f32_16x16x32_bf16 v[24:27], v[224:227], v[172:175], 0
	v_mfma_f32_16x16x32_bf16 v[20:23], v[216:219], v[180:183], 0
	v_mfma_f32_16x16x32_bf16 v[16:19], v[224:227], v[180:183], 0
	v_mfma_f32_16x16x32_bf16 v[12:15], v[216:219], v[200:203], 0
	v_mfma_f32_16x16x32_bf16 v[8:11], v[224:227], v[200:203], 0
	v_mfma_f32_16x16x32_bf16 v[4:7], v[216:219], v[208:211], 0
	v_mfma_f32_16x16x32_bf16 v[0:3], v[224:227], v[208:211], 0
	v_mfma_f32_16x16x32_bf16 v[28:31], v[220:223], v[176:179], v[28:31]
	v_mfma_f32_16x16x32_bf16 v[24:27], v[228:231], v[176:179], v[24:27]
	v_mfma_f32_16x16x32_bf16 v[20:23], v[220:223], v[196:199], v[20:23]
	v_mfma_f32_16x16x32_bf16 v[16:19], v[228:231], v[196:199], v[16:19]
	v_mfma_f32_16x16x32_bf16 v[12:15], v[220:223], v[204:207], v[12:15]
	v_mfma_f32_16x16x32_bf16 v[8:11], v[228:231], v[204:207], v[8:11]
	v_mfma_f32_16x16x32_bf16 v[4:7], v[220:223], v[212:215], v[4:7]
	v_mfma_f32_16x16x32_bf16 v[0:3], v[228:231], v[212:215], v[0:3]
	v_or_b32_e32 v156, 0x18000, v150
	v_add_u32_e32 v158, 0x18100, v150
	s_barrier
	v_add_u32_e32 v157, 0x18400, v150
	ds_read_b128 v[164:167], v156
	ds_read_b128 v[168:171], v157
	v_add_u32_e32 v159, 0x18500, v150
	ds_read_b128 v[172:175], v158
	ds_read_b128 v[176:179], v159
	s_mov_b32 m0, s92
	ds_read_b128 v[180:183], v151 offset:32768
	ds_read_b128 v[196:199], v151 offset:33792
	ds_read_b128 v[200:203], v151 offset:34816
	ds_read_b128 v[204:207], v151 offset:35840
	ds_read_b128 v[208:211], v151 offset:36864
	ds_read_b128 v[212:215], v151 offset:37888
	ds_read_b128 v[216:219], v151 offset:38912
	ds_read_b128 v[220:223], v151 offset:39936
	global_load_lds_dwordx4 v232, s[6:7]
	s_mov_b32 m0, s0
	s_nop 0
	global_load_lds_dwordx4 v233, s[6:7]
	s_waitcnt lgkmcnt(8)
	s_barrier
	s_waitcnt lgkmcnt(0)
	s_waitcnt lgkmcnt(0)
	v_mfma_f32_16x16x32_bf16 v[126:129], v[164:167], v[180:183], v[126:129]
	v_mfma_f32_16x16x32_bf16 v[122:125], v[172:175], v[180:183], v[122:125]
	v_mfma_f32_16x16x32_bf16 v[118:121], v[164:167], v[200:203], v[118:121]
	v_mfma_f32_16x16x32_bf16 v[114:117], v[172:175], v[200:203], v[114:117]
	v_mfma_f32_16x16x32_bf16 v[110:113], v[164:167], v[208:211], v[110:113]
	v_mfma_f32_16x16x32_bf16 v[106:109], v[172:175], v[208:211], v[106:109]
	v_mfma_f32_16x16x32_bf16 v[102:105], v[164:167], v[216:219], v[102:105]
	v_mfma_f32_16x16x32_bf16 v[98:101], v[172:175], v[216:219], v[98:101]
	v_mfma_f32_16x16x32_bf16 v[126:129], v[168:171], v[196:199], v[126:129]
	v_mfma_f32_16x16x32_bf16 v[122:125], v[176:179], v[196:199], v[122:125]
	v_mfma_f32_16x16x32_bf16 v[118:121], v[168:171], v[204:207], v[118:121]
	v_mfma_f32_16x16x32_bf16 v[114:117], v[176:179], v[204:207], v[114:117]
	v_mfma_f32_16x16x32_bf16 v[110:113], v[168:171], v[212:215], v[110:113]
	v_mfma_f32_16x16x32_bf16 v[106:109], v[176:179], v[212:215], v[106:109]
	v_mfma_f32_16x16x32_bf16 v[102:105], v[168:171], v[220:223], v[102:105]
	v_mfma_f32_16x16x32_bf16 v[98:101], v[176:179], v[220:223], v[98:101]
	s_barrier
	s_mov_b32 m0, s1
	v_or_b32_e32 v160, 0x1c000, v150
	v_add_u32_e32 v162, 0x1c100, v150
	v_add_u32_e32 v240, 0x180, v240
	v_add_u32_e32 v161, 0x1c400, v150
	ds_read_b128 v[224:227], v160
	ds_read_b128 v[228:231], v161
	v_add_u32_e32 v163, 0x1c500, v150
	ds_read_b128 v[232:235], v162
	ds_read_b128 v[236:239], v163
	global_load_lds_dwordx4 v240, s[16:17]
	v_add_u32_e32 v241, 0x180, v241
	s_mov_b32 m0, s12
	s_nop 0
	global_load_lds_dwordx4 v241, s[16:17]
	s_barrier
	s_waitcnt lgkmcnt(0)
	s_waitcnt lgkmcnt(0)
	v_mfma_f32_16x16x32_bf16 v[92:95], v[224:227], v[180:183], v[92:95]
	v_mfma_f32_16x16x32_bf16 v[88:91], v[232:235], v[180:183], v[88:91]
	v_mfma_f32_16x16x32_bf16 v[84:87], v[224:227], v[200:203], v[84:87]
	v_mfma_f32_16x16x32_bf16 v[80:83], v[232:235], v[200:203], v[80:83]
	v_mfma_f32_16x16x32_bf16 v[76:79], v[224:227], v[208:211], v[76:79]
	v_mfma_f32_16x16x32_bf16 v[72:75], v[232:235], v[208:211], v[72:75]
	v_mfma_f32_16x16x32_bf16 v[68:71], v[224:227], v[216:219], v[68:71]
	v_mfma_f32_16x16x32_bf16 v[64:67], v[232:235], v[216:219], v[64:67]
	v_mfma_f32_16x16x32_bf16 v[92:95], v[228:231], v[196:199], v[92:95]
	v_mfma_f32_16x16x32_bf16 v[88:91], v[236:239], v[196:199], v[88:91]
	v_mfma_f32_16x16x32_bf16 v[84:87], v[228:231], v[204:207], v[84:87]
	v_mfma_f32_16x16x32_bf16 v[80:83], v[236:239], v[204:207], v[80:83]
	v_mfma_f32_16x16x32_bf16 v[76:79], v[228:231], v[212:215], v[76:79]
	v_mfma_f32_16x16x32_bf16 v[72:75], v[236:239], v[212:215], v[72:75]
	v_mfma_f32_16x16x32_bf16 v[68:71], v[228:231], v[220:223], v[68:71]
	v_mfma_f32_16x16x32_bf16 v[64:67], v[236:239], v[220:223], v[64:67]
	s_mov_b32 m0, s13
	s_barrier
	ds_read_b128 v[180:183], v151 offset:49152
	ds_read_b128 v[196:199], v151 offset:50176
	ds_read_b128 v[200:203], v151 offset:51200
	ds_read_b128 v[204:207], v151 offset:52224
	ds_read_b128 v[208:211], v151 offset:53248
	ds_read_b128 v[212:215], v151 offset:54272
	ds_read_b128 v[216:219], v151 offset:55296
	ds_read_b128 v[220:223], v151 offset:56320
	global_load_lds_dwordx4 v240, s[18:19]
	s_mov_b32 m0, s14
	s_nop 0
	global_load_lds_dwordx4 v241, s[18:19]
	s_barrier
; #define WAIT_V(n) asm volatile("s_waitcnt vmcnt(%0)" ::"n"(n) : "memory")
; #define WAIT_L(n) asm volatile("s_waitcnt lgkmcnt(%0)" ::"n"(n) : "memory")
; #define SBAR() __builtin_amdgcn_sched_barrier(0)
; #define STAGE(P, base, kt) do { _Pragma("unroll") for (int _i = 0; _i < 2; ++_i)                                        \
;       __builtin_amdgcn_global_load_lds((const unsigned*)((base) + (size_t)(sOff[_i] + (unsigned)(kt) * (BK * 2))),        \
;                                        (unsigned*)((P) + wid * 1024 + _i * 8192), 16, 0, 0); } while (0)
; #define LDA(dst, b, h) _Pragma("unroll") for (int m = 0; m < 4; ++m) _Pragma("unroll") for (int k = 0; k < 2; ++k) \
;       dst[m][k] = *(const bf16x8*)(SA(b, h) + aoff + (m * 2048 + k * 1024))
; #define LDB(dst, b, h) _Pragma("unroll") for (int n = 0; n < 2; ++n) _Pragma("unroll") for (int k = 0; k < 2; ++k) \
;       dst[n][k] = *(const bf16x8*)(SB(b, h) + boff + (n * 256 + k * 1024))
; #define BAR __builtin_amdgcn_s_barrier()
; template <int EPI, int N, int K>
; __device__ __forceinline__ void phase_gemm(const Params& p, const u16* __restrict__ A, const u16* __restrict__ Bt, int nM, char* shm,
;                            u16* __restrict__ outp, float* __restrict__ rowss) {
;     ...
;       LDB(B0, 0, 0); SBAR(); LDA(At, 0, 0); STAGE(SA(1, 1), A1, t + 1);
;       WAIT_L(8); BAR; WAIT_L(0); MMA(0, 0, At, B0); BAR; SBAR();
;       LDB(B1, 0, 1); STAGE(SB(0, 0), B0p, t + 2);
;       BAR; WAIT_L(0); MMA(0, 1, At, B1); BAR;
;       LDA(At, 0, 1); STAGE(SA(0, 0), A0, t + 2);
;       BAR; WAIT_L(0); MMA(1, 0, At, B0); BAR; SBAR();
;       STAGE(SB(0, 1), B1p, t + 2);
;       WAIT_V(6); BAR; MMA(1, 1, At, B1); BAR;
;       LDB(B0, 1, 0); SBAR(); LDA(At, 1, 0); STAGE(SA(0, 1), A1, t + 2);
;       WAIT_L(8); BAR; WAIT_L(0); MMA(0, 0, At, B0); BAR; SBAR();
;       LDB(B1, 1, 1); STAGE(SB(1, 0), B0p, t + 3);
;       BAR; WAIT_L(0); MMA(0, 1, At, B1); BAR;
;       LDA(At, 1, 1); STAGE(SA(1, 0), A0, t + 3);
;       BAR; WAIT_L(0); MMA(1, 0, At, B0); BAR; SBAR();
;       STAGE(SB(1, 1), B1p, t + 3);
;       WAIT_V(6); BAR; MMA(1, 1, At, B1); BAR;
	s_waitcnt lgkmcnt(0)
	s_waitcnt lgkmcnt(0)
	v_mfma_f32_16x16x32_bf16 v[60:63], v[164:167], v[180:183], v[60:63]
	v_mfma_f32_16x16x32_bf16 v[56:59], v[172:175], v[180:183], v[56:59]
	v_mfma_f32_16x16x32_bf16 v[52:55], v[164:167], v[200:203], v[52:55]
	v_mfma_f32_16x16x32_bf16 v[48:51], v[172:175], v[200:203], v[48:51]
	v_mfma_f32_16x16x32_bf16 v[44:47], v[164:167], v[208:211], v[44:47]
	v_mfma_f32_16x16x32_bf16 v[40:43], v[172:175], v[208:211], v[40:43]
	v_mfma_f32_16x16x32_bf16 v[36:39], v[164:167], v[216:219], v[36:39]
	v_mfma_f32_16x16x32_bf16 v[32:35], v[172:175], v[216:219], v[32:35]
	v_mfma_f32_16x16x32_bf16 v[60:63], v[168:171], v[196:199], v[60:63]
	v_mfma_f32_16x16x32_bf16 v[56:59], v[176:179], v[196:199], v[56:59]
	v_mfma_f32_16x16x32_bf16 v[52:55], v[168:171], v[204:207], v[52:55]
	v_mfma_f32_16x16x32_bf16 v[48:51], v[176:179], v[204:207], v[48:51]
	v_mfma_f32_16x16x32_bf16 v[44:47], v[168:171], v[212:215], v[44:47]
	v_mfma_f32_16x16x32_bf16 v[40:43], v[176:179], v[212:215], v[40:43]
	v_mfma_f32_16x16x32_bf16 v[36:39], v[168:171], v[220:223], v[36:39]
	v_mfma_f32_16x16x32_bf16 v[32:35], v[176:179], v[220:223], v[32:35]
	s_barrier
	s_mov_b32 m0, s15
	s_nop 0
	global_load_lds_dwordx4 v240, s[8:9]
	s_mov_b32 m0, s4
	s_nop 0
	global_load_lds_dwordx4 v241, s[8:9]
	s_waitcnt vmcnt(6)
	s_barrier
	v_mfma_f32_16x16x32_bf16 v[28:31], v[224:227], v[180:183], v[28:31]
	v_mfma_f32_16x16x32_bf16 v[24:27], v[232:235], v[180:183], v[24:27]
	v_mfma_f32_16x16x32_bf16 v[20:23], v[224:227], v[200:203], v[20:23]
	v_mfma_f32_16x16x32_bf16 v[16:19], v[232:235], v[200:203], v[16:19]
	v_mfma_f32_16x16x32_bf16 v[12:15], v[224:227], v[208:211], v[12:15]
	v_mfma_f32_16x16x32_bf16 v[8:11], v[232:235], v[208:211], v[8:11]
	v_mfma_f32_16x16x32_bf16 v[4:7], v[224:227], v[216:219], v[4:7]
	v_mfma_f32_16x16x32_bf16 v[0:3], v[232:235], v[216:219], v[0:3]
	v_mfma_f32_16x16x32_bf16 v[28:31], v[228:231], v[196:199], v[28:31]
	v_mfma_f32_16x16x32_bf16 v[24:27], v[236:239], v[196:199], v[24:27]
	v_mfma_f32_16x16x32_bf16 v[20:23], v[228:231], v[204:207], v[20:23]
	v_mfma_f32_16x16x32_bf16 v[16:19], v[236:239], v[204:207], v[16:19]
	v_mfma_f32_16x16x32_bf16 v[12:15], v[228:231], v[212:215], v[12:15]
	v_mfma_f32_16x16x32_bf16 v[8:11], v[236:239], v[212:215], v[8:11]
	v_mfma_f32_16x16x32_bf16 v[4:7], v[228:231], v[220:223], v[4:7]
	v_mfma_f32_16x16x32_bf16 v[0:3], v[236:239], v[220:223], v[0:3]
	s_add_i32 s11, s11, 2
	v_add_u32_e32 v130, 0x100, v130
	s_cmp_lt_u32 s11, 12
	v_add_u32_e32 v96, 0x100, v96
	s_barrier
.LBB0_379:
	v_or_b32_e32 v131, 0x10000, v150
	v_add_u32_e32 v133, 0x10100, v150
	v_add_u32_e32 v132, 0x10400, v150
	ds_read_b128 v[156:159], v131
	ds_read_b128 v[160:163], v132
	v_add_u32_e32 v146, 0x10500, v150
	ds_read_b128 v[164:167], v133
	ds_read_b128 v[168:171], v146
	v_add_u32_e32 v240, v147, v96
	s_add_i32 s26, s94, 0xc000
	v_add_u32_e32 v148, 0x80, v240
	s_mov_b32 m0, s26
	v_add_u32_e32 v241, v147, v130
	s_add_i32 s25, s94, 0xe000
	ds_read_b128 v[172:175], v151
	ds_read_b128 v[176:179], v151 offset:1024
	ds_read_b128 v[180:183], v151 offset:2048
	ds_read_b128 v[196:199], v151 offset:3072
	ds_read_b128 v[200:203], v151 offset:4096
	ds_read_b128 v[204:207], v151 offset:5120
	ds_read_b128 v[208:211], v151 offset:6144
	ds_read_b128 v[212:215], v151 offset:7168
	global_load_lds_dwordx4 v148, s[6:7]
	v_add_u32_e32 v148, 0x80, v241
	s_mov_b32 m0, s25
	s_nop 0
	global_load_lds_dwordx4 v148, s[6:7]
	s_waitcnt lgkmcnt(8)
	s_barrier
	s_waitcnt lgkmcnt(0)
	s_waitcnt lgkmcnt(0)
	v_mfma_f32_16x16x32_bf16 v[126:129], v[156:159], v[172:175], v[126:129]
	v_mfma_f32_16x16x32_bf16 v[122:125], v[164:167], v[172:175], v[122:125]
	v_mfma_f32_16x16x32_bf16 v[118:121], v[156:159], v[180:183], v[118:121]
	v_mfma_f32_16x16x32_bf16 v[114:117], v[164:167], v[180:183], v[114:117]
	v_mfma_f32_16x16x32_bf16 v[110:113], v[156:159], v[200:203], v[110:113]
	v_mfma_f32_16x16x32_bf16 v[106:109], v[164:167], v[200:203], v[106:109]
	v_mfma_f32_16x16x32_bf16 v[102:105], v[156:159], v[208:211], v[102:105]
	v_mfma_f32_16x16x32_bf16 v[98:101], v[164:167], v[208:211], v[98:101]
	v_mfma_f32_16x16x32_bf16 v[126:129], v[160:163], v[176:179], v[126:129]
	v_mfma_f32_16x16x32_bf16 v[122:125], v[168:171], v[176:179], v[122:125]
	v_mfma_f32_16x16x32_bf16 v[118:121], v[160:163], v[196:199], v[118:121]
	v_mfma_f32_16x16x32_bf16 v[114:117], v[168:171], v[196:199], v[114:117]
	v_mfma_f32_16x16x32_bf16 v[110:113], v[160:163], v[204:207], v[110:113]
	v_mfma_f32_16x16x32_bf16 v[106:109], v[168:171], v[204:207], v[106:109]
	v_mfma_f32_16x16x32_bf16 v[102:105], v[160:163], v[212:215], v[102:105]
	v_mfma_f32_16x16x32_bf16 v[98:101], v[168:171], v[212:215], v[98:101]
	s_barrier
	s_mov_b32 m0, s22
	v_or_b32_e32 v148, 0x14000, v150
	v_add_u32_e32 v154, 0x14100, v150
	v_add_u32_e32 v232, 0x100, v240
	v_add_u32_e32 v149, 0x14400, v150
	ds_read_b128 v[216:219], v148
	ds_read_b128 v[220:223], v149
	v_add_u32_e32 v155, 0x14500, v150
	ds_read_b128 v[224:227], v154
	ds_read_b128 v[228:231], v155
	global_load_lds_dwordx4 v232, s[16:17]
	v_add_u32_e32 v233, 0x100, v241
	s_mov_b32 m0, s23
	s_nop 0
	global_load_lds_dwordx4 v233, s[16:17]
	s_barrier
; #define WAIT_V(n) asm volatile("s_waitcnt vmcnt(%0)" ::"n"(n) : "memory")
; #define WAIT_L(n) asm volatile("s_waitcnt lgkmcnt(%0)" ::"n"(n) : "memory")
; #define SBAR() __builtin_amdgcn_sched_barrier(0)
; #define STAGE(P, base, kt) do { _Pragma("unroll") for (int _i = 0; _i < 2; ++_i)                                        \
;       __builtin_amdgcn_global_load_lds((const unsigned*)((base) + (size_t)(sOff[_i] + (unsigned)(kt) * (BK * 2))),        \
;                                        (unsigned*)((P) + wid * 1024 + _i * 8192), 16, 0, 0); } while (0)
; #define LDA(dst, b, h) _Pragma("unroll") for (int m = 0; m < 4; ++m) _Pragma("unroll") for (int k = 0; k < 2; ++k) \
;       dst[m][k] = *(const bf16x8*)(SA(b, h) + aoff + (m * 2048 + k * 1024))
; #define LDB(dst, b, h) _Pragma("unroll") for (int n = 0; n < 2; ++n) _Pragma("unroll") for (int k = 0; k < 2; ++k) \
;       dst[n][k] = *(const bf16x8*)(SB(b, h) + boff + (n * 256 + k * 1024))
; #define BAR __builtin_amdgcn_s_barrier()
; template <int EPI, int N, int K>
; __device__ __forceinline__ void phase_gemm(const Params& p, const u16* __restrict__ A, const u16* __restrict__ Bt, int nM, char* shm,
;                            u16* __restrict__ outp, float* __restrict__ rowss) {
;     ...
;       LDB(B1, 0, 1); STAGE(SB(0, 0), B0p, t + 2);
;       BAR; WAIT_L(0); MMA(0, 1, At, B1); BAR;
;       LDA(At, 0, 1); STAGE(SA(0, 0), A0, t + 2);
;       BAR; WAIT_L(0); MMA(1, 0, At, B0); BAR; SBAR();
;       STAGE(SB(0, 1), B1p, t + 2);
;       WAIT_V(6); BAR; MMA(1, 1, At, B1); BAR;
;       LDB(B0, 1, 0); SBAR(); LDA(At, 1, 0); STAGE(SA(0, 1), A1, t + 2);
;       WAIT_L(8); BAR; WAIT_L(0); MMA(0, 0, At, B0); BAR; SBAR();
;       LDB(B1, 1, 1); STAGE(SB(1, 0), B0p, t + 3);
;       BAR; WAIT_L(0); MMA(0, 1, At, B1); BAR;
;       LDA(At, 1, 1); STAGE(SA(1, 0), A0, t + 3);
;       BAR; WAIT_L(0); MMA(1, 0, At, B0); BAR; SBAR();
;       STAGE(SB(1, 1), B1p, t + 3);
;       WAIT_V(6); BAR; MMA(1, 1, At, B1); BAR;
	s_waitcnt lgkmcnt(0)
	s_waitcnt lgkmcnt(0)
	v_mfma_f32_16x16x32_bf16 v[92:95], v[216:219], v[172:175], v[92:95]
	v_mfma_f32_16x16x32_bf16 v[88:91], v[224:227], v[172:175], v[88:91]
	v_mfma_f32_16x16x32_bf16 v[84:87], v[216:219], v[180:183], v[84:87]
	v_mfma_f32_16x16x32_bf16 v[80:83], v[224:227], v[180:183], v[80:83]
	v_mfma_f32_16x16x32_bf16 v[76:79], v[216:219], v[200:203], v[76:79]
	v_mfma_f32_16x16x32_bf16 v[72:75], v[224:227], v[200:203], v[72:75]
	v_mfma_f32_16x16x32_bf16 v[68:71], v[216:219], v[208:211], v[68:71]
	v_mfma_f32_16x16x32_bf16 v[64:67], v[224:227], v[208:211], v[64:67]
	v_mfma_f32_16x16x32_bf16 v[92:95], v[220:223], v[176:179], v[92:95]
	v_mfma_f32_16x16x32_bf16 v[88:91], v[228:231], v[176:179], v[88:91]
	v_mfma_f32_16x16x32_bf16 v[84:87], v[220:223], v[196:199], v[84:87]
	v_mfma_f32_16x16x32_bf16 v[80:83], v[228:231], v[196:199], v[80:83]
	v_mfma_f32_16x16x32_bf16 v[76:79], v[220:223], v[204:207], v[76:79]
	v_mfma_f32_16x16x32_bf16 v[72:75], v[228:231], v[204:207], v[72:75]
	v_mfma_f32_16x16x32_bf16 v[68:71], v[220:223], v[212:215], v[68:71]
	v_mfma_f32_16x16x32_bf16 v[64:67], v[228:231], v[212:215], v[64:67]
	s_mov_b32 m0, s94
	s_barrier
	ds_read_b128 v[172:175], v151 offset:16384
	ds_read_b128 v[176:179], v151 offset:17408
	ds_read_b128 v[180:183], v151 offset:18432
	ds_read_b128 v[196:199], v151 offset:19456
	ds_read_b128 v[200:203], v151 offset:20480
	ds_read_b128 v[204:207], v151 offset:21504
	ds_read_b128 v[208:211], v151 offset:22528
	ds_read_b128 v[212:215], v151 offset:23552
	global_load_lds_dwordx4 v232, s[18:19]
	s_mov_b32 m0, s95
	s_nop 0
	global_load_lds_dwordx4 v233, s[18:19]
	s_barrier
	s_waitcnt lgkmcnt(0)
	s_waitcnt lgkmcnt(0)
	v_mfma_f32_16x16x32_bf16 v[60:63], v[156:159], v[172:175], v[60:63]
	v_mfma_f32_16x16x32_bf16 v[56:59], v[164:167], v[172:175], v[56:59]
	v_mfma_f32_16x16x32_bf16 v[52:55], v[156:159], v[180:183], v[52:55]
	v_mfma_f32_16x16x32_bf16 v[48:51], v[164:167], v[180:183], v[48:51]
	v_mfma_f32_16x16x32_bf16 v[44:47], v[156:159], v[200:203], v[44:47]
	v_mfma_f32_16x16x32_bf16 v[40:43], v[164:167], v[200:203], v[40:43]
	v_mfma_f32_16x16x32_bf16 v[36:39], v[156:159], v[208:211], v[36:39]
	v_mfma_f32_16x16x32_bf16 v[32:35], v[164:167], v[208:211], v[32:35]
	v_mfma_f32_16x16x32_bf16 v[60:63], v[160:163], v[176:179], v[60:63]
	v_mfma_f32_16x16x32_bf16 v[56:59], v[168:171], v[176:179], v[56:59]
	v_mfma_f32_16x16x32_bf16 v[52:55], v[160:163], v[196:199], v[52:55]
	v_mfma_f32_16x16x32_bf16 v[48:51], v[168:171], v[196:199], v[48:51]
	v_mfma_f32_16x16x32_bf16 v[44:47], v[160:163], v[204:207], v[44:47]
	v_mfma_f32_16x16x32_bf16 v[40:43], v[168:171], v[204:207], v[40:43]
	v_mfma_f32_16x16x32_bf16 v[36:39], v[160:163], v[212:215], v[36:39]
	v_mfma_f32_16x16x32_bf16 v[32:35], v[168:171], v[212:215], v[32:35]
	s_barrier
	s_mov_b32 m0, s2
	s_nop 0
	global_load_lds_dwordx4 v232, s[8:9]
	s_mov_b32 m0, s3
	s_nop 0
	global_load_lds_dwordx4 v233, s[8:9]
	s_waitcnt vmcnt(6)
	s_barrier
	v_mfma_f32_16x16x32_bf16 v[28:31], v[216:219], v[172:175], v[28:31]
	v_mfma_f32_16x16x32_bf16 v[24:27], v[224:227], v[172:175], v[24:27]
	v_mfma_f32_16x16x32_bf16 v[20:23], v[216:219], v[180:183], v[20:23]
	v_mfma_f32_16x16x32_bf16 v[16:19], v[224:227], v[180:183], v[16:19]
	v_mfma_f32_16x16x32_bf16 v[12:15], v[216:219], v[200:203], v[12:15]
	v_mfma_f32_16x16x32_bf16 v[8:11], v[224:227], v[200:203], v[8:11]
	v_mfma_f32_16x16x32_bf16 v[4:7], v[216:219], v[208:211], v[4:7]
	v_mfma_f32_16x16x32_bf16 v[0:3], v[224:227], v[208:211], v[0:3]
	v_mfma_f32_16x16x32_bf16 v[28:31], v[220:223], v[176:179], v[28:31]
	v_mfma_f32_16x16x32_bf16 v[24:27], v[228:231], v[176:179], v[24:27]
	v_mfma_f32_16x16x32_bf16 v[20:23], v[220:223], v[196:199], v[20:23]
	v_mfma_f32_16x16x32_bf16 v[16:19], v[228:231], v[196:199], v[16:19]
	v_mfma_f32_16x16x32_bf16 v[12:15], v[220:223], v[204:207], v[12:15]
	v_mfma_f32_16x16x32_bf16 v[8:11], v[228:231], v[204:207], v[8:11]
	v_mfma_f32_16x16x32_bf16 v[4:7], v[220:223], v[212:215], v[4:7]
	v_mfma_f32_16x16x32_bf16 v[0:3], v[228:231], v[212:215], v[0:3]
	v_or_b32_e32 v156, 0x18000, v150
	v_add_u32_e32 v158, 0x18100, v150
	s_barrier
	v_add_u32_e32 v157, 0x18400, v150
	ds_read_b128 v[164:167], v156
	ds_read_b128 v[168:171], v157
	v_add_u32_e32 v159, 0x18500, v150
	ds_read_b128 v[172:175], v158
	ds_read_b128 v[176:179], v159
	s_mov_b32 m0, s92
	ds_read_b128 v[180:183], v151 offset:32768
	ds_read_b128 v[196:199], v151 offset:33792
	ds_read_b128 v[200:203], v151 offset:34816
	ds_read_b128 v[204:207], v151 offset:35840
	ds_read_b128 v[208:211], v151 offset:36864
	ds_read_b128 v[212:215], v151 offset:37888
	ds_read_b128 v[216:219], v151 offset:38912
	ds_read_b128 v[220:223], v151 offset:39936
	global_load_lds_dwordx4 v232, s[6:7]
	s_mov_b32 m0, s0
	s_nop 0
	global_load_lds_dwordx4 v233, s[6:7]
	s_waitcnt lgkmcnt(8)
	s_barrier
	s_waitcnt lgkmcnt(0)
	s_waitcnt lgkmcnt(0)
	v_mfma_f32_16x16x32_bf16 v[126:129], v[164:167], v[180:183], v[126:129]
	v_mfma_f32_16x16x32_bf16 v[122:125], v[172:175], v[180:183], v[122:125]
	v_mfma_f32_16x16x32_bf16 v[118:121], v[164:167], v[200:203], v[118:121]
	v_mfma_f32_16x16x32_bf16 v[114:117], v[172:175], v[200:203], v[114:117]
	v_mfma_f32_16x16x32_bf16 v[110:113], v[164:167], v[208:211], v[110:113]
	v_mfma_f32_16x16x32_bf16 v[106:109], v[172:175], v[208:211], v[106:109]
	v_mfma_f32_16x16x32_bf16 v[102:105], v[164:167], v[216:219], v[102:105]
	v_mfma_f32_16x16x32_bf16 v[98:101], v[172:175], v[216:219], v[98:101]
	v_mfma_f32_16x16x32_bf16 v[126:129], v[168:171], v[196:199], v[126:129]
	v_mfma_f32_16x16x32_bf16 v[122:125], v[176:179], v[196:199], v[122:125]
	v_mfma_f32_16x16x32_bf16 v[118:121], v[168:171], v[204:207], v[118:121]
	v_mfma_f32_16x16x32_bf16 v[114:117], v[176:179], v[204:207], v[114:117]
	v_mfma_f32_16x16x32_bf16 v[110:113], v[168:171], v[212:215], v[110:113]
	v_mfma_f32_16x16x32_bf16 v[106:109], v[176:179], v[212:215], v[106:109]
	v_mfma_f32_16x16x32_bf16 v[102:105], v[168:171], v[220:223], v[102:105]
	v_mfma_f32_16x16x32_bf16 v[98:101], v[176:179], v[220:223], v[98:101]
	s_barrier
; #define WAIT_V(n) asm volatile("s_waitcnt vmcnt(%0)" ::"n"(n) : "memory")
; #define WAIT_L(n) asm volatile("s_waitcnt lgkmcnt(%0)" ::"n"(n) : "memory")
; #define SBAR() __builtin_amdgcn_sched_barrier(0)
; #define STAGE(P, base, kt) do { _Pragma("unroll") for (int _i = 0; _i < 2; ++_i)                                        \
;       __builtin_amdgcn_global_load_lds((const unsigned*)((base) + (size_t)(sOff[_i] + (unsigned)(kt) * (BK * 2))),        \
;                                        (unsigned*)((P) + wid * 1024 + _i * 8192), 16, 0, 0); } while (0)
; #define LDA(dst, b, h) _Pragma("unroll") for (int m = 0; m < 4; ++m) _Pragma("unroll") for (int k = 0; k < 2; ++k) \
;       dst[m][k] = *(const bf16x8*)(SA(b, h) + aoff + (m * 2048 + k * 1024))
; #define LDB(dst, b, h) _Pragma("unroll") for (int n = 0; n < 2; ++n) _Pragma("unroll") for (int k = 0; k < 2; ++k) \
;       dst[n][k] = *(const bf16x8*)(SB(b, h) + boff + (n * 256 + k * 1024))
; #define BAR __builtin_amdgcn_s_barrier()
; template <int EPI, int N, int K>
; __device__ __forceinline__ void phase_gemm(const Params& p, const u16* __restrict__ A, const u16* __restrict__ Bt, int nM, char* shm,
;                            u16* __restrict__ outp, float* __restrict__ rowss) {
;     ...
;       LDB(B0, 1, 0); SBAR(); LDA(At, 1, 0); STAGE(SA(0, 1), A1, t + 2);
;       WAIT_L(8); BAR; WAIT_L(0); MMA(0, 0, At, B0); BAR; SBAR();
;       LDB(B1, 1, 1); STAGE(SB(1, 0), B0p, t + 3);
;       BAR; WAIT_L(0); MMA(0, 1, At, B1); BAR;
;       LDA(At, 1, 1); STAGE(SA(1, 0), A0, t + 3);
;       BAR; WAIT_L(0); MMA(1, 0, At, B0); BAR; SBAR();
;       STAGE(SB(1, 1), B1p, t + 3);
;       WAIT_V(6); BAR; MMA(1, 1, At, B1); BAR;
;     }
;     { LDB(B0, 0, 0); LDA(At, 0, 0); STAGE(SA(1, 1), A1, nt - 1);
	s_mov_b32 m0, s1
	v_or_b32_e32 v160, 0x1c000, v150
	v_add_u32_e32 v162, 0x1c100, v150
	v_add_u32_e32 v240, 0x180, v240
	v_add_u32_e32 v161, 0x1c400, v150
	ds_read_b128 v[224:227], v160
	ds_read_b128 v[228:231], v161
	v_add_u32_e32 v163, 0x1c500, v150
	ds_read_b128 v[232:235], v162
	ds_read_b128 v[236:239], v163
	global_load_lds_dwordx4 v240, s[16:17]
	v_add_u32_e32 v241, 0x180, v241
	s_mov_b32 m0, s12
	s_nop 0
	global_load_lds_dwordx4 v241, s[16:17]
	s_barrier
	s_waitcnt lgkmcnt(0)
	s_waitcnt lgkmcnt(0)
	v_mfma_f32_16x16x32_bf16 v[92:95], v[224:227], v[180:183], v[92:95]
	v_mfma_f32_16x16x32_bf16 v[88:91], v[232:235], v[180:183], v[88:91]
	v_mfma_f32_16x16x32_bf16 v[84:87], v[224:227], v[200:203], v[84:87]
	v_mfma_f32_16x16x32_bf16 v[80:83], v[232:235], v[200:203], v[80:83]
	v_mfma_f32_16x16x32_bf16 v[76:79], v[224:227], v[208:211], v[76:79]
	v_mfma_f32_16x16x32_bf16 v[72:75], v[232:235], v[208:211], v[72:75]
	v_mfma_f32_16x16x32_bf16 v[68:71], v[224:227], v[216:219], v[68:71]
	v_mfma_f32_16x16x32_bf16 v[64:67], v[232:235], v[216:219], v[64:67]
	v_mfma_f32_16x16x32_bf16 v[92:95], v[228:231], v[196:199], v[92:95]
	v_mfma_f32_16x16x32_bf16 v[88:91], v[236:239], v[196:199], v[88:91]
	v_mfma_f32_16x16x32_bf16 v[84:87], v[228:231], v[204:207], v[84:87]
	v_mfma_f32_16x16x32_bf16 v[80:83], v[236:239], v[204:207], v[80:83]
	v_mfma_f32_16x16x32_bf16 v[76:79], v[228:231], v[212:215], v[76:79]
	v_mfma_f32_16x16x32_bf16 v[72:75], v[236:239], v[212:215], v[72:75]
	v_mfma_f32_16x16x32_bf16 v[68:71], v[228:231], v[220:223], v[68:71]
	v_mfma_f32_16x16x32_bf16 v[64:67], v[236:239], v[220:223], v[64:67]
	s_mov_b32 m0, s13
	s_barrier
	ds_read_b128 v[180:183], v151 offset:49152
	ds_read_b128 v[196:199], v151 offset:50176
	ds_read_b128 v[200:203], v151 offset:51200
	ds_read_b128 v[204:207], v151 offset:52224
	ds_read_b128 v[208:211], v151 offset:53248
	ds_read_b128 v[212:215], v151 offset:54272
	ds_read_b128 v[216:219], v151 offset:55296
	ds_read_b128 v[220:223], v151 offset:56320
	global_load_lds_dwordx4 v240, s[18:19]
	s_mov_b32 m0, s14
	s_nop 0
	global_load_lds_dwordx4 v241, s[18:19]
	s_barrier
	s_waitcnt lgkmcnt(0)
	s_waitcnt lgkmcnt(0)
	v_mfma_f32_16x16x32_bf16 v[60:63], v[164:167], v[180:183], v[60:63]
	v_mfma_f32_16x16x32_bf16 v[56:59], v[172:175], v[180:183], v[56:59]
	v_mfma_f32_16x16x32_bf16 v[52:55], v[164:167], v[200:203], v[52:55]
	v_mfma_f32_16x16x32_bf16 v[48:51], v[172:175], v[200:203], v[48:51]
	v_mfma_f32_16x16x32_bf16 v[44:47], v[164:167], v[208:211], v[44:47]
	v_mfma_f32_16x16x32_bf16 v[40:43], v[172:175], v[208:211], v[40:43]
	v_mfma_f32_16x16x32_bf16 v[36:39], v[164:167], v[216:219], v[36:39]
	v_mfma_f32_16x16x32_bf16 v[32:35], v[172:175], v[216:219], v[32:35]
	v_mfma_f32_16x16x32_bf16 v[60:63], v[168:171], v[196:199], v[60:63]
	v_mfma_f32_16x16x32_bf16 v[56:59], v[176:179], v[196:199], v[56:59]
	v_mfma_f32_16x16x32_bf16 v[52:55], v[168:171], v[204:207], v[52:55]
	v_mfma_f32_16x16x32_bf16 v[48:51], v[176:179], v[204:207], v[48:51]
	v_mfma_f32_16x16x32_bf16 v[44:47], v[168:171], v[212:215], v[44:47]
	v_mfma_f32_16x16x32_bf16 v[40:43], v[176:179], v[212:215], v[40:43]
	v_mfma_f32_16x16x32_bf16 v[36:39], v[168:171], v[220:223], v[36:39]
	v_mfma_f32_16x16x32_bf16 v[32:35], v[176:179], v[220:223], v[32:35]
	s_barrier
	s_mov_b32 m0, s15
	s_nop 0
	global_load_lds_dwordx4 v240, s[8:9]
	s_mov_b32 m0, s4
	s_nop 0
	global_load_lds_dwordx4 v241, s[8:9]
	s_waitcnt vmcnt(6)
	s_barrier
	v_mfma_f32_16x16x32_bf16 v[28:31], v[224:227], v[180:183], v[28:31]
	v_mfma_f32_16x16x32_bf16 v[24:27], v[232:235], v[180:183], v[24:27]
	v_mfma_f32_16x16x32_bf16 v[20:23], v[224:227], v[200:203], v[20:23]
	v_mfma_f32_16x16x32_bf16 v[16:19], v[232:235], v[200:203], v[16:19]
	v_mfma_f32_16x16x32_bf16 v[12:15], v[224:227], v[208:211], v[12:15]
	v_mfma_f32_16x16x32_bf16 v[8:11], v[232:235], v[208:211], v[8:11]
	v_mfma_f32_16x16x32_bf16 v[4:7], v[224:227], v[216:219], v[4:7]
	v_mfma_f32_16x16x32_bf16 v[0:3], v[232:235], v[216:219], v[0:3]
	v_mfma_f32_16x16x32_bf16 v[28:31], v[228:231], v[196:199], v[28:31]
	v_mfma_f32_16x16x32_bf16 v[24:27], v[236:239], v[196:199], v[24:27]
	v_mfma_f32_16x16x32_bf16 v[20:23], v[228:231], v[204:207], v[20:23]
	v_mfma_f32_16x16x32_bf16 v[16:19], v[236:239], v[204:207], v[16:19]
	v_mfma_f32_16x16x32_bf16 v[12:15], v[228:231], v[212:215], v[12:15]
	v_mfma_f32_16x16x32_bf16 v[8:11], v[236:239], v[212:215], v[8:11]
	v_mfma_f32_16x16x32_bf16 v[4:7], v[228:231], v[220:223], v[4:7]
	v_mfma_f32_16x16x32_bf16 v[0:3], v[236:239], v[220:223], v[0:3]
	s_add_i32 s11, s11, 2
	v_add_u32_e32 v130, 0x100, v130
	s_cmp_lt_u32 s11, 12
	v_add_u32_e32 v96, 0x100, v96
	s_barrier
	s_cbranch_scc1 .LBB0_379
	s_mov_b32 m0, s26
	v_lshl_add_u64 v[220:221], s[6:7], 0, v[142:143]
	ds_read_b128 v[164:167], v131
	ds_read_b128 v[168:171], v132
	ds_read_b128 v[130:133], v133
	ds_read_b128 v[172:175], v146
	ds_read_b128 v[176:179], v151
	ds_read_b128 v[180:183], v151 offset:1024
	ds_read_b128 v[196:199], v151 offset:2048
	ds_read_b128 v[200:203], v151 offset:3072
	ds_read_b128 v[204:207], v151 offset:4096
	ds_read_b128 v[208:211], v151 offset:5120
	ds_read_b128 v[212:215], v151 offset:6144
	ds_read_b128 v[216:219], v151 offset:7168
	global_load_lds_dwordx4 v[220:221], off
	v_lshl_add_u64 v[220:221], s[6:7], 0, v[144:145]
	s_mov_b32 m0, s25
	s_nop 0
	global_load_lds_dwordx4 v[220:221], off
	s_barrier
; #define WAIT_V(n) asm volatile("s_waitcnt vmcnt(%0)" ::"n"(n) : "memory")
; #define WAIT_L(n) asm volatile("s_waitcnt lgkmcnt(%0)" ::"n"(n) : "memory")
; #define STAGE(P, base, kt) do { _Pragma("unroll") for (int _i = 0; _i < 2; ++_i)                                        \
;       __builtin_amdgcn_global_load_lds((const unsigned*)((base) + (size_t)(sOff[_i] + (unsigned)(kt) * (BK * 2))),        \
;                                        (unsigned*)((P) + wid * 1024 + _i * 8192), 16, 0, 0); } while (0)
; #define LDA(dst, b, h) _Pragma("unroll") for (int m = 0; m < 4; ++m) _Pragma("unroll") for (int k = 0; k < 2; ++k) \
;       dst[m][k] = *(const bf16x8*)(SA(b, h) + aoff + (m * 2048 + k * 1024))
; #define LDB(dst, b, h) _Pragma("unroll") for (int n = 0; n < 2; ++n) _Pragma("unroll") for (int k = 0; k < 2; ++k) \
;       dst[n][k] = *(const bf16x8*)(SB(b, h) + boff + (n * 256 + k * 1024))
; #define BAR __builtin_amdgcn_s_barrier()
; template <int EPI, int N, int K>
; __device__ __forceinline__ void phase_gemm(const Params& p, const u16* __restrict__ A, const u16* __restrict__ Bt, int nM, char* shm,
;                            u16* __restrict__ outp, float* __restrict__ rowss) {
;     ...
;     { LDB(B0, 0, 0); LDA(At, 0, 0); STAGE(SA(1, 1), A1, nt - 1);
;       BAR; WAIT_L(0); MMA(0, 0, At, B0); BAR;
;       LDB(B1, 0, 1); BAR; WAIT_L(0); MMA(0, 1, At, B1); BAR;
;       LDA(At, 0, 1); WAIT_V(4); BAR; WAIT_L(0); MMA(1, 0, At, B0); MMA(1, 1, At, B1); BAR; }
;     { LDB(B0, 1, 0); LDA(At, 1, 0); WAIT_V(2); BAR; WAIT_L(0); MMA(0, 0, At, B0); BAR;
	s_waitcnt lgkmcnt(0)
	s_waitcnt lgkmcnt(0)
	v_mfma_f32_16x16x32_bf16 v[126:129], v[164:167], v[176:179], v[126:129]
	v_mfma_f32_16x16x32_bf16 v[122:125], v[130:133], v[176:179], v[122:125]
	v_mfma_f32_16x16x32_bf16 v[118:121], v[164:167], v[196:199], v[118:121]
	v_mfma_f32_16x16x32_bf16 v[114:117], v[130:133], v[196:199], v[114:117]
	v_mfma_f32_16x16x32_bf16 v[102:105], v[164:167], v[212:215], v[102:105]
	v_mfma_f32_16x16x32_bf16 v[98:101], v[130:133], v[212:215], v[98:101]
	v_mfma_f32_16x16x32_bf16 v[126:129], v[168:171], v[180:183], v[126:129]
	v_mfma_f32_16x16x32_bf16 v[122:125], v[172:175], v[180:183], v[122:125]
	v_mfma_f32_16x16x32_bf16 v[118:121], v[168:171], v[200:203], v[118:121]
	v_mfma_f32_16x16x32_bf16 v[114:117], v[172:175], v[200:203], v[114:117]
	v_mfma_f32_16x16x32_bf16 v[110:113], v[164:167], v[204:207], v[110:113]
	v_mfma_f32_16x16x32_bf16 v[106:109], v[130:133], v[204:207], v[106:109]
	v_mfma_f32_16x16x32_bf16 v[102:105], v[168:171], v[216:219], v[102:105]
	v_mfma_f32_16x16x32_bf16 v[98:101], v[172:175], v[216:219], v[98:101]
	v_mfma_f32_16x16x32_bf16 v[220:223], v[168:171], v[208:211], v[110:113]
	v_mfma_f32_16x16x32_bf16 v[224:227], v[172:175], v[208:211], v[106:109]
	s_barrier
	s_nop 1
	ds_read_b128 v[106:109], v148
	ds_read_b128 v[110:113], v149
	ds_read_b128 v[228:231], v154
	ds_read_b128 v[232:235], v155
	s_barrier
	s_waitcnt lgkmcnt(0)
	s_waitcnt lgkmcnt(0)
	v_mfma_f32_16x16x32_bf16 v[84:87], v[106:109], v[196:199], v[84:87]
	v_mfma_f32_16x16x32_bf16 v[80:83], v[228:231], v[196:199], v[80:83]
	v_mfma_f32_16x16x32_bf16 v[68:71], v[106:109], v[212:215], v[68:71]
	v_mfma_f32_16x16x32_bf16 v[64:67], v[228:231], v[212:215], v[64:67]
	v_mfma_f32_16x16x32_bf16 v[92:95], v[106:109], v[176:179], v[92:95]
	v_mfma_f32_16x16x32_bf16 v[88:91], v[228:231], v[176:179], v[88:91]
	v_mfma_f32_16x16x32_bf16 v[84:87], v[110:113], v[200:203], v[84:87]
	v_mfma_f32_16x16x32_bf16 v[80:83], v[232:235], v[200:203], v[80:83]
	v_mfma_f32_16x16x32_bf16 v[76:79], v[106:109], v[204:207], v[76:79]
	v_mfma_f32_16x16x32_bf16 v[72:75], v[228:231], v[204:207], v[72:75]
	v_mfma_f32_16x16x32_bf16 v[68:71], v[110:113], v[216:219], v[68:71]
	v_mfma_f32_16x16x32_bf16 v[64:67], v[232:235], v[216:219], v[64:67]
	v_mfma_f32_16x16x32_bf16 v[236:239], v[110:113], v[180:183], v[92:95]
	v_mfma_f32_16x16x32_bf16 v[176:179], v[232:235], v[180:183], v[88:91]
	v_mfma_f32_16x16x32_bf16 v[180:183], v[110:113], v[208:211], v[76:79]
	v_mfma_f32_16x16x32_bf16 v[196:199], v[232:235], v[208:211], v[72:75]
	s_barrier
	s_nop 0
	ds_read_b128 v[72:75], v151 offset:16384
	ds_read_b128 v[76:79], v151 offset:17408
	ds_read_b128 v[88:91], v151 offset:18432
	ds_read_b128 v[92:95], v151 offset:19456
	ds_read_b128 v[200:203], v151 offset:20480
	ds_read_b128 v[204:207], v151 offset:21504
	ds_read_b128 v[208:211], v151 offset:22528
	ds_read_b128 v[212:215], v151 offset:23552
	s_waitcnt vmcnt(4)
	s_barrier
	s_waitcnt lgkmcnt(0)
	s_waitcnt lgkmcnt(0)
	v_mfma_f32_16x16x32_bf16 v[60:63], v[164:167], v[72:75], v[60:63]
	v_mfma_f32_16x16x32_bf16 v[56:59], v[130:133], v[72:75], v[56:59]
	v_mfma_f32_16x16x32_bf16 v[52:55], v[164:167], v[88:91], v[52:55]
	v_mfma_f32_16x16x32_bf16 v[48:51], v[130:133], v[88:91], v[48:51]
	v_mfma_f32_16x16x32_bf16 v[36:39], v[164:167], v[208:211], v[36:39]
	v_mfma_f32_16x16x32_bf16 v[32:35], v[130:133], v[208:211], v[32:35]
	v_mfma_f32_16x16x32_bf16 v[60:63], v[168:171], v[76:79], v[60:63]
	v_mfma_f32_16x16x32_bf16 v[56:59], v[172:175], v[76:79], v[56:59]
	v_mfma_f32_16x16x32_bf16 v[52:55], v[168:171], v[92:95], v[52:55]
	v_mfma_f32_16x16x32_bf16 v[48:51], v[172:175], v[92:95], v[48:51]
	v_mfma_f32_16x16x32_bf16 v[44:47], v[164:167], v[200:203], v[44:47]
	v_mfma_f32_16x16x32_bf16 v[40:43], v[130:133], v[200:203], v[40:43]
	v_mfma_f32_16x16x32_bf16 v[36:39], v[168:171], v[212:215], v[36:39]
	v_mfma_f32_16x16x32_bf16 v[32:35], v[172:175], v[212:215], v[32:35]
	v_mfma_f32_16x16x32_bf16 v[216:219], v[168:171], v[204:207], v[44:47]
	v_mfma_f32_16x16x32_bf16 v[240:243], v[172:175], v[204:207], v[40:43]
	v_mfma_f32_16x16x32_bf16 v[20:23], v[106:109], v[88:91], v[20:23]
	v_mfma_f32_16x16x32_bf16 v[16:19], v[228:231], v[88:91], v[16:19]
	v_mfma_f32_16x16x32_bf16 v[4:7], v[106:109], v[208:211], v[4:7]
	v_mfma_f32_16x16x32_bf16 v[0:3], v[228:231], v[208:211], v[0:3]
	v_mfma_f32_16x16x32_bf16 v[28:31], v[106:109], v[72:75], v[28:31]
	v_mfma_f32_16x16x32_bf16 v[24:27], v[228:231], v[72:75], v[24:27]
	v_mfma_f32_16x16x32_bf16 v[20:23], v[110:113], v[92:95], v[20:23]
	v_mfma_f32_16x16x32_bf16 v[16:19], v[232:235], v[92:95], v[16:19]
	v_mfma_f32_16x16x32_bf16 v[12:15], v[106:109], v[200:203], v[12:15]
	v_mfma_f32_16x16x32_bf16 v[8:11], v[228:231], v[200:203], v[8:11]
	v_mfma_f32_16x16x32_bf16 v[4:7], v[110:113], v[212:215], v[4:7]
	v_mfma_f32_16x16x32_bf16 v[0:3], v[232:235], v[212:215], v[0:3]
	v_mfma_f32_16x16x32_bf16 v[130:133], v[110:113], v[76:79], v[28:31]
	v_mfma_f32_16x16x32_bf16 v[164:167], v[232:235], v[76:79], v[24:27]
	v_mfma_f32_16x16x32_bf16 v[168:171], v[110:113], v[204:207], v[12:15]
	v_mfma_f32_16x16x32_bf16 v[172:175], v[232:235], v[204:207], v[8:11]
	s_barrier
; #define WAIT_V(n) asm volatile("s_waitcnt vmcnt(%0)" ::"n"(n) : "memory")
; #define WAIT_L(n) asm volatile("s_waitcnt lgkmcnt(%0)" ::"n"(n) : "memory")
; #define LDA(dst, b, h) _Pragma("unroll") for (int m = 0; m < 4; ++m) _Pragma("unroll") for (int k = 0; k < 2; ++k) \
;       dst[m][k] = *(const bf16x8*)(SA(b, h) + aoff + (m * 2048 + k * 1024))
; #define LDB(dst, b, h) _Pragma("unroll") for (int n = 0; n < 2; ++n) _Pragma("unroll") for (int k = 0; k < 2; ++k) \
;       dst[n][k] = *(const bf16x8*)(SB(b, h) + boff + (n * 256 + k * 1024))
; #define BAR __builtin_amdgcn_s_barrier()
; template <int EPI, int N, int K>
; __device__ __forceinline__ void phase_gemm(const Params& p, const u16* __restrict__ A, const u16* __restrict__ Bt, int nM, char* shm,
;                            u16* __restrict__ outp, float* __restrict__ rowss) {
;     ...
;     { LDB(B0, 1, 0); LDA(At, 1, 0); WAIT_V(2); BAR; WAIT_L(0); MMA(0, 0, At, B0); BAR;
;       LDB(B1, 1, 1); WAIT_V(0); BAR; WAIT_L(0); MMA(0, 1, At, B1); BAR;
;       LDA(At, 1, 1); BAR; WAIT_L(0); MMA(1, 0, At, B0); MMA(1, 1, At, B1); BAR; }
;     if (wr == 0) BAR;
	s_nop 0
	ds_read_b128 v[8:11], v156
	ds_read_b128 v[12:15], v157
	ds_read_b128 v[154:157], v158
	ds_read_b128 v[200:203], v159
	ds_read_b128 v[24:27], v151 offset:32768
	ds_read_b128 v[28:31], v151 offset:33792
	ds_read_b128 v[40:43], v151 offset:34816
	ds_read_b128 v[44:47], v151 offset:35840
	ds_read_b128 v[204:207], v151 offset:36864
	ds_read_b128 v[208:211], v151 offset:37888
	ds_read_b128 v[212:215], v151 offset:38912
	ds_read_b128 v[228:231], v151 offset:39936
	s_waitcnt vmcnt(2)
	s_barrier
	s_waitcnt lgkmcnt(0)
	s_waitcnt lgkmcnt(0)
	v_mfma_f32_16x16x32_bf16 v[72:75], v[8:11], v[24:27], v[126:129]
	v_mfma_f32_16x16x32_bf16 v[126:129], v[12:15], v[28:31], v[72:75]
	v_mfma_f32_16x16x32_bf16 v[72:75], v[154:157], v[24:27], v[122:125]
	v_mfma_f32_16x16x32_bf16 v[122:125], v[200:203], v[28:31], v[72:75]
	v_mfma_f32_16x16x32_bf16 v[72:75], v[8:11], v[40:43], v[118:121]
	v_mfma_f32_16x16x32_bf16 v[110:113], v[12:15], v[44:47], v[72:75]
	v_mfma_f32_16x16x32_bf16 v[72:75], v[154:157], v[40:43], v[114:117]
	v_mfma_f32_16x16x32_bf16 v[106:109], v[200:203], v[44:47], v[72:75]
	v_mfma_f32_16x16x32_bf16 v[72:75], v[8:11], v[204:207], v[220:223]
	v_mfma_f32_16x16x32_bf16 v[92:95], v[12:15], v[208:211], v[72:75]
	v_mfma_f32_16x16x32_bf16 v[72:75], v[154:157], v[204:207], v[224:227]
	v_mfma_f32_16x16x32_bf16 v[88:91], v[200:203], v[208:211], v[72:75]
	v_mfma_f32_16x16x32_bf16 v[72:75], v[8:11], v[212:215], v[102:105]
	v_mfma_f32_16x16x32_bf16 v[76:79], v[12:15], v[228:231], v[72:75]
	v_mfma_f32_16x16x32_bf16 v[72:75], v[154:157], v[212:215], v[98:101]
	v_mfma_f32_16x16x32_bf16 v[72:75], v[200:203], v[228:231], v[72:75]
	s_barrier
	ds_read_b128 v[220:223], v160
	ds_read_b128 v[158:161], v161
	ds_read_b128 v[224:227], v162
	ds_read_b128 v[232:235], v163
	s_waitcnt vmcnt(0)
	s_barrier
	s_waitcnt lgkmcnt(0)
	s_waitcnt lgkmcnt(0)
	v_mfma_f32_16x16x32_bf16 v[98:101], v[220:223], v[24:27], v[236:239]
	v_mfma_f32_16x16x32_bf16 v[24:27], v[224:227], v[24:27], v[176:179]
	v_mfma_f32_16x16x32_bf16 v[114:117], v[232:235], v[28:31], v[24:27]
	v_mfma_f32_16x16x32_bf16 v[24:27], v[220:223], v[40:43], v[84:87]
	v_mfma_f32_16x16x32_bf16 v[102:105], v[158:161], v[44:47], v[24:27]
	v_mfma_f32_16x16x32_bf16 v[24:27], v[224:227], v[40:43], v[80:83]
	v_mfma_f32_16x16x32_bf16 v[118:121], v[158:161], v[28:31], v[98:101]
	v_mfma_f32_16x16x32_bf16 v[98:101], v[232:235], v[44:47], v[24:27]
	v_mfma_f32_16x16x32_bf16 v[24:27], v[220:223], v[204:207], v[180:183]
	v_mfma_f32_16x16x32_bf16 v[84:87], v[158:161], v[208:211], v[24:27]
	v_mfma_f32_16x16x32_bf16 v[24:27], v[224:227], v[204:207], v[196:199]
	v_mfma_f32_16x16x32_bf16 v[80:83], v[232:235], v[208:211], v[24:27]
	v_mfma_f32_16x16x32_bf16 v[24:27], v[220:223], v[212:215], v[68:71]
	v_mfma_f32_16x16x32_bf16 v[68:71], v[158:161], v[228:231], v[24:27]
	v_mfma_f32_16x16x32_bf16 v[24:27], v[224:227], v[212:215], v[64:67]
	v_mfma_f32_16x16x32_bf16 v[64:67], v[232:235], v[228:231], v[24:27]
	s_barrier
	ds_read_b128 v[176:179], v151 offset:49152
	ds_read_b128 v[180:183], v151 offset:50176
	ds_read_b128 v[196:199], v151 offset:51200
	ds_read_b128 v[204:207], v151 offset:52224
	ds_read_b128 v[208:211], v151 offset:53248
	ds_read_b128 v[212:215], v151 offset:54272
	ds_read_b128 v[228:231], v151 offset:55296
	ds_read_b128 v[236:239], v151 offset:56320
	s_barrier
	s_waitcnt lgkmcnt(0)
	s_waitcnt lgkmcnt(0)
	v_mfma_f32_16x16x32_bf16 v[24:27], v[8:11], v[176:179], v[60:63]
	v_mfma_f32_16x16x32_bf16 v[60:63], v[12:15], v[180:183], v[24:27]
	v_mfma_f32_16x16x32_bf16 v[24:27], v[154:157], v[176:179], v[56:59]
	v_mfma_f32_16x16x32_bf16 v[56:59], v[200:203], v[180:183], v[24:27]
	v_mfma_f32_16x16x32_bf16 v[24:27], v[8:11], v[196:199], v[52:55]
	v_mfma_f32_16x16x32_bf16 v[44:47], v[12:15], v[204:207], v[24:27]
	v_mfma_f32_16x16x32_bf16 v[24:27], v[154:157], v[196:199], v[48:51]
	v_mfma_f32_16x16x32_bf16 v[40:43], v[200:203], v[204:207], v[24:27]
	v_mfma_f32_16x16x32_bf16 v[24:27], v[8:11], v[208:211], v[216:219]
	v_mfma_f32_16x16x32_bf16 v[8:11], v[8:11], v[228:231], v[36:39]
	v_mfma_f32_16x16x32_bf16 v[28:31], v[12:15], v[212:215], v[24:27]
	v_mfma_f32_16x16x32_bf16 v[24:27], v[154:157], v[208:211], v[240:243]
	v_mfma_f32_16x16x32_bf16 v[12:15], v[12:15], v[236:239], v[8:11]
	v_mfma_f32_16x16x32_bf16 v[8:11], v[154:157], v[228:231], v[32:35]
	v_mfma_f32_16x16x32_bf16 v[24:27], v[200:203], v[212:215], v[24:27]
	v_mfma_f32_16x16x32_bf16 v[8:11], v[200:203], v[236:239], v[8:11]
	v_mfma_f32_16x16x32_bf16 v[32:35], v[220:223], v[176:179], v[130:133]
	v_mfma_f32_16x16x32_bf16 v[52:55], v[158:161], v[180:183], v[32:35]
	v_mfma_f32_16x16x32_bf16 v[32:35], v[224:227], v[176:179], v[164:167]
	v_mfma_f32_16x16x32_bf16 v[16:19], v[224:227], v[196:199], v[16:19]
	v_mfma_f32_16x16x32_bf16 v[48:51], v[232:235], v[180:183], v[32:35]
	v_mfma_f32_16x16x32_bf16 v[20:23], v[220:223], v[196:199], v[20:23]
	v_mfma_f32_16x16x32_bf16 v[32:35], v[232:235], v[204:207], v[16:19]
	v_mfma_f32_16x16x32_bf16 v[16:19], v[220:223], v[208:211], v[168:171]
	v_mfma_f32_16x16x32_bf16 v[36:39], v[158:161], v[204:207], v[20:23]
	v_mfma_f32_16x16x32_bf16 v[20:23], v[158:161], v[212:215], v[16:19]
	v_mfma_f32_16x16x32_bf16 v[16:19], v[224:227], v[208:211], v[172:175]
	v_mfma_f32_16x16x32_bf16 v[4:7], v[220:223], v[228:231], v[4:7]
	v_mfma_f32_16x16x32_bf16 v[0:3], v[224:227], v[228:231], v[0:3]
	v_mfma_f32_16x16x32_bf16 v[16:19], v[232:235], v[212:215], v[16:19]
	v_mfma_f32_16x16x32_bf16 v[4:7], v[158:161], v[236:239], v[4:7]
	v_mfma_f32_16x16x32_bf16 v[0:3], v[232:235], v[236:239], v[0:3]
	s_andn2_b64 vcc, exec, s[62:63]
	s_barrier
	s_cbranch_vccnz .LBB0_382
	s_barrier

; #define WAIT_V(n) asm volatile("s_waitcnt vmcnt(%0)" ::"n"(n) : "memory")
; #define WAIT_L(n) asm volatile("s_waitcnt lgkmcnt(%0)" ::"n"(n) : "memory")
; #define SBAR() __builtin_amdgcn_sched_barrier(0)
; #define STAGE(P, base, kt) do { _Pragma("unroll") for (int _i = 0; _i < 2; ++_i)                                        \
;       __builtin_amdgcn_global_load_lds((const unsigned*)((base) + (size_t)(sOff[_i] + (unsigned)(kt) * (BK * 2))),        \
;                                        (unsigned*)((P) + wid * 1024 + _i * 8192), 16, 0, 0); } while (0)
; #define LDA(dst, b, h) _Pragma("unroll") for (int m = 0; m < 4; ++m) _Pragma("unroll") for (int k = 0; k < 2; ++k) \
;       dst[m][k] = *(const bf16x8*)(SA(b, h) + aoff + (m * 2048 + k * 1024))
; #define LDB(dst, b, h) _Pragma("unroll") for (int n = 0; n < 2; ++n) _Pragma("unroll") for (int k = 0; k < 2; ++k) \
;       dst[n][k] = *(const bf16x8*)(SB(b, h) + boff + (n * 256 + k * 1024))
; #define BAR __builtin_amdgcn_s_barrier()
; template <int EPI, int N, int K>
; __device__ __forceinline__ void phase_gemm(const Params& p, const u16* __restrict__ A, const u16* __restrict__ Bt, int nM, char* shm,
;                            u16* __restrict__ outp, float* __restrict__ rowss) {
;     ...
;     const char* A1 = A0 + (size_t)128 * K * 2;
;     const char* B1p = B0p + (size_t)128 * K * 2;
;     f32x4 acc[2][2][4][2] = {};
;     bf16x8 At[4][2], B0[2][2], B1[2][2];
;     if (wr == 1) BAR;
;     WAIT_V(0); BAR;
;     BAR;
;     for (int t = 0; t < nt - 2; t += 2) {
;       LDB(B0, 0, 0); SBAR(); LDA(At, 0, 0); STAGE(SA(1, 1), A1, t + 1);
;       WAIT_L(8); BAR; WAIT_L(0); MMA(0, 0, At, B0); BAR; SBAR();
;       LDB(B1, 0, 1); STAGE(SB(0, 0), B0p, t + 2);
;       BAR; WAIT_L(0); MMA(0, 1, At, B1); BAR;
;       LDA(At, 0, 1); STAGE(SA(0, 0), A0, t + 2);
;       BAR; WAIT_L(0); MMA(1, 0, At, B0); BAR; SBAR();
;       STAGE(SB(0, 1), B1p, t + 2);
;       WAIT_V(6); BAR; MMA(1, 1, At, B1); BAR;
.LBB0_432:
	s_add_u32 s16, s10, 0x40000
	s_addc_u32 s17, s11, 0
	s_waitcnt vmcnt(0)
	s_add_u32 s18, s8, 0x40000
	s_addc_u32 s19, s9, 0
	s_mov_b32 s22, -2
	v_mov_b32_e32 v96, v148
	v_mov_b32_e32 v142, v147
	s_barrier
	s_barrier
	v_or_b32_e32 v143, 0x10000, v145
	v_add_u32_e32 v150, 0x10100, v145
	v_add_u32_e32 v149, 0x10400, v145
	ds_read_b128 v[156:159], v143
	ds_read_b128 v[160:163], v149
	v_add_u32_e32 v151, 0x10500, v145
	ds_read_b128 v[164:167], v150
	ds_read_b128 v[168:171], v151
	v_add_u32_e32 v204, v144, v96
	s_add_i32 s62, s5, 0xc000
	v_add_u32_e32 v152, 0x80, v204
	s_mov_b32 m0, s62
	v_add_u32_e32 v205, v144, v142
	s_add_i32 s23, s5, 0xe000
	ds_read_b128 v[172:175], v146
	ds_read_b128 v[176:179], v146 offset:1024
	ds_read_b128 v[180:183], v146 offset:2048
	ds_read_b128 v[196:199], v146 offset:3072
	ds_read_b128 v[200:203], v146 offset:4096
	ds_read_b128 v[208:211], v146 offset:5120
	ds_read_b128 v[212:215], v146 offset:6144
	ds_read_b128 v[216:219], v146 offset:7168
	global_load_lds_dwordx4 v152, s[16:17]
	v_add_u32_e32 v152, 0x80, v205
	s_mov_b32 m0, s23
	s_nop 0
	global_load_lds_dwordx4 v152, s[16:17]
	s_waitcnt lgkmcnt(8)
	s_barrier
	s_waitcnt lgkmcnt(0)
	s_waitcnt lgkmcnt(0)
	v_mfma_f32_16x16x32_bf16 v[126:129], v[156:159], v[172:175], 0
	v_mfma_f32_16x16x32_bf16 v[122:125], v[164:167], v[172:175], 0
	v_mfma_f32_16x16x32_bf16 v[118:121], v[156:159], v[180:183], 0
	v_mfma_f32_16x16x32_bf16 v[114:117], v[164:167], v[180:183], 0
	v_mfma_f32_16x16x32_bf16 v[110:113], v[156:159], v[200:203], 0
	v_mfma_f32_16x16x32_bf16 v[106:109], v[164:167], v[200:203], 0
	v_mfma_f32_16x16x32_bf16 v[102:105], v[156:159], v[212:215], 0
	v_mfma_f32_16x16x32_bf16 v[98:101], v[164:167], v[212:215], 0
	v_mfma_f32_16x16x32_bf16 v[126:129], v[160:163], v[176:179], v[126:129]
	v_mfma_f32_16x16x32_bf16 v[122:125], v[168:171], v[176:179], v[122:125]
	v_mfma_f32_16x16x32_bf16 v[118:121], v[160:163], v[196:199], v[118:121]
	v_mfma_f32_16x16x32_bf16 v[114:117], v[168:171], v[196:199], v[114:117]
	v_mfma_f32_16x16x32_bf16 v[110:113], v[160:163], v[208:211], v[110:113]
	v_mfma_f32_16x16x32_bf16 v[106:109], v[168:171], v[208:211], v[106:109]
	v_mfma_f32_16x16x32_bf16 v[102:105], v[160:163], v[216:219], v[102:105]
	v_mfma_f32_16x16x32_bf16 v[98:101], v[168:171], v[216:219], v[98:101]
	s_barrier
	s_mov_b32 m0, s25
	v_or_b32_e32 v152, 0x14000, v145
	v_add_u32_e32 v154, 0x14100, v145
	v_add_u32_e32 v206, 0x100, v204
	v_add_u32_e32 v153, 0x14400, v145
	ds_read_b128 v[220:223], v152
	ds_read_b128 v[224:227], v153
	v_add_u32_e32 v155, 0x14500, v145
	ds_read_b128 v[228:231], v154
	ds_read_b128 v[232:235], v155
	global_load_lds_dwordx4 v206, s[8:9]
	v_add_u32_e32 v207, 0x100, v205
	s_mov_b32 m0, s26
	s_nop 0
	global_load_lds_dwordx4 v207, s[8:9]
	s_barrier
	s_waitcnt lgkmcnt(0)
	s_waitcnt lgkmcnt(0)
	v_mfma_f32_16x16x32_bf16 v[92:95], v[220:223], v[172:175], 0
	v_mfma_f32_16x16x32_bf16 v[88:91], v[228:231], v[172:175], 0
	v_mfma_f32_16x16x32_bf16 v[84:87], v[220:223], v[180:183], 0
	v_mfma_f32_16x16x32_bf16 v[80:83], v[228:231], v[180:183], 0
	v_mfma_f32_16x16x32_bf16 v[76:79], v[220:223], v[200:203], 0
	v_mfma_f32_16x16x32_bf16 v[72:75], v[228:231], v[200:203], 0
	v_mfma_f32_16x16x32_bf16 v[68:71], v[220:223], v[212:215], 0
	v_mfma_f32_16x16x32_bf16 v[64:67], v[228:231], v[212:215], 0
	v_mfma_f32_16x16x32_bf16 v[92:95], v[224:227], v[176:179], v[92:95]
	v_mfma_f32_16x16x32_bf16 v[88:91], v[232:235], v[176:179], v[88:91]
	v_mfma_f32_16x16x32_bf16 v[84:87], v[224:227], v[196:199], v[84:87]
	v_mfma_f32_16x16x32_bf16 v[80:83], v[232:235], v[196:199], v[80:83]
	v_mfma_f32_16x16x32_bf16 v[76:79], v[224:227], v[208:211], v[76:79]
	v_mfma_f32_16x16x32_bf16 v[72:75], v[232:235], v[208:211], v[72:75]
	v_mfma_f32_16x16x32_bf16 v[68:71], v[224:227], v[216:219], v[68:71]
	v_mfma_f32_16x16x32_bf16 v[64:67], v[232:235], v[216:219], v[64:67]
	s_mov_b32 m0, s5
	s_barrier
	ds_read_b128 v[172:175], v146 offset:16384
	ds_read_b128 v[176:179], v146 offset:17408
	ds_read_b128 v[180:183], v146 offset:18432
	ds_read_b128 v[196:199], v146 offset:19456
	ds_read_b128 v[200:203], v146 offset:20480
	ds_read_b128 v[208:211], v146 offset:21504
	ds_read_b128 v[212:215], v146 offset:22528
	ds_read_b128 v[216:219], v146 offset:23552
	global_load_lds_dwordx4 v206, s[10:11]
	s_mov_b32 m0, s24
	s_nop 0
	global_load_lds_dwordx4 v207, s[10:11]
	s_barrier
	s_waitcnt lgkmcnt(0)
	s_waitcnt lgkmcnt(0)
	v_mfma_f32_16x16x32_bf16 v[60:63], v[156:159], v[172:175], 0
	v_mfma_f32_16x16x32_bf16 v[56:59], v[164:167], v[172:175], 0
	v_mfma_f32_16x16x32_bf16 v[52:55], v[156:159], v[180:183], 0
	v_mfma_f32_16x16x32_bf16 v[48:51], v[164:167], v[180:183], 0
	v_mfma_f32_16x16x32_bf16 v[44:47], v[156:159], v[200:203], 0
	v_mfma_f32_16x16x32_bf16 v[40:43], v[164:167], v[200:203], 0
	v_mfma_f32_16x16x32_bf16 v[36:39], v[156:159], v[212:215], 0
	v_mfma_f32_16x16x32_bf16 v[32:35], v[164:167], v[212:215], 0
	v_mfma_f32_16x16x32_bf16 v[60:63], v[160:163], v[176:179], v[60:63]
	v_mfma_f32_16x16x32_bf16 v[56:59], v[168:171], v[176:179], v[56:59]
	v_mfma_f32_16x16x32_bf16 v[52:55], v[160:163], v[196:199], v[52:55]
	v_mfma_f32_16x16x32_bf16 v[48:51], v[168:171], v[196:199], v[48:51]
	v_mfma_f32_16x16x32_bf16 v[44:47], v[160:163], v[208:211], v[44:47]
	v_mfma_f32_16x16x32_bf16 v[40:43], v[168:171], v[208:211], v[40:43]
	v_mfma_f32_16x16x32_bf16 v[36:39], v[160:163], v[216:219], v[36:39]
	v_mfma_f32_16x16x32_bf16 v[32:35], v[168:171], v[216:219], v[32:35]
	s_barrier
	s_mov_b32 m0, s27
	s_nop 0
	global_load_lds_dwordx4 v206, s[18:19]
	s_mov_b32 m0, s28
	s_nop 0
	global_load_lds_dwordx4 v207, s[18:19]
	s_waitcnt vmcnt(6)
	s_barrier
; #define WAIT_V(n) asm volatile("s_waitcnt vmcnt(%0)" ::"n"(n) : "memory")
; #define WAIT_L(n) asm volatile("s_waitcnt lgkmcnt(%0)" ::"n"(n) : "memory")
; #define SBAR() __builtin_amdgcn_sched_barrier(0)
; #define STAGE(P, base, kt) do { _Pragma("unroll") for (int _i = 0; _i < 2; ++_i)                                        \
;       __builtin_amdgcn_global_load_lds((const unsigned*)((base) + (size_t)(sOff[_i] + (unsigned)(kt) * (BK * 2))),        \
;                                        (unsigned*)((P) + wid * 1024 + _i * 8192), 16, 0, 0); } while (0)
; #define LDA(dst, b, h) _Pragma("unroll") for (int m = 0; m < 4; ++m) _Pragma("unroll") for (int k = 0; k < 2; ++k) \
;       dst[m][k] = *(const bf16x8*)(SA(b, h) + aoff + (m * 2048 + k * 1024))
; #define LDB(dst, b, h) _Pragma("unroll") for (int n = 0; n < 2; ++n) _Pragma("unroll") for (int k = 0; k < 2; ++k) \
;       dst[n][k] = *(const bf16x8*)(SB(b, h) + boff + (n * 256 + k * 1024))
; #define BAR __builtin_amdgcn_s_barrier()
; template <int EPI, int N, int K>
; __device__ __forceinline__ void phase_gemm(const Params& p, const u16* __restrict__ A, const u16* __restrict__ Bt, int nM, char* shm,
;                            u16* __restrict__ outp, float* __restrict__ rowss) {
;     ...
;       WAIT_V(6); BAR; MMA(1, 1, At, B1); BAR;
;       LDB(B0, 1, 0); SBAR(); LDA(At, 1, 0); STAGE(SA(0, 1), A1, t + 2);
;       WAIT_L(8); BAR; WAIT_L(0); MMA(0, 0, At, B0); BAR; SBAR();
;       LDB(B1, 1, 1); STAGE(SB(1, 0), B0p, t + 3);
;       BAR; WAIT_L(0); MMA(0, 1, At, B1); BAR;
;       LDA(At, 1, 1); STAGE(SA(1, 0), A0, t + 3);
;       BAR; WAIT_L(0); MMA(1, 0, At, B0); BAR; SBAR();
;       STAGE(SB(1, 1), B1p, t + 3);
	v_mfma_f32_16x16x32_bf16 v[28:31], v[220:223], v[172:175], 0
	v_mfma_f32_16x16x32_bf16 v[24:27], v[228:231], v[172:175], 0
	v_mfma_f32_16x16x32_bf16 v[20:23], v[220:223], v[180:183], 0
	v_mfma_f32_16x16x32_bf16 v[16:19], v[228:231], v[180:183], 0
	v_mfma_f32_16x16x32_bf16 v[12:15], v[220:223], v[200:203], 0
	v_mfma_f32_16x16x32_bf16 v[8:11], v[228:231], v[200:203], 0
	v_mfma_f32_16x16x32_bf16 v[4:7], v[220:223], v[212:215], 0
	v_mfma_f32_16x16x32_bf16 v[0:3], v[228:231], v[212:215], 0
	v_mfma_f32_16x16x32_bf16 v[28:31], v[224:227], v[176:179], v[28:31]
	v_mfma_f32_16x16x32_bf16 v[24:27], v[232:235], v[176:179], v[24:27]
	v_mfma_f32_16x16x32_bf16 v[20:23], v[224:227], v[196:199], v[20:23]
	v_mfma_f32_16x16x32_bf16 v[16:19], v[232:235], v[196:199], v[16:19]
	v_mfma_f32_16x16x32_bf16 v[12:15], v[224:227], v[208:211], v[12:15]
	v_mfma_f32_16x16x32_bf16 v[8:11], v[232:235], v[208:211], v[8:11]
	v_mfma_f32_16x16x32_bf16 v[4:7], v[224:227], v[216:219], v[4:7]
	v_mfma_f32_16x16x32_bf16 v[0:3], v[232:235], v[216:219], v[0:3]
	v_or_b32_e32 v156, 0x18000, v145
	v_add_u32_e32 v158, 0x18100, v145
	s_barrier
	v_add_u32_e32 v157, 0x18400, v145
	ds_read_b128 v[164:167], v156
	ds_read_b128 v[168:171], v157
	v_add_u32_e32 v159, 0x18500, v145
	ds_read_b128 v[172:175], v158
	ds_read_b128 v[176:179], v159
	s_mov_b32 m0, s29
	ds_read_b128 v[180:183], v146 offset:32768
	ds_read_b128 v[196:199], v146 offset:33792
	ds_read_b128 v[200:203], v146 offset:34816
	ds_read_b128 v[208:211], v146 offset:35840
	ds_read_b128 v[212:215], v146 offset:36864
	ds_read_b128 v[216:219], v146 offset:37888
	ds_read_b128 v[220:223], v146 offset:38912
	ds_read_b128 v[224:227], v146 offset:39936
	global_load_lds_dwordx4 v206, s[16:17]
	s_mov_b32 m0, s30
	s_nop 0
	global_load_lds_dwordx4 v207, s[16:17]
	s_waitcnt lgkmcnt(8)
	s_barrier
	s_waitcnt lgkmcnt(0)
	s_waitcnt lgkmcnt(0)
	v_mfma_f32_16x16x32_bf16 v[126:129], v[164:167], v[180:183], v[126:129]
	v_mfma_f32_16x16x32_bf16 v[122:125], v[172:175], v[180:183], v[122:125]
	v_mfma_f32_16x16x32_bf16 v[118:121], v[164:167], v[200:203], v[118:121]
	v_mfma_f32_16x16x32_bf16 v[114:117], v[172:175], v[200:203], v[114:117]
	v_mfma_f32_16x16x32_bf16 v[110:113], v[164:167], v[212:215], v[110:113]
	v_mfma_f32_16x16x32_bf16 v[106:109], v[172:175], v[212:215], v[106:109]
	v_mfma_f32_16x16x32_bf16 v[102:105], v[164:167], v[220:223], v[102:105]
	v_mfma_f32_16x16x32_bf16 v[98:101], v[172:175], v[220:223], v[98:101]
	v_mfma_f32_16x16x32_bf16 v[126:129], v[168:171], v[196:199], v[126:129]
	v_mfma_f32_16x16x32_bf16 v[122:125], v[176:179], v[196:199], v[122:125]
	v_mfma_f32_16x16x32_bf16 v[118:121], v[168:171], v[208:211], v[118:121]
	v_mfma_f32_16x16x32_bf16 v[114:117], v[176:179], v[208:211], v[114:117]
	v_mfma_f32_16x16x32_bf16 v[110:113], v[168:171], v[216:219], v[110:113]
	v_mfma_f32_16x16x32_bf16 v[106:109], v[176:179], v[216:219], v[106:109]
	v_mfma_f32_16x16x32_bf16 v[102:105], v[168:171], v[224:227], v[102:105]
	v_mfma_f32_16x16x32_bf16 v[98:101], v[176:179], v[224:227], v[98:101]
	s_barrier
	s_mov_b32 m0, s31
	v_or_b32_e32 v160, 0x1c000, v145
	v_add_u32_e32 v162, 0x1c100, v145
	v_add_u32_e32 v204, 0x180, v204
	v_add_u32_e32 v161, 0x1c400, v145
	ds_read_b128 v[228:231], v160
	ds_read_b128 v[232:235], v161
	v_add_u32_e32 v163, 0x1c500, v145
	ds_read_b128 v[236:239], v162
	ds_read_b128 v[240:243], v163
	global_load_lds_dwordx4 v204, s[8:9]
	v_add_u32_e32 v205, 0x180, v205
	s_mov_b32 m0, s33
	s_nop 0
	global_load_lds_dwordx4 v205, s[8:9]
	s_barrier
	s_waitcnt lgkmcnt(0)
	s_waitcnt lgkmcnt(0)
	v_mfma_f32_16x16x32_bf16 v[92:95], v[228:231], v[180:183], v[92:95]
	v_mfma_f32_16x16x32_bf16 v[88:91], v[236:239], v[180:183], v[88:91]
	v_mfma_f32_16x16x32_bf16 v[84:87], v[228:231], v[200:203], v[84:87]
	v_mfma_f32_16x16x32_bf16 v[80:83], v[236:239], v[200:203], v[80:83]
	v_mfma_f32_16x16x32_bf16 v[76:79], v[228:231], v[212:215], v[76:79]
	v_mfma_f32_16x16x32_bf16 v[72:75], v[236:239], v[212:215], v[72:75]
	v_mfma_f32_16x16x32_bf16 v[68:71], v[228:231], v[220:223], v[68:71]
	v_mfma_f32_16x16x32_bf16 v[64:67], v[236:239], v[220:223], v[64:67]
	v_mfma_f32_16x16x32_bf16 v[92:95], v[232:235], v[196:199], v[92:95]
	v_mfma_f32_16x16x32_bf16 v[88:91], v[240:243], v[196:199], v[88:91]
	v_mfma_f32_16x16x32_bf16 v[84:87], v[232:235], v[208:211], v[84:87]
	v_mfma_f32_16x16x32_bf16 v[80:83], v[240:243], v[208:211], v[80:83]
	v_mfma_f32_16x16x32_bf16 v[76:79], v[232:235], v[216:219], v[76:79]
	v_mfma_f32_16x16x32_bf16 v[72:75], v[240:243], v[216:219], v[72:75]
	v_mfma_f32_16x16x32_bf16 v[68:71], v[232:235], v[224:227], v[68:71]
	v_mfma_f32_16x16x32_bf16 v[64:67], v[240:243], v[224:227], v[64:67]
	s_mov_b32 m0, s35
	s_barrier
	ds_read_b128 v[180:183], v146 offset:49152
	ds_read_b128 v[196:199], v146 offset:50176
	ds_read_b128 v[200:203], v146 offset:51200
	ds_read_b128 v[208:211], v146 offset:52224
	ds_read_b128 v[212:215], v146 offset:53248
	ds_read_b128 v[216:219], v146 offset:54272
	ds_read_b128 v[220:223], v146 offset:55296
	ds_read_b128 v[224:227], v146 offset:56320
	global_load_lds_dwordx4 v204, s[10:11]
	s_mov_b32 m0, s52
	s_nop 0
	global_load_lds_dwordx4 v205, s[10:11]
	s_barrier
; #define WAIT_V(n) asm volatile("s_waitcnt vmcnt(%0)" ::"n"(n) : "memory")
; #define WAIT_L(n) asm volatile("s_waitcnt lgkmcnt(%0)" ::"n"(n) : "memory")
; #define SBAR() __builtin_amdgcn_sched_barrier(0)
; #define STAGE(P, base, kt) do { _Pragma("unroll") for (int _i = 0; _i < 2; ++_i)                                        \
;       __builtin_amdgcn_global_load_lds((const unsigned*)((base) + (size_t)(sOff[_i] + (unsigned)(kt) * (BK * 2))),        \
;                                        (unsigned*)((P) + wid * 1024 + _i * 8192), 16, 0, 0); } while (0)
; #define LDA(dst, b, h) _Pragma("unroll") for (int m = 0; m < 4; ++m) _Pragma("unroll") for (int k = 0; k < 2; ++k) \
;       dst[m][k] = *(const bf16x8*)(SA(b, h) + aoff + (m * 2048 + k * 1024))
; #define LDB(dst, b, h) _Pragma("unroll") for (int n = 0; n < 2; ++n) _Pragma("unroll") for (int k = 0; k < 2; ++k) \
;       dst[n][k] = *(const bf16x8*)(SB(b, h) + boff + (n * 256 + k * 1024))
; #define BAR __builtin_amdgcn_s_barrier()
; template <int EPI, int N, int K>
; __device__ __forceinline__ void phase_gemm(const Params& p, const u16* __restrict__ A, const u16* __restrict__ Bt, int nM, char* shm,
;                            u16* __restrict__ outp, float* __restrict__ rowss) {
;     ...
;       LDB(B0, 0, 0); SBAR(); LDA(At, 0, 0); STAGE(SA(1, 1), A1, t + 1);
;       WAIT_L(8); BAR; WAIT_L(0); MMA(0, 0, At, B0); BAR; SBAR();
;       LDB(B1, 0, 1); STAGE(SB(0, 0), B0p, t + 2);
;       BAR; WAIT_L(0); MMA(0, 1, At, B1); BAR;
;       LDA(At, 0, 1); STAGE(SA(0, 0), A0, t + 2);
;       BAR; WAIT_L(0); MMA(1, 0, At, B0); BAR; SBAR();
;       STAGE(SB(0, 1), B1p, t + 2);
;       WAIT_V(6); BAR; MMA(1, 1, At, B1); BAR;
;       LDB(B0, 1, 0); SBAR(); LDA(At, 1, 0); STAGE(SA(0, 1), A1, t + 2);
;       WAIT_L(8); BAR; WAIT_L(0); MMA(0, 0, At, B0); BAR; SBAR();
;       LDB(B1, 1, 1); STAGE(SB(1, 0), B0p, t + 3);
;       BAR; WAIT_L(0); MMA(0, 1, At, B1); BAR;
;       LDA(At, 1, 1); STAGE(SA(1, 0), A0, t + 3);
;       BAR; WAIT_L(0); MMA(1, 0, At, B0); BAR; SBAR();
;       STAGE(SB(1, 1), B1p, t + 3);
;       WAIT_V(6); BAR; MMA(1, 1, At, B1); BAR;
	s_waitcnt lgkmcnt(0)
	s_waitcnt lgkmcnt(0)
	v_mfma_f32_16x16x32_bf16 v[60:63], v[164:167], v[180:183], v[60:63]
	v_mfma_f32_16x16x32_bf16 v[56:59], v[172:175], v[180:183], v[56:59]
	v_mfma_f32_16x16x32_bf16 v[52:55], v[164:167], v[200:203], v[52:55]
	v_mfma_f32_16x16x32_bf16 v[48:51], v[172:175], v[200:203], v[48:51]
	v_mfma_f32_16x16x32_bf16 v[44:47], v[164:167], v[212:215], v[44:47]
	v_mfma_f32_16x16x32_bf16 v[40:43], v[172:175], v[212:215], v[40:43]
	v_mfma_f32_16x16x32_bf16 v[36:39], v[164:167], v[220:223], v[36:39]
	v_mfma_f32_16x16x32_bf16 v[32:35], v[172:175], v[220:223], v[32:35]
	v_mfma_f32_16x16x32_bf16 v[60:63], v[168:171], v[196:199], v[60:63]
	v_mfma_f32_16x16x32_bf16 v[56:59], v[176:179], v[196:199], v[56:59]
	v_mfma_f32_16x16x32_bf16 v[52:55], v[168:171], v[208:211], v[52:55]
	v_mfma_f32_16x16x32_bf16 v[48:51], v[176:179], v[208:211], v[48:51]
	v_mfma_f32_16x16x32_bf16 v[44:47], v[168:171], v[216:219], v[44:47]
	v_mfma_f32_16x16x32_bf16 v[40:43], v[176:179], v[216:219], v[40:43]
	v_mfma_f32_16x16x32_bf16 v[36:39], v[168:171], v[224:227], v[36:39]
	v_mfma_f32_16x16x32_bf16 v[32:35], v[176:179], v[224:227], v[32:35]
	s_barrier
	s_mov_b32 m0, s53
	s_nop 0
	global_load_lds_dwordx4 v204, s[18:19]
	s_mov_b32 m0, s54
	s_nop 0
	global_load_lds_dwordx4 v205, s[18:19]
	s_waitcnt vmcnt(6)
	s_barrier
	v_mfma_f32_16x16x32_bf16 v[28:31], v[228:231], v[180:183], v[28:31]
	v_mfma_f32_16x16x32_bf16 v[24:27], v[236:239], v[180:183], v[24:27]
	v_mfma_f32_16x16x32_bf16 v[20:23], v[228:231], v[200:203], v[20:23]
	v_mfma_f32_16x16x32_bf16 v[16:19], v[236:239], v[200:203], v[16:19]
	v_mfma_f32_16x16x32_bf16 v[12:15], v[228:231], v[212:215], v[12:15]
	v_mfma_f32_16x16x32_bf16 v[8:11], v[236:239], v[212:215], v[8:11]
	v_mfma_f32_16x16x32_bf16 v[4:7], v[228:231], v[220:223], v[4:7]
	v_mfma_f32_16x16x32_bf16 v[0:3], v[236:239], v[220:223], v[0:3]
	v_mfma_f32_16x16x32_bf16 v[28:31], v[232:235], v[196:199], v[28:31]
	v_mfma_f32_16x16x32_bf16 v[24:27], v[240:243], v[196:199], v[24:27]
	v_mfma_f32_16x16x32_bf16 v[20:23], v[232:235], v[208:211], v[20:23]
	v_mfma_f32_16x16x32_bf16 v[16:19], v[240:243], v[208:211], v[16:19]
	v_mfma_f32_16x16x32_bf16 v[12:15], v[232:235], v[216:219], v[12:15]
	v_mfma_f32_16x16x32_bf16 v[8:11], v[240:243], v[216:219], v[8:11]
	v_mfma_f32_16x16x32_bf16 v[4:7], v[232:235], v[224:227], v[4:7]
	v_mfma_f32_16x16x32_bf16 v[0:3], v[240:243], v[224:227], v[0:3]
	s_add_i32 s22, s22, 2
	v_add_u32_e32 v142, 0x100, v142
	s_cmp_lt_u32 s22, 12
	v_add_u32_e32 v96, 0x100, v96
	s_barrier
.LBB0_433:
	v_or_b32_e32 v143, 0x10000, v145
	v_add_u32_e32 v150, 0x10100, v145
	v_add_u32_e32 v149, 0x10400, v145
	ds_read_b128 v[156:159], v143
	ds_read_b128 v[160:163], v149
	v_add_u32_e32 v151, 0x10500, v145
	ds_read_b128 v[164:167], v150
	ds_read_b128 v[168:171], v151
	v_add_u32_e32 v204, v144, v96
	s_add_i32 s62, s5, 0xc000
	v_add_u32_e32 v152, 0x80, v204
	s_mov_b32 m0, s62
	v_add_u32_e32 v205, v144, v142
	s_add_i32 s23, s5, 0xe000
	ds_read_b128 v[172:175], v146
	ds_read_b128 v[176:179], v146 offset:1024
	ds_read_b128 v[180:183], v146 offset:2048
	ds_read_b128 v[196:199], v146 offset:3072
	ds_read_b128 v[200:203], v146 offset:4096
	ds_read_b128 v[208:211], v146 offset:5120
	ds_read_b128 v[212:215], v146 offset:6144
	ds_read_b128 v[216:219], v146 offset:7168
	global_load_lds_dwordx4 v152, s[16:17]
	v_add_u32_e32 v152, 0x80, v205
	s_mov_b32 m0, s23
	s_nop 0
	global_load_lds_dwordx4 v152, s[16:17]
	s_waitcnt lgkmcnt(8)
	s_barrier
	s_waitcnt lgkmcnt(0)
	s_waitcnt lgkmcnt(0)
	v_mfma_f32_16x16x32_bf16 v[126:129], v[156:159], v[172:175], v[126:129]
	v_mfma_f32_16x16x32_bf16 v[122:125], v[164:167], v[172:175], v[122:125]
	v_mfma_f32_16x16x32_bf16 v[118:121], v[156:159], v[180:183], v[118:121]
	v_mfma_f32_16x16x32_bf16 v[114:117], v[164:167], v[180:183], v[114:117]
	v_mfma_f32_16x16x32_bf16 v[110:113], v[156:159], v[200:203], v[110:113]
	v_mfma_f32_16x16x32_bf16 v[106:109], v[164:167], v[200:203], v[106:109]
	v_mfma_f32_16x16x32_bf16 v[102:105], v[156:159], v[212:215], v[102:105]
	v_mfma_f32_16x16x32_bf16 v[98:101], v[164:167], v[212:215], v[98:101]
	v_mfma_f32_16x16x32_bf16 v[126:129], v[160:163], v[176:179], v[126:129]
	v_mfma_f32_16x16x32_bf16 v[122:125], v[168:171], v[176:179], v[122:125]
	v_mfma_f32_16x16x32_bf16 v[118:121], v[160:163], v[196:199], v[118:121]
	v_mfma_f32_16x16x32_bf16 v[114:117], v[168:171], v[196:199], v[114:117]
	v_mfma_f32_16x16x32_bf16 v[110:113], v[160:163], v[208:211], v[110:113]
	v_mfma_f32_16x16x32_bf16 v[106:109], v[168:171], v[208:211], v[106:109]
	v_mfma_f32_16x16x32_bf16 v[102:105], v[160:163], v[216:219], v[102:105]
	v_mfma_f32_16x16x32_bf16 v[98:101], v[168:171], v[216:219], v[98:101]
	s_barrier
	s_mov_b32 m0, s25
	v_or_b32_e32 v152, 0x14000, v145
	v_add_u32_e32 v154, 0x14100, v145
	v_add_u32_e32 v206, 0x100, v204
	v_add_u32_e32 v153, 0x14400, v145
	ds_read_b128 v[220:223], v152
	ds_read_b128 v[224:227], v153
	v_add_u32_e32 v155, 0x14500, v145
	ds_read_b128 v[228:231], v154
	ds_read_b128 v[232:235], v155
	global_load_lds_dwordx4 v206, s[8:9]
	v_add_u32_e32 v207, 0x100, v205
	s_mov_b32 m0, s26
	s_nop 0
	global_load_lds_dwordx4 v207, s[8:9]
	s_barrier
; #define WAIT_V(n) asm volatile("s_waitcnt vmcnt(%0)" ::"n"(n) : "memory")
; #define WAIT_L(n) asm volatile("s_waitcnt lgkmcnt(%0)" ::"n"(n) : "memory")
; #define SBAR() __builtin_amdgcn_sched_barrier(0)
; #define STAGE(P, base, kt) do { _Pragma("unroll") for (int _i = 0; _i < 2; ++_i)                                        \
;       __builtin_amdgcn_global_load_lds((const unsigned*)((base) + (size_t)(sOff[_i] + (unsigned)(kt) * (BK * 2))),        \
;                                        (unsigned*)((P) + wid * 1024 + _i * 8192), 16, 0, 0); } while (0)
; #define LDA(dst, b, h) _Pragma("unroll") for (int m = 0; m < 4; ++m) _Pragma("unroll") for (int k = 0; k < 2; ++k) \
;       dst[m][k] = *(const bf16x8*)(SA(b, h) + aoff + (m * 2048 + k * 1024))
; #define LDB(dst, b, h) _Pragma("unroll") for (int n = 0; n < 2; ++n) _Pragma("unroll") for (int k = 0; k < 2; ++k) \
;       dst[n][k] = *(const bf16x8*)(SB(b, h) + boff + (n * 256 + k * 1024))
; #define BAR __builtin_amdgcn_s_barrier()
; template <int EPI, int N, int K>
; __device__ __forceinline__ void phase_gemm(const Params& p, const u16* __restrict__ A, const u16* __restrict__ Bt, int nM, char* shm,
;                            u16* __restrict__ outp, float* __restrict__ rowss) {
;     ...
;       LDB(B1, 0, 1); STAGE(SB(0, 0), B0p, t + 2);
;       BAR; WAIT_L(0); MMA(0, 1, At, B1); BAR;
;       LDA(At, 0, 1); STAGE(SA(0, 0), A0, t + 2);
;       BAR; WAIT_L(0); MMA(1, 0, At, B0); BAR; SBAR();
;       STAGE(SB(0, 1), B1p, t + 2);
;       WAIT_V(6); BAR; MMA(1, 1, At, B1); BAR;
;       LDB(B0, 1, 0); SBAR(); LDA(At, 1, 0); STAGE(SA(0, 1), A1, t + 2);
;       WAIT_L(8); BAR; WAIT_L(0); MMA(0, 0, At, B0); BAR; SBAR();
;       LDB(B1, 1, 1); STAGE(SB(1, 0), B0p, t + 3);
;       BAR; WAIT_L(0); MMA(0, 1, At, B1); BAR;
;       LDA(At, 1, 1); STAGE(SA(1, 0), A0, t + 3);
;       BAR; WAIT_L(0); MMA(1, 0, At, B0); BAR; SBAR();
;       STAGE(SB(1, 1), B1p, t + 3);
;       WAIT_V(6); BAR; MMA(1, 1, At, B1); BAR;
	s_waitcnt lgkmcnt(0)
	s_waitcnt lgkmcnt(0)
	v_mfma_f32_16x16x32_bf16 v[92:95], v[220:223], v[172:175], v[92:95]
	v_mfma_f32_16x16x32_bf16 v[88:91], v[228:231], v[172:175], v[88:91]
	v_mfma_f32_16x16x32_bf16 v[84:87], v[220:223], v[180:183], v[84:87]
	v_mfma_f32_16x16x32_bf16 v[80:83], v[228:231], v[180:183], v[80:83]
	v_mfma_f32_16x16x32_bf16 v[76:79], v[220:223], v[200:203], v[76:79]
	v_mfma_f32_16x16x32_bf16 v[72:75], v[228:231], v[200:203], v[72:75]
	v_mfma_f32_16x16x32_bf16 v[68:71], v[220:223], v[212:215], v[68:71]
	v_mfma_f32_16x16x32_bf16 v[64:67], v[228:231], v[212:215], v[64:67]
	v_mfma_f32_16x16x32_bf16 v[92:95], v[224:227], v[176:179], v[92:95]
	v_mfma_f32_16x16x32_bf16 v[88:91], v[232:235], v[176:179], v[88:91]
	v_mfma_f32_16x16x32_bf16 v[84:87], v[224:227], v[196:199], v[84:87]
	v_mfma_f32_16x16x32_bf16 v[80:83], v[232:235], v[196:199], v[80:83]
	v_mfma_f32_16x16x32_bf16 v[76:79], v[224:227], v[208:211], v[76:79]
	v_mfma_f32_16x16x32_bf16 v[72:75], v[232:235], v[208:211], v[72:75]
	v_mfma_f32_16x16x32_bf16 v[68:71], v[224:227], v[216:219], v[68:71]
	v_mfma_f32_16x16x32_bf16 v[64:67], v[232:235], v[216:219], v[64:67]
	s_mov_b32 m0, s5
	s_barrier
	ds_read_b128 v[172:175], v146 offset:16384
	ds_read_b128 v[176:179], v146 offset:17408
	ds_read_b128 v[180:183], v146 offset:18432
	ds_read_b128 v[196:199], v146 offset:19456
	ds_read_b128 v[200:203], v146 offset:20480
	ds_read_b128 v[208:211], v146 offset:21504
	ds_read_b128 v[212:215], v146 offset:22528
	ds_read_b128 v[216:219], v146 offset:23552
	global_load_lds_dwordx4 v206, s[10:11]
	s_mov_b32 m0, s24
	s_nop 0
	global_load_lds_dwordx4 v207, s[10:11]
	s_barrier
	s_waitcnt lgkmcnt(0)
	s_waitcnt lgkmcnt(0)
	v_mfma_f32_16x16x32_bf16 v[60:63], v[156:159], v[172:175], v[60:63]
	v_mfma_f32_16x16x32_bf16 v[56:59], v[164:167], v[172:175], v[56:59]
	v_mfma_f32_16x16x32_bf16 v[52:55], v[156:159], v[180:183], v[52:55]
	v_mfma_f32_16x16x32_bf16 v[48:51], v[164:167], v[180:183], v[48:51]
	v_mfma_f32_16x16x32_bf16 v[44:47], v[156:159], v[200:203], v[44:47]
	v_mfma_f32_16x16x32_bf16 v[40:43], v[164:167], v[200:203], v[40:43]
	v_mfma_f32_16x16x32_bf16 v[36:39], v[156:159], v[212:215], v[36:39]
	v_mfma_f32_16x16x32_bf16 v[32:35], v[164:167], v[212:215], v[32:35]
	v_mfma_f32_16x16x32_bf16 v[60:63], v[160:163], v[176:179], v[60:63]
	v_mfma_f32_16x16x32_bf16 v[56:59], v[168:171], v[176:179], v[56:59]
	v_mfma_f32_16x16x32_bf16 v[52:55], v[160:163], v[196:199], v[52:55]
	v_mfma_f32_16x16x32_bf16 v[48:51], v[168:171], v[196:199], v[48:51]
	v_mfma_f32_16x16x32_bf16 v[44:47], v[160:163], v[208:211], v[44:47]
	v_mfma_f32_16x16x32_bf16 v[40:43], v[168:171], v[208:211], v[40:43]
	v_mfma_f32_16x16x32_bf16 v[36:39], v[160:163], v[216:219], v[36:39]
	v_mfma_f32_16x16x32_bf16 v[32:35], v[168:171], v[216:219], v[32:35]
	s_barrier
	s_mov_b32 m0, s27
	s_nop 0
	global_load_lds_dwordx4 v206, s[18:19]
	s_mov_b32 m0, s28
	s_nop 0
	global_load_lds_dwordx4 v207, s[18:19]
	s_waitcnt vmcnt(6)
	s_barrier
	v_mfma_f32_16x16x32_bf16 v[28:31], v[220:223], v[172:175], v[28:31]
	v_mfma_f32_16x16x32_bf16 v[24:27], v[228:231], v[172:175], v[24:27]
	v_mfma_f32_16x16x32_bf16 v[20:23], v[220:223], v[180:183], v[20:23]
	v_mfma_f32_16x16x32_bf16 v[16:19], v[228:231], v[180:183], v[16:19]
	v_mfma_f32_16x16x32_bf16 v[12:15], v[220:223], v[200:203], v[12:15]
	v_mfma_f32_16x16x32_bf16 v[8:11], v[228:231], v[200:203], v[8:11]
	v_mfma_f32_16x16x32_bf16 v[4:7], v[220:223], v[212:215], v[4:7]
	v_mfma_f32_16x16x32_bf16 v[0:3], v[228:231], v[212:215], v[0:3]
	v_mfma_f32_16x16x32_bf16 v[28:31], v[224:227], v[176:179], v[28:31]
	v_mfma_f32_16x16x32_bf16 v[24:27], v[232:235], v[176:179], v[24:27]
	v_mfma_f32_16x16x32_bf16 v[20:23], v[224:227], v[196:199], v[20:23]
	v_mfma_f32_16x16x32_bf16 v[16:19], v[232:235], v[196:199], v[16:19]
	v_mfma_f32_16x16x32_bf16 v[12:15], v[224:227], v[208:211], v[12:15]
	v_mfma_f32_16x16x32_bf16 v[8:11], v[232:235], v[208:211], v[8:11]
	v_mfma_f32_16x16x32_bf16 v[4:7], v[224:227], v[216:219], v[4:7]
	v_mfma_f32_16x16x32_bf16 v[0:3], v[232:235], v[216:219], v[0:3]
	v_or_b32_e32 v156, 0x18000, v145
	v_add_u32_e32 v158, 0x18100, v145
	s_barrier
	v_add_u32_e32 v157, 0x18400, v145
	ds_read_b128 v[164:167], v156
	ds_read_b128 v[168:171], v157
	v_add_u32_e32 v159, 0x18500, v145
	ds_read_b128 v[172:175], v158
	ds_read_b128 v[176:179], v159
	s_mov_b32 m0, s29
	ds_read_b128 v[180:183], v146 offset:32768
	ds_read_b128 v[196:199], v146 offset:33792
	ds_read_b128 v[200:203], v146 offset:34816
	ds_read_b128 v[208:211], v146 offset:35840
	ds_read_b128 v[212:215], v146 offset:36864
	ds_read_b128 v[216:219], v146 offset:37888
	ds_read_b128 v[220:223], v146 offset:38912
	ds_read_b128 v[224:227], v146 offset:39936
	global_load_lds_dwordx4 v206, s[16:17]
	s_mov_b32 m0, s30
	s_nop 0
	global_load_lds_dwordx4 v207, s[16:17]
	s_waitcnt lgkmcnt(8)
	s_barrier
	s_waitcnt lgkmcnt(0)
	s_waitcnt lgkmcnt(0)
	v_mfma_f32_16x16x32_bf16 v[126:129], v[164:167], v[180:183], v[126:129]
	v_mfma_f32_16x16x32_bf16 v[122:125], v[172:175], v[180:183], v[122:125]
	v_mfma_f32_16x16x32_bf16 v[118:121], v[164:167], v[200:203], v[118:121]
	v_mfma_f32_16x16x32_bf16 v[114:117], v[172:175], v[200:203], v[114:117]
	v_mfma_f32_16x16x32_bf16 v[110:113], v[164:167], v[212:215], v[110:113]
	v_mfma_f32_16x16x32_bf16 v[106:109], v[172:175], v[212:215], v[106:109]
	v_mfma_f32_16x16x32_bf16 v[102:105], v[164:167], v[220:223], v[102:105]
	v_mfma_f32_16x16x32_bf16 v[98:101], v[172:175], v[220:223], v[98:101]
	v_mfma_f32_16x16x32_bf16 v[126:129], v[168:171], v[196:199], v[126:129]
	v_mfma_f32_16x16x32_bf16 v[122:125], v[176:179], v[196:199], v[122:125]
	v_mfma_f32_16x16x32_bf16 v[118:121], v[168:171], v[208:211], v[118:121]
	v_mfma_f32_16x16x32_bf16 v[114:117], v[176:179], v[208:211], v[114:117]
	v_mfma_f32_16x16x32_bf16 v[110:113], v[168:171], v[216:219], v[110:113]
	v_mfma_f32_16x16x32_bf16 v[106:109], v[176:179], v[216:219], v[106:109]
	v_mfma_f32_16x16x32_bf16 v[102:105], v[168:171], v[224:227], v[102:105]
	v_mfma_f32_16x16x32_bf16 v[98:101], v[176:179], v[224:227], v[98:101]
	s_barrier
; #define WAIT_V(n) asm volatile("s_waitcnt vmcnt(%0)" ::"n"(n) : "memory")
; #define WAIT_L(n) asm volatile("s_waitcnt lgkmcnt(%0)" ::"n"(n) : "memory")
; #define SBAR() __builtin_amdgcn_sched_barrier(0)
; #define STAGE(P, base, kt) do { _Pragma("unroll") for (int _i = 0; _i < 2; ++_i)                                        \
;       __builtin_amdgcn_global_load_lds((const unsigned*)((base) + (size_t)(sOff[_i] + (unsigned)(kt) * (BK * 2))),        \
;                                        (unsigned*)((P) + wid * 1024 + _i * 8192), 16, 0, 0); } while (0)
; #define LDA(dst, b, h) _Pragma("unroll") for (int m = 0; m < 4; ++m) _Pragma("unroll") for (int k = 0; k < 2; ++k) \
;       dst[m][k] = *(const bf16x8*)(SA(b, h) + aoff + (m * 2048 + k * 1024))
; #define LDB(dst, b, h) _Pragma("unroll") for (int n = 0; n < 2; ++n) _Pragma("unroll") for (int k = 0; k < 2; ++k) \
;       dst[n][k] = *(const bf16x8*)(SB(b, h) + boff + (n * 256 + k * 1024))
; #define BAR __builtin_amdgcn_s_barrier()
; template <int EPI, int N, int K>
; __device__ __forceinline__ void phase_gemm(const Params& p, const u16* __restrict__ A, const u16* __restrict__ Bt, int nM, char* shm,
;                            u16* __restrict__ outp, float* __restrict__ rowss) {
;     ...
;       LDB(B0, 1, 0); SBAR(); LDA(At, 1, 0); STAGE(SA(0, 1), A1, t + 2);
;       WAIT_L(8); BAR; WAIT_L(0); MMA(0, 0, At, B0); BAR; SBAR();
;       LDB(B1, 1, 1); STAGE(SB(1, 0), B0p, t + 3);
;       BAR; WAIT_L(0); MMA(0, 1, At, B1); BAR;
;       LDA(At, 1, 1); STAGE(SA(1, 0), A0, t + 3);
;       BAR; WAIT_L(0); MMA(1, 0, At, B0); BAR; SBAR();
;       STAGE(SB(1, 1), B1p, t + 3);
;       WAIT_V(6); BAR; MMA(1, 1, At, B1); BAR;
;     }
;     { LDB(B0, 0, 0); LDA(At, 0, 0); STAGE(SA(1, 1), A1, nt - 1);
	s_mov_b32 m0, s31
	v_or_b32_e32 v160, 0x1c000, v145
	v_add_u32_e32 v162, 0x1c100, v145
	v_add_u32_e32 v204, 0x180, v204
	v_add_u32_e32 v161, 0x1c400, v145
	ds_read_b128 v[228:231], v160
	ds_read_b128 v[232:235], v161
	v_add_u32_e32 v163, 0x1c500, v145
	ds_read_b128 v[236:239], v162
	ds_read_b128 v[240:243], v163
	global_load_lds_dwordx4 v204, s[8:9]
	v_add_u32_e32 v205, 0x180, v205
	s_mov_b32 m0, s33
	s_nop 0
	global_load_lds_dwordx4 v205, s[8:9]
	s_barrier
	s_waitcnt lgkmcnt(0)
	s_waitcnt lgkmcnt(0)
	v_mfma_f32_16x16x32_bf16 v[92:95], v[228:231], v[180:183], v[92:95]
	v_mfma_f32_16x16x32_bf16 v[88:91], v[236:239], v[180:183], v[88:91]
	v_mfma_f32_16x16x32_bf16 v[84:87], v[228:231], v[200:203], v[84:87]
	v_mfma_f32_16x16x32_bf16 v[80:83], v[236:239], v[200:203], v[80:83]
	v_mfma_f32_16x16x32_bf16 v[76:79], v[228:231], v[212:215], v[76:79]
	v_mfma_f32_16x16x32_bf16 v[72:75], v[236:239], v[212:215], v[72:75]
	v_mfma_f32_16x16x32_bf16 v[68:71], v[228:231], v[220:223], v[68:71]
	v_mfma_f32_16x16x32_bf16 v[64:67], v[236:239], v[220:223], v[64:67]
	v_mfma_f32_16x16x32_bf16 v[92:95], v[232:235], v[196:199], v[92:95]
	v_mfma_f32_16x16x32_bf16 v[88:91], v[240:243], v[196:199], v[88:91]
	v_mfma_f32_16x16x32_bf16 v[84:87], v[232:235], v[208:211], v[84:87]
	v_mfma_f32_16x16x32_bf16 v[80:83], v[240:243], v[208:211], v[80:83]
	v_mfma_f32_16x16x32_bf16 v[76:79], v[232:235], v[216:219], v[76:79]
	v_mfma_f32_16x16x32_bf16 v[72:75], v[240:243], v[216:219], v[72:75]
	v_mfma_f32_16x16x32_bf16 v[68:71], v[232:235], v[224:227], v[68:71]
	v_mfma_f32_16x16x32_bf16 v[64:67], v[240:243], v[224:227], v[64:67]
	s_mov_b32 m0, s35
	s_barrier
	ds_read_b128 v[180:183], v146 offset:49152
	ds_read_b128 v[196:199], v146 offset:50176
	ds_read_b128 v[200:203], v146 offset:51200
	ds_read_b128 v[208:211], v146 offset:52224
	ds_read_b128 v[212:215], v146 offset:53248
	ds_read_b128 v[216:219], v146 offset:54272
	ds_read_b128 v[220:223], v146 offset:55296
	ds_read_b128 v[224:227], v146 offset:56320
	global_load_lds_dwordx4 v204, s[10:11]
	s_mov_b32 m0, s52
	s_nop 0
	global_load_lds_dwordx4 v205, s[10:11]
	s_barrier
	s_waitcnt lgkmcnt(0)
	s_waitcnt lgkmcnt(0)
	v_mfma_f32_16x16x32_bf16 v[60:63], v[164:167], v[180:183], v[60:63]
	v_mfma_f32_16x16x32_bf16 v[56:59], v[172:175], v[180:183], v[56:59]
	v_mfma_f32_16x16x32_bf16 v[52:55], v[164:167], v[200:203], v[52:55]
	v_mfma_f32_16x16x32_bf16 v[48:51], v[172:175], v[200:203], v[48:51]
	v_mfma_f32_16x16x32_bf16 v[44:47], v[164:167], v[212:215], v[44:47]
	v_mfma_f32_16x16x32_bf16 v[40:43], v[172:175], v[212:215], v[40:43]
	v_mfma_f32_16x16x32_bf16 v[36:39], v[164:167], v[220:223], v[36:39]
	v_mfma_f32_16x16x32_bf16 v[32:35], v[172:175], v[220:223], v[32:35]
	v_mfma_f32_16x16x32_bf16 v[60:63], v[168:171], v[196:199], v[60:63]
	v_mfma_f32_16x16x32_bf16 v[56:59], v[176:179], v[196:199], v[56:59]
	v_mfma_f32_16x16x32_bf16 v[52:55], v[168:171], v[208:211], v[52:55]
	v_mfma_f32_16x16x32_bf16 v[48:51], v[176:179], v[208:211], v[48:51]
	v_mfma_f32_16x16x32_bf16 v[44:47], v[168:171], v[216:219], v[44:47]
	v_mfma_f32_16x16x32_bf16 v[40:43], v[176:179], v[216:219], v[40:43]
	v_mfma_f32_16x16x32_bf16 v[36:39], v[168:171], v[224:227], v[36:39]
	v_mfma_f32_16x16x32_bf16 v[32:35], v[176:179], v[224:227], v[32:35]
	s_barrier
	s_mov_b32 m0, s53
	s_nop 0
	global_load_lds_dwordx4 v204, s[18:19]
	s_mov_b32 m0, s54
	s_nop 0
	global_load_lds_dwordx4 v205, s[18:19]
	s_waitcnt vmcnt(6)
	s_barrier
	v_mfma_f32_16x16x32_bf16 v[28:31], v[228:231], v[180:183], v[28:31]
	v_mfma_f32_16x16x32_bf16 v[24:27], v[236:239], v[180:183], v[24:27]
	v_mfma_f32_16x16x32_bf16 v[20:23], v[228:231], v[200:203], v[20:23]
	v_mfma_f32_16x16x32_bf16 v[16:19], v[236:239], v[200:203], v[16:19]
	v_mfma_f32_16x16x32_bf16 v[12:15], v[228:231], v[212:215], v[12:15]
	v_mfma_f32_16x16x32_bf16 v[8:11], v[236:239], v[212:215], v[8:11]
	v_mfma_f32_16x16x32_bf16 v[4:7], v[228:231], v[220:223], v[4:7]
	v_mfma_f32_16x16x32_bf16 v[0:3], v[236:239], v[220:223], v[0:3]
	v_mfma_f32_16x16x32_bf16 v[28:31], v[232:235], v[196:199], v[28:31]
	v_mfma_f32_16x16x32_bf16 v[24:27], v[240:243], v[196:199], v[24:27]
	v_mfma_f32_16x16x32_bf16 v[20:23], v[232:235], v[208:211], v[20:23]
	v_mfma_f32_16x16x32_bf16 v[16:19], v[240:243], v[208:211], v[16:19]
	v_mfma_f32_16x16x32_bf16 v[12:15], v[232:235], v[216:219], v[12:15]
	v_mfma_f32_16x16x32_bf16 v[8:11], v[240:243], v[216:219], v[8:11]
	v_mfma_f32_16x16x32_bf16 v[4:7], v[232:235], v[224:227], v[4:7]
	v_mfma_f32_16x16x32_bf16 v[0:3], v[240:243], v[224:227], v[0:3]
	s_add_i32 s22, s22, 2
	v_add_u32_e32 v142, 0x100, v142
	s_cmp_lt_u32 s22, 12
	v_add_u32_e32 v96, 0x100, v96
	s_barrier
	s_cbranch_scc1 .LBB0_433
	s_mov_b32 m0, s62
	ds_read_b128 v[164:167], v143
	ds_read_b128 v[168:171], v149
	ds_read_b128 v[172:175], v150
	ds_read_b128 v[176:179], v151
	ds_read_b128 v[180:183], v146
	ds_read_b128 v[196:199], v146 offset:1024
	ds_read_b128 v[200:203], v146 offset:2048
	ds_read_b128 v[208:211], v146 offset:3072
	ds_read_b128 v[212:215], v146 offset:4096
	ds_read_b128 v[216:219], v146 offset:5120
	ds_read_b128 v[220:223], v146 offset:6144
	ds_read_b128 v[224:227], v146 offset:7168
	v_lshl_add_u64 v[142:143], s[16:17], 0, v[138:139]
	global_load_lds_dwordx4 v[142:143], off
	v_lshl_add_u64 v[142:143], s[16:17], 0, v[140:141]
	s_mov_b32 m0, s23
	s_nop 0
	global_load_lds_dwordx4 v[142:143], off
	s_barrier
; #define WAIT_V(n) asm volatile("s_waitcnt vmcnt(%0)" ::"n"(n) : "memory")
; #define WAIT_L(n) asm volatile("s_waitcnt lgkmcnt(%0)" ::"n"(n) : "memory")
; #define STAGE(P, base, kt) do { _Pragma("unroll") for (int _i = 0; _i < 2; ++_i)                                        \
;       __builtin_amdgcn_global_load_lds((const unsigned*)((base) + (size_t)(sOff[_i] + (unsigned)(kt) * (BK * 2))),        \
;                                        (unsigned*)((P) + wid * 1024 + _i * 8192), 16, 0, 0); } while (0)
; #define LDA(dst, b, h) _Pragma("unroll") for (int m = 0; m < 4; ++m) _Pragma("unroll") for (int k = 0; k < 2; ++k) \
;       dst[m][k] = *(const bf16x8*)(SA(b, h) + aoff + (m * 2048 + k * 1024))
; #define LDB(dst, b, h) _Pragma("unroll") for (int n = 0; n < 2; ++n) _Pragma("unroll") for (int k = 0; k < 2; ++k) \
;       dst[n][k] = *(const bf16x8*)(SB(b, h) + boff + (n * 256 + k * 1024))
; #define BAR __builtin_amdgcn_s_barrier()
; template <int EPI, int N, int K>
; __device__ __forceinline__ void phase_gemm(const Params& p, const u16* __restrict__ A, const u16* __restrict__ Bt, int nM, char* shm,
;                            u16* __restrict__ outp, float* __restrict__ rowss) {
;     ...
;     { LDB(B0, 0, 0); LDA(At, 0, 0); STAGE(SA(1, 1), A1, nt - 1);
;       BAR; WAIT_L(0); MMA(0, 0, At, B0); BAR;
;       LDB(B1, 0, 1); BAR; WAIT_L(0); MMA(0, 1, At, B1); BAR;
;       LDA(At, 0, 1); WAIT_V(4); BAR; WAIT_L(0); MMA(1, 0, At, B0); MMA(1, 1, At, B1); BAR; }
;     { LDB(B0, 1, 0); LDA(At, 1, 0); WAIT_V(2); BAR; WAIT_L(0); MMA(0, 0, At, B0); BAR;
	s_waitcnt lgkmcnt(0)
	s_waitcnt lgkmcnt(0)
	v_mfma_f32_16x16x32_bf16 v[126:129], v[164:167], v[180:183], v[126:129]
	v_mfma_f32_16x16x32_bf16 v[122:125], v[172:175], v[180:183], v[122:125]
	v_mfma_f32_16x16x32_bf16 v[110:113], v[164:167], v[212:215], v[110:113]
	v_mfma_f32_16x16x32_bf16 v[106:109], v[172:175], v[212:215], v[106:109]
	v_mfma_f32_16x16x32_bf16 v[126:129], v[168:171], v[196:199], v[126:129]
	v_mfma_f32_16x16x32_bf16 v[122:125], v[176:179], v[196:199], v[122:125]
	v_mfma_f32_16x16x32_bf16 v[118:121], v[164:167], v[200:203], v[118:121]
	v_mfma_f32_16x16x32_bf16 v[114:117], v[172:175], v[200:203], v[114:117]
	v_mfma_f32_16x16x32_bf16 v[110:113], v[168:171], v[216:219], v[110:113]
	v_mfma_f32_16x16x32_bf16 v[106:109], v[176:179], v[216:219], v[106:109]
	v_mfma_f32_16x16x32_bf16 v[102:105], v[164:167], v[220:223], v[102:105]
	v_mfma_f32_16x16x32_bf16 v[98:101], v[172:175], v[220:223], v[98:101]
	v_mfma_f32_16x16x32_bf16 v[228:231], v[168:171], v[208:211], v[118:121]
	v_mfma_f32_16x16x32_bf16 v[232:235], v[176:179], v[208:211], v[114:117]
	v_mfma_f32_16x16x32_bf16 v[236:239], v[168:171], v[224:227], v[102:105]
	v_mfma_f32_16x16x32_bf16 v[240:243], v[176:179], v[224:227], v[98:101]
	s_barrier
	s_nop 1
	ds_read_b128 v[98:101], v152
	ds_read_b128 v[102:105], v153
	ds_read_b128 v[114:117], v154
	ds_read_b128 v[118:121], v155
	s_barrier
	s_waitcnt lgkmcnt(0)
	s_waitcnt lgkmcnt(0)
	v_mfma_f32_16x16x32_bf16 v[92:95], v[98:101], v[180:183], v[92:95]
	v_mfma_f32_16x16x32_bf16 v[88:91], v[114:117], v[180:183], v[88:91]
	v_mfma_f32_16x16x32_bf16 v[76:79], v[98:101], v[212:215], v[76:79]
	v_mfma_f32_16x16x32_bf16 v[72:75], v[114:117], v[212:215], v[72:75]
	v_mfma_f32_16x16x32_bf16 v[68:71], v[98:101], v[220:223], v[68:71]
	v_mfma_f32_16x16x32_bf16 v[64:67], v[114:117], v[220:223], v[64:67]
	v_mfma_f32_16x16x32_bf16 v[92:95], v[102:105], v[196:199], v[92:95]
	v_mfma_f32_16x16x32_bf16 v[88:91], v[118:121], v[196:199], v[88:91]
	v_mfma_f32_16x16x32_bf16 v[84:87], v[98:101], v[200:203], v[84:87]
	v_mfma_f32_16x16x32_bf16 v[80:83], v[114:117], v[200:203], v[80:83]
	v_mfma_f32_16x16x32_bf16 v[76:79], v[102:105], v[216:219], v[76:79]
	v_mfma_f32_16x16x32_bf16 v[72:75], v[118:121], v[216:219], v[72:75]
	v_mfma_f32_16x16x32_bf16 v[68:71], v[102:105], v[224:227], v[68:71]
	v_mfma_f32_16x16x32_bf16 v[64:67], v[118:121], v[224:227], v[64:67]
	v_mfma_f32_16x16x32_bf16 v[150:153], v[102:105], v[208:211], v[84:87]
	v_mfma_f32_16x16x32_bf16 v[180:183], v[118:121], v[208:211], v[80:83]
	s_barrier
	s_nop 0
	ds_read_b128 v[80:83], v146 offset:16384
	ds_read_b128 v[84:87], v146 offset:17408
	ds_read_b128 v[196:199], v146 offset:18432
	ds_read_b128 v[200:203], v146 offset:19456
	ds_read_b128 v[208:211], v146 offset:20480
	ds_read_b128 v[212:215], v146 offset:21504
	ds_read_b128 v[216:219], v146 offset:22528
	ds_read_b128 v[220:223], v146 offset:23552
	s_waitcnt vmcnt(4)
	s_barrier
	s_waitcnt lgkmcnt(0)
	s_waitcnt lgkmcnt(0)
	v_mfma_f32_16x16x32_bf16 v[56:59], v[172:175], v[80:83], v[56:59]
	v_mfma_f32_16x16x32_bf16 v[52:55], v[164:167], v[196:199], v[52:55]
	v_mfma_f32_16x16x32_bf16 v[40:43], v[172:175], v[208:211], v[40:43]
	v_mfma_f32_16x16x32_bf16 v[32:35], v[172:175], v[216:219], v[32:35]
	v_mfma_f32_16x16x32_bf16 v[60:63], v[164:167], v[80:83], v[60:63]
	v_mfma_f32_16x16x32_bf16 v[56:59], v[176:179], v[84:87], v[56:59]
	v_mfma_f32_16x16x32_bf16 v[52:55], v[168:171], v[200:203], v[52:55]
	v_mfma_f32_16x16x32_bf16 v[48:51], v[172:175], v[196:199], v[48:51]
	v_mfma_f32_16x16x32_bf16 v[44:47], v[164:167], v[208:211], v[44:47]
	v_mfma_f32_16x16x32_bf16 v[40:43], v[176:179], v[212:215], v[40:43]
	v_mfma_f32_16x16x32_bf16 v[36:39], v[164:167], v[216:219], v[36:39]
	v_mfma_f32_16x16x32_bf16 v[32:35], v[176:179], v[220:223], v[32:35]
	v_mfma_f32_16x16x32_bf16 v[224:227], v[168:171], v[84:87], v[60:63]
	v_mfma_f32_16x16x32_bf16 v[244:247], v[176:179], v[200:203], v[48:51]
	v_mfma_f32_16x16x32_bf16 v[248:251], v[168:171], v[212:215], v[44:47]
	v_mfma_f32_16x16x32_bf16 v[164:167], v[168:171], v[220:223], v[36:39]
	v_mfma_f32_16x16x32_bf16 v[24:27], v[114:117], v[80:83], v[24:27]
	v_mfma_f32_16x16x32_bf16 v[16:19], v[114:117], v[196:199], v[16:19]
	v_mfma_f32_16x16x32_bf16 v[8:11], v[114:117], v[208:211], v[8:11]
	v_mfma_f32_16x16x32_bf16 v[0:3], v[114:117], v[216:219], v[0:3]
	v_mfma_f32_16x16x32_bf16 v[28:31], v[98:101], v[80:83], v[28:31]
	v_mfma_f32_16x16x32_bf16 v[24:27], v[118:121], v[84:87], v[24:27]
	v_mfma_f32_16x16x32_bf16 v[20:23], v[98:101], v[196:199], v[20:23]
	v_mfma_f32_16x16x32_bf16 v[16:19], v[118:121], v[200:203], v[16:19]
	v_mfma_f32_16x16x32_bf16 v[12:15], v[98:101], v[208:211], v[12:15]
	v_mfma_f32_16x16x32_bf16 v[8:11], v[118:121], v[212:215], v[8:11]
	v_mfma_f32_16x16x32_bf16 v[4:7], v[98:101], v[216:219], v[4:7]
	v_mfma_f32_16x16x32_bf16 v[0:3], v[118:121], v[220:223], v[0:3]
	v_mfma_f32_16x16x32_bf16 v[168:171], v[102:105], v[84:87], v[28:31]
	v_mfma_f32_16x16x32_bf16 v[172:175], v[102:105], v[200:203], v[20:23]
	v_mfma_f32_16x16x32_bf16 v[176:179], v[102:105], v[212:215], v[12:15]
	v_mfma_f32_16x16x32_bf16 v[196:199], v[102:105], v[220:223], v[4:7]
	s_barrier
; #define WAIT_V(n) asm volatile("s_waitcnt vmcnt(%0)" ::"n"(n) : "memory")
; #define WAIT_L(n) asm volatile("s_waitcnt lgkmcnt(%0)" ::"n"(n) : "memory")
; #define LDA(dst, b, h) _Pragma("unroll") for (int m = 0; m < 4; ++m) _Pragma("unroll") for (int k = 0; k < 2; ++k) \
;       dst[m][k] = *(const bf16x8*)(SA(b, h) + aoff + (m * 2048 + k * 1024))
; #define LDB(dst, b, h) _Pragma("unroll") for (int n = 0; n < 2; ++n) _Pragma("unroll") for (int k = 0; k < 2; ++k) \
;       dst[n][k] = *(const bf16x8*)(SB(b, h) + boff + (n * 256 + k * 1024))
; #define BAR __builtin_amdgcn_s_barrier()
; template <int EPI, int N, int K>
; __device__ __forceinline__ void phase_gemm(const Params& p, const u16* __restrict__ A, const u16* __restrict__ Bt, int nM, char* shm,
;                            u16* __restrict__ outp, float* __restrict__ rowss) {
;     ...
;     { LDB(B0, 1, 0); LDA(At, 1, 0); WAIT_V(2); BAR; WAIT_L(0); MMA(0, 0, At, B0); BAR;
;       LDB(B1, 1, 1); WAIT_V(0); BAR; WAIT_L(0); MMA(0, 1, At, B1); BAR;
;       LDA(At, 1, 1); BAR; WAIT_L(0); MMA(1, 0, At, B0); MMA(1, 1, At, B1); BAR; }
;     if (wr == 0) BAR;
	s_nop 0
	ds_read_b128 v[4:7], v156
	ds_read_b128 v[12:15], v157
	ds_read_b128 v[154:157], v158
	ds_read_b128 v[200:203], v159
	ds_read_b128 v[20:23], v146 offset:32768
	ds_read_b128 v[28:31], v146 offset:33792
	ds_read_b128 v[36:39], v146 offset:34816
	ds_read_b128 v[44:47], v146 offset:35840
	ds_read_b128 v[208:211], v146 offset:36864
	ds_read_b128 v[212:215], v146 offset:37888
	ds_read_b128 v[216:219], v146 offset:38912
	ds_read_b128 v[220:223], v146 offset:39936
	s_waitcnt vmcnt(2)
	s_barrier
	s_waitcnt lgkmcnt(0)
	s_waitcnt lgkmcnt(0)
	v_mfma_f32_16x16x32_bf16 v[48:51], v[4:7], v[20:23], v[126:129]
	v_mfma_f32_16x16x32_bf16 v[118:121], v[12:15], v[28:31], v[48:51]
	v_mfma_f32_16x16x32_bf16 v[48:51], v[154:157], v[20:23], v[122:125]
	v_mfma_f32_16x16x32_bf16 v[114:117], v[200:203], v[28:31], v[48:51]
	v_mfma_f32_16x16x32_bf16 v[48:51], v[4:7], v[36:39], v[228:231]
	v_mfma_f32_16x16x32_bf16 v[102:105], v[12:15], v[44:47], v[48:51]
	v_mfma_f32_16x16x32_bf16 v[48:51], v[154:157], v[36:39], v[232:235]
	v_mfma_f32_16x16x32_bf16 v[98:101], v[200:203], v[44:47], v[48:51]
	v_mfma_f32_16x16x32_bf16 v[48:51], v[4:7], v[208:211], v[110:113]
	v_mfma_f32_16x16x32_bf16 v[84:87], v[12:15], v[212:215], v[48:51]
	v_mfma_f32_16x16x32_bf16 v[48:51], v[154:157], v[208:211], v[106:109]
	v_mfma_f32_16x16x32_bf16 v[80:83], v[200:203], v[212:215], v[48:51]
	v_mfma_f32_16x16x32_bf16 v[48:51], v[4:7], v[216:219], v[236:239]
	v_mfma_f32_16x16x32_bf16 v[60:63], v[12:15], v[220:223], v[48:51]
	v_mfma_f32_16x16x32_bf16 v[48:51], v[154:157], v[216:219], v[240:243]
	v_mfma_f32_16x16x32_bf16 v[48:51], v[200:203], v[220:223], v[48:51]
	s_barrier
	ds_read_b128 v[228:231], v160
	ds_read_b128 v[158:161], v161
	ds_read_b128 v[232:235], v162
	ds_read_b128 v[236:239], v163
	s_waitcnt vmcnt(0)
	s_barrier
	s_waitcnt lgkmcnt(0)
	s_waitcnt lgkmcnt(0)
	v_mfma_f32_16x16x32_bf16 v[92:95], v[228:231], v[20:23], v[92:95]
	v_mfma_f32_16x16x32_bf16 v[20:23], v[232:235], v[20:23], v[88:91]
	v_mfma_f32_16x16x32_bf16 v[122:125], v[236:239], v[28:31], v[20:23]
	v_mfma_f32_16x16x32_bf16 v[20:23], v[228:231], v[36:39], v[150:153]
	v_mfma_f32_16x16x32_bf16 v[110:113], v[158:161], v[44:47], v[20:23]
	v_mfma_f32_16x16x32_bf16 v[20:23], v[232:235], v[36:39], v[180:183]
	v_mfma_f32_16x16x32_bf16 v[106:109], v[236:239], v[44:47], v[20:23]
	v_mfma_f32_16x16x32_bf16 v[20:23], v[228:231], v[208:211], v[76:79]
	v_mfma_f32_16x16x32_bf16 v[126:129], v[158:161], v[28:31], v[92:95]
	v_mfma_f32_16x16x32_bf16 v[92:95], v[158:161], v[212:215], v[20:23]
	v_mfma_f32_16x16x32_bf16 v[20:23], v[232:235], v[208:211], v[72:75]
	v_mfma_f32_16x16x32_bf16 v[88:91], v[236:239], v[212:215], v[20:23]
	v_mfma_f32_16x16x32_bf16 v[20:23], v[228:231], v[216:219], v[68:71]
	v_mfma_f32_16x16x32_bf16 v[76:79], v[158:161], v[220:223], v[20:23]
	v_mfma_f32_16x16x32_bf16 v[20:23], v[232:235], v[216:219], v[64:67]
	v_mfma_f32_16x16x32_bf16 v[64:67], v[236:239], v[220:223], v[20:23]
	s_barrier
	ds_read_b128 v[150:153], v146 offset:49152
	ds_read_b128 v[180:183], v146 offset:50176
	ds_read_b128 v[208:211], v146 offset:51200
	ds_read_b128 v[212:215], v146 offset:52224
	ds_read_b128 v[216:219], v146 offset:53248
	ds_read_b128 v[220:223], v146 offset:54272
	ds_read_b128 v[240:243], v146 offset:55296
	ds_read_b128 v[204:207], v146 offset:56320
	s_barrier
	s_waitcnt lgkmcnt(0)
	s_waitcnt lgkmcnt(0)
	v_mfma_f32_16x16x32_bf16 v[20:23], v[4:7], v[150:153], v[224:227]
	v_mfma_f32_16x16x32_bf16 v[72:75], v[12:15], v[180:183], v[20:23]
	v_mfma_f32_16x16x32_bf16 v[20:23], v[154:157], v[150:153], v[56:59]
	v_mfma_f32_16x16x32_bf16 v[56:59], v[200:203], v[180:183], v[20:23]
	v_mfma_f32_16x16x32_bf16 v[20:23], v[4:7], v[208:211], v[52:55]
	v_mfma_f32_16x16x32_bf16 v[44:47], v[12:15], v[212:215], v[20:23]
	v_mfma_f32_16x16x32_bf16 v[20:23], v[154:157], v[208:211], v[244:247]
	v_mfma_f32_16x16x32_bf16 v[36:39], v[200:203], v[212:215], v[20:23]
	v_mfma_f32_16x16x32_bf16 v[20:23], v[4:7], v[216:219], v[248:251]
	v_mfma_f32_16x16x32_bf16 v[4:7], v[4:7], v[240:243], v[164:167]
	v_mfma_f32_16x16x32_bf16 v[28:31], v[12:15], v[220:223], v[20:23]
	v_mfma_f32_16x16x32_bf16 v[20:23], v[154:157], v[216:219], v[40:43]
	v_mfma_f32_16x16x32_bf16 v[12:15], v[12:15], v[204:207], v[4:7]
	v_mfma_f32_16x16x32_bf16 v[4:7], v[154:157], v[240:243], v[32:35]
	v_mfma_f32_16x16x32_bf16 v[20:23], v[200:203], v[220:223], v[20:23]
	v_mfma_f32_16x16x32_bf16 v[4:7], v[200:203], v[204:207], v[4:7]
	v_mfma_f32_16x16x32_bf16 v[32:35], v[228:231], v[150:153], v[168:171]
	v_mfma_f32_16x16x32_bf16 v[24:27], v[232:235], v[150:153], v[24:27]
	v_mfma_f32_16x16x32_bf16 v[16:19], v[232:235], v[208:211], v[16:19]
	v_mfma_f32_16x16x32_bf16 v[68:71], v[158:161], v[180:183], v[32:35]
	v_mfma_f32_16x16x32_bf16 v[52:55], v[236:239], v[180:183], v[24:27]
	v_mfma_f32_16x16x32_bf16 v[24:27], v[228:231], v[208:211], v[172:175]
	v_mfma_f32_16x16x32_bf16 v[32:35], v[236:239], v[212:215], v[16:19]
	v_mfma_f32_16x16x32_bf16 v[16:19], v[228:231], v[216:219], v[176:179]
	v_mfma_f32_16x16x32_bf16 v[8:11], v[232:235], v[216:219], v[8:11]
	v_mfma_f32_16x16x32_bf16 v[40:43], v[158:161], v[212:215], v[24:27]
	v_mfma_f32_16x16x32_bf16 v[24:27], v[158:161], v[220:223], v[16:19]
	v_mfma_f32_16x16x32_bf16 v[16:19], v[236:239], v[220:223], v[8:11]
	v_mfma_f32_16x16x32_bf16 v[8:11], v[228:231], v[240:243], v[196:199]
	v_mfma_f32_16x16x32_bf16 v[0:3], v[232:235], v[240:243], v[0:3]
	v_mfma_f32_16x16x32_bf16 v[8:11], v[158:161], v[204:207], v[8:11]
	v_mfma_f32_16x16x32_bf16 v[0:3], v[236:239], v[204:207], v[0:3]
	s_andn2_b64 vcc, exec, s[56:57]
	s_barrier
	s_cbranch_vccnz .LBB0_436
	s_barrier

; #define WAIT_V(n) asm volatile("s_waitcnt vmcnt(%0)" ::"n"(n) : "memory")
; #define WAIT_L(n) asm volatile("s_waitcnt lgkmcnt(%0)" ::"n"(n) : "memory")
; #define SBAR() __builtin_amdgcn_sched_barrier(0)
; #define STAGE(P, base, kt) do { _Pragma("unroll") for (int _i = 0; _i < 2; ++_i)                                        \
;       __builtin_amdgcn_global_load_lds((const unsigned*)((base) + (size_t)(sOff[_i] + (unsigned)(kt) * (BK * 2))),        \
;                                        (unsigned*)((P) + wid * 1024 + _i * 8192), 16, 0, 0); } while (0)
; #define LDA(dst, b, h) _Pragma("unroll") for (int m = 0; m < 4; ++m) _Pragma("unroll") for (int k = 0; k < 2; ++k) \
;       dst[m][k] = *(const bf16x8*)(SA(b, h) + aoff + (m * 2048 + k * 1024))
; #define LDB(dst, b, h) _Pragma("unroll") for (int n = 0; n < 2; ++n) _Pragma("unroll") for (int k = 0; k < 2; ++k) \
;       dst[n][k] = *(const bf16x8*)(SB(b, h) + boff + (n * 256 + k * 1024))
; #define BAR __builtin_amdgcn_s_barrier()
; template <int EPI, int N, int K>
; __device__ __forceinline__ void phase_gemm(const Params& p, const u16* __restrict__ A, const u16* __restrict__ Bt, int nM, char* shm,
;                            u16* __restrict__ outp, float* __restrict__ rowss) {
;     ...
;     const char* A1 = A0 + (size_t)128 * K * 2;
;     const char* B1p = B0p + (size_t)128 * K * 2;
;     f32x4 acc[2][2][4][2] = {};
;     bf16x8 At[4][2], B0[2][2], B1[2][2];
;     if (wr == 1) BAR;
;     WAIT_V(0); BAR;
;     BAR;
;     for (int t = 0; t < nt - 2; t += 2) {
;       LDB(B0, 0, 0); SBAR(); LDA(At, 0, 0); STAGE(SA(1, 1), A1, t + 1);
;       WAIT_L(8); BAR; WAIT_L(0); MMA(0, 0, At, B0); BAR; SBAR();
;       LDB(B1, 0, 1); STAGE(SB(0, 0), B0p, t + 2);
;       BAR; WAIT_L(0); MMA(0, 1, At, B1); BAR;
;       LDA(At, 0, 1); STAGE(SA(0, 0), A0, t + 2);
;       BAR; WAIT_L(0); MMA(1, 0, At, B0); BAR; SBAR();
;       STAGE(SB(0, 1), B1p, t + 2);
;       WAIT_V(6); BAR; MMA(1, 1, At, B1); BAR;
.LBB0_516:
	s_add_u32 s4, s12, 0xb0000
	s_addc_u32 s5, s13, 0
	s_waitcnt vmcnt(0)
	s_add_u32 s18, s10, 0xb0000
	s_addc_u32 s19, s11, 0
	s_mov_b32 s58, -2
	v_mov_b32_e32 v96, v150
	v_mov_b32_e32 v142, v149
	s_waitcnt lgkmcnt(0)
	s_barrier
	s_barrier
	v_or_b32_e32 v143, 0x10000, v146
	v_add_u32_e32 v145, 0x10100, v146
	v_add_u32_e32 v144, 0x10400, v146
	ds_read_b128 v[156:159], v143
	ds_read_b128 v[160:163], v144
	v_add_u32_e32 v151, 0x10500, v146
	ds_read_b128 v[164:167], v145
	ds_read_b128 v[168:171], v151
	v_add_u32_e32 v204, v148, v96
	s_add_i32 s60, s25, 0xc000
	v_add_u32_e32 v152, 0x80, v204
	s_mov_b32 m0, s60
	v_add_u32_e32 v205, v148, v142
	s_add_i32 s59, s25, 0xe000
	ds_read_b128 v[172:175], v147
	ds_read_b128 v[176:179], v147 offset:1024
	ds_read_b128 v[180:183], v147 offset:2048
	ds_read_b128 v[196:199], v147 offset:3072
	ds_read_b128 v[200:203], v147 offset:4096
	ds_read_b128 v[208:211], v147 offset:5120
	ds_read_b128 v[212:215], v147 offset:6144
	ds_read_b128 v[216:219], v147 offset:7168
	global_load_lds_dwordx4 v152, s[4:5]
	v_add_u32_e32 v152, 0x80, v205
	s_mov_b32 m0, s59
	s_nop 0
	global_load_lds_dwordx4 v152, s[4:5]
	s_waitcnt lgkmcnt(8)
	s_barrier
	s_waitcnt lgkmcnt(0)
	s_waitcnt lgkmcnt(0)
	v_mfma_f32_16x16x32_bf16 v[126:129], v[156:159], v[172:175], 0
	v_mfma_f32_16x16x32_bf16 v[122:125], v[164:167], v[172:175], 0
	v_mfma_f32_16x16x32_bf16 v[118:121], v[156:159], v[180:183], 0
	v_mfma_f32_16x16x32_bf16 v[114:117], v[164:167], v[180:183], 0
	v_mfma_f32_16x16x32_bf16 v[110:113], v[156:159], v[200:203], 0
	v_mfma_f32_16x16x32_bf16 v[106:109], v[164:167], v[200:203], 0
	v_mfma_f32_16x16x32_bf16 v[102:105], v[156:159], v[212:215], 0
	v_mfma_f32_16x16x32_bf16 v[98:101], v[164:167], v[212:215], 0
	v_mfma_f32_16x16x32_bf16 v[126:129], v[160:163], v[176:179], v[126:129]
	v_mfma_f32_16x16x32_bf16 v[122:125], v[168:171], v[176:179], v[122:125]
	v_mfma_f32_16x16x32_bf16 v[118:121], v[160:163], v[196:199], v[118:121]
	v_mfma_f32_16x16x32_bf16 v[114:117], v[168:171], v[196:199], v[114:117]
	v_mfma_f32_16x16x32_bf16 v[110:113], v[160:163], v[208:211], v[110:113]
	v_mfma_f32_16x16x32_bf16 v[106:109], v[168:171], v[208:211], v[106:109]
	v_mfma_f32_16x16x32_bf16 v[102:105], v[160:163], v[216:219], v[102:105]
	v_mfma_f32_16x16x32_bf16 v[98:101], v[168:171], v[216:219], v[98:101]
	s_barrier
	s_mov_b32 m0, s28
	v_or_b32_e32 v152, 0x14000, v146
	v_add_u32_e32 v154, 0x14100, v146
	v_add_u32_e32 v206, 0x100, v204
	v_add_u32_e32 v153, 0x14400, v146
	ds_read_b128 v[220:223], v152
	ds_read_b128 v[224:227], v153
	v_add_u32_e32 v155, 0x14500, v146
	ds_read_b128 v[228:231], v154
	ds_read_b128 v[232:235], v155
	global_load_lds_dwordx4 v206, s[10:11]
	v_add_u32_e32 v207, 0x100, v205
	s_mov_b32 m0, s29
	s_nop 0
	global_load_lds_dwordx4 v207, s[10:11]
	s_barrier
	s_waitcnt lgkmcnt(0)
	s_waitcnt lgkmcnt(0)
	v_mfma_f32_16x16x32_bf16 v[92:95], v[220:223], v[172:175], 0
	v_mfma_f32_16x16x32_bf16 v[88:91], v[228:231], v[172:175], 0
	v_mfma_f32_16x16x32_bf16 v[84:87], v[220:223], v[180:183], 0
	v_mfma_f32_16x16x32_bf16 v[80:83], v[228:231], v[180:183], 0
	v_mfma_f32_16x16x32_bf16 v[76:79], v[220:223], v[200:203], 0
	v_mfma_f32_16x16x32_bf16 v[72:75], v[228:231], v[200:203], 0
	v_mfma_f32_16x16x32_bf16 v[68:71], v[220:223], v[212:215], 0
	v_mfma_f32_16x16x32_bf16 v[64:67], v[228:231], v[212:215], 0
	v_mfma_f32_16x16x32_bf16 v[92:95], v[224:227], v[176:179], v[92:95]
	v_mfma_f32_16x16x32_bf16 v[88:91], v[232:235], v[176:179], v[88:91]
	v_mfma_f32_16x16x32_bf16 v[84:87], v[224:227], v[196:199], v[84:87]
	v_mfma_f32_16x16x32_bf16 v[80:83], v[232:235], v[196:199], v[80:83]
	v_mfma_f32_16x16x32_bf16 v[76:79], v[224:227], v[208:211], v[76:79]
	v_mfma_f32_16x16x32_bf16 v[72:75], v[232:235], v[208:211], v[72:75]
	v_mfma_f32_16x16x32_bf16 v[68:71], v[224:227], v[216:219], v[68:71]
	v_mfma_f32_16x16x32_bf16 v[64:67], v[232:235], v[216:219], v[64:67]
	s_mov_b32 m0, s25
	s_barrier
	ds_read_b128 v[172:175], v147 offset:16384
	ds_read_b128 v[176:179], v147 offset:17408
	ds_read_b128 v[180:183], v147 offset:18432
	ds_read_b128 v[196:199], v147 offset:19456
	ds_read_b128 v[200:203], v147 offset:20480
	ds_read_b128 v[208:211], v147 offset:21504
	ds_read_b128 v[212:215], v147 offset:22528
	ds_read_b128 v[216:219], v147 offset:23552
	global_load_lds_dwordx4 v206, s[12:13]
	s_mov_b32 m0, s26
	s_nop 0
	global_load_lds_dwordx4 v207, s[12:13]
	s_barrier
	s_waitcnt lgkmcnt(0)
	s_waitcnt lgkmcnt(0)
	v_mfma_f32_16x16x32_bf16 v[60:63], v[156:159], v[172:175], 0
	v_mfma_f32_16x16x32_bf16 v[56:59], v[164:167], v[172:175], 0
	v_mfma_f32_16x16x32_bf16 v[52:55], v[156:159], v[180:183], 0
	v_mfma_f32_16x16x32_bf16 v[48:51], v[164:167], v[180:183], 0
	v_mfma_f32_16x16x32_bf16 v[44:47], v[156:159], v[200:203], 0
	v_mfma_f32_16x16x32_bf16 v[40:43], v[164:167], v[200:203], 0
	v_mfma_f32_16x16x32_bf16 v[36:39], v[156:159], v[212:215], 0
	v_mfma_f32_16x16x32_bf16 v[32:35], v[164:167], v[212:215], 0
	v_mfma_f32_16x16x32_bf16 v[60:63], v[160:163], v[176:179], v[60:63]
	v_mfma_f32_16x16x32_bf16 v[56:59], v[168:171], v[176:179], v[56:59]
	v_mfma_f32_16x16x32_bf16 v[52:55], v[160:163], v[196:199], v[52:55]
	v_mfma_f32_16x16x32_bf16 v[48:51], v[168:171], v[196:199], v[48:51]
	v_mfma_f32_16x16x32_bf16 v[44:47], v[160:163], v[208:211], v[44:47]
	v_mfma_f32_16x16x32_bf16 v[40:43], v[168:171], v[208:211], v[40:43]
	v_mfma_f32_16x16x32_bf16 v[36:39], v[160:163], v[216:219], v[36:39]
	v_mfma_f32_16x16x32_bf16 v[32:35], v[168:171], v[216:219], v[32:35]
	s_barrier
	s_mov_b32 m0, s30
	s_nop 0
	global_load_lds_dwordx4 v206, s[18:19]
	s_mov_b32 m0, s31
	s_nop 0
	global_load_lds_dwordx4 v207, s[18:19]
	s_waitcnt vmcnt(6)
	s_barrier
; #define WAIT_V(n) asm volatile("s_waitcnt vmcnt(%0)" ::"n"(n) : "memory")
; #define WAIT_L(n) asm volatile("s_waitcnt lgkmcnt(%0)" ::"n"(n) : "memory")
; #define SBAR() __builtin_amdgcn_sched_barrier(0)
; #define STAGE(P, base, kt) do { _Pragma("unroll") for (int _i = 0; _i < 2; ++_i)                                        \
;       __builtin_amdgcn_global_load_lds((const unsigned*)((base) + (size_t)(sOff[_i] + (unsigned)(kt) * (BK * 2))),        \
;                                        (unsigned*)((P) + wid * 1024 + _i * 8192), 16, 0, 0); } while (0)
; #define LDA(dst, b, h) _Pragma("unroll") for (int m = 0; m < 4; ++m) _Pragma("unroll") for (int k = 0; k < 2; ++k) \
;       dst[m][k] = *(const bf16x8*)(SA(b, h) + aoff + (m * 2048 + k * 1024))
; #define LDB(dst, b, h) _Pragma("unroll") for (int n = 0; n < 2; ++n) _Pragma("unroll") for (int k = 0; k < 2; ++k) \
;       dst[n][k] = *(const bf16x8*)(SB(b, h) + boff + (n * 256 + k * 1024))
; #define BAR __builtin_amdgcn_s_barrier()
; template <int EPI, int N, int K>
; __device__ __forceinline__ void phase_gemm(const Params& p, const u16* __restrict__ A, const u16* __restrict__ Bt, int nM, char* shm,
;                            u16* __restrict__ outp, float* __restrict__ rowss) {
;     ...
;       WAIT_V(6); BAR; MMA(1, 1, At, B1); BAR;
;       LDB(B0, 1, 0); SBAR(); LDA(At, 1, 0); STAGE(SA(0, 1), A1, t + 2);
;       WAIT_L(8); BAR; WAIT_L(0); MMA(0, 0, At, B0); BAR; SBAR();
;       LDB(B1, 1, 1); STAGE(SB(1, 0), B0p, t + 3);
;       BAR; WAIT_L(0); MMA(0, 1, At, B1); BAR;
;       LDA(At, 1, 1); STAGE(SA(1, 0), A0, t + 3);
;       BAR; WAIT_L(0); MMA(1, 0, At, B0); BAR; SBAR();
;       STAGE(SB(1, 1), B1p, t + 3);
	v_mfma_f32_16x16x32_bf16 v[28:31], v[220:223], v[172:175], 0
	v_mfma_f32_16x16x32_bf16 v[24:27], v[228:231], v[172:175], 0
	v_mfma_f32_16x16x32_bf16 v[20:23], v[220:223], v[180:183], 0
	v_mfma_f32_16x16x32_bf16 v[16:19], v[228:231], v[180:183], 0
	v_mfma_f32_16x16x32_bf16 v[12:15], v[220:223], v[200:203], 0
	v_mfma_f32_16x16x32_bf16 v[8:11], v[228:231], v[200:203], 0
	v_mfma_f32_16x16x32_bf16 v[4:7], v[220:223], v[212:215], 0
	v_mfma_f32_16x16x32_bf16 v[0:3], v[228:231], v[212:215], 0
	v_mfma_f32_16x16x32_bf16 v[28:31], v[224:227], v[176:179], v[28:31]
	v_mfma_f32_16x16x32_bf16 v[24:27], v[232:235], v[176:179], v[24:27]
	v_mfma_f32_16x16x32_bf16 v[20:23], v[224:227], v[196:199], v[20:23]
	v_mfma_f32_16x16x32_bf16 v[16:19], v[232:235], v[196:199], v[16:19]
	v_mfma_f32_16x16x32_bf16 v[12:15], v[224:227], v[208:211], v[12:15]
	v_mfma_f32_16x16x32_bf16 v[8:11], v[232:235], v[208:211], v[8:11]
	v_mfma_f32_16x16x32_bf16 v[4:7], v[224:227], v[216:219], v[4:7]
	v_mfma_f32_16x16x32_bf16 v[0:3], v[232:235], v[216:219], v[0:3]
	v_or_b32_e32 v156, 0x18000, v146
	v_add_u32_e32 v158, 0x18100, v146
	s_barrier
	v_add_u32_e32 v157, 0x18400, v146
	ds_read_b128 v[164:167], v156
	ds_read_b128 v[168:171], v157
	v_add_u32_e32 v159, 0x18500, v146
	ds_read_b128 v[172:175], v158
	ds_read_b128 v[176:179], v159
	s_mov_b32 m0, s33
	ds_read_b128 v[180:183], v147 offset:32768
	ds_read_b128 v[196:199], v147 offset:33792
	ds_read_b128 v[200:203], v147 offset:34816
	ds_read_b128 v[208:211], v147 offset:35840
	ds_read_b128 v[212:215], v147 offset:36864
	ds_read_b128 v[216:219], v147 offset:37888
	ds_read_b128 v[220:223], v147 offset:38912
	ds_read_b128 v[224:227], v147 offset:39936
	global_load_lds_dwordx4 v206, s[4:5]
	s_mov_b32 m0, s35
	s_nop 0
	global_load_lds_dwordx4 v207, s[4:5]
	s_waitcnt lgkmcnt(8)
	s_barrier
	s_waitcnt lgkmcnt(0)
	s_waitcnt lgkmcnt(0)
	v_mfma_f32_16x16x32_bf16 v[126:129], v[164:167], v[180:183], v[126:129]
	v_mfma_f32_16x16x32_bf16 v[122:125], v[172:175], v[180:183], v[122:125]
	v_mfma_f32_16x16x32_bf16 v[118:121], v[164:167], v[200:203], v[118:121]
	v_mfma_f32_16x16x32_bf16 v[114:117], v[172:175], v[200:203], v[114:117]
	v_mfma_f32_16x16x32_bf16 v[110:113], v[164:167], v[212:215], v[110:113]
	v_mfma_f32_16x16x32_bf16 v[106:109], v[172:175], v[212:215], v[106:109]
	v_mfma_f32_16x16x32_bf16 v[102:105], v[164:167], v[220:223], v[102:105]
	v_mfma_f32_16x16x32_bf16 v[98:101], v[172:175], v[220:223], v[98:101]
	v_mfma_f32_16x16x32_bf16 v[126:129], v[168:171], v[196:199], v[126:129]
	v_mfma_f32_16x16x32_bf16 v[122:125], v[176:179], v[196:199], v[122:125]
	v_mfma_f32_16x16x32_bf16 v[118:121], v[168:171], v[208:211], v[118:121]
	v_mfma_f32_16x16x32_bf16 v[114:117], v[176:179], v[208:211], v[114:117]
	v_mfma_f32_16x16x32_bf16 v[110:113], v[168:171], v[216:219], v[110:113]
	v_mfma_f32_16x16x32_bf16 v[106:109], v[176:179], v[216:219], v[106:109]
	v_mfma_f32_16x16x32_bf16 v[102:105], v[168:171], v[224:227], v[102:105]
	v_mfma_f32_16x16x32_bf16 v[98:101], v[176:179], v[224:227], v[98:101]
	s_barrier
	s_mov_b32 m0, s92
	v_or_b32_e32 v160, 0x1c000, v146
	v_add_u32_e32 v162, 0x1c100, v146
	v_add_u32_e32 v204, 0x180, v204
	v_add_u32_e32 v161, 0x1c400, v146
	ds_read_b128 v[228:231], v160
	ds_read_b128 v[232:235], v161
	v_add_u32_e32 v163, 0x1c500, v146
	ds_read_b128 v[236:239], v162
	ds_read_b128 v[240:243], v163
	global_load_lds_dwordx4 v204, s[10:11]
	v_add_u32_e32 v205, 0x180, v205
	s_mov_b32 m0, s93
	s_nop 0
	global_load_lds_dwordx4 v205, s[10:11]
	s_barrier
	s_waitcnt lgkmcnt(0)
	s_waitcnt lgkmcnt(0)
	v_mfma_f32_16x16x32_bf16 v[92:95], v[228:231], v[180:183], v[92:95]
	v_mfma_f32_16x16x32_bf16 v[88:91], v[236:239], v[180:183], v[88:91]
	v_mfma_f32_16x16x32_bf16 v[84:87], v[228:231], v[200:203], v[84:87]
	v_mfma_f32_16x16x32_bf16 v[80:83], v[236:239], v[200:203], v[80:83]
	v_mfma_f32_16x16x32_bf16 v[76:79], v[228:231], v[212:215], v[76:79]
	v_mfma_f32_16x16x32_bf16 v[72:75], v[236:239], v[212:215], v[72:75]
	v_mfma_f32_16x16x32_bf16 v[68:71], v[228:231], v[220:223], v[68:71]
	v_mfma_f32_16x16x32_bf16 v[64:67], v[236:239], v[220:223], v[64:67]
	v_mfma_f32_16x16x32_bf16 v[92:95], v[232:235], v[196:199], v[92:95]
	v_mfma_f32_16x16x32_bf16 v[88:91], v[240:243], v[196:199], v[88:91]
	v_mfma_f32_16x16x32_bf16 v[84:87], v[232:235], v[208:211], v[84:87]
	v_mfma_f32_16x16x32_bf16 v[80:83], v[240:243], v[208:211], v[80:83]
	v_mfma_f32_16x16x32_bf16 v[76:79], v[232:235], v[216:219], v[76:79]
	v_mfma_f32_16x16x32_bf16 v[72:75], v[240:243], v[216:219], v[72:75]
	v_mfma_f32_16x16x32_bf16 v[68:71], v[232:235], v[224:227], v[68:71]
	v_mfma_f32_16x16x32_bf16 v[64:67], v[240:243], v[224:227], v[64:67]
	s_mov_b32 m0, s94
	s_barrier
	ds_read_b128 v[180:183], v147 offset:49152
	ds_read_b128 v[196:199], v147 offset:50176
	ds_read_b128 v[200:203], v147 offset:51200
	ds_read_b128 v[208:211], v147 offset:52224
	ds_read_b128 v[212:215], v147 offset:53248
	ds_read_b128 v[216:219], v147 offset:54272
	ds_read_b128 v[220:223], v147 offset:55296
	ds_read_b128 v[224:227], v147 offset:56320
	global_load_lds_dwordx4 v204, s[12:13]
	s_mov_b32 m0, s52
	s_nop 0
	global_load_lds_dwordx4 v205, s[12:13]
	s_barrier
; #define WAIT_V(n) asm volatile("s_waitcnt vmcnt(%0)" ::"n"(n) : "memory")
; #define WAIT_L(n) asm volatile("s_waitcnt lgkmcnt(%0)" ::"n"(n) : "memory")
; #define SBAR() __builtin_amdgcn_sched_barrier(0)
; #define STAGE(P, base, kt) do { _Pragma("unroll") for (int _i = 0; _i < 2; ++_i)                                        \
;       __builtin_amdgcn_global_load_lds((const unsigned*)((base) + (size_t)(sOff[_i] + (unsigned)(kt) * (BK * 2))),        \
;                                        (unsigned*)((P) + wid * 1024 + _i * 8192), 16, 0, 0); } while (0)
; #define LDA(dst, b, h) _Pragma("unroll") for (int m = 0; m < 4; ++m) _Pragma("unroll") for (int k = 0; k < 2; ++k) \
;       dst[m][k] = *(const bf16x8*)(SA(b, h) + aoff + (m * 2048 + k * 1024))
; #define LDB(dst, b, h) _Pragma("unroll") for (int n = 0; n < 2; ++n) _Pragma("unroll") for (int k = 0; k < 2; ++k) \
;       dst[n][k] = *(const bf16x8*)(SB(b, h) + boff + (n * 256 + k * 1024))
; #define BAR __builtin_amdgcn_s_barrier()
; template <int EPI, int N, int K>
; __device__ __forceinline__ void phase_gemm(const Params& p, const u16* __restrict__ A, const u16* __restrict__ Bt, int nM, char* shm,
;                            u16* __restrict__ outp, float* __restrict__ rowss) {
;     ...
;       LDB(B0, 0, 0); SBAR(); LDA(At, 0, 0); STAGE(SA(1, 1), A1, t + 1);
;       WAIT_L(8); BAR; WAIT_L(0); MMA(0, 0, At, B0); BAR; SBAR();
;       LDB(B1, 0, 1); STAGE(SB(0, 0), B0p, t + 2);
;       BAR; WAIT_L(0); MMA(0, 1, At, B1); BAR;
;       LDA(At, 0, 1); STAGE(SA(0, 0), A0, t + 2);
;       BAR; WAIT_L(0); MMA(1, 0, At, B0); BAR; SBAR();
;       STAGE(SB(0, 1), B1p, t + 2);
;       WAIT_V(6); BAR; MMA(1, 1, At, B1); BAR;
;       LDB(B0, 1, 0); SBAR(); LDA(At, 1, 0); STAGE(SA(0, 1), A1, t + 2);
;       WAIT_L(8); BAR; WAIT_L(0); MMA(0, 0, At, B0); BAR; SBAR();
;       LDB(B1, 1, 1); STAGE(SB(1, 0), B0p, t + 3);
;       BAR; WAIT_L(0); MMA(0, 1, At, B1); BAR;
;       LDA(At, 1, 1); STAGE(SA(1, 0), A0, t + 3);
;       BAR; WAIT_L(0); MMA(1, 0, At, B0); BAR; SBAR();
;       STAGE(SB(1, 1), B1p, t + 3);
;       WAIT_V(6); BAR; MMA(1, 1, At, B1); BAR;
	s_waitcnt lgkmcnt(0)
	s_waitcnt lgkmcnt(0)
	v_mfma_f32_16x16x32_bf16 v[60:63], v[164:167], v[180:183], v[60:63]
	v_mfma_f32_16x16x32_bf16 v[56:59], v[172:175], v[180:183], v[56:59]
	v_mfma_f32_16x16x32_bf16 v[52:55], v[164:167], v[200:203], v[52:55]
	v_mfma_f32_16x16x32_bf16 v[48:51], v[172:175], v[200:203], v[48:51]
	v_mfma_f32_16x16x32_bf16 v[44:47], v[164:167], v[212:215], v[44:47]
	v_mfma_f32_16x16x32_bf16 v[40:43], v[172:175], v[212:215], v[40:43]
	v_mfma_f32_16x16x32_bf16 v[36:39], v[164:167], v[220:223], v[36:39]
	v_mfma_f32_16x16x32_bf16 v[32:35], v[172:175], v[220:223], v[32:35]
	v_mfma_f32_16x16x32_bf16 v[60:63], v[168:171], v[196:199], v[60:63]
	v_mfma_f32_16x16x32_bf16 v[56:59], v[176:179], v[196:199], v[56:59]
	v_mfma_f32_16x16x32_bf16 v[52:55], v[168:171], v[208:211], v[52:55]
	v_mfma_f32_16x16x32_bf16 v[48:51], v[176:179], v[208:211], v[48:51]
	v_mfma_f32_16x16x32_bf16 v[44:47], v[168:171], v[216:219], v[44:47]
	v_mfma_f32_16x16x32_bf16 v[40:43], v[176:179], v[216:219], v[40:43]
	v_mfma_f32_16x16x32_bf16 v[36:39], v[168:171], v[224:227], v[36:39]
	v_mfma_f32_16x16x32_bf16 v[32:35], v[176:179], v[224:227], v[32:35]
	s_barrier
	s_mov_b32 m0, s53
	s_nop 0
	global_load_lds_dwordx4 v204, s[18:19]
	s_mov_b32 m0, s54
	s_nop 0
	global_load_lds_dwordx4 v205, s[18:19]
	s_waitcnt vmcnt(6)
	s_barrier
	v_mfma_f32_16x16x32_bf16 v[28:31], v[228:231], v[180:183], v[28:31]
	v_mfma_f32_16x16x32_bf16 v[24:27], v[236:239], v[180:183], v[24:27]
	v_mfma_f32_16x16x32_bf16 v[20:23], v[228:231], v[200:203], v[20:23]
	v_mfma_f32_16x16x32_bf16 v[16:19], v[236:239], v[200:203], v[16:19]
	v_mfma_f32_16x16x32_bf16 v[12:15], v[228:231], v[212:215], v[12:15]
	v_mfma_f32_16x16x32_bf16 v[8:11], v[236:239], v[212:215], v[8:11]
	v_mfma_f32_16x16x32_bf16 v[4:7], v[228:231], v[220:223], v[4:7]
	v_mfma_f32_16x16x32_bf16 v[0:3], v[236:239], v[220:223], v[0:3]
	v_mfma_f32_16x16x32_bf16 v[28:31], v[232:235], v[196:199], v[28:31]
	v_mfma_f32_16x16x32_bf16 v[24:27], v[240:243], v[196:199], v[24:27]
	v_mfma_f32_16x16x32_bf16 v[20:23], v[232:235], v[208:211], v[20:23]
	v_mfma_f32_16x16x32_bf16 v[16:19], v[240:243], v[208:211], v[16:19]
	v_mfma_f32_16x16x32_bf16 v[12:15], v[232:235], v[216:219], v[12:15]
	v_mfma_f32_16x16x32_bf16 v[8:11], v[240:243], v[216:219], v[8:11]
	v_mfma_f32_16x16x32_bf16 v[4:7], v[232:235], v[224:227], v[4:7]
	v_mfma_f32_16x16x32_bf16 v[0:3], v[240:243], v[224:227], v[0:3]
	s_add_i32 s58, s58, 2
	v_add_u32_e32 v142, 0x100, v142
	s_cmp_lt_u32 s58, 40
	v_add_u32_e32 v96, 0x100, v96
	s_barrier
.LBB0_517:
	v_or_b32_e32 v143, 0x10000, v146
	v_add_u32_e32 v145, 0x10100, v146
	v_add_u32_e32 v144, 0x10400, v146
	ds_read_b128 v[156:159], v143
	ds_read_b128 v[160:163], v144
	v_add_u32_e32 v151, 0x10500, v146
	ds_read_b128 v[164:167], v145
	ds_read_b128 v[168:171], v151
	v_add_u32_e32 v204, v148, v96
	s_add_i32 s60, s25, 0xc000
	v_add_u32_e32 v152, 0x80, v204
	s_mov_b32 m0, s60
	v_add_u32_e32 v205, v148, v142
	s_add_i32 s59, s25, 0xe000
	ds_read_b128 v[172:175], v147
	ds_read_b128 v[176:179], v147 offset:1024
	ds_read_b128 v[180:183], v147 offset:2048
	ds_read_b128 v[196:199], v147 offset:3072
	ds_read_b128 v[200:203], v147 offset:4096
	ds_read_b128 v[208:211], v147 offset:5120
	ds_read_b128 v[212:215], v147 offset:6144
	ds_read_b128 v[216:219], v147 offset:7168
	global_load_lds_dwordx4 v152, s[4:5]
	v_add_u32_e32 v152, 0x80, v205
	s_mov_b32 m0, s59
	s_nop 0
	global_load_lds_dwordx4 v152, s[4:5]
	s_waitcnt lgkmcnt(8)
	s_barrier
	s_waitcnt lgkmcnt(0)
	s_waitcnt lgkmcnt(0)
	v_mfma_f32_16x16x32_bf16 v[126:129], v[156:159], v[172:175], v[126:129]
	v_mfma_f32_16x16x32_bf16 v[122:125], v[164:167], v[172:175], v[122:125]
	v_mfma_f32_16x16x32_bf16 v[118:121], v[156:159], v[180:183], v[118:121]
	v_mfma_f32_16x16x32_bf16 v[114:117], v[164:167], v[180:183], v[114:117]
	v_mfma_f32_16x16x32_bf16 v[110:113], v[156:159], v[200:203], v[110:113]
	v_mfma_f32_16x16x32_bf16 v[106:109], v[164:167], v[200:203], v[106:109]
	v_mfma_f32_16x16x32_bf16 v[102:105], v[156:159], v[212:215], v[102:105]
	v_mfma_f32_16x16x32_bf16 v[98:101], v[164:167], v[212:215], v[98:101]
	v_mfma_f32_16x16x32_bf16 v[126:129], v[160:163], v[176:179], v[126:129]
	v_mfma_f32_16x16x32_bf16 v[122:125], v[168:171], v[176:179], v[122:125]
	v_mfma_f32_16x16x32_bf16 v[118:121], v[160:163], v[196:199], v[118:121]
	v_mfma_f32_16x16x32_bf16 v[114:117], v[168:171], v[196:199], v[114:117]
	v_mfma_f32_16x16x32_bf16 v[110:113], v[160:163], v[208:211], v[110:113]
	v_mfma_f32_16x16x32_bf16 v[106:109], v[168:171], v[208:211], v[106:109]
	v_mfma_f32_16x16x32_bf16 v[102:105], v[160:163], v[216:219], v[102:105]
	v_mfma_f32_16x16x32_bf16 v[98:101], v[168:171], v[216:219], v[98:101]
	s_barrier
	s_mov_b32 m0, s28
	v_or_b32_e32 v152, 0x14000, v146
	v_add_u32_e32 v154, 0x14100, v146
	v_add_u32_e32 v206, 0x100, v204
	v_add_u32_e32 v153, 0x14400, v146
	ds_read_b128 v[220:223], v152
	ds_read_b128 v[224:227], v153
	v_add_u32_e32 v155, 0x14500, v146
	ds_read_b128 v[228:231], v154
	ds_read_b128 v[232:235], v155
	global_load_lds_dwordx4 v206, s[10:11]
	v_add_u32_e32 v207, 0x100, v205
	s_mov_b32 m0, s29
	s_nop 0
	global_load_lds_dwordx4 v207, s[10:11]
	s_barrier
; #define WAIT_V(n) asm volatile("s_waitcnt vmcnt(%0)" ::"n"(n) : "memory")
; #define WAIT_L(n) asm volatile("s_waitcnt lgkmcnt(%0)" ::"n"(n) : "memory")
; #define SBAR() __builtin_amdgcn_sched_barrier(0)
; #define STAGE(P, base, kt) do { _Pragma("unroll") for (int _i = 0; _i < 2; ++_i)                                        \
;       __builtin_amdgcn_global_load_lds((const unsigned*)((base) + (size_t)(sOff[_i] + (unsigned)(kt) * (BK * 2))),        \
;                                        (unsigned*)((P) + wid * 1024 + _i * 8192), 16, 0, 0); } while (0)
; #define LDA(dst, b, h) _Pragma("unroll") for (int m = 0; m < 4; ++m) _Pragma("unroll") for (int k = 0; k < 2; ++k) \
;       dst[m][k] = *(const bf16x8*)(SA(b, h) + aoff + (m * 2048 + k * 1024))
; #define LDB(dst, b, h) _Pragma("unroll") for (int n = 0; n < 2; ++n) _Pragma("unroll") for (int k = 0; k < 2; ++k) \
;       dst[n][k] = *(const bf16x8*)(SB(b, h) + boff + (n * 256 + k * 1024))
; #define BAR __builtin_amdgcn_s_barrier()
; template <int EPI, int N, int K>
; __device__ __forceinline__ void phase_gemm(const Params& p, const u16* __restrict__ A, const u16* __restrict__ Bt, int nM, char* shm,
;                            u16* __restrict__ outp, float* __restrict__ rowss) {
;     ...
;       LDB(B1, 0, 1); STAGE(SB(0, 0), B0p, t + 2);
;       BAR; WAIT_L(0); MMA(0, 1, At, B1); BAR;
;       LDA(At, 0, 1); STAGE(SA(0, 0), A0, t + 2);
;       BAR; WAIT_L(0); MMA(1, 0, At, B0); BAR; SBAR();
;       STAGE(SB(0, 1), B1p, t + 2);
;       WAIT_V(6); BAR; MMA(1, 1, At, B1); BAR;
;       LDB(B0, 1, 0); SBAR(); LDA(At, 1, 0); STAGE(SA(0, 1), A1, t + 2);
;       WAIT_L(8); BAR; WAIT_L(0); MMA(0, 0, At, B0); BAR; SBAR();
;       LDB(B1, 1, 1); STAGE(SB(1, 0), B0p, t + 3);
;       BAR; WAIT_L(0); MMA(0, 1, At, B1); BAR;
;       LDA(At, 1, 1); STAGE(SA(1, 0), A0, t + 3);
;       BAR; WAIT_L(0); MMA(1, 0, At, B0); BAR; SBAR();
;       STAGE(SB(1, 1), B1p, t + 3);
;       WAIT_V(6); BAR; MMA(1, 1, At, B1); BAR;
	s_waitcnt lgkmcnt(0)
	s_waitcnt lgkmcnt(0)
	v_mfma_f32_16x16x32_bf16 v[92:95], v[220:223], v[172:175], v[92:95]
	v_mfma_f32_16x16x32_bf16 v[88:91], v[228:231], v[172:175], v[88:91]
	v_mfma_f32_16x16x32_bf16 v[84:87], v[220:223], v[180:183], v[84:87]
	v_mfma_f32_16x16x32_bf16 v[80:83], v[228:231], v[180:183], v[80:83]
	v_mfma_f32_16x16x32_bf16 v[76:79], v[220:223], v[200:203], v[76:79]
	v_mfma_f32_16x16x32_bf16 v[72:75], v[228:231], v[200:203], v[72:75]
	v_mfma_f32_16x16x32_bf16 v[68:71], v[220:223], v[212:215], v[68:71]
	v_mfma_f32_16x16x32_bf16 v[64:67], v[228:231], v[212:215], v[64:67]
	v_mfma_f32_16x16x32_bf16 v[92:95], v[224:227], v[176:179], v[92:95]
	v_mfma_f32_16x16x32_bf16 v[88:91], v[232:235], v[176:179], v[88:91]
	v_mfma_f32_16x16x32_bf16 v[84:87], v[224:227], v[196:199], v[84:87]
	v_mfma_f32_16x16x32_bf16 v[80:83], v[232:235], v[196:199], v[80:83]
	v_mfma_f32_16x16x32_bf16 v[76:79], v[224:227], v[208:211], v[76:79]
	v_mfma_f32_16x16x32_bf16 v[72:75], v[232:235], v[208:211], v[72:75]
	v_mfma_f32_16x16x32_bf16 v[68:71], v[224:227], v[216:219], v[68:71]
	v_mfma_f32_16x16x32_bf16 v[64:67], v[232:235], v[216:219], v[64:67]
	s_mov_b32 m0, s25
	s_barrier
	ds_read_b128 v[172:175], v147 offset:16384
	ds_read_b128 v[176:179], v147 offset:17408
	ds_read_b128 v[180:183], v147 offset:18432
	ds_read_b128 v[196:199], v147 offset:19456
	ds_read_b128 v[200:203], v147 offset:20480
	ds_read_b128 v[208:211], v147 offset:21504
	ds_read_b128 v[212:215], v147 offset:22528
	ds_read_b128 v[216:219], v147 offset:23552
	global_load_lds_dwordx4 v206, s[12:13]
	s_mov_b32 m0, s26
	s_nop 0
	global_load_lds_dwordx4 v207, s[12:13]
	s_barrier
	s_waitcnt lgkmcnt(0)
	s_waitcnt lgkmcnt(0)
	v_mfma_f32_16x16x32_bf16 v[60:63], v[156:159], v[172:175], v[60:63]
	v_mfma_f32_16x16x32_bf16 v[56:59], v[164:167], v[172:175], v[56:59]
	v_mfma_f32_16x16x32_bf16 v[52:55], v[156:159], v[180:183], v[52:55]
	v_mfma_f32_16x16x32_bf16 v[48:51], v[164:167], v[180:183], v[48:51]
	v_mfma_f32_16x16x32_bf16 v[44:47], v[156:159], v[200:203], v[44:47]
	v_mfma_f32_16x16x32_bf16 v[40:43], v[164:167], v[200:203], v[40:43]
	v_mfma_f32_16x16x32_bf16 v[36:39], v[156:159], v[212:215], v[36:39]
	v_mfma_f32_16x16x32_bf16 v[32:35], v[164:167], v[212:215], v[32:35]
	v_mfma_f32_16x16x32_bf16 v[60:63], v[160:163], v[176:179], v[60:63]
	v_mfma_f32_16x16x32_bf16 v[56:59], v[168:171], v[176:179], v[56:59]
	v_mfma_f32_16x16x32_bf16 v[52:55], v[160:163], v[196:199], v[52:55]
	v_mfma_f32_16x16x32_bf16 v[48:51], v[168:171], v[196:199], v[48:51]
	v_mfma_f32_16x16x32_bf16 v[44:47], v[160:163], v[208:211], v[44:47]
	v_mfma_f32_16x16x32_bf16 v[40:43], v[168:171], v[208:211], v[40:43]
	v_mfma_f32_16x16x32_bf16 v[36:39], v[160:163], v[216:219], v[36:39]
	v_mfma_f32_16x16x32_bf16 v[32:35], v[168:171], v[216:219], v[32:35]
	s_barrier
	s_mov_b32 m0, s30
	s_nop 0
	global_load_lds_dwordx4 v206, s[18:19]
	s_mov_b32 m0, s31
	s_nop 0
	global_load_lds_dwordx4 v207, s[18:19]
	s_waitcnt vmcnt(6)
	s_barrier
	v_mfma_f32_16x16x32_bf16 v[28:31], v[220:223], v[172:175], v[28:31]
	v_mfma_f32_16x16x32_bf16 v[24:27], v[228:231], v[172:175], v[24:27]
	v_mfma_f32_16x16x32_bf16 v[20:23], v[220:223], v[180:183], v[20:23]
	v_mfma_f32_16x16x32_bf16 v[16:19], v[228:231], v[180:183], v[16:19]
	v_mfma_f32_16x16x32_bf16 v[12:15], v[220:223], v[200:203], v[12:15]
	v_mfma_f32_16x16x32_bf16 v[8:11], v[228:231], v[200:203], v[8:11]
	v_mfma_f32_16x16x32_bf16 v[4:7], v[220:223], v[212:215], v[4:7]
	v_mfma_f32_16x16x32_bf16 v[0:3], v[228:231], v[212:215], v[0:3]
	v_mfma_f32_16x16x32_bf16 v[28:31], v[224:227], v[176:179], v[28:31]
	v_mfma_f32_16x16x32_bf16 v[24:27], v[232:235], v[176:179], v[24:27]
	v_mfma_f32_16x16x32_bf16 v[20:23], v[224:227], v[196:199], v[20:23]
	v_mfma_f32_16x16x32_bf16 v[16:19], v[232:235], v[196:199], v[16:19]
	v_mfma_f32_16x16x32_bf16 v[12:15], v[224:227], v[208:211], v[12:15]
	v_mfma_f32_16x16x32_bf16 v[8:11], v[232:235], v[208:211], v[8:11]
	v_mfma_f32_16x16x32_bf16 v[4:7], v[224:227], v[216:219], v[4:7]
	v_mfma_f32_16x16x32_bf16 v[0:3], v[232:235], v[216:219], v[0:3]
	v_or_b32_e32 v156, 0x18000, v146
	v_add_u32_e32 v158, 0x18100, v146
	s_barrier
	v_add_u32_e32 v157, 0x18400, v146
	ds_read_b128 v[164:167], v156
	ds_read_b128 v[168:171], v157
	v_add_u32_e32 v159, 0x18500, v146
	ds_read_b128 v[172:175], v158
	ds_read_b128 v[176:179], v159
	s_mov_b32 m0, s33
	ds_read_b128 v[180:183], v147 offset:32768
	ds_read_b128 v[196:199], v147 offset:33792
	ds_read_b128 v[200:203], v147 offset:34816
	ds_read_b128 v[208:211], v147 offset:35840
	ds_read_b128 v[212:215], v147 offset:36864
	ds_read_b128 v[216:219], v147 offset:37888
	ds_read_b128 v[220:223], v147 offset:38912
	ds_read_b128 v[224:227], v147 offset:39936
	global_load_lds_dwordx4 v206, s[4:5]
	s_mov_b32 m0, s35
	s_nop 0
	global_load_lds_dwordx4 v207, s[4:5]
	s_waitcnt lgkmcnt(8)
	s_barrier
	s_waitcnt lgkmcnt(0)
	s_waitcnt lgkmcnt(0)
	v_mfma_f32_16x16x32_bf16 v[126:129], v[164:167], v[180:183], v[126:129]
	v_mfma_f32_16x16x32_bf16 v[122:125], v[172:175], v[180:183], v[122:125]
	v_mfma_f32_16x16x32_bf16 v[118:121], v[164:167], v[200:203], v[118:121]
	v_mfma_f32_16x16x32_bf16 v[114:117], v[172:175], v[200:203], v[114:117]
	v_mfma_f32_16x16x32_bf16 v[110:113], v[164:167], v[212:215], v[110:113]
	v_mfma_f32_16x16x32_bf16 v[106:109], v[172:175], v[212:215], v[106:109]
	v_mfma_f32_16x16x32_bf16 v[102:105], v[164:167], v[220:223], v[102:105]
	v_mfma_f32_16x16x32_bf16 v[98:101], v[172:175], v[220:223], v[98:101]
	v_mfma_f32_16x16x32_bf16 v[126:129], v[168:171], v[196:199], v[126:129]
	v_mfma_f32_16x16x32_bf16 v[122:125], v[176:179], v[196:199], v[122:125]
	v_mfma_f32_16x16x32_bf16 v[118:121], v[168:171], v[208:211], v[118:121]
	v_mfma_f32_16x16x32_bf16 v[114:117], v[176:179], v[208:211], v[114:117]
	v_mfma_f32_16x16x32_bf16 v[110:113], v[168:171], v[216:219], v[110:113]
	v_mfma_f32_16x16x32_bf16 v[106:109], v[176:179], v[216:219], v[106:109]
	v_mfma_f32_16x16x32_bf16 v[102:105], v[168:171], v[224:227], v[102:105]
	v_mfma_f32_16x16x32_bf16 v[98:101], v[176:179], v[224:227], v[98:101]
	s_barrier
; #define WAIT_V(n) asm volatile("s_waitcnt vmcnt(%0)" ::"n"(n) : "memory")
; #define WAIT_L(n) asm volatile("s_waitcnt lgkmcnt(%0)" ::"n"(n) : "memory")
; #define SBAR() __builtin_amdgcn_sched_barrier(0)
; #define STAGE(P, base, kt) do { _Pragma("unroll") for (int _i = 0; _i < 2; ++_i)                                        \
;       __builtin_amdgcn_global_load_lds((const unsigned*)((base) + (size_t)(sOff[_i] + (unsigned)(kt) * (BK * 2))),        \
;                                        (unsigned*)((P) + wid * 1024 + _i * 8192), 16, 0, 0); } while (0)
; #define LDA(dst, b, h) _Pragma("unroll") for (int m = 0; m < 4; ++m) _Pragma("unroll") for (int k = 0; k < 2; ++k) \
;       dst[m][k] = *(const bf16x8*)(SA(b, h) + aoff + (m * 2048 + k * 1024))
; #define LDB(dst, b, h) _Pragma("unroll") for (int n = 0; n < 2; ++n) _Pragma("unroll") for (int k = 0; k < 2; ++k) \
;       dst[n][k] = *(const bf16x8*)(SB(b, h) + boff + (n * 256 + k * 1024))
; #define BAR __builtin_amdgcn_s_barrier()
; template <int EPI, int N, int K>
; __device__ __forceinline__ void phase_gemm(const Params& p, const u16* __restrict__ A, const u16* __restrict__ Bt, int nM, char* shm,
;                            u16* __restrict__ outp, float* __restrict__ rowss) {
;     ...
;       LDB(B0, 1, 0); SBAR(); LDA(At, 1, 0); STAGE(SA(0, 1), A1, t + 2);
;       WAIT_L(8); BAR; WAIT_L(0); MMA(0, 0, At, B0); BAR; SBAR();
;       LDB(B1, 1, 1); STAGE(SB(1, 0), B0p, t + 3);
;       BAR; WAIT_L(0); MMA(0, 1, At, B1); BAR;
;       LDA(At, 1, 1); STAGE(SA(1, 0), A0, t + 3);
;       BAR; WAIT_L(0); MMA(1, 0, At, B0); BAR; SBAR();
;       STAGE(SB(1, 1), B1p, t + 3);
;       WAIT_V(6); BAR; MMA(1, 1, At, B1); BAR;
;     }
;     { LDB(B0, 0, 0); LDA(At, 0, 0); STAGE(SA(1, 1), A1, nt - 1);
	s_mov_b32 m0, s92
	v_or_b32_e32 v160, 0x1c000, v146
	v_add_u32_e32 v162, 0x1c100, v146
	v_add_u32_e32 v204, 0x180, v204
	v_add_u32_e32 v161, 0x1c400, v146
	ds_read_b128 v[228:231], v160
	ds_read_b128 v[232:235], v161
	v_add_u32_e32 v163, 0x1c500, v146
	ds_read_b128 v[236:239], v162
	ds_read_b128 v[240:243], v163
	global_load_lds_dwordx4 v204, s[10:11]
	v_add_u32_e32 v205, 0x180, v205
	s_mov_b32 m0, s93
	s_nop 0
	global_load_lds_dwordx4 v205, s[10:11]
	s_barrier
	s_waitcnt lgkmcnt(0)
	s_waitcnt lgkmcnt(0)
	v_mfma_f32_16x16x32_bf16 v[92:95], v[228:231], v[180:183], v[92:95]
	v_mfma_f32_16x16x32_bf16 v[88:91], v[236:239], v[180:183], v[88:91]
	v_mfma_f32_16x16x32_bf16 v[84:87], v[228:231], v[200:203], v[84:87]
	v_mfma_f32_16x16x32_bf16 v[80:83], v[236:239], v[200:203], v[80:83]
	v_mfma_f32_16x16x32_bf16 v[76:79], v[228:231], v[212:215], v[76:79]
	v_mfma_f32_16x16x32_bf16 v[72:75], v[236:239], v[212:215], v[72:75]
	v_mfma_f32_16x16x32_bf16 v[68:71], v[228:231], v[220:223], v[68:71]
	v_mfma_f32_16x16x32_bf16 v[64:67], v[236:239], v[220:223], v[64:67]
	v_mfma_f32_16x16x32_bf16 v[92:95], v[232:235], v[196:199], v[92:95]
	v_mfma_f32_16x16x32_bf16 v[88:91], v[240:243], v[196:199], v[88:91]
	v_mfma_f32_16x16x32_bf16 v[84:87], v[232:235], v[208:211], v[84:87]
	v_mfma_f32_16x16x32_bf16 v[80:83], v[240:243], v[208:211], v[80:83]
	v_mfma_f32_16x16x32_bf16 v[76:79], v[232:235], v[216:219], v[76:79]
	v_mfma_f32_16x16x32_bf16 v[72:75], v[240:243], v[216:219], v[72:75]
	v_mfma_f32_16x16x32_bf16 v[68:71], v[232:235], v[224:227], v[68:71]
	v_mfma_f32_16x16x32_bf16 v[64:67], v[240:243], v[224:227], v[64:67]
	s_mov_b32 m0, s94
	s_barrier
	ds_read_b128 v[180:183], v147 offset:49152
	ds_read_b128 v[196:199], v147 offset:50176
	ds_read_b128 v[200:203], v147 offset:51200
	ds_read_b128 v[208:211], v147 offset:52224
	ds_read_b128 v[212:215], v147 offset:53248
	ds_read_b128 v[216:219], v147 offset:54272
	ds_read_b128 v[220:223], v147 offset:55296
	ds_read_b128 v[224:227], v147 offset:56320
	global_load_lds_dwordx4 v204, s[12:13]
	s_mov_b32 m0, s52
	s_nop 0
	global_load_lds_dwordx4 v205, s[12:13]
	s_barrier
	s_waitcnt lgkmcnt(0)
	s_waitcnt lgkmcnt(0)
	v_mfma_f32_16x16x32_bf16 v[60:63], v[164:167], v[180:183], v[60:63]
	v_mfma_f32_16x16x32_bf16 v[56:59], v[172:175], v[180:183], v[56:59]
	v_mfma_f32_16x16x32_bf16 v[52:55], v[164:167], v[200:203], v[52:55]
	v_mfma_f32_16x16x32_bf16 v[48:51], v[172:175], v[200:203], v[48:51]
	v_mfma_f32_16x16x32_bf16 v[44:47], v[164:167], v[212:215], v[44:47]
	v_mfma_f32_16x16x32_bf16 v[40:43], v[172:175], v[212:215], v[40:43]
	v_mfma_f32_16x16x32_bf16 v[36:39], v[164:167], v[220:223], v[36:39]
	v_mfma_f32_16x16x32_bf16 v[32:35], v[172:175], v[220:223], v[32:35]
	v_mfma_f32_16x16x32_bf16 v[60:63], v[168:171], v[196:199], v[60:63]
	v_mfma_f32_16x16x32_bf16 v[56:59], v[176:179], v[196:199], v[56:59]
	v_mfma_f32_16x16x32_bf16 v[52:55], v[168:171], v[208:211], v[52:55]
	v_mfma_f32_16x16x32_bf16 v[48:51], v[176:179], v[208:211], v[48:51]
	v_mfma_f32_16x16x32_bf16 v[44:47], v[168:171], v[216:219], v[44:47]
	v_mfma_f32_16x16x32_bf16 v[40:43], v[176:179], v[216:219], v[40:43]
	v_mfma_f32_16x16x32_bf16 v[36:39], v[168:171], v[224:227], v[36:39]
	v_mfma_f32_16x16x32_bf16 v[32:35], v[176:179], v[224:227], v[32:35]
	s_barrier
	s_mov_b32 m0, s53
	s_nop 0
	global_load_lds_dwordx4 v204, s[18:19]
	s_mov_b32 m0, s54
	s_nop 0
	global_load_lds_dwordx4 v205, s[18:19]
	s_waitcnt vmcnt(6)
	s_barrier
	v_mfma_f32_16x16x32_bf16 v[28:31], v[228:231], v[180:183], v[28:31]
	v_mfma_f32_16x16x32_bf16 v[24:27], v[236:239], v[180:183], v[24:27]
	v_mfma_f32_16x16x32_bf16 v[20:23], v[228:231], v[200:203], v[20:23]
	v_mfma_f32_16x16x32_bf16 v[16:19], v[236:239], v[200:203], v[16:19]
	v_mfma_f32_16x16x32_bf16 v[12:15], v[228:231], v[212:215], v[12:15]
	v_mfma_f32_16x16x32_bf16 v[8:11], v[236:239], v[212:215], v[8:11]
	v_mfma_f32_16x16x32_bf16 v[4:7], v[228:231], v[220:223], v[4:7]
	v_mfma_f32_16x16x32_bf16 v[0:3], v[236:239], v[220:223], v[0:3]
	v_mfma_f32_16x16x32_bf16 v[28:31], v[232:235], v[196:199], v[28:31]
	v_mfma_f32_16x16x32_bf16 v[24:27], v[240:243], v[196:199], v[24:27]
	v_mfma_f32_16x16x32_bf16 v[20:23], v[232:235], v[208:211], v[20:23]
	v_mfma_f32_16x16x32_bf16 v[16:19], v[240:243], v[208:211], v[16:19]
	v_mfma_f32_16x16x32_bf16 v[12:15], v[232:235], v[216:219], v[12:15]
	v_mfma_f32_16x16x32_bf16 v[8:11], v[240:243], v[216:219], v[8:11]
	v_mfma_f32_16x16x32_bf16 v[4:7], v[232:235], v[224:227], v[4:7]
	v_mfma_f32_16x16x32_bf16 v[0:3], v[240:243], v[224:227], v[0:3]
	s_add_i32 s58, s58, 2
	v_add_u32_e32 v142, 0x100, v142
	s_cmp_lt_u32 s58, 40
	v_add_u32_e32 v96, 0x100, v96
	s_barrier
	s_cbranch_scc1 .LBB0_517
	s_mov_b32 m0, s60
	v_lshl_add_u64 v[204:205], s[4:5], 0, v[138:139]
	ds_read_b128 v[164:167], v143
	ds_read_b128 v[168:171], v144
	ds_read_b128 v[142:145], v145
	ds_read_b128 v[172:175], v151
	ds_read_b128 v[176:179], v147
	ds_read_b128 v[180:183], v147 offset:1024
	ds_read_b128 v[196:199], v147 offset:2048
	ds_read_b128 v[200:203], v147 offset:3072
	ds_read_b128 v[208:211], v147 offset:4096
	ds_read_b128 v[212:215], v147 offset:5120
	ds_read_b128 v[216:219], v147 offset:6144
	ds_read_b128 v[220:223], v147 offset:7168
	global_load_lds_dwordx4 v[204:205], off
	v_lshl_add_u64 v[204:205], s[4:5], 0, v[140:141]
	s_mov_b32 m0, s59
	s_nop 0
	global_load_lds_dwordx4 v[204:205], off
	s_barrier
; #define WAIT_V(n) asm volatile("s_waitcnt vmcnt(%0)" ::"n"(n) : "memory")
; #define WAIT_L(n) asm volatile("s_waitcnt lgkmcnt(%0)" ::"n"(n) : "memory")
; #define STAGE(P, base, kt) do { _Pragma("unroll") for (int _i = 0; _i < 2; ++_i)                                        \
;       __builtin_amdgcn_global_load_lds((const unsigned*)((base) + (size_t)(sOff[_i] + (unsigned)(kt) * (BK * 2))),        \
;                                        (unsigned*)((P) + wid * 1024 + _i * 8192), 16, 0, 0); } while (0)
; #define LDA(dst, b, h) _Pragma("unroll") for (int m = 0; m < 4; ++m) _Pragma("unroll") for (int k = 0; k < 2; ++k) \
;       dst[m][k] = *(const bf16x8*)(SA(b, h) + aoff + (m * 2048 + k * 1024))
; #define LDB(dst, b, h) _Pragma("unroll") for (int n = 0; n < 2; ++n) _Pragma("unroll") for (int k = 0; k < 2; ++k) \
;       dst[n][k] = *(const bf16x8*)(SB(b, h) + boff + (n * 256 + k * 1024))
; #define BAR __builtin_amdgcn_s_barrier()
; template <int EPI, int N, int K>
; __device__ __forceinline__ void phase_gemm(const Params& p, const u16* __restrict__ A, const u16* __restrict__ Bt, int nM, char* shm,
;                            u16* __restrict__ outp, float* __restrict__ rowss) {
;     ...
;     { LDB(B0, 0, 0); LDA(At, 0, 0); STAGE(SA(1, 1), A1, nt - 1);
;       BAR; WAIT_L(0); MMA(0, 0, At, B0); BAR;
;       LDB(B1, 0, 1); BAR; WAIT_L(0); MMA(0, 1, At, B1); BAR;
;       LDA(At, 0, 1); WAIT_V(4); BAR; WAIT_L(0); MMA(1, 0, At, B0); MMA(1, 1, At, B1); BAR; }
;     { LDB(B0, 1, 0); LDA(At, 1, 0); WAIT_V(2); BAR; WAIT_L(0); MMA(0, 0, At, B0); BAR;
	s_waitcnt lgkmcnt(0)
	s_waitcnt lgkmcnt(0)
	v_mfma_f32_16x16x32_bf16 v[126:129], v[164:167], v[176:179], v[126:129]
	v_mfma_f32_16x16x32_bf16 v[122:125], v[142:145], v[176:179], v[122:125]
	v_mfma_f32_16x16x32_bf16 v[118:121], v[164:167], v[196:199], v[118:121]
	v_mfma_f32_16x16x32_bf16 v[102:105], v[164:167], v[216:219], v[102:105]
	v_mfma_f32_16x16x32_bf16 v[98:101], v[142:145], v[216:219], v[98:101]
	v_mfma_f32_16x16x32_bf16 v[126:129], v[168:171], v[180:183], v[126:129]
	v_mfma_f32_16x16x32_bf16 v[122:125], v[172:175], v[180:183], v[122:125]
	v_mfma_f32_16x16x32_bf16 v[118:121], v[168:171], v[200:203], v[118:121]
	v_mfma_f32_16x16x32_bf16 v[114:117], v[142:145], v[196:199], v[114:117]
	v_mfma_f32_16x16x32_bf16 v[110:113], v[164:167], v[208:211], v[110:113]
	v_mfma_f32_16x16x32_bf16 v[106:109], v[142:145], v[208:211], v[106:109]
	v_mfma_f32_16x16x32_bf16 v[102:105], v[168:171], v[220:223], v[102:105]
	v_mfma_f32_16x16x32_bf16 v[98:101], v[172:175], v[220:223], v[98:101]
	v_mfma_f32_16x16x32_bf16 v[224:227], v[172:175], v[200:203], v[114:117]
	v_mfma_f32_16x16x32_bf16 v[228:231], v[168:171], v[212:215], v[110:113]
	v_mfma_f32_16x16x32_bf16 v[232:235], v[172:175], v[212:215], v[106:109]
	s_barrier
	s_nop 0
	ds_read_b128 v[106:109], v152
	ds_read_b128 v[110:113], v153
	ds_read_b128 v[114:117], v154
	ds_read_b128 v[152:155], v155
	s_barrier
	s_waitcnt lgkmcnt(0)
	s_waitcnt lgkmcnt(0)
	v_mfma_f32_16x16x32_bf16 v[84:87], v[106:109], v[196:199], v[84:87]
	v_mfma_f32_16x16x32_bf16 v[80:83], v[114:117], v[196:199], v[80:83]
	v_mfma_f32_16x16x32_bf16 v[68:71], v[106:109], v[216:219], v[68:71]
	v_mfma_f32_16x16x32_bf16 v[92:95], v[106:109], v[176:179], v[92:95]
	v_mfma_f32_16x16x32_bf16 v[88:91], v[114:117], v[176:179], v[88:91]
	v_mfma_f32_16x16x32_bf16 v[84:87], v[110:113], v[200:203], v[84:87]
	v_mfma_f32_16x16x32_bf16 v[80:83], v[152:155], v[200:203], v[80:83]
	v_mfma_f32_16x16x32_bf16 v[76:79], v[106:109], v[208:211], v[76:79]
	v_mfma_f32_16x16x32_bf16 v[72:75], v[114:117], v[208:211], v[72:75]
	v_mfma_f32_16x16x32_bf16 v[68:71], v[110:113], v[220:223], v[68:71]
	v_mfma_f32_16x16x32_bf16 v[64:67], v[114:117], v[216:219], v[64:67]
	v_mfma_f32_16x16x32_bf16 v[236:239], v[110:113], v[180:183], v[92:95]
	v_mfma_f32_16x16x32_bf16 v[176:179], v[152:155], v[180:183], v[88:91]
	v_mfma_f32_16x16x32_bf16 v[180:183], v[110:113], v[212:215], v[76:79]
	v_mfma_f32_16x16x32_bf16 v[196:199], v[152:155], v[212:215], v[72:75]
	v_mfma_f32_16x16x32_bf16 v[200:203], v[152:155], v[220:223], v[64:67]
	s_barrier
	s_nop 0
	ds_read_b128 v[64:67], v147 offset:16384
	ds_read_b128 v[72:75], v147 offset:17408
	ds_read_b128 v[76:79], v147 offset:18432
	ds_read_b128 v[88:91], v147 offset:19456
	ds_read_b128 v[92:95], v147 offset:20480
	ds_read_b128 v[208:211], v147 offset:21504
	ds_read_b128 v[212:215], v147 offset:22528
	ds_read_b128 v[216:219], v147 offset:23552
	s_waitcnt vmcnt(4)
	s_barrier
	s_waitcnt lgkmcnt(0)
	s_waitcnt lgkmcnt(0)
	v_mfma_f32_16x16x32_bf16 v[60:63], v[164:167], v[64:67], v[60:63]
	v_mfma_f32_16x16x32_bf16 v[52:55], v[164:167], v[76:79], v[52:55]
	v_mfma_f32_16x16x32_bf16 v[48:51], v[142:145], v[76:79], v[48:51]
	v_mfma_f32_16x16x32_bf16 v[36:39], v[164:167], v[212:215], v[36:39]
	v_mfma_f32_16x16x32_bf16 v[32:35], v[142:145], v[212:215], v[32:35]
	v_mfma_f32_16x16x32_bf16 v[60:63], v[168:171], v[72:75], v[60:63]
	v_mfma_f32_16x16x32_bf16 v[56:59], v[142:145], v[64:67], v[56:59]
	v_mfma_f32_16x16x32_bf16 v[52:55], v[168:171], v[88:91], v[52:55]
	v_mfma_f32_16x16x32_bf16 v[48:51], v[172:175], v[88:91], v[48:51]
	v_mfma_f32_16x16x32_bf16 v[44:47], v[164:167], v[92:95], v[44:47]
	v_mfma_f32_16x16x32_bf16 v[40:43], v[142:145], v[92:95], v[40:43]
	v_mfma_f32_16x16x32_bf16 v[36:39], v[168:171], v[216:219], v[36:39]
	v_mfma_f32_16x16x32_bf16 v[32:35], v[172:175], v[216:219], v[32:35]
	v_mfma_f32_16x16x32_bf16 v[220:223], v[172:175], v[72:75], v[56:59]
	v_mfma_f32_16x16x32_bf16 v[240:243], v[168:171], v[208:211], v[44:47]
	v_mfma_f32_16x16x32_bf16 v[244:247], v[172:175], v[208:211], v[40:43]
	v_mfma_f32_16x16x32_bf16 v[20:23], v[106:109], v[76:79], v[20:23]
	v_mfma_f32_16x16x32_bf16 v[16:19], v[114:117], v[76:79], v[16:19]
	v_mfma_f32_16x16x32_bf16 v[4:7], v[106:109], v[212:215], v[4:7]
	v_mfma_f32_16x16x32_bf16 v[28:31], v[106:109], v[64:67], v[28:31]
	v_mfma_f32_16x16x32_bf16 v[24:27], v[114:117], v[64:67], v[24:27]
	v_mfma_f32_16x16x32_bf16 v[20:23], v[110:113], v[88:91], v[20:23]
	v_mfma_f32_16x16x32_bf16 v[16:19], v[152:155], v[88:91], v[16:19]
	v_mfma_f32_16x16x32_bf16 v[12:15], v[106:109], v[92:95], v[12:15]
	v_mfma_f32_16x16x32_bf16 v[8:11], v[114:117], v[92:95], v[8:11]
	v_mfma_f32_16x16x32_bf16 v[4:7], v[110:113], v[216:219], v[4:7]
	v_mfma_f32_16x16x32_bf16 v[0:3], v[114:117], v[212:215], v[0:3]
	v_mfma_f32_16x16x32_bf16 v[142:145], v[110:113], v[72:75], v[28:31]
	v_mfma_f32_16x16x32_bf16 v[164:167], v[152:155], v[72:75], v[24:27]
	v_mfma_f32_16x16x32_bf16 v[168:171], v[110:113], v[208:211], v[12:15]
	v_mfma_f32_16x16x32_bf16 v[172:175], v[152:155], v[208:211], v[8:11]
	v_mfma_f32_16x16x32_bf16 v[152:155], v[152:155], v[216:219], v[0:3]
	s_barrier
; #define WAIT_V(n) asm volatile("s_waitcnt vmcnt(%0)" ::"n"(n) : "memory")
; #define WAIT_L(n) asm volatile("s_waitcnt lgkmcnt(%0)" ::"n"(n) : "memory")
; #define LDA(dst, b, h) _Pragma("unroll") for (int m = 0; m < 4; ++m) _Pragma("unroll") for (int k = 0; k < 2; ++k) \
;       dst[m][k] = *(const bf16x8*)(SA(b, h) + aoff + (m * 2048 + k * 1024))
; #define LDB(dst, b, h) _Pragma("unroll") for (int n = 0; n < 2; ++n) _Pragma("unroll") for (int k = 0; k < 2; ++k) \
;       dst[n][k] = *(const bf16x8*)(SB(b, h) + boff + (n * 256 + k * 1024))
; #define BAR __builtin_amdgcn_s_barrier()
; template <int EPI, int N, int K>
; __device__ __forceinline__ void phase_gemm(const Params& p, const u16* __restrict__ A, const u16* __restrict__ Bt, int nM, char* shm,
;                            u16* __restrict__ outp, float* __restrict__ rowss) {
;     ...
;     { LDB(B0, 1, 0); LDA(At, 1, 0); WAIT_V(2); BAR; WAIT_L(0); MMA(0, 0, At, B0); BAR;
;       LDB(B1, 1, 1); WAIT_V(0); BAR; WAIT_L(0); MMA(0, 1, At, B1); BAR;
;       LDA(At, 1, 1); BAR; WAIT_L(0); MMA(1, 0, At, B0); MMA(1, 1, At, B1); BAR; }
;     if (wr == 0) BAR;
	s_nop 0
	ds_read_b128 v[0:3], v156
	ds_read_b128 v[8:11], v157
	ds_read_b128 v[12:15], v158
	ds_read_b128 v[156:159], v159
	ds_read_b128 v[24:27], v147 offset:32768
	ds_read_b128 v[28:31], v147 offset:33792
	ds_read_b128 v[40:43], v147 offset:34816
	ds_read_b128 v[44:47], v147 offset:35840
	ds_read_b128 v[56:59], v147 offset:36864
	ds_read_b128 v[64:67], v147 offset:37888
	ds_read_b128 v[208:211], v147 offset:38912
	ds_read_b128 v[212:215], v147 offset:39936
	s_waitcnt vmcnt(2)
	s_barrier
	s_waitcnt lgkmcnt(0)
	s_waitcnt lgkmcnt(0)
	v_mfma_f32_16x16x32_bf16 v[72:75], v[0:3], v[24:27], v[126:129]
	v_mfma_f32_16x16x32_bf16 v[126:129], v[8:11], v[28:31], v[72:75]
	v_mfma_f32_16x16x32_bf16 v[72:75], v[12:15], v[24:27], v[122:125]
	v_mfma_f32_16x16x32_bf16 v[114:117], v[156:159], v[28:31], v[72:75]
	v_mfma_f32_16x16x32_bf16 v[72:75], v[0:3], v[40:43], v[118:121]
	v_mfma_f32_16x16x32_bf16 v[106:109], v[8:11], v[44:47], v[72:75]
	v_mfma_f32_16x16x32_bf16 v[72:75], v[12:15], v[40:43], v[224:227]
	v_mfma_f32_16x16x32_bf16 v[110:113], v[156:159], v[44:47], v[72:75]
	v_mfma_f32_16x16x32_bf16 v[72:75], v[0:3], v[56:59], v[228:231]
	v_mfma_f32_16x16x32_bf16 v[88:91], v[8:11], v[64:67], v[72:75]
	v_mfma_f32_16x16x32_bf16 v[72:75], v[12:15], v[56:59], v[232:235]
	v_mfma_f32_16x16x32_bf16 v[92:95], v[156:159], v[64:67], v[72:75]
	v_mfma_f32_16x16x32_bf16 v[72:75], v[0:3], v[208:211], v[102:105]
	v_mfma_f32_16x16x32_bf16 v[76:79], v[12:15], v[208:211], v[98:101]
	v_mfma_f32_16x16x32_bf16 v[72:75], v[8:11], v[212:215], v[72:75]
	v_mfma_f32_16x16x32_bf16 v[76:79], v[156:159], v[212:215], v[76:79]
	s_barrier
	ds_read_b128 v[216:219], v160
	ds_read_b128 v[224:227], v161
	ds_read_b128 v[228:231], v162
	ds_read_b128 v[160:163], v163
	s_waitcnt vmcnt(0)
	s_barrier
	s_waitcnt lgkmcnt(0)
	s_waitcnt lgkmcnt(0)
	v_mfma_f32_16x16x32_bf16 v[98:101], v[216:219], v[24:27], v[236:239]
	v_mfma_f32_16x16x32_bf16 v[24:27], v[228:231], v[24:27], v[176:179]
	v_mfma_f32_16x16x32_bf16 v[122:125], v[160:163], v[28:31], v[24:27]
	v_mfma_f32_16x16x32_bf16 v[24:27], v[216:219], v[40:43], v[84:87]
	v_mfma_f32_16x16x32_bf16 v[118:121], v[224:227], v[28:31], v[98:101]
	v_mfma_f32_16x16x32_bf16 v[98:101], v[224:227], v[44:47], v[24:27]
	v_mfma_f32_16x16x32_bf16 v[24:27], v[228:231], v[40:43], v[80:83]
	v_mfma_f32_16x16x32_bf16 v[102:105], v[160:163], v[44:47], v[24:27]
	v_mfma_f32_16x16x32_bf16 v[24:27], v[216:219], v[56:59], v[180:183]
	v_mfma_f32_16x16x32_bf16 v[80:83], v[224:227], v[64:67], v[24:27]
	v_mfma_f32_16x16x32_bf16 v[24:27], v[228:231], v[56:59], v[196:199]
	v_mfma_f32_16x16x32_bf16 v[84:87], v[160:163], v[64:67], v[24:27]
	v_mfma_f32_16x16x32_bf16 v[24:27], v[216:219], v[208:211], v[68:71]
	v_mfma_f32_16x16x32_bf16 v[64:67], v[224:227], v[212:215], v[24:27]
	v_mfma_f32_16x16x32_bf16 v[24:27], v[228:231], v[208:211], v[200:203]
	v_mfma_f32_16x16x32_bf16 v[68:71], v[160:163], v[212:215], v[24:27]
	s_barrier
	ds_read_b128 v[176:179], v147 offset:49152
	ds_read_b128 v[180:183], v147 offset:50176
	ds_read_b128 v[196:199], v147 offset:51200
	ds_read_b128 v[200:203], v147 offset:52224
	ds_read_b128 v[208:211], v147 offset:53248
	ds_read_b128 v[212:215], v147 offset:54272
	ds_read_b128 v[232:235], v147 offset:55296
	ds_read_b128 v[236:239], v147 offset:56320
	s_barrier
	s_waitcnt lgkmcnt(0)
	s_waitcnt lgkmcnt(0)
	v_mfma_f32_16x16x32_bf16 v[24:27], v[0:3], v[176:179], v[60:63]
	v_mfma_f32_16x16x32_bf16 v[56:59], v[8:11], v[180:183], v[24:27]
	v_mfma_f32_16x16x32_bf16 v[24:27], v[12:15], v[176:179], v[220:223]
	v_mfma_f32_16x16x32_bf16 v[60:63], v[156:159], v[180:183], v[24:27]
	v_mfma_f32_16x16x32_bf16 v[24:27], v[0:3], v[196:199], v[52:55]
	v_mfma_f32_16x16x32_bf16 v[40:43], v[8:11], v[200:203], v[24:27]
	v_mfma_f32_16x16x32_bf16 v[24:27], v[12:15], v[196:199], v[48:51]
	v_mfma_f32_16x16x32_bf16 v[44:47], v[156:159], v[200:203], v[24:27]
	v_mfma_f32_16x16x32_bf16 v[24:27], v[0:3], v[208:211], v[240:243]
	v_mfma_f32_16x16x32_bf16 v[0:3], v[0:3], v[232:235], v[36:39]
	v_mfma_f32_16x16x32_bf16 v[24:27], v[8:11], v[212:215], v[24:27]
	v_mfma_f32_16x16x32_bf16 v[28:31], v[12:15], v[208:211], v[244:247]
	v_mfma_f32_16x16x32_bf16 v[8:11], v[8:11], v[236:239], v[0:3]
	v_mfma_f32_16x16x32_bf16 v[0:3], v[12:15], v[232:235], v[32:35]
	v_mfma_f32_16x16x32_bf16 v[28:31], v[156:159], v[212:215], v[28:31]
	v_mfma_f32_16x16x32_bf16 v[12:15], v[156:159], v[236:239], v[0:3]
	v_mfma_f32_16x16x32_bf16 v[0:3], v[216:219], v[176:179], v[142:145]
	v_mfma_f32_16x16x32_bf16 v[48:51], v[224:227], v[180:183], v[0:3]
	v_mfma_f32_16x16x32_bf16 v[0:3], v[228:231], v[176:179], v[164:167]
	v_mfma_f32_16x16x32_bf16 v[52:55], v[160:163], v[180:183], v[0:3]
	v_mfma_f32_16x16x32_bf16 v[0:3], v[216:219], v[196:199], v[20:23]
	v_mfma_f32_16x16x32_bf16 v[32:35], v[224:227], v[200:203], v[0:3]
	v_mfma_f32_16x16x32_bf16 v[0:3], v[228:231], v[196:199], v[16:19]
	v_mfma_f32_16x16x32_bf16 v[36:39], v[160:163], v[200:203], v[0:3]
	v_mfma_f32_16x16x32_bf16 v[0:3], v[216:219], v[208:211], v[168:171]
	v_mfma_f32_16x16x32_bf16 v[16:19], v[224:227], v[212:215], v[0:3]
	v_mfma_f32_16x16x32_bf16 v[0:3], v[228:231], v[208:211], v[172:175]
	v_mfma_f32_16x16x32_bf16 v[20:23], v[160:163], v[212:215], v[0:3]
	v_mfma_f32_16x16x32_bf16 v[0:3], v[216:219], v[232:235], v[4:7]
	v_mfma_f32_16x16x32_bf16 v[4:7], v[228:231], v[232:235], v[152:155]
	v_mfma_f32_16x16x32_bf16 v[0:3], v[224:227], v[236:239], v[0:3]
	v_mfma_f32_16x16x32_bf16 v[4:7], v[160:163], v[236:239], v[4:7]
	s_andn2_b64 vcc, exec, s[16:17]
	s_barrier
	s_cbranch_vccnz .LBB0_520
	s_barrier

; #define WAIT_V(n) asm volatile("s_waitcnt vmcnt(%0)" ::"n"(n) : "memory")
; #define WAIT_L(n) asm volatile("s_waitcnt lgkmcnt(%0)" ::"n"(n) : "memory")
; #define SBAR() __builtin_amdgcn_sched_barrier(0)
; #define STAGE(P, base, kt) do { _Pragma("unroll") for (int _i = 0; _i < 2; ++_i)                                        \
;       __builtin_amdgcn_global_load_lds((const unsigned*)((base) + (size_t)(sOff[_i] + (unsigned)(kt) * (BK * 2))),        \
;                                        (unsigned*)((P) + wid * 1024 + _i * 8192), 16, 0, 0); } while (0)
; #define LDA(dst, b, h) _Pragma("unroll") for (int m = 0; m < 4; ++m) _Pragma("unroll") for (int k = 0; k < 2; ++k) \
;       dst[m][k] = *(const bf16x8*)(SA(b, h) + aoff + (m * 2048 + k * 1024))
; #define LDB(dst, b, h) _Pragma("unroll") for (int n = 0; n < 2; ++n) _Pragma("unroll") for (int k = 0; k < 2; ++k) \
;       dst[n][k] = *(const bf16x8*)(SB(b, h) + boff + (n * 256 + k * 1024))
; #define BAR __builtin_amdgcn_s_barrier()
; template <int EPI, int N, int K>
; __device__ __forceinline__ void phase_gemm(const Params& p, const u16* __restrict__ A, const u16* __restrict__ Bt, int nM, char* shm,
;                            u16* __restrict__ outp, float* __restrict__ rowss) {
;     ...
;     const char* A1 = A0 + (size_t)128 * K * 2;
;     const char* B1p = B0p + (size_t)128 * K * 2;
;     f32x4 acc[2][2][4][2] = {};
;     bf16x8 At[4][2], B0[2][2], B1[2][2];
;     if (wr == 1) BAR;
;     WAIT_V(0); BAR;
;     BAR;
;     for (int t = 0; t < nt - 2; t += 2) {
;       LDB(B0, 0, 0); SBAR(); LDA(At, 0, 0); STAGE(SA(1, 1), A1, t + 1);
;       WAIT_L(8); BAR; WAIT_L(0); MMA(0, 0, At, B0); BAR; SBAR();
;       LDB(B1, 0, 1); STAGE(SB(0, 0), B0p, t + 2);
;       BAR; WAIT_L(0); MMA(0, 1, At, B1); BAR;
;       LDA(At, 0, 1); STAGE(SA(0, 0), A0, t + 2);
;       BAR; WAIT_L(0); MMA(1, 0, At, B0); BAR; SBAR();
;       STAGE(SB(0, 1), B1p, t + 2);
;       WAIT_V(6); BAR; MMA(1, 1, At, B1); BAR;
.LBB0_552:
	s_add_u32 s14, s8, 0x40000
	s_addc_u32 s15, s9, 0
	s_waitcnt vmcnt(0)
	s_add_u32 s16, s6, 0x40000
	s_addc_u32 s17, s7, 0
	s_mov_b32 s53, -2
	v_mov_b32_e32 v140, v146
	v_mov_b32_e32 v141, v145
	s_barrier
	s_barrier
	v_or_b32_e32 v147, 0x10000, v143
	v_add_u32_e32 v149, 0x10100, v143
	v_add_u32_e32 v148, 0x10400, v143
	ds_read_b128 v[156:159], v147
	ds_read_b128 v[160:163], v148
	v_add_u32_e32 v150, 0x10500, v143
	ds_read_b128 v[164:167], v149
	ds_read_b128 v[168:171], v150
	v_add_u32_e32 v196, v142, v140
	s_add_i32 s55, s19, 0xc000
	v_add_u32_e32 v151, 0x80, v196
	s_mov_b32 m0, s55
	v_add_u32_e32 v197, v142, v141
	s_add_i32 s54, s19, 0xe000
	ds_read_b128 v[172:175], v144
	ds_read_b128 v[176:179], v144 offset:1024
	ds_read_b128 v[180:183], v144 offset:2048
	ds_read_b128 v[208:211], v144 offset:3072
	ds_read_b128 v[212:215], v144 offset:4096
	ds_read_b128 v[216:219], v144 offset:5120
	ds_read_b128 v[220:223], v144 offset:6144
	ds_read_b128 v[224:227], v144 offset:7168
	global_load_lds_dwordx4 v151, s[14:15]
	v_add_u32_e32 v151, 0x80, v197
	s_mov_b32 m0, s54
	s_nop 0
	global_load_lds_dwordx4 v151, s[14:15]
	s_waitcnt lgkmcnt(8)
	s_barrier
	s_waitcnt lgkmcnt(0)
	s_waitcnt lgkmcnt(0)
	v_mfma_f32_16x16x32_bf16 v[126:129], v[156:159], v[172:175], 0
	v_mfma_f32_16x16x32_bf16 v[122:125], v[164:167], v[172:175], 0
	v_mfma_f32_16x16x32_bf16 v[118:121], v[156:159], v[180:183], 0
	v_mfma_f32_16x16x32_bf16 v[114:117], v[164:167], v[180:183], 0
	v_mfma_f32_16x16x32_bf16 v[110:113], v[156:159], v[212:215], 0
	v_mfma_f32_16x16x32_bf16 v[106:109], v[164:167], v[212:215], 0
	v_mfma_f32_16x16x32_bf16 v[102:105], v[156:159], v[220:223], 0
	v_mfma_f32_16x16x32_bf16 v[98:101], v[164:167], v[220:223], 0
	v_mfma_f32_16x16x32_bf16 v[126:129], v[160:163], v[176:179], v[126:129]
	v_mfma_f32_16x16x32_bf16 v[122:125], v[168:171], v[176:179], v[122:125]
	v_mfma_f32_16x16x32_bf16 v[118:121], v[160:163], v[208:211], v[118:121]
	v_mfma_f32_16x16x32_bf16 v[114:117], v[168:171], v[208:211], v[114:117]
	v_mfma_f32_16x16x32_bf16 v[110:113], v[160:163], v[216:219], v[110:113]
	v_mfma_f32_16x16x32_bf16 v[106:109], v[168:171], v[216:219], v[106:109]
	v_mfma_f32_16x16x32_bf16 v[102:105], v[160:163], v[224:227], v[102:105]
	v_mfma_f32_16x16x32_bf16 v[98:101], v[168:171], v[224:227], v[98:101]
	s_barrier
	s_mov_b32 m0, s23
	v_or_b32_e32 v151, 0x14000, v143
	v_add_u32_e32 v153, 0x14100, v143
	v_add_u32_e32 v198, 0x100, v196
	v_add_u32_e32 v152, 0x14400, v143
	ds_read_b128 v[228:231], v151
	ds_read_b128 v[232:235], v152
	v_add_u32_e32 v154, 0x14500, v143
	ds_read_b128 v[236:239], v153
	ds_read_b128 v[240:243], v154
	global_load_lds_dwordx4 v198, s[6:7]
	v_add_u32_e32 v199, 0x100, v197
	s_mov_b32 m0, s92
	s_nop 0
	global_load_lds_dwordx4 v199, s[6:7]
	s_barrier
	s_waitcnt lgkmcnt(0)
	s_waitcnt lgkmcnt(0)
	v_mfma_f32_16x16x32_bf16 v[92:95], v[228:231], v[172:175], 0
	v_mfma_f32_16x16x32_bf16 v[88:91], v[236:239], v[172:175], 0
	v_mfma_f32_16x16x32_bf16 v[84:87], v[228:231], v[180:183], 0
	v_mfma_f32_16x16x32_bf16 v[80:83], v[236:239], v[180:183], 0
	v_mfma_f32_16x16x32_bf16 v[76:79], v[228:231], v[212:215], 0
	v_mfma_f32_16x16x32_bf16 v[72:75], v[236:239], v[212:215], 0
	v_mfma_f32_16x16x32_bf16 v[68:71], v[228:231], v[220:223], 0
	v_mfma_f32_16x16x32_bf16 v[64:67], v[236:239], v[220:223], 0
	v_mfma_f32_16x16x32_bf16 v[92:95], v[232:235], v[176:179], v[92:95]
	v_mfma_f32_16x16x32_bf16 v[88:91], v[240:243], v[176:179], v[88:91]
	v_mfma_f32_16x16x32_bf16 v[84:87], v[232:235], v[208:211], v[84:87]
	v_mfma_f32_16x16x32_bf16 v[80:83], v[240:243], v[208:211], v[80:83]
	v_mfma_f32_16x16x32_bf16 v[76:79], v[232:235], v[216:219], v[76:79]
	v_mfma_f32_16x16x32_bf16 v[72:75], v[240:243], v[216:219], v[72:75]
	v_mfma_f32_16x16x32_bf16 v[68:71], v[232:235], v[224:227], v[68:71]
	v_mfma_f32_16x16x32_bf16 v[64:67], v[240:243], v[224:227], v[64:67]
	s_mov_b32 m0, s19
	s_barrier
	ds_read_b128 v[172:175], v144 offset:16384
	ds_read_b128 v[176:179], v144 offset:17408
	ds_read_b128 v[180:183], v144 offset:18432
	ds_read_b128 v[208:211], v144 offset:19456
	ds_read_b128 v[212:215], v144 offset:20480
	ds_read_b128 v[216:219], v144 offset:21504
	ds_read_b128 v[220:223], v144 offset:22528
	ds_read_b128 v[224:227], v144 offset:23552
	global_load_lds_dwordx4 v198, s[8:9]
	s_mov_b32 m0, s22
	s_nop 0
	global_load_lds_dwordx4 v199, s[8:9]
	s_barrier
	s_waitcnt lgkmcnt(0)
	s_waitcnt lgkmcnt(0)
	v_mfma_f32_16x16x32_bf16 v[60:63], v[156:159], v[172:175], 0
	v_mfma_f32_16x16x32_bf16 v[56:59], v[164:167], v[172:175], 0
	v_mfma_f32_16x16x32_bf16 v[52:55], v[156:159], v[180:183], 0
	v_mfma_f32_16x16x32_bf16 v[48:51], v[164:167], v[180:183], 0
	v_mfma_f32_16x16x32_bf16 v[44:47], v[156:159], v[212:215], 0
	v_mfma_f32_16x16x32_bf16 v[40:43], v[164:167], v[212:215], 0
	v_mfma_f32_16x16x32_bf16 v[36:39], v[156:159], v[220:223], 0
	v_mfma_f32_16x16x32_bf16 v[32:35], v[164:167], v[220:223], 0
	v_mfma_f32_16x16x32_bf16 v[60:63], v[160:163], v[176:179], v[60:63]
	v_mfma_f32_16x16x32_bf16 v[56:59], v[168:171], v[176:179], v[56:59]
	v_mfma_f32_16x16x32_bf16 v[52:55], v[160:163], v[208:211], v[52:55]
	v_mfma_f32_16x16x32_bf16 v[48:51], v[168:171], v[208:211], v[48:51]
	v_mfma_f32_16x16x32_bf16 v[44:47], v[160:163], v[216:219], v[44:47]
	v_mfma_f32_16x16x32_bf16 v[40:43], v[168:171], v[216:219], v[40:43]
	v_mfma_f32_16x16x32_bf16 v[36:39], v[160:163], v[224:227], v[36:39]
	v_mfma_f32_16x16x32_bf16 v[32:35], v[168:171], v[224:227], v[32:35]
	s_barrier
	s_mov_b32 m0, s94
	s_nop 0
	global_load_lds_dwordx4 v198, s[16:17]
	s_mov_b32 m0, s95
	s_nop 0
	global_load_lds_dwordx4 v199, s[16:17]
	s_waitcnt vmcnt(6)
	s_barrier
; #define WAIT_V(n) asm volatile("s_waitcnt vmcnt(%0)" ::"n"(n) : "memory")
; #define WAIT_L(n) asm volatile("s_waitcnt lgkmcnt(%0)" ::"n"(n) : "memory")
; #define SBAR() __builtin_amdgcn_sched_barrier(0)
; #define STAGE(P, base, kt) do { _Pragma("unroll") for (int _i = 0; _i < 2; ++_i)                                        \
;       __builtin_amdgcn_global_load_lds((const unsigned*)((base) + (size_t)(sOff[_i] + (unsigned)(kt) * (BK * 2))),        \
;                                        (unsigned*)((P) + wid * 1024 + _i * 8192), 16, 0, 0); } while (0)
; #define LDA(dst, b, h) _Pragma("unroll") for (int m = 0; m < 4; ++m) _Pragma("unroll") for (int k = 0; k < 2; ++k) \
;       dst[m][k] = *(const bf16x8*)(SA(b, h) + aoff + (m * 2048 + k * 1024))
; #define LDB(dst, b, h) _Pragma("unroll") for (int n = 0; n < 2; ++n) _Pragma("unroll") for (int k = 0; k < 2; ++k) \
;       dst[n][k] = *(const bf16x8*)(SB(b, h) + boff + (n * 256 + k * 1024))
; #define BAR __builtin_amdgcn_s_barrier()
; template <int EPI, int N, int K>
; __device__ __forceinline__ void phase_gemm(const Params& p, const u16* __restrict__ A, const u16* __restrict__ Bt, int nM, char* shm,
;                            u16* __restrict__ outp, float* __restrict__ rowss) {
;     ...
;       WAIT_V(6); BAR; MMA(1, 1, At, B1); BAR;
;       LDB(B0, 1, 0); SBAR(); LDA(At, 1, 0); STAGE(SA(0, 1), A1, t + 2);
;       WAIT_L(8); BAR; WAIT_L(0); MMA(0, 0, At, B0); BAR; SBAR();
;       LDB(B1, 1, 1); STAGE(SB(1, 0), B0p, t + 3);
;       BAR; WAIT_L(0); MMA(0, 1, At, B1); BAR;
;       LDA(At, 1, 1); STAGE(SA(1, 0), A0, t + 3);
;       BAR; WAIT_L(0); MMA(1, 0, At, B0); BAR; SBAR();
;       STAGE(SB(1, 1), B1p, t + 3);
	v_mfma_f32_16x16x32_bf16 v[28:31], v[228:231], v[172:175], 0
	v_mfma_f32_16x16x32_bf16 v[24:27], v[236:239], v[172:175], 0
	v_mfma_f32_16x16x32_bf16 v[20:23], v[228:231], v[180:183], 0
	v_mfma_f32_16x16x32_bf16 v[16:19], v[236:239], v[180:183], 0
	v_mfma_f32_16x16x32_bf16 v[12:15], v[228:231], v[212:215], 0
	v_mfma_f32_16x16x32_bf16 v[8:11], v[236:239], v[212:215], 0
	v_mfma_f32_16x16x32_bf16 v[4:7], v[228:231], v[220:223], 0
	v_mfma_f32_16x16x32_bf16 v[0:3], v[236:239], v[220:223], 0
	v_mfma_f32_16x16x32_bf16 v[28:31], v[232:235], v[176:179], v[28:31]
	v_mfma_f32_16x16x32_bf16 v[24:27], v[240:243], v[176:179], v[24:27]
	v_mfma_f32_16x16x32_bf16 v[20:23], v[232:235], v[208:211], v[20:23]
	v_mfma_f32_16x16x32_bf16 v[16:19], v[240:243], v[208:211], v[16:19]
	v_mfma_f32_16x16x32_bf16 v[12:15], v[232:235], v[216:219], v[12:15]
	v_mfma_f32_16x16x32_bf16 v[8:11], v[240:243], v[216:219], v[8:11]
	v_mfma_f32_16x16x32_bf16 v[4:7], v[232:235], v[224:227], v[4:7]
	v_mfma_f32_16x16x32_bf16 v[0:3], v[240:243], v[224:227], v[0:3]
	v_or_b32_e32 v155, 0x18000, v143
	v_add_u32_e32 v157, 0x18100, v143
	s_barrier
	v_add_u32_e32 v156, 0x18400, v143
	ds_read_b128 v[164:167], v155
	ds_read_b128 v[168:171], v156
	v_add_u32_e32 v158, 0x18500, v143
	ds_read_b128 v[172:175], v157
	ds_read_b128 v[176:179], v158
	s_mov_b32 m0, s96
	ds_read_b128 v[180:183], v144 offset:32768
	ds_read_b128 v[208:211], v144 offset:33792
	ds_read_b128 v[212:215], v144 offset:34816
	ds_read_b128 v[216:219], v144 offset:35840
	ds_read_b128 v[220:223], v144 offset:36864
	ds_read_b128 v[224:227], v144 offset:37888
	ds_read_b128 v[228:231], v144 offset:38912
	ds_read_b128 v[232:235], v144 offset:39936
	global_load_lds_dwordx4 v198, s[14:15]
	s_mov_b32 m0, s33
	s_nop 0
	global_load_lds_dwordx4 v199, s[14:15]
	s_waitcnt lgkmcnt(8)
	s_barrier
	s_waitcnt lgkmcnt(0)
	s_waitcnt lgkmcnt(0)
	v_mfma_f32_16x16x32_bf16 v[126:129], v[164:167], v[180:183], v[126:129]
	v_mfma_f32_16x16x32_bf16 v[122:125], v[172:175], v[180:183], v[122:125]
	v_mfma_f32_16x16x32_bf16 v[118:121], v[164:167], v[212:215], v[118:121]
	v_mfma_f32_16x16x32_bf16 v[114:117], v[172:175], v[212:215], v[114:117]
	v_mfma_f32_16x16x32_bf16 v[110:113], v[164:167], v[220:223], v[110:113]
	v_mfma_f32_16x16x32_bf16 v[106:109], v[172:175], v[220:223], v[106:109]
	v_mfma_f32_16x16x32_bf16 v[102:105], v[164:167], v[228:231], v[102:105]
	v_mfma_f32_16x16x32_bf16 v[98:101], v[172:175], v[228:231], v[98:101]
	v_mfma_f32_16x16x32_bf16 v[126:129], v[168:171], v[208:211], v[126:129]
	v_mfma_f32_16x16x32_bf16 v[122:125], v[176:179], v[208:211], v[122:125]
	v_mfma_f32_16x16x32_bf16 v[118:121], v[168:171], v[216:219], v[118:121]
	v_mfma_f32_16x16x32_bf16 v[114:117], v[176:179], v[216:219], v[114:117]
	v_mfma_f32_16x16x32_bf16 v[110:113], v[168:171], v[224:227], v[110:113]
	v_mfma_f32_16x16x32_bf16 v[106:109], v[176:179], v[224:227], v[106:109]
	v_mfma_f32_16x16x32_bf16 v[102:105], v[168:171], v[232:235], v[102:105]
	v_mfma_f32_16x16x32_bf16 v[98:101], v[176:179], v[232:235], v[98:101]
	s_barrier
	s_mov_b32 m0, s35
	v_or_b32_e32 v159, 0x1c000, v143
	v_add_u32_e32 v161, 0x1c100, v143
	v_add_u32_e32 v163, 0x180, v196
	v_add_u32_e32 v160, 0x1c400, v143
	ds_read_b128 v[236:239], v159
	ds_read_b128 v[240:243], v160
	v_add_u32_e32 v162, 0x1c500, v143
	ds_read_b128 v[244:247], v161
	ds_read_b128 v[248:251], v162
	global_load_lds_dwordx4 v163, s[6:7]
	v_add_u32_e32 v196, 0x180, v197
	s_mov_b32 m0, s93
	s_nop 0
	global_load_lds_dwordx4 v196, s[6:7]
	s_barrier
	s_waitcnt lgkmcnt(0)
	s_waitcnt lgkmcnt(0)
	v_mfma_f32_16x16x32_bf16 v[92:95], v[236:239], v[180:183], v[92:95]
	v_mfma_f32_16x16x32_bf16 v[88:91], v[244:247], v[180:183], v[88:91]
	v_mfma_f32_16x16x32_bf16 v[84:87], v[236:239], v[212:215], v[84:87]
	v_mfma_f32_16x16x32_bf16 v[80:83], v[244:247], v[212:215], v[80:83]
	v_mfma_f32_16x16x32_bf16 v[76:79], v[236:239], v[220:223], v[76:79]
	v_mfma_f32_16x16x32_bf16 v[72:75], v[244:247], v[220:223], v[72:75]
	v_mfma_f32_16x16x32_bf16 v[68:71], v[236:239], v[228:231], v[68:71]
	v_mfma_f32_16x16x32_bf16 v[64:67], v[244:247], v[228:231], v[64:67]
	v_mfma_f32_16x16x32_bf16 v[92:95], v[240:243], v[208:211], v[92:95]
	v_mfma_f32_16x16x32_bf16 v[88:91], v[248:251], v[208:211], v[88:91]
	v_mfma_f32_16x16x32_bf16 v[84:87], v[240:243], v[216:219], v[84:87]
	v_mfma_f32_16x16x32_bf16 v[80:83], v[248:251], v[216:219], v[80:83]
	v_mfma_f32_16x16x32_bf16 v[76:79], v[240:243], v[224:227], v[76:79]
	v_mfma_f32_16x16x32_bf16 v[72:75], v[248:251], v[224:227], v[72:75]
	v_mfma_f32_16x16x32_bf16 v[68:71], v[240:243], v[232:235], v[68:71]
	v_mfma_f32_16x16x32_bf16 v[64:67], v[248:251], v[232:235], v[64:67]
	s_mov_b32 m0, s24
	s_barrier
	ds_read_b128 v[180:183], v144 offset:49152
	ds_read_b128 v[208:211], v144 offset:50176
	ds_read_b128 v[212:215], v144 offset:51200
	ds_read_b128 v[216:219], v144 offset:52224
	ds_read_b128 v[220:223], v144 offset:53248
	ds_read_b128 v[224:227], v144 offset:54272
	ds_read_b128 v[228:231], v144 offset:55296
	ds_read_b128 v[232:235], v144 offset:56320
	global_load_lds_dwordx4 v163, s[8:9]
	s_mov_b32 m0, s25
	s_nop 0
	global_load_lds_dwordx4 v196, s[8:9]
	s_barrier
; #define WAIT_V(n) asm volatile("s_waitcnt vmcnt(%0)" ::"n"(n) : "memory")
; #define WAIT_L(n) asm volatile("s_waitcnt lgkmcnt(%0)" ::"n"(n) : "memory")
; #define SBAR() __builtin_amdgcn_sched_barrier(0)
; #define STAGE(P, base, kt) do { _Pragma("unroll") for (int _i = 0; _i < 2; ++_i)                                        \
;       __builtin_amdgcn_global_load_lds((const unsigned*)((base) + (size_t)(sOff[_i] + (unsigned)(kt) * (BK * 2))),        \
;                                        (unsigned*)((P) + wid * 1024 + _i * 8192), 16, 0, 0); } while (0)
; #define LDA(dst, b, h) _Pragma("unroll") for (int m = 0; m < 4; ++m) _Pragma("unroll") for (int k = 0; k < 2; ++k) \
;       dst[m][k] = *(const bf16x8*)(SA(b, h) + aoff + (m * 2048 + k * 1024))
; #define LDB(dst, b, h) _Pragma("unroll") for (int n = 0; n < 2; ++n) _Pragma("unroll") for (int k = 0; k < 2; ++k) \
;       dst[n][k] = *(const bf16x8*)(SB(b, h) + boff + (n * 256 + k * 1024))
; #define BAR __builtin_amdgcn_s_barrier()
; template <int EPI, int N, int K>
; __device__ __forceinline__ void phase_gemm(const Params& p, const u16* __restrict__ A, const u16* __restrict__ Bt, int nM, char* shm,
;                            u16* __restrict__ outp, float* __restrict__ rowss) {
;     ...
;       LDB(B0, 0, 0); SBAR(); LDA(At, 0, 0); STAGE(SA(1, 1), A1, t + 1);
;       WAIT_L(8); BAR; WAIT_L(0); MMA(0, 0, At, B0); BAR; SBAR();
;       LDB(B1, 0, 1); STAGE(SB(0, 0), B0p, t + 2);
;     ...
;       BAR; WAIT_L(0); MMA(1, 0, At, B0); BAR; SBAR();
;       STAGE(SB(1, 1), B1p, t + 3);
;       WAIT_V(6); BAR; MMA(1, 1, At, B1); BAR;
	s_waitcnt lgkmcnt(0)
	s_waitcnt lgkmcnt(0)
	v_mfma_f32_16x16x32_bf16 v[60:63], v[164:167], v[180:183], v[60:63]
	v_mfma_f32_16x16x32_bf16 v[56:59], v[172:175], v[180:183], v[56:59]
	v_mfma_f32_16x16x32_bf16 v[52:55], v[164:167], v[212:215], v[52:55]
	v_mfma_f32_16x16x32_bf16 v[48:51], v[172:175], v[212:215], v[48:51]
	v_mfma_f32_16x16x32_bf16 v[44:47], v[164:167], v[220:223], v[44:47]
	v_mfma_f32_16x16x32_bf16 v[40:43], v[172:175], v[220:223], v[40:43]
	v_mfma_f32_16x16x32_bf16 v[36:39], v[164:167], v[228:231], v[36:39]
	v_mfma_f32_16x16x32_bf16 v[32:35], v[172:175], v[228:231], v[32:35]
	v_mfma_f32_16x16x32_bf16 v[60:63], v[168:171], v[208:211], v[60:63]
	v_mfma_f32_16x16x32_bf16 v[56:59], v[176:179], v[208:211], v[56:59]
	v_mfma_f32_16x16x32_bf16 v[52:55], v[168:171], v[216:219], v[52:55]
	v_mfma_f32_16x16x32_bf16 v[48:51], v[176:179], v[216:219], v[48:51]
	v_mfma_f32_16x16x32_bf16 v[44:47], v[168:171], v[224:227], v[44:47]
	v_mfma_f32_16x16x32_bf16 v[40:43], v[176:179], v[224:227], v[40:43]
	v_mfma_f32_16x16x32_bf16 v[36:39], v[168:171], v[232:235], v[36:39]
	v_mfma_f32_16x16x32_bf16 v[32:35], v[176:179], v[232:235], v[32:35]
	s_barrier
	s_mov_b32 m0, s26
	s_nop 0
	global_load_lds_dwordx4 v163, s[16:17]
	s_mov_b32 m0, s27
	s_nop 0
	global_load_lds_dwordx4 v196, s[16:17]
	s_waitcnt vmcnt(6)
	s_barrier
	v_mfma_f32_16x16x32_bf16 v[28:31], v[236:239], v[180:183], v[28:31]
	v_mfma_f32_16x16x32_bf16 v[24:27], v[244:247], v[180:183], v[24:27]
	v_mfma_f32_16x16x32_bf16 v[20:23], v[236:239], v[212:215], v[20:23]
	v_mfma_f32_16x16x32_bf16 v[16:19], v[244:247], v[212:215], v[16:19]
	v_mfma_f32_16x16x32_bf16 v[12:15], v[236:239], v[220:223], v[12:15]
	v_mfma_f32_16x16x32_bf16 v[8:11], v[244:247], v[220:223], v[8:11]
	v_mfma_f32_16x16x32_bf16 v[4:7], v[236:239], v[228:231], v[4:7]
	v_mfma_f32_16x16x32_bf16 v[0:3], v[244:247], v[228:231], v[0:3]
	v_mfma_f32_16x16x32_bf16 v[28:31], v[240:243], v[208:211], v[28:31]
	v_mfma_f32_16x16x32_bf16 v[24:27], v[248:251], v[208:211], v[24:27]
	v_mfma_f32_16x16x32_bf16 v[20:23], v[240:243], v[216:219], v[20:23]
	v_mfma_f32_16x16x32_bf16 v[16:19], v[248:251], v[216:219], v[16:19]
	v_mfma_f32_16x16x32_bf16 v[12:15], v[240:243], v[224:227], v[12:15]
	v_mfma_f32_16x16x32_bf16 v[8:11], v[248:251], v[224:227], v[8:11]
	v_mfma_f32_16x16x32_bf16 v[4:7], v[240:243], v[232:235], v[4:7]
	v_mfma_f32_16x16x32_bf16 v[0:3], v[248:251], v[232:235], v[0:3]
	s_add_i32 s53, s53, 2
	v_add_u32_e32 v141, 0x100, v141
	s_cmp_lt_u32 s53, 12
	v_add_u32_e32 v140, 0x100, v140
	s_barrier
.LBB0_553:
	v_or_b32_e32 v147, 0x10000, v143
	v_add_u32_e32 v149, 0x10100, v143
	v_add_u32_e32 v148, 0x10400, v143
	ds_read_b128 v[156:159], v147
	ds_read_b128 v[160:163], v148
	v_add_u32_e32 v150, 0x10500, v143
	ds_read_b128 v[164:167], v149
	ds_read_b128 v[168:171], v150
	v_add_u32_e32 v196, v142, v140
	s_add_i32 s55, s19, 0xc000
	v_add_u32_e32 v151, 0x80, v196
	s_mov_b32 m0, s55
	v_add_u32_e32 v197, v142, v141
	s_add_i32 s54, s19, 0xe000
	ds_read_b128 v[172:175], v144
	ds_read_b128 v[176:179], v144 offset:1024
	ds_read_b128 v[180:183], v144 offset:2048
	ds_read_b128 v[208:211], v144 offset:3072
	ds_read_b128 v[212:215], v144 offset:4096
	ds_read_b128 v[216:219], v144 offset:5120
	ds_read_b128 v[220:223], v144 offset:6144
	ds_read_b128 v[224:227], v144 offset:7168
	global_load_lds_dwordx4 v151, s[14:15]
	v_add_u32_e32 v151, 0x80, v197
	s_mov_b32 m0, s54
	s_nop 0
	global_load_lds_dwordx4 v151, s[14:15]
	s_waitcnt lgkmcnt(8)
	s_barrier
	s_waitcnt lgkmcnt(0)
	s_waitcnt lgkmcnt(0)
	v_mfma_f32_16x16x32_bf16 v[126:129], v[156:159], v[172:175], v[126:129]
	v_mfma_f32_16x16x32_bf16 v[122:125], v[164:167], v[172:175], v[122:125]
	v_mfma_f32_16x16x32_bf16 v[118:121], v[156:159], v[180:183], v[118:121]
	v_mfma_f32_16x16x32_bf16 v[114:117], v[164:167], v[180:183], v[114:117]
	v_mfma_f32_16x16x32_bf16 v[110:113], v[156:159], v[212:215], v[110:113]
	v_mfma_f32_16x16x32_bf16 v[106:109], v[164:167], v[212:215], v[106:109]
	v_mfma_f32_16x16x32_bf16 v[102:105], v[156:159], v[220:223], v[102:105]
	v_mfma_f32_16x16x32_bf16 v[98:101], v[164:167], v[220:223], v[98:101]
	v_mfma_f32_16x16x32_bf16 v[126:129], v[160:163], v[176:179], v[126:129]
	v_mfma_f32_16x16x32_bf16 v[122:125], v[168:171], v[176:179], v[122:125]
	v_mfma_f32_16x16x32_bf16 v[118:121], v[160:163], v[208:211], v[118:121]
	v_mfma_f32_16x16x32_bf16 v[114:117], v[168:171], v[208:211], v[114:117]
	v_mfma_f32_16x16x32_bf16 v[110:113], v[160:163], v[216:219], v[110:113]
	v_mfma_f32_16x16x32_bf16 v[106:109], v[168:171], v[216:219], v[106:109]
	v_mfma_f32_16x16x32_bf16 v[102:105], v[160:163], v[224:227], v[102:105]
	v_mfma_f32_16x16x32_bf16 v[98:101], v[168:171], v[224:227], v[98:101]
	s_barrier
	s_mov_b32 m0, s23
	v_or_b32_e32 v151, 0x14000, v143
	v_add_u32_e32 v153, 0x14100, v143
	v_add_u32_e32 v198, 0x100, v196
	v_add_u32_e32 v152, 0x14400, v143
	ds_read_b128 v[228:231], v151
	ds_read_b128 v[232:235], v152
	v_add_u32_e32 v154, 0x14500, v143
	ds_read_b128 v[236:239], v153
	ds_read_b128 v[240:243], v154
	global_load_lds_dwordx4 v198, s[6:7]
	v_add_u32_e32 v199, 0x100, v197
	s_mov_b32 m0, s92
	s_nop 0
	global_load_lds_dwordx4 v199, s[6:7]
	s_barrier
; #define WAIT_V(n) asm volatile("s_waitcnt vmcnt(%0)" ::"n"(n) : "memory")
; #define WAIT_L(n) asm volatile("s_waitcnt lgkmcnt(%0)" ::"n"(n) : "memory")
; #define SBAR() __builtin_amdgcn_sched_barrier(0)
; #define STAGE(P, base, kt) do { _Pragma("unroll") for (int _i = 0; _i < 2; ++_i)                                        \
;       __builtin_amdgcn_global_load_lds((const unsigned*)((base) + (size_t)(sOff[_i] + (unsigned)(kt) * (BK * 2))),        \
;                                        (unsigned*)((P) + wid * 1024 + _i * 8192), 16, 0, 0); } while (0)
; #define LDA(dst, b, h) _Pragma("unroll") for (int m = 0; m < 4; ++m) _Pragma("unroll") for (int k = 0; k < 2; ++k) \
;       dst[m][k] = *(const bf16x8*)(SA(b, h) + aoff + (m * 2048 + k * 1024))
; #define LDB(dst, b, h) _Pragma("unroll") for (int n = 0; n < 2; ++n) _Pragma("unroll") for (int k = 0; k < 2; ++k) \
;       dst[n][k] = *(const bf16x8*)(SB(b, h) + boff + (n * 256 + k * 1024))
; #define BAR __builtin_amdgcn_s_barrier()
; template <int EPI, int N, int K>
; __device__ __forceinline__ void phase_gemm(const Params& p, const u16* __restrict__ A, const u16* __restrict__ Bt, int nM, char* shm,
;                            u16* __restrict__ outp, float* __restrict__ rowss) {
;     ...
;       BAR; WAIT_L(0); MMA(0, 1, At, B1); BAR;
;       LDA(At, 0, 1); STAGE(SA(0, 0), A0, t + 2);
;       BAR; WAIT_L(0); MMA(1, 0, At, B0); BAR; SBAR();
;       STAGE(SB(0, 1), B1p, t + 2);
;       WAIT_V(6); BAR; MMA(1, 1, At, B1); BAR;
;       LDB(B0, 1, 0); SBAR(); LDA(At, 1, 0); STAGE(SA(0, 1), A1, t + 2);
;       WAIT_L(8); BAR; WAIT_L(0); MMA(0, 0, At, B0); BAR; SBAR();
	s_waitcnt lgkmcnt(0)
	s_waitcnt lgkmcnt(0)
	v_mfma_f32_16x16x32_bf16 v[92:95], v[228:231], v[172:175], v[92:95]
	v_mfma_f32_16x16x32_bf16 v[88:91], v[236:239], v[172:175], v[88:91]
	v_mfma_f32_16x16x32_bf16 v[84:87], v[228:231], v[180:183], v[84:87]
	v_mfma_f32_16x16x32_bf16 v[80:83], v[236:239], v[180:183], v[80:83]
	v_mfma_f32_16x16x32_bf16 v[76:79], v[228:231], v[212:215], v[76:79]
	v_mfma_f32_16x16x32_bf16 v[72:75], v[236:239], v[212:215], v[72:75]
	v_mfma_f32_16x16x32_bf16 v[68:71], v[228:231], v[220:223], v[68:71]
	v_mfma_f32_16x16x32_bf16 v[64:67], v[236:239], v[220:223], v[64:67]
	v_mfma_f32_16x16x32_bf16 v[92:95], v[232:235], v[176:179], v[92:95]
	v_mfma_f32_16x16x32_bf16 v[88:91], v[240:243], v[176:179], v[88:91]
	v_mfma_f32_16x16x32_bf16 v[84:87], v[232:235], v[208:211], v[84:87]
	v_mfma_f32_16x16x32_bf16 v[80:83], v[240:243], v[208:211], v[80:83]
	v_mfma_f32_16x16x32_bf16 v[76:79], v[232:235], v[216:219], v[76:79]
	v_mfma_f32_16x16x32_bf16 v[72:75], v[240:243], v[216:219], v[72:75]
	v_mfma_f32_16x16x32_bf16 v[68:71], v[232:235], v[224:227], v[68:71]
	v_mfma_f32_16x16x32_bf16 v[64:67], v[240:243], v[224:227], v[64:67]
	s_mov_b32 m0, s19
	s_barrier
	ds_read_b128 v[172:175], v144 offset:16384
	ds_read_b128 v[176:179], v144 offset:17408
	ds_read_b128 v[180:183], v144 offset:18432
	ds_read_b128 v[208:211], v144 offset:19456
	ds_read_b128 v[212:215], v144 offset:20480
	ds_read_b128 v[216:219], v144 offset:21504
	ds_read_b128 v[220:223], v144 offset:22528
	ds_read_b128 v[224:227], v144 offset:23552
	global_load_lds_dwordx4 v198, s[8:9]
	s_mov_b32 m0, s22
	s_nop 0
	global_load_lds_dwordx4 v199, s[8:9]
	s_barrier
	s_waitcnt lgkmcnt(0)
	s_waitcnt lgkmcnt(0)
	v_mfma_f32_16x16x32_bf16 v[60:63], v[156:159], v[172:175], v[60:63]
	v_mfma_f32_16x16x32_bf16 v[56:59], v[164:167], v[172:175], v[56:59]
	v_mfma_f32_16x16x32_bf16 v[52:55], v[156:159], v[180:183], v[52:55]
	v_mfma_f32_16x16x32_bf16 v[48:51], v[164:167], v[180:183], v[48:51]
	v_mfma_f32_16x16x32_bf16 v[44:47], v[156:159], v[212:215], v[44:47]
	v_mfma_f32_16x16x32_bf16 v[40:43], v[164:167], v[212:215], v[40:43]
	v_mfma_f32_16x16x32_bf16 v[36:39], v[156:159], v[220:223], v[36:39]
	v_mfma_f32_16x16x32_bf16 v[32:35], v[164:167], v[220:223], v[32:35]
	v_mfma_f32_16x16x32_bf16 v[60:63], v[160:163], v[176:179], v[60:63]
	v_mfma_f32_16x16x32_bf16 v[56:59], v[168:171], v[176:179], v[56:59]
	v_mfma_f32_16x16x32_bf16 v[52:55], v[160:163], v[208:211], v[52:55]
	v_mfma_f32_16x16x32_bf16 v[48:51], v[168:171], v[208:211], v[48:51]
	v_mfma_f32_16x16x32_bf16 v[44:47], v[160:163], v[216:219], v[44:47]
	v_mfma_f32_16x16x32_bf16 v[40:43], v[168:171], v[216:219], v[40:43]
	v_mfma_f32_16x16x32_bf16 v[36:39], v[160:163], v[224:227], v[36:39]
	v_mfma_f32_16x16x32_bf16 v[32:35], v[168:171], v[224:227], v[32:35]
	s_barrier
	s_mov_b32 m0, s94
	s_nop 0
	global_load_lds_dwordx4 v198, s[16:17]
	s_mov_b32 m0, s95
	s_nop 0
	global_load_lds_dwordx4 v199, s[16:17]
	s_waitcnt vmcnt(6)
	s_barrier
	v_mfma_f32_16x16x32_bf16 v[28:31], v[228:231], v[172:175], v[28:31]
	v_mfma_f32_16x16x32_bf16 v[24:27], v[236:239], v[172:175], v[24:27]
	v_mfma_f32_16x16x32_bf16 v[20:23], v[228:231], v[180:183], v[20:23]
	v_mfma_f32_16x16x32_bf16 v[16:19], v[236:239], v[180:183], v[16:19]
	v_mfma_f32_16x16x32_bf16 v[12:15], v[228:231], v[212:215], v[12:15]
	v_mfma_f32_16x16x32_bf16 v[8:11], v[236:239], v[212:215], v[8:11]
	v_mfma_f32_16x16x32_bf16 v[4:7], v[228:231], v[220:223], v[4:7]
	v_mfma_f32_16x16x32_bf16 v[0:3], v[236:239], v[220:223], v[0:3]
	v_mfma_f32_16x16x32_bf16 v[28:31], v[232:235], v[176:179], v[28:31]
	v_mfma_f32_16x16x32_bf16 v[24:27], v[240:243], v[176:179], v[24:27]
	v_mfma_f32_16x16x32_bf16 v[20:23], v[232:235], v[208:211], v[20:23]
	v_mfma_f32_16x16x32_bf16 v[16:19], v[240:243], v[208:211], v[16:19]
	v_mfma_f32_16x16x32_bf16 v[12:15], v[232:235], v[216:219], v[12:15]
	v_mfma_f32_16x16x32_bf16 v[8:11], v[240:243], v[216:219], v[8:11]
	v_mfma_f32_16x16x32_bf16 v[4:7], v[232:235], v[224:227], v[4:7]
	v_mfma_f32_16x16x32_bf16 v[0:3], v[240:243], v[224:227], v[0:3]
	v_or_b32_e32 v155, 0x18000, v143
	v_add_u32_e32 v157, 0x18100, v143
	s_barrier
	v_add_u32_e32 v156, 0x18400, v143
	ds_read_b128 v[164:167], v155
	ds_read_b128 v[168:171], v156
	v_add_u32_e32 v158, 0x18500, v143
	ds_read_b128 v[172:175], v157
	ds_read_b128 v[176:179], v158
	s_mov_b32 m0, s96
	ds_read_b128 v[180:183], v144 offset:32768
	ds_read_b128 v[208:211], v144 offset:33792
	ds_read_b128 v[212:215], v144 offset:34816
	ds_read_b128 v[216:219], v144 offset:35840
	ds_read_b128 v[220:223], v144 offset:36864
	ds_read_b128 v[224:227], v144 offset:37888
	ds_read_b128 v[228:231], v144 offset:38912
	ds_read_b128 v[232:235], v144 offset:39936
	global_load_lds_dwordx4 v198, s[14:15]
	s_mov_b32 m0, s33
	s_nop 0
	global_load_lds_dwordx4 v199, s[14:15]
	s_waitcnt lgkmcnt(8)
	s_barrier
	s_waitcnt lgkmcnt(0)
	s_waitcnt lgkmcnt(0)
	v_mfma_f32_16x16x32_bf16 v[126:129], v[164:167], v[180:183], v[126:129]
	v_mfma_f32_16x16x32_bf16 v[122:125], v[172:175], v[180:183], v[122:125]
	v_mfma_f32_16x16x32_bf16 v[118:121], v[164:167], v[212:215], v[118:121]
	v_mfma_f32_16x16x32_bf16 v[114:117], v[172:175], v[212:215], v[114:117]
	v_mfma_f32_16x16x32_bf16 v[110:113], v[164:167], v[220:223], v[110:113]
	v_mfma_f32_16x16x32_bf16 v[106:109], v[172:175], v[220:223], v[106:109]
	v_mfma_f32_16x16x32_bf16 v[102:105], v[164:167], v[228:231], v[102:105]
	v_mfma_f32_16x16x32_bf16 v[98:101], v[172:175], v[228:231], v[98:101]
	v_mfma_f32_16x16x32_bf16 v[126:129], v[168:171], v[208:211], v[126:129]
	v_mfma_f32_16x16x32_bf16 v[122:125], v[176:179], v[208:211], v[122:125]
	v_mfma_f32_16x16x32_bf16 v[118:121], v[168:171], v[216:219], v[118:121]
	v_mfma_f32_16x16x32_bf16 v[114:117], v[176:179], v[216:219], v[114:117]
	v_mfma_f32_16x16x32_bf16 v[110:113], v[168:171], v[224:227], v[110:113]
	v_mfma_f32_16x16x32_bf16 v[106:109], v[176:179], v[224:227], v[106:109]
	v_mfma_f32_16x16x32_bf16 v[102:105], v[168:171], v[232:235], v[102:105]
	v_mfma_f32_16x16x32_bf16 v[98:101], v[176:179], v[232:235], v[98:101]
	s_barrier
; #define WAIT_V(n) asm volatile("s_waitcnt vmcnt(%0)" ::"n"(n) : "memory")
; #define WAIT_L(n) asm volatile("s_waitcnt lgkmcnt(%0)" ::"n"(n) : "memory")
; #define SBAR() __builtin_amdgcn_sched_barrier(0)
; #define STAGE(P, base, kt) do { _Pragma("unroll") for (int _i = 0; _i < 2; ++_i)                                        \
;       __builtin_amdgcn_global_load_lds((const unsigned*)((base) + (size_t)(sOff[_i] + (unsigned)(kt) * (BK * 2))),        \
;                                        (unsigned*)((P) + wid * 1024 + _i * 8192), 16, 0, 0); } while (0)
; #define LDA(dst, b, h) _Pragma("unroll") for (int m = 0; m < 4; ++m) _Pragma("unroll") for (int k = 0; k < 2; ++k) \
;       dst[m][k] = *(const bf16x8*)(SA(b, h) + aoff + (m * 2048 + k * 1024))
; #define LDB(dst, b, h) _Pragma("unroll") for (int n = 0; n < 2; ++n) _Pragma("unroll") for (int k = 0; k < 2; ++k) \
;       dst[n][k] = *(const bf16x8*)(SB(b, h) + boff + (n * 256 + k * 1024))
; #define BAR __builtin_amdgcn_s_barrier()
; template <int EPI, int N, int K>
; __device__ __forceinline__ void phase_gemm(const Params& p, const u16* __restrict__ A, const u16* __restrict__ Bt, int nM, char* shm,
;                            u16* __restrict__ outp, float* __restrict__ rowss) {
;     ...
;       LDB(B1, 1, 1); STAGE(SB(1, 0), B0p, t + 3);
;       BAR; WAIT_L(0); MMA(0, 1, At, B1); BAR;
;       LDA(At, 1, 1); STAGE(SA(1, 0), A0, t + 3);
;       BAR; WAIT_L(0); MMA(1, 0, At, B0); BAR; SBAR();
;       STAGE(SB(1, 1), B1p, t + 3);
;       WAIT_V(6); BAR; MMA(1, 1, At, B1); BAR;
;     }
;     { LDB(B0, 0, 0); LDA(At, 0, 0); STAGE(SA(1, 1), A1, nt - 1);
	s_mov_b32 m0, s35
	v_or_b32_e32 v159, 0x1c000, v143
	v_add_u32_e32 v161, 0x1c100, v143
	v_add_u32_e32 v163, 0x180, v196
	v_add_u32_e32 v160, 0x1c400, v143
	ds_read_b128 v[236:239], v159
	ds_read_b128 v[240:243], v160
	v_add_u32_e32 v162, 0x1c500, v143
	ds_read_b128 v[244:247], v161
	ds_read_b128 v[248:251], v162
	global_load_lds_dwordx4 v163, s[6:7]
	v_add_u32_e32 v196, 0x180, v197
	s_mov_b32 m0, s93
	s_nop 0
	global_load_lds_dwordx4 v196, s[6:7]
	s_barrier
	s_waitcnt lgkmcnt(0)
	s_waitcnt lgkmcnt(0)
	v_mfma_f32_16x16x32_bf16 v[92:95], v[236:239], v[180:183], v[92:95]
	v_mfma_f32_16x16x32_bf16 v[88:91], v[244:247], v[180:183], v[88:91]
	v_mfma_f32_16x16x32_bf16 v[84:87], v[236:239], v[212:215], v[84:87]
	v_mfma_f32_16x16x32_bf16 v[80:83], v[244:247], v[212:215], v[80:83]
	v_mfma_f32_16x16x32_bf16 v[76:79], v[236:239], v[220:223], v[76:79]
	v_mfma_f32_16x16x32_bf16 v[72:75], v[244:247], v[220:223], v[72:75]
	v_mfma_f32_16x16x32_bf16 v[68:71], v[236:239], v[228:231], v[68:71]
	v_mfma_f32_16x16x32_bf16 v[64:67], v[244:247], v[228:231], v[64:67]
	v_mfma_f32_16x16x32_bf16 v[92:95], v[240:243], v[208:211], v[92:95]
	v_mfma_f32_16x16x32_bf16 v[88:91], v[248:251], v[208:211], v[88:91]
	v_mfma_f32_16x16x32_bf16 v[84:87], v[240:243], v[216:219], v[84:87]
	v_mfma_f32_16x16x32_bf16 v[80:83], v[248:251], v[216:219], v[80:83]
	v_mfma_f32_16x16x32_bf16 v[76:79], v[240:243], v[224:227], v[76:79]
	v_mfma_f32_16x16x32_bf16 v[72:75], v[248:251], v[224:227], v[72:75]
	v_mfma_f32_16x16x32_bf16 v[68:71], v[240:243], v[232:235], v[68:71]
	v_mfma_f32_16x16x32_bf16 v[64:67], v[248:251], v[232:235], v[64:67]
	s_mov_b32 m0, s24
	s_barrier
	ds_read_b128 v[180:183], v144 offset:49152
	ds_read_b128 v[208:211], v144 offset:50176
	ds_read_b128 v[212:215], v144 offset:51200
	ds_read_b128 v[216:219], v144 offset:52224
	ds_read_b128 v[220:223], v144 offset:53248
	ds_read_b128 v[224:227], v144 offset:54272
	ds_read_b128 v[228:231], v144 offset:55296
	ds_read_b128 v[232:235], v144 offset:56320
	global_load_lds_dwordx4 v163, s[8:9]
	s_mov_b32 m0, s25
	s_nop 0
	global_load_lds_dwordx4 v196, s[8:9]
	s_barrier
	s_waitcnt lgkmcnt(0)
	s_waitcnt lgkmcnt(0)
	v_mfma_f32_16x16x32_bf16 v[60:63], v[164:167], v[180:183], v[60:63]
	v_mfma_f32_16x16x32_bf16 v[56:59], v[172:175], v[180:183], v[56:59]
	v_mfma_f32_16x16x32_bf16 v[52:55], v[164:167], v[212:215], v[52:55]
	v_mfma_f32_16x16x32_bf16 v[48:51], v[172:175], v[212:215], v[48:51]
	v_mfma_f32_16x16x32_bf16 v[44:47], v[164:167], v[220:223], v[44:47]
	v_mfma_f32_16x16x32_bf16 v[40:43], v[172:175], v[220:223], v[40:43]
	v_mfma_f32_16x16x32_bf16 v[36:39], v[164:167], v[228:231], v[36:39]
	v_mfma_f32_16x16x32_bf16 v[32:35], v[172:175], v[228:231], v[32:35]
	v_mfma_f32_16x16x32_bf16 v[60:63], v[168:171], v[208:211], v[60:63]
	v_mfma_f32_16x16x32_bf16 v[56:59], v[176:179], v[208:211], v[56:59]
	v_mfma_f32_16x16x32_bf16 v[52:55], v[168:171], v[216:219], v[52:55]
	v_mfma_f32_16x16x32_bf16 v[48:51], v[176:179], v[216:219], v[48:51]
	v_mfma_f32_16x16x32_bf16 v[44:47], v[168:171], v[224:227], v[44:47]
	v_mfma_f32_16x16x32_bf16 v[40:43], v[176:179], v[224:227], v[40:43]
	v_mfma_f32_16x16x32_bf16 v[36:39], v[168:171], v[232:235], v[36:39]
	v_mfma_f32_16x16x32_bf16 v[32:35], v[176:179], v[232:235], v[32:35]
	s_barrier
	s_mov_b32 m0, s26
	s_nop 0
	global_load_lds_dwordx4 v163, s[16:17]
	s_mov_b32 m0, s27
	s_nop 0
	global_load_lds_dwordx4 v196, s[16:17]
	s_waitcnt vmcnt(6)
	s_barrier
	v_mfma_f32_16x16x32_bf16 v[28:31], v[236:239], v[180:183], v[28:31]
	v_mfma_f32_16x16x32_bf16 v[24:27], v[244:247], v[180:183], v[24:27]
	v_mfma_f32_16x16x32_bf16 v[20:23], v[236:239], v[212:215], v[20:23]
	v_mfma_f32_16x16x32_bf16 v[16:19], v[244:247], v[212:215], v[16:19]
	v_mfma_f32_16x16x32_bf16 v[12:15], v[236:239], v[220:223], v[12:15]
	v_mfma_f32_16x16x32_bf16 v[8:11], v[244:247], v[220:223], v[8:11]
	v_mfma_f32_16x16x32_bf16 v[4:7], v[236:239], v[228:231], v[4:7]
	v_mfma_f32_16x16x32_bf16 v[0:3], v[244:247], v[228:231], v[0:3]
	v_mfma_f32_16x16x32_bf16 v[28:31], v[240:243], v[208:211], v[28:31]
	v_mfma_f32_16x16x32_bf16 v[24:27], v[248:251], v[208:211], v[24:27]
	v_mfma_f32_16x16x32_bf16 v[20:23], v[240:243], v[216:219], v[20:23]
	v_mfma_f32_16x16x32_bf16 v[16:19], v[248:251], v[216:219], v[16:19]
	v_mfma_f32_16x16x32_bf16 v[12:15], v[240:243], v[224:227], v[12:15]
	v_mfma_f32_16x16x32_bf16 v[8:11], v[248:251], v[224:227], v[8:11]
	v_mfma_f32_16x16x32_bf16 v[4:7], v[240:243], v[232:235], v[4:7]
	v_mfma_f32_16x16x32_bf16 v[0:3], v[248:251], v[232:235], v[0:3]
	s_add_i32 s53, s53, 2
	v_add_u32_e32 v141, 0x100, v141
	s_cmp_lt_u32 s53, 12
	v_add_u32_e32 v140, 0x100, v140
	s_barrier
	s_cbranch_scc1 .LBB0_553
	s_mov_b32 m0, s55
	v_lshl_add_u64 v[140:141], s[14:15], 0, v[136:137]
	ds_read_b128 v[164:167], v147
	ds_read_b128 v[168:171], v148
	ds_read_b128 v[172:175], v149
	ds_read_b128 v[176:179], v150
	ds_read_b128 v[180:183], v144
	ds_read_b128 v[208:211], v144 offset:1024
	ds_read_b128 v[212:215], v144 offset:2048
	ds_read_b128 v[216:219], v144 offset:3072
	ds_read_b128 v[220:223], v144 offset:4096
	ds_read_b128 v[224:227], v144 offset:5120
	ds_read_b128 v[228:231], v144 offset:6144
	ds_read_b128 v[232:235], v144 offset:7168
	global_load_lds_dwordx4 v[140:141], off
	v_lshl_add_u64 v[140:141], s[14:15], 0, v[138:139]
	s_mov_b32 m0, s54
	s_nop 0
	global_load_lds_dwordx4 v[140:141], off
	s_barrier
; #define WAIT_V(n) asm volatile("s_waitcnt vmcnt(%0)" ::"n"(n) : "memory")
; #define WAIT_L(n) asm volatile("s_waitcnt lgkmcnt(%0)" ::"n"(n) : "memory")
; #define STAGE(P, base, kt) do { _Pragma("unroll") for (int _i = 0; _i < 2; ++_i)                                        \
;       __builtin_amdgcn_global_load_lds((const unsigned*)((base) + (size_t)(sOff[_i] + (unsigned)(kt) * (BK * 2))),        \
;                                        (unsigned*)((P) + wid * 1024 + _i * 8192), 16, 0, 0); } while (0)
; #define LDA(dst, b, h) _Pragma("unroll") for (int m = 0; m < 4; ++m) _Pragma("unroll") for (int k = 0; k < 2; ++k) \
;       dst[m][k] = *(const bf16x8*)(SA(b, h) + aoff + (m * 2048 + k * 1024))
; #define LDB(dst, b, h) _Pragma("unroll") for (int n = 0; n < 2; ++n) _Pragma("unroll") for (int k = 0; k < 2; ++k) \
;       dst[n][k] = *(const bf16x8*)(SB(b, h) + boff + (n * 256 + k * 1024))
; #define BAR __builtin_amdgcn_s_barrier()
; template <int EPI, int N, int K>
; __device__ __forceinline__ void phase_gemm(const Params& p, const u16* __restrict__ A, const u16* __restrict__ Bt, int nM, char* shm,
;                            u16* __restrict__ outp, float* __restrict__ rowss) {
;     ...
;     { LDB(B0, 0, 0); LDA(At, 0, 0); STAGE(SA(1, 1), A1, nt - 1);
;       BAR; WAIT_L(0); MMA(0, 0, At, B0); BAR;
;       LDB(B1, 0, 1); BAR; WAIT_L(0); MMA(0, 1, At, B1); BAR;
;       LDA(At, 0, 1); WAIT_V(4); BAR; WAIT_L(0); MMA(1, 0, At, B0); MMA(1, 1, At, B1); BAR; }
	s_waitcnt lgkmcnt(0)
	s_waitcnt lgkmcnt(0)
	v_mfma_f32_16x16x32_bf16 v[126:129], v[164:167], v[180:183], v[126:129]
	v_mfma_f32_16x16x32_bf16 v[118:121], v[164:167], v[212:215], v[118:121]
	v_mfma_f32_16x16x32_bf16 v[110:113], v[164:167], v[220:223], v[110:113]
	v_mfma_f32_16x16x32_bf16 v[102:105], v[164:167], v[228:231], v[102:105]
	v_mfma_f32_16x16x32_bf16 v[126:129], v[168:171], v[208:211], v[126:129]
	v_mfma_f32_16x16x32_bf16 v[122:125], v[172:175], v[180:183], v[122:125]
	v_mfma_f32_16x16x32_bf16 v[118:121], v[168:171], v[216:219], v[118:121]
	v_mfma_f32_16x16x32_bf16 v[114:117], v[172:175], v[212:215], v[114:117]
	v_mfma_f32_16x16x32_bf16 v[110:113], v[168:171], v[224:227], v[110:113]
	v_mfma_f32_16x16x32_bf16 v[106:109], v[172:175], v[220:223], v[106:109]
	v_mfma_f32_16x16x32_bf16 v[102:105], v[168:171], v[232:235], v[102:105]
	v_mfma_f32_16x16x32_bf16 v[98:101], v[172:175], v[228:231], v[98:101]
	v_mfma_f32_16x16x32_bf16 v[236:239], v[176:179], v[208:211], v[122:125]
	v_mfma_f32_16x16x32_bf16 v[240:243], v[176:179], v[216:219], v[114:117]
	v_mfma_f32_16x16x32_bf16 v[244:247], v[176:179], v[224:227], v[106:109]
	v_mfma_f32_16x16x32_bf16 v[248:251], v[176:179], v[232:235], v[98:101]
	s_barrier
	s_nop 1
	ds_read_b128 v[98:101], v151
	ds_read_b128 v[106:109], v152
	ds_read_b128 v[114:117], v153
	ds_read_b128 v[122:125], v154
	s_barrier
	s_waitcnt lgkmcnt(0)
	s_waitcnt lgkmcnt(0)
	v_mfma_f32_16x16x32_bf16 v[92:95], v[98:101], v[180:183], v[92:95]
	v_mfma_f32_16x16x32_bf16 v[84:87], v[98:101], v[212:215], v[84:87]
	v_mfma_f32_16x16x32_bf16 v[76:79], v[98:101], v[220:223], v[76:79]
	v_mfma_f32_16x16x32_bf16 v[68:71], v[98:101], v[228:231], v[68:71]
	v_mfma_f32_16x16x32_bf16 v[92:95], v[106:109], v[208:211], v[92:95]
	v_mfma_f32_16x16x32_bf16 v[88:91], v[114:117], v[180:183], v[88:91]
	v_mfma_f32_16x16x32_bf16 v[84:87], v[106:109], v[216:219], v[84:87]
	v_mfma_f32_16x16x32_bf16 v[80:83], v[114:117], v[212:215], v[80:83]
	v_mfma_f32_16x16x32_bf16 v[76:79], v[106:109], v[224:227], v[76:79]
	v_mfma_f32_16x16x32_bf16 v[72:75], v[114:117], v[220:223], v[72:75]
	v_mfma_f32_16x16x32_bf16 v[68:71], v[106:109], v[232:235], v[68:71]
	v_mfma_f32_16x16x32_bf16 v[64:67], v[114:117], v[228:231], v[64:67]
	v_mfma_f32_16x16x32_bf16 v[148:151], v[122:125], v[208:211], v[88:91]
	v_mfma_f32_16x16x32_bf16 v[180:183], v[122:125], v[216:219], v[80:83]
	v_mfma_f32_16x16x32_bf16 v[208:211], v[122:125], v[224:227], v[72:75]
	v_mfma_f32_16x16x32_bf16 v[212:215], v[122:125], v[232:235], v[64:67]
	s_barrier
	s_nop 1
	ds_read_b128 v[64:67], v144 offset:16384
	ds_read_b128 v[72:75], v144 offset:17408
	ds_read_b128 v[80:83], v144 offset:18432
	ds_read_b128 v[88:91], v144 offset:19456
	ds_read_b128 v[216:219], v144 offset:20480
	ds_read_b128 v[220:223], v144 offset:21504
	ds_read_b128 v[224:227], v144 offset:22528
	ds_read_b128 v[228:231], v144 offset:23552
	s_waitcnt vmcnt(4)
	s_barrier
	s_waitcnt lgkmcnt(0)
	s_waitcnt lgkmcnt(0)
	v_mfma_f32_16x16x32_bf16 v[60:63], v[164:167], v[64:67], v[60:63]
	v_mfma_f32_16x16x32_bf16 v[52:55], v[164:167], v[80:83], v[52:55]
	v_mfma_f32_16x16x32_bf16 v[44:47], v[164:167], v[216:219], v[44:47]
	v_mfma_f32_16x16x32_bf16 v[36:39], v[164:167], v[224:227], v[36:39]
	v_mfma_f32_16x16x32_bf16 v[60:63], v[168:171], v[72:75], v[60:63]
	v_mfma_f32_16x16x32_bf16 v[56:59], v[172:175], v[64:67], v[56:59]
	v_mfma_f32_16x16x32_bf16 v[52:55], v[168:171], v[88:91], v[52:55]
	v_mfma_f32_16x16x32_bf16 v[48:51], v[172:175], v[80:83], v[48:51]
	v_mfma_f32_16x16x32_bf16 v[44:47], v[168:171], v[220:223], v[44:47]
	v_mfma_f32_16x16x32_bf16 v[40:43], v[172:175], v[216:219], v[40:43]
	v_mfma_f32_16x16x32_bf16 v[36:39], v[168:171], v[228:231], v[36:39]
	v_mfma_f32_16x16x32_bf16 v[32:35], v[172:175], v[224:227], v[32:35]
	v_mfma_f32_16x16x32_bf16 v[232:235], v[176:179], v[72:75], v[56:59]
	v_mfma_f32_16x16x32_bf16 v[196:199], v[176:179], v[88:91], v[48:51]
	v_mfma_f32_16x16x32_bf16 v[200:203], v[176:179], v[220:223], v[40:43]
	v_mfma_f32_16x16x32_bf16 v[164:167], v[176:179], v[228:231], v[32:35]
	v_mfma_f32_16x16x32_bf16 v[28:31], v[98:101], v[64:67], v[28:31]
	v_mfma_f32_16x16x32_bf16 v[20:23], v[98:101], v[80:83], v[20:23]
	v_mfma_f32_16x16x32_bf16 v[12:15], v[98:101], v[216:219], v[12:15]
	v_mfma_f32_16x16x32_bf16 v[4:7], v[98:101], v[224:227], v[4:7]
	v_mfma_f32_16x16x32_bf16 v[28:31], v[106:109], v[72:75], v[28:31]
	v_mfma_f32_16x16x32_bf16 v[24:27], v[114:117], v[64:67], v[24:27]
	v_mfma_f32_16x16x32_bf16 v[20:23], v[106:109], v[88:91], v[20:23]
	v_mfma_f32_16x16x32_bf16 v[16:19], v[114:117], v[80:83], v[16:19]
	v_mfma_f32_16x16x32_bf16 v[12:15], v[106:109], v[220:223], v[12:15]
	v_mfma_f32_16x16x32_bf16 v[8:11], v[114:117], v[216:219], v[8:11]
	v_mfma_f32_16x16x32_bf16 v[4:7], v[106:109], v[228:231], v[4:7]
	v_mfma_f32_16x16x32_bf16 v[0:3], v[114:117], v[224:227], v[0:3]
	v_mfma_f32_16x16x32_bf16 v[168:171], v[122:125], v[72:75], v[24:27]
	v_mfma_f32_16x16x32_bf16 v[172:175], v[122:125], v[88:91], v[16:19]
	v_mfma_f32_16x16x32_bf16 v[176:179], v[122:125], v[220:223], v[8:11]
	v_mfma_f32_16x16x32_bf16 v[216:219], v[122:125], v[228:231], v[0:3]
	s_barrier
; #define WAIT_V(n) asm volatile("s_waitcnt vmcnt(%0)" ::"n"(n) : "memory")
; #define WAIT_L(n) asm volatile("s_waitcnt lgkmcnt(%0)" ::"n"(n) : "memory")
; #define LDA(dst, b, h) _Pragma("unroll") for (int m = 0; m < 4; ++m) _Pragma("unroll") for (int k = 0; k < 2; ++k) \
;       dst[m][k] = *(const bf16x8*)(SA(b, h) + aoff + (m * 2048 + k * 1024))
; #define LDB(dst, b, h) _Pragma("unroll") for (int n = 0; n < 2; ++n) _Pragma("unroll") for (int k = 0; k < 2; ++k) \
;       dst[n][k] = *(const bf16x8*)(SB(b, h) + boff + (n * 256 + k * 1024))
; #define BAR __builtin_amdgcn_s_barrier()
; template <int EPI, int N, int K>
; __device__ __forceinline__ void phase_gemm(const Params& p, const u16* __restrict__ A, const u16* __restrict__ Bt, int nM, char* shm,
;                            u16* __restrict__ outp, float* __restrict__ rowss) {
;     ...
;     { LDB(B0, 1, 0); LDA(At, 1, 0); WAIT_V(2); BAR; WAIT_L(0); MMA(0, 0, At, B0); BAR;
;       LDB(B1, 1, 1); WAIT_V(0); BAR; WAIT_L(0); MMA(0, 1, At, B1); BAR;
;       LDA(At, 1, 1); BAR; WAIT_L(0); MMA(1, 0, At, B0); MMA(1, 1, At, B1); BAR; }
;     if (wr == 0) BAR;
	s_nop 1
	ds_read_b128 v[0:3], v155
	ds_read_b128 v[8:11], v156
	ds_read_b128 v[152:155], v157
	ds_read_b128 v[220:223], v158
	ds_read_b128 v[16:19], v144 offset:32768
	ds_read_b128 v[24:27], v144 offset:33792
	ds_read_b128 v[32:35], v144 offset:34816
	ds_read_b128 v[40:43], v144 offset:35840
	ds_read_b128 v[48:51], v144 offset:36864
	ds_read_b128 v[56:59], v144 offset:37888
	ds_read_b128 v[224:227], v144 offset:38912
	ds_read_b128 v[228:231], v144 offset:39936
	s_waitcnt vmcnt(2)
	s_barrier
	s_waitcnt lgkmcnt(0)
	s_waitcnt lgkmcnt(0)
	v_mfma_f32_16x16x32_bf16 v[64:67], v[0:3], v[16:19], v[126:129]
	v_mfma_f32_16x16x32_bf16 v[122:125], v[8:11], v[24:27], v[64:67]
	v_mfma_f32_16x16x32_bf16 v[64:67], v[152:155], v[16:19], v[236:239]
	v_mfma_f32_16x16x32_bf16 v[114:117], v[220:223], v[24:27], v[64:67]
	v_mfma_f32_16x16x32_bf16 v[64:67], v[0:3], v[32:35], v[118:121]
	v_mfma_f32_16x16x32_bf16 v[106:109], v[8:11], v[40:43], v[64:67]
	v_mfma_f32_16x16x32_bf16 v[64:67], v[152:155], v[32:35], v[240:243]
	v_mfma_f32_16x16x32_bf16 v[98:101], v[220:223], v[40:43], v[64:67]
	v_mfma_f32_16x16x32_bf16 v[64:67], v[0:3], v[48:51], v[110:113]
	v_mfma_f32_16x16x32_bf16 v[88:91], v[8:11], v[56:59], v[64:67]
	v_mfma_f32_16x16x32_bf16 v[64:67], v[152:155], v[48:51], v[244:247]
	v_mfma_f32_16x16x32_bf16 v[80:83], v[220:223], v[56:59], v[64:67]
	v_mfma_f32_16x16x32_bf16 v[64:67], v[0:3], v[224:227], v[102:105]
	v_mfma_f32_16x16x32_bf16 v[72:75], v[8:11], v[228:231], v[64:67]
	v_mfma_f32_16x16x32_bf16 v[64:67], v[152:155], v[224:227], v[248:251]
	v_mfma_f32_16x16x32_bf16 v[64:67], v[220:223], v[228:231], v[64:67]
	s_barrier
	ds_read_b128 v[156:159], v159
	ds_read_b128 v[236:239], v160
	ds_read_b128 v[240:243], v161
	ds_read_b128 v[160:163], v162
	s_waitcnt vmcnt(0)
	s_barrier
	s_waitcnt lgkmcnt(0)
	s_waitcnt lgkmcnt(0)
	v_mfma_f32_16x16x32_bf16 v[92:95], v[156:159], v[16:19], v[92:95]
	v_mfma_f32_16x16x32_bf16 v[16:19], v[240:243], v[16:19], v[148:151]
	v_mfma_f32_16x16x32_bf16 v[118:121], v[160:163], v[24:27], v[16:19]
	v_mfma_f32_16x16x32_bf16 v[16:19], v[156:159], v[32:35], v[84:87]
	v_mfma_f32_16x16x32_bf16 v[110:113], v[236:239], v[40:43], v[16:19]
	v_mfma_f32_16x16x32_bf16 v[16:19], v[240:243], v[32:35], v[180:183]
	v_mfma_f32_16x16x32_bf16 v[102:105], v[160:163], v[40:43], v[16:19]
	v_mfma_f32_16x16x32_bf16 v[16:19], v[156:159], v[48:51], v[76:79]
	v_mfma_f32_16x16x32_bf16 v[126:129], v[236:239], v[24:27], v[92:95]
	v_mfma_f32_16x16x32_bf16 v[92:95], v[236:239], v[56:59], v[16:19]
	v_mfma_f32_16x16x32_bf16 v[16:19], v[240:243], v[48:51], v[208:211]
	v_mfma_f32_16x16x32_bf16 v[84:87], v[160:163], v[56:59], v[16:19]
	v_mfma_f32_16x16x32_bf16 v[16:19], v[156:159], v[224:227], v[68:71]
	v_mfma_f32_16x16x32_bf16 v[76:79], v[236:239], v[228:231], v[16:19]
	v_mfma_f32_16x16x32_bf16 v[16:19], v[240:243], v[224:227], v[212:215]
	v_mfma_f32_16x16x32_bf16 v[68:71], v[160:163], v[228:231], v[16:19]
	s_barrier
	ds_read_b128 v[148:151], v144 offset:49152
	ds_read_b128 v[180:183], v144 offset:50176
	ds_read_b128 v[208:211], v144 offset:51200
	ds_read_b128 v[212:215], v144 offset:52224
	ds_read_b128 v[224:227], v144 offset:53248
	ds_read_b128 v[228:231], v144 offset:54272
	ds_read_b128 v[244:247], v144 offset:55296
	ds_read_b128 v[248:251], v144 offset:56320
	s_barrier
	s_waitcnt lgkmcnt(0)
	s_waitcnt lgkmcnt(0)
	v_mfma_f32_16x16x32_bf16 v[16:19], v[0:3], v[148:151], v[60:63]
	v_mfma_f32_16x16x32_bf16 v[56:59], v[8:11], v[180:183], v[16:19]
	v_mfma_f32_16x16x32_bf16 v[16:19], v[152:155], v[148:151], v[232:235]
	v_mfma_f32_16x16x32_bf16 v[48:51], v[220:223], v[180:183], v[16:19]
	v_mfma_f32_16x16x32_bf16 v[16:19], v[0:3], v[208:211], v[52:55]
	v_mfma_f32_16x16x32_bf16 v[40:43], v[8:11], v[212:215], v[16:19]
	v_mfma_f32_16x16x32_bf16 v[16:19], v[152:155], v[208:211], v[196:199]
	v_mfma_f32_16x16x32_bf16 v[32:35], v[220:223], v[212:215], v[16:19]
	v_mfma_f32_16x16x32_bf16 v[16:19], v[0:3], v[224:227], v[44:47]
	v_mfma_f32_16x16x32_bf16 v[0:3], v[0:3], v[244:247], v[36:39]
	v_mfma_f32_16x16x32_bf16 v[24:27], v[8:11], v[228:231], v[16:19]
	v_mfma_f32_16x16x32_bf16 v[16:19], v[152:155], v[224:227], v[200:203]
	v_mfma_f32_16x16x32_bf16 v[8:11], v[8:11], v[248:251], v[0:3]
	v_mfma_f32_16x16x32_bf16 v[0:3], v[152:155], v[244:247], v[164:167]
	v_mfma_f32_16x16x32_bf16 v[16:19], v[220:223], v[228:231], v[16:19]
	v_mfma_f32_16x16x32_bf16 v[0:3], v[220:223], v[248:251], v[0:3]
	v_mfma_f32_16x16x32_bf16 v[28:31], v[156:159], v[148:151], v[28:31]
	v_mfma_f32_16x16x32_bf16 v[60:63], v[236:239], v[180:183], v[28:31]
	v_mfma_f32_16x16x32_bf16 v[28:31], v[240:243], v[148:151], v[168:171]
	v_mfma_f32_16x16x32_bf16 v[20:23], v[156:159], v[208:211], v[20:23]
	v_mfma_f32_16x16x32_bf16 v[12:15], v[156:159], v[224:227], v[12:15]
	v_mfma_f32_16x16x32_bf16 v[52:55], v[160:163], v[180:183], v[28:31]
	v_mfma_f32_16x16x32_bf16 v[44:47], v[236:239], v[212:215], v[20:23]
	v_mfma_f32_16x16x32_bf16 v[20:23], v[240:243], v[208:211], v[172:175]
	v_mfma_f32_16x16x32_bf16 v[28:31], v[236:239], v[228:231], v[12:15]
	v_mfma_f32_16x16x32_bf16 v[12:15], v[240:243], v[224:227], v[176:179]
	v_mfma_f32_16x16x32_bf16 v[4:7], v[156:159], v[244:247], v[4:7]
	v_mfma_f32_16x16x32_bf16 v[36:39], v[160:163], v[212:215], v[20:23]
	v_mfma_f32_16x16x32_bf16 v[20:23], v[160:163], v[228:231], v[12:15]
	v_mfma_f32_16x16x32_bf16 v[12:15], v[236:239], v[248:251], v[4:7]
	v_mfma_f32_16x16x32_bf16 v[4:7], v[240:243], v[244:247], v[216:219]
	v_mfma_f32_16x16x32_bf16 v[4:7], v[160:163], v[248:251], v[4:7]
	s_andn2_b64 vcc, exec, s[12:13]
	s_barrier
	s_cbranch_vccnz .LBB0_556
	s_barrier
